# first-trip copies: MFMAs also issued as accumulate chains of two (k0 with srcC=0, then k1 on the same accumulator)
# speedup vs baseline: 1.0050x; 1.0001x over previous
.LBB0_74:
	s_ashr_i32 s27, s26, 31
	s_lshl_b64 s[28:29], s[26:27], 19
	s_add_u32 s28, s3, s28
	s_addc_u32 s29, s35, s29
	s_and_b64 s[30:31], s[4:5], exec
	s_cselect_b32 s27, s29, s49
	s_cselect_b32 s68, s28, s48
	s_ashr_i32 s23, s22, 31
	s_lshl_b64 s[30:31], s[22:23], 19
	s_add_u32 s30, s50, s30
	s_addc_u32 s31, s51, s31
	s_and_b64 s[70:71], s[4:5], exec
	s_cselect_b32 s69, s31, s47
	s_cselect_b32 s70, s30, s46
	s_lshl_b32 s23, s44, 8
	v_add_u32_e32 v0, s23, v148
	s_add_u32 s71, s46, 0x100
	v_ashrrev_i32_e32 v1, 31, v0
	s_addc_u32 s74, s47, 0
	v_lshl_add_u64 v[144:145], v[0:1], 4, s[12:13]
	s_add_u32 s44, s48, 0x40080
	s_addc_u32 s45, s49, 0
	s_mov_b32 s75, -2
	s_mov_b64 s[46:47], 0
	s_cmp_eq_u32 s59, 1
	s_cbranch_scc1 .Lfa_0
	v_add_u32_e32 v153, s64, v147
	ds_read_b128 v[160:163], v153
	v_xor_b32_e32 v253, 64, v153
	ds_read_b128 v[164:167], v253
	ds_read_b128 v[168:171], v153 offset:2048
	ds_read_b128 v[172:175], v253 offset:2048
	v_add_u32_e32 v153, s65, v147
	ds_read_b128 v[176:179], v153
	v_xor_b32_e32 v253, 64, v153
	ds_read_b128 v[180:183], v253
	ds_read_b128 v[186:189], v153 offset:2048
	ds_read_b128 v[190:193], v253 offset:2048
	s_add_u32 s48, s44, 0xfffc0080
	s_addc_u32 s49, s45, -1
	s_and_b64 s[46:47], s[46:47], exec
	s_cselect_b32 s49, s27, s49
	s_cselect_b32 s48, s68, s48
	s_cselect_b32 s47, s69, s74
	s_cselect_b32 s46, s70, s71
	v_lshl_add_u64 v[154:155], s[44:45], 0, v[138:139]
	s_add_i32 m0, s55, 0xc000
	ds_read_b128 v[194:197], v150
	v_xor_b32_e32 v253, 64, v150
	ds_read_b128 v[198:201], v253
	ds_read_b128 v[202:205], v150 offset:2048
	ds_read_b128 v[206:209], v253 offset:2048
	ds_read_b128 v[210:213], v150 offset:4096
	ds_read_b128 v[214:217], v253 offset:4096
	ds_read_b128 v[218:221], v150 offset:6144
	ds_read_b128 v[222:225], v253 offset:6144
	global_load_lds_dwordx4 v[154:155], off
	v_lshl_add_u64 v[154:155], s[44:45], 0, v[136:137]
	s_add_i32 m0, s55, 0xe000
	s_nop 0
	global_load_lds_dwordx4 v[154:155], off
	s_waitcnt vmcnt(16)
	s_waitcnt lgkmcnt(0)
	s_setprio 1
	s_barrier
	v_mfma_f32_16x16x32_bf16 v[124:127], v[160:163], v[194:197], 0
	v_mfma_f32_16x16x32_bf16 v[124:127], v[164:167], v[198:201], v[124:127]
	v_mfma_f32_16x16x32_bf16 v[116:119], v[168:171], v[194:197], 0
	v_mfma_f32_16x16x32_bf16 v[116:119], v[172:175], v[198:201], v[116:119]
	v_mfma_f32_16x16x32_bf16 v[108:111], v[160:163], v[202:205], 0
	v_mfma_f32_16x16x32_bf16 v[108:111], v[164:167], v[206:209], v[108:111]
	v_mfma_f32_16x16x32_bf16 v[100:103], v[168:171], v[202:205], 0
	v_mfma_f32_16x16x32_bf16 v[100:103], v[172:175], v[206:209], v[100:103]
	v_mfma_f32_16x16x32_bf16 v[92:95], v[160:163], v[210:213], 0
	v_mfma_f32_16x16x32_bf16 v[92:95], v[164:167], v[214:217], v[92:95]
	v_mfma_f32_16x16x32_bf16 v[84:87], v[168:171], v[210:213], 0
	v_mfma_f32_16x16x32_bf16 v[84:87], v[172:175], v[214:217], v[84:87]
	v_mfma_f32_16x16x32_bf16 v[76:79], v[160:163], v[218:221], 0
	v_mfma_f32_16x16x32_bf16 v[76:79], v[164:167], v[222:225], v[76:79]
	v_mfma_f32_16x16x32_bf16 v[68:71], v[168:171], v[218:221], 0
	v_mfma_f32_16x16x32_bf16 v[68:71], v[172:175], v[222:225], v[68:71]
	s_setprio 0
	s_setprio 1
	v_mfma_f32_16x16x32_bf16 v[120:123], v[176:179], v[194:197], 0
	v_mfma_f32_16x16x32_bf16 v[120:123], v[180:183], v[198:201], v[120:123]
	v_mfma_f32_16x16x32_bf16 v[112:115], v[186:189], v[194:197], 0
	v_mfma_f32_16x16x32_bf16 v[112:115], v[190:193], v[198:201], v[112:115]
	v_mfma_f32_16x16x32_bf16 v[104:107], v[176:179], v[202:205], 0
	v_mfma_f32_16x16x32_bf16 v[104:107], v[180:183], v[206:209], v[104:107]
	v_mfma_f32_16x16x32_bf16 v[96:99], v[186:189], v[202:205], 0
	v_mfma_f32_16x16x32_bf16 v[96:99], v[190:193], v[206:209], v[96:99]
	v_mfma_f32_16x16x32_bf16 v[88:91], v[176:179], v[210:213], 0
	v_mfma_f32_16x16x32_bf16 v[88:91], v[180:183], v[214:217], v[88:91]
	v_mfma_f32_16x16x32_bf16 v[80:83], v[186:189], v[210:213], 0
	v_mfma_f32_16x16x32_bf16 v[80:83], v[190:193], v[214:217], v[80:83]
	v_mfma_f32_16x16x32_bf16 v[72:75], v[176:179], v[218:221], 0
	v_mfma_f32_16x16x32_bf16 v[72:75], v[180:183], v[222:225], v[72:75]
	v_mfma_f32_16x16x32_bf16 v[64:67], v[186:189], v[218:221], 0
	v_mfma_f32_16x16x32_bf16 v[64:67], v[190:193], v[222:225], v[64:67]
	s_barrier
	s_setprio 0
	s_add_i32 s76, s64, s52
	v_lshl_add_u64 v[154:155], s[46:47], 0, v[132:133]
	s_mov_b32 m0, s76
	ds_read_b128 v[194:197], v150 offset:16384
	v_xor_b32_e32 v253, 64, v150
	ds_read_b128 v[198:201], v253 offset:16384
	ds_read_b128 v[202:205], v150 offset:18432
	ds_read_b128 v[206:209], v253 offset:18432
	ds_read_b128 v[210:213], v150 offset:20480
	ds_read_b128 v[214:217], v253 offset:20480
	ds_read_b128 v[218:221], v150 offset:22528
	ds_read_b128 v[222:225], v253 offset:22528
	global_load_lds_dwordx4 v[154:155], off
	s_add_i32 m0, s76, 0x2000
	s_add_u32 s76, s46, 0x40000
	v_lshl_add_u64 v[226:227], s[46:47], 0, v[128:129]
	s_addc_u32 s77, s47, 0
	s_add_i32 s78, s65, s52
	global_load_lds_dwordx4 v[226:227], off
	v_lshl_add_u64 v[228:229], s[76:77], 0, v[132:133]
	s_mov_b32 m0, s78
	v_lshl_add_u64 v[230:231], s[48:49], 0, v[130:131]
	global_load_lds_dwordx4 v[228:229], off
	v_lshl_add_u64 v[228:229], s[76:77], 0, v[128:129]
	s_add_i32 m0, s78, 0x2000
	s_nop 0
	global_load_lds_dwordx4 v[228:229], off
	v_lshl_add_u64 v[228:229], s[48:49], 0, v[134:135]
	s_mov_b32 m0, s55
	s_nop 0
	global_load_lds_dwordx4 v[228:229], off
	s_mov_b32 m0, s56
	s_nop 0
	global_load_lds_dwordx4 v[230:231], off
	s_waitcnt vmcnt(16)
	s_waitcnt lgkmcnt(0)
	s_setprio 1
	s_barrier
	v_mfma_f32_16x16x32_bf16 v[60:63], v[160:163], v[194:197], 0
	v_mfma_f32_16x16x32_bf16 v[60:63], v[164:167], v[198:201], v[60:63]
	v_mfma_f32_16x16x32_bf16 v[52:55], v[168:171], v[194:197], 0
	v_mfma_f32_16x16x32_bf16 v[52:55], v[172:175], v[198:201], v[52:55]
	v_mfma_f32_16x16x32_bf16 v[44:47], v[160:163], v[202:205], 0
	v_mfma_f32_16x16x32_bf16 v[44:47], v[164:167], v[206:209], v[44:47]
	v_mfma_f32_16x16x32_bf16 v[36:39], v[168:171], v[202:205], 0
	v_mfma_f32_16x16x32_bf16 v[36:39], v[172:175], v[206:209], v[36:39]
	v_mfma_f32_16x16x32_bf16 v[28:31], v[160:163], v[210:213], 0
	v_mfma_f32_16x16x32_bf16 v[28:31], v[164:167], v[214:217], v[28:31]
	v_mfma_f32_16x16x32_bf16 v[20:23], v[168:171], v[210:213], 0
	v_mfma_f32_16x16x32_bf16 v[20:23], v[172:175], v[214:217], v[20:23]
	v_mfma_f32_16x16x32_bf16 v[12:15], v[160:163], v[218:221], 0
	v_mfma_f32_16x16x32_bf16 v[12:15], v[164:167], v[222:225], v[12:15]
	v_mfma_f32_16x16x32_bf16 v[4:7], v[168:171], v[218:221], 0
	v_mfma_f32_16x16x32_bf16 v[4:7], v[172:175], v[222:225], v[4:7]
	s_setprio 0
	s_setprio 1
	v_mfma_f32_16x16x32_bf16 v[56:59], v[176:179], v[194:197], 0
	v_mfma_f32_16x16x32_bf16 v[56:59], v[180:183], v[198:201], v[56:59]
	v_mfma_f32_16x16x32_bf16 v[48:51], v[186:189], v[194:197], 0
	v_mfma_f32_16x16x32_bf16 v[48:51], v[190:193], v[198:201], v[48:51]
	v_mfma_f32_16x16x32_bf16 v[40:43], v[176:179], v[202:205], 0
	v_mfma_f32_16x16x32_bf16 v[40:43], v[180:183], v[206:209], v[40:43]
	v_mfma_f32_16x16x32_bf16 v[32:35], v[186:189], v[202:205], 0
	v_mfma_f32_16x16x32_bf16 v[32:35], v[190:193], v[206:209], v[32:35]
	v_mfma_f32_16x16x32_bf16 v[24:27], v[176:179], v[210:213], 0
	v_mfma_f32_16x16x32_bf16 v[24:27], v[180:183], v[214:217], v[24:27]
	v_mfma_f32_16x16x32_bf16 v[16:19], v[186:189], v[210:213], 0
	v_mfma_f32_16x16x32_bf16 v[16:19], v[190:193], v[214:217], v[16:19]
	v_mfma_f32_16x16x32_bf16 v[8:11], v[176:179], v[218:221], 0
	v_mfma_f32_16x16x32_bf16 v[8:11], v[180:183], v[222:225], v[8:11]
	v_mfma_f32_16x16x32_bf16 v[0:3], v[186:189], v[218:221], 0
	v_mfma_f32_16x16x32_bf16 v[0:3], v[190:193], v[222:225], v[0:3]
	s_barrier
	s_setprio 0
	s_add_i32 s76, 0, 0x18000
	v_add_u32_e32 v153, s76, v147
	s_add_i32 s77, 0, 0x1c000
	ds_read_b128 v[160:163], v153
	v_xor_b32_e32 v253, 64, v153
	ds_read_b128 v[164:167], v253
	ds_read_b128 v[168:171], v153 offset:2048
	ds_read_b128 v[172:175], v253 offset:2048
	v_add_u32_e32 v153, s77, v147
	ds_read_b128 v[176:179], v153
	v_xor_b32_e32 v253, 64, v153
	ds_read_b128 v[180:183], v253
	ds_read_b128 v[186:189], v153 offset:2048
	ds_read_b128 v[190:193], v253 offset:2048
	s_add_u32 s48, s48, 0x40000
	s_addc_u32 s49, s49, 0
	s_mov_b32 m0, s57
	v_lshl_add_u64 v[232:233], s[48:49], 0, v[134:135]
	ds_read_b128 v[194:197], v150 offset:32768
	v_xor_b32_e32 v253, 64, v150
	ds_read_b128 v[198:201], v253 offset:32768
	ds_read_b128 v[202:205], v150 offset:34816
	ds_read_b128 v[206:209], v253 offset:34816
	ds_read_b128 v[210:213], v150 offset:36864
	ds_read_b128 v[214:217], v253 offset:36864
	ds_read_b128 v[218:221], v150 offset:38912
	ds_read_b128 v[222:225], v253 offset:38912
	global_load_lds_dwordx4 v[232:233], off
	v_lshl_add_u64 v[232:233], s[48:49], 0, v[130:131]
	s_mov_b32 m0, s58
	s_nop 0
	global_load_lds_dwordx4 v[232:233], off
	s_waitcnt vmcnt(8)
	s_waitcnt lgkmcnt(0)
	s_setprio 1
	s_barrier
	v_mfma_f32_16x16x32_bf16 v[124:127], v[160:163], v[194:197], v[124:127]
	v_mfma_f32_16x16x32_bf16 v[124:127], v[164:167], v[198:201], v[124:127]
	v_mfma_f32_16x16x32_bf16 v[116:119], v[172:175], v[198:201], v[116:119]
	v_mfma_f32_16x16x32_bf16 v[116:119], v[168:171], v[194:197], v[116:119]
	v_mfma_f32_16x16x32_bf16 v[100:103], v[168:171], v[202:205], v[100:103]
	v_mfma_f32_16x16x32_bf16 v[100:103], v[172:175], v[206:209], v[100:103]
	v_mfma_f32_16x16x32_bf16 v[108:111], v[164:167], v[206:209], v[108:111]
	v_mfma_f32_16x16x32_bf16 v[108:111], v[160:163], v[202:205], v[108:111]
	v_mfma_f32_16x16x32_bf16 v[92:95], v[160:163], v[210:213], v[92:95]
	v_mfma_f32_16x16x32_bf16 v[92:95], v[164:167], v[214:217], v[92:95]
	v_mfma_f32_16x16x32_bf16 v[84:87], v[172:175], v[214:217], v[84:87]
	v_mfma_f32_16x16x32_bf16 v[84:87], v[168:171], v[210:213], v[84:87]
	v_mfma_f32_16x16x32_bf16 v[68:71], v[168:171], v[218:221], v[68:71]
	v_mfma_f32_16x16x32_bf16 v[68:71], v[172:175], v[222:225], v[68:71]
	v_mfma_f32_16x16x32_bf16 v[76:79], v[164:167], v[222:225], v[76:79]
	v_mfma_f32_16x16x32_bf16 v[76:79], v[160:163], v[218:221], v[76:79]
	s_setprio 0
	s_setprio 1
	v_mfma_f32_16x16x32_bf16 v[120:123], v[176:179], v[194:197], v[120:123]
	v_mfma_f32_16x16x32_bf16 v[120:123], v[180:183], v[198:201], v[120:123]
	v_mfma_f32_16x16x32_bf16 v[112:115], v[190:193], v[198:201], v[112:115]
	v_mfma_f32_16x16x32_bf16 v[112:115], v[186:189], v[194:197], v[112:115]
	v_mfma_f32_16x16x32_bf16 v[96:99], v[186:189], v[202:205], v[96:99]
	v_mfma_f32_16x16x32_bf16 v[96:99], v[190:193], v[206:209], v[96:99]
	v_mfma_f32_16x16x32_bf16 v[104:107], v[180:183], v[206:209], v[104:107]
	v_mfma_f32_16x16x32_bf16 v[104:107], v[176:179], v[202:205], v[104:107]
	v_mfma_f32_16x16x32_bf16 v[88:91], v[176:179], v[210:213], v[88:91]
	v_mfma_f32_16x16x32_bf16 v[88:91], v[180:183], v[214:217], v[88:91]
	v_mfma_f32_16x16x32_bf16 v[80:83], v[190:193], v[214:217], v[80:83]
	v_mfma_f32_16x16x32_bf16 v[80:83], v[186:189], v[210:213], v[80:83]
	v_mfma_f32_16x16x32_bf16 v[64:67], v[186:189], v[218:221], v[64:67]
	v_mfma_f32_16x16x32_bf16 v[64:67], v[190:193], v[222:225], v[64:67]
	v_mfma_f32_16x16x32_bf16 v[72:75], v[180:183], v[222:225], v[72:75]
	v_mfma_f32_16x16x32_bf16 v[72:75], v[176:179], v[218:221], v[72:75]
	s_barrier
	s_setprio 0
	s_add_i32 s48, s76, s52
	v_lshl_add_u64 v[154:155], v[154:155], 0, s[14:15]
	s_mov_b32 m0, s48
	ds_read_b128 v[194:197], v150 offset:49152
	v_xor_b32_e32 v253, 64, v150
	ds_read_b128 v[198:201], v253 offset:49152
	ds_read_b128 v[202:205], v150 offset:51200
	ds_read_b128 v[206:209], v253 offset:51200
	ds_read_b128 v[210:213], v150 offset:53248
	ds_read_b128 v[214:217], v253 offset:53248
	ds_read_b128 v[218:221], v150 offset:55296
	ds_read_b128 v[222:225], v253 offset:55296
	global_load_lds_dwordx4 v[154:155], off
	s_add_i32 m0, s48, 0x2000
	s_add_u32 s46, s46, 0x40080
	v_lshl_add_u64 v[154:155], v[226:227], 0, s[14:15]
	s_addc_u32 s47, s47, 0
	s_add_i32 s48, s77, s52
	global_load_lds_dwordx4 v[154:155], off
	v_lshl_add_u64 v[154:155], s[46:47], 0, v[132:133]
	s_mov_b32 m0, s48
	s_nop 0
	global_load_lds_dwordx4 v[154:155], off
	v_lshl_add_u64 v[154:155], s[46:47], 0, v[128:129]
	s_add_i32 m0, s48, 0x2000
	s_nop 0
	global_load_lds_dwordx4 v[154:155], off
	v_lshl_add_u64 v[154:155], v[228:229], 0, s[14:15]
	s_mov_b32 m0, s60
	s_nop 0
	global_load_lds_dwordx4 v[154:155], off
	v_lshl_add_u64 v[154:155], v[230:231], 0, s[14:15]
	s_mov_b32 m0, s61
	s_nop 0
	global_load_lds_dwordx4 v[154:155], off
	s_waitcnt vmcnt(8)
	s_waitcnt lgkmcnt(0)
	s_setprio 1
	s_barrier
	v_mfma_f32_16x16x32_bf16 v[60:63], v[160:163], v[194:197], v[60:63]
	v_mfma_f32_16x16x32_bf16 v[60:63], v[164:167], v[198:201], v[60:63]
	v_mfma_f32_16x16x32_bf16 v[52:55], v[172:175], v[198:201], v[52:55]
	v_mfma_f32_16x16x32_bf16 v[52:55], v[168:171], v[194:197], v[52:55]
	v_mfma_f32_16x16x32_bf16 v[36:39], v[168:171], v[202:205], v[36:39]
	v_mfma_f32_16x16x32_bf16 v[36:39], v[172:175], v[206:209], v[36:39]
	v_mfma_f32_16x16x32_bf16 v[44:47], v[164:167], v[206:209], v[44:47]
	v_mfma_f32_16x16x32_bf16 v[44:47], v[160:163], v[202:205], v[44:47]
	v_mfma_f32_16x16x32_bf16 v[28:31], v[160:163], v[210:213], v[28:31]
	v_mfma_f32_16x16x32_bf16 v[28:31], v[164:167], v[214:217], v[28:31]
	v_mfma_f32_16x16x32_bf16 v[20:23], v[172:175], v[214:217], v[20:23]
	v_mfma_f32_16x16x32_bf16 v[20:23], v[168:171], v[210:213], v[20:23]
	v_mfma_f32_16x16x32_bf16 v[4:7], v[168:171], v[218:221], v[4:7]
	v_mfma_f32_16x16x32_bf16 v[4:7], v[172:175], v[222:225], v[4:7]
	v_mfma_f32_16x16x32_bf16 v[12:15], v[164:167], v[222:225], v[12:15]
	v_mfma_f32_16x16x32_bf16 v[12:15], v[160:163], v[218:221], v[12:15]
	s_setprio 0
	s_setprio 1
	v_mfma_f32_16x16x32_bf16 v[56:59], v[176:179], v[194:197], v[56:59]
	v_mfma_f32_16x16x32_bf16 v[56:59], v[180:183], v[198:201], v[56:59]
	v_mfma_f32_16x16x32_bf16 v[48:51], v[190:193], v[198:201], v[48:51]
	v_mfma_f32_16x16x32_bf16 v[48:51], v[186:189], v[194:197], v[48:51]
	v_mfma_f32_16x16x32_bf16 v[32:35], v[186:189], v[202:205], v[32:35]
	v_mfma_f32_16x16x32_bf16 v[32:35], v[190:193], v[206:209], v[32:35]
	v_mfma_f32_16x16x32_bf16 v[40:43], v[180:183], v[206:209], v[40:43]
	v_mfma_f32_16x16x32_bf16 v[40:43], v[176:179], v[202:205], v[40:43]
	v_mfma_f32_16x16x32_bf16 v[24:27], v[176:179], v[210:213], v[24:27]
	v_mfma_f32_16x16x32_bf16 v[24:27], v[180:183], v[214:217], v[24:27]
	v_mfma_f32_16x16x32_bf16 v[16:19], v[190:193], v[214:217], v[16:19]
	v_mfma_f32_16x16x32_bf16 v[16:19], v[186:189], v[210:213], v[16:19]
	v_mfma_f32_16x16x32_bf16 v[0:3], v[186:189], v[218:221], v[0:3]
	v_mfma_f32_16x16x32_bf16 v[0:3], v[190:193], v[222:225], v[0:3]
	v_mfma_f32_16x16x32_bf16 v[8:11], v[180:183], v[222:225], v[8:11]
	v_mfma_f32_16x16x32_bf16 v[8:11], v[176:179], v[218:221], v[8:11]
	s_barrier
	s_setprio 0
	s_add_i32 s75, s75, 2
	s_add_u32 s71, s71, 0x100
	s_addc_u32 s74, s74, 0
	s_add_u32 s44, s44, 0x100
	s_addc_u32 s45, s45, 0
	s_branch .LBB0_76
.Lfa_0:
	v_add_u32_e32 v153, s64, v147
	ds_read_b128 v[160:163], v153
	v_xor_b32_e32 v253, 64, v153
	ds_read_b128 v[164:167], v253
	ds_read_b128 v[168:171], v153 offset:2048
	ds_read_b128 v[172:175], v253 offset:2048
	v_add_u32_e32 v153, s65, v147
	ds_read_b128 v[176:179], v153
	v_xor_b32_e32 v253, 64, v153
	ds_read_b128 v[180:183], v253
	ds_read_b128 v[186:189], v153 offset:2048
	ds_read_b128 v[190:193], v253 offset:2048
	s_add_u32 s48, s44, 0xfffc0080
	s_addc_u32 s49, s45, -1
	s_and_b64 s[46:47], s[46:47], exec
	s_cselect_b32 s49, s27, s49
	s_cselect_b32 s48, s68, s48
	s_cselect_b32 s47, s69, s74
	s_cselect_b32 s46, s70, s71
	v_lshl_add_u64 v[154:155], s[44:45], 0, v[138:139]
	s_add_i32 m0, s55, 0xc000
	ds_read_b128 v[194:197], v150
	v_xor_b32_e32 v253, 64, v150
	ds_read_b128 v[198:201], v253
	ds_read_b128 v[202:205], v150 offset:2048
	ds_read_b128 v[206:209], v253 offset:2048
	ds_read_b128 v[210:213], v150 offset:4096
	ds_read_b128 v[214:217], v253 offset:4096
	ds_read_b128 v[218:221], v150 offset:6144
	ds_read_b128 v[222:225], v253 offset:6144
	global_load_lds_dwordx4 v[154:155], off
	v_lshl_add_u64 v[154:155], s[44:45], 0, v[136:137]
	s_add_i32 m0, s55, 0xe000
	s_nop 0
	global_load_lds_dwordx4 v[154:155], off
	s_waitcnt vmcnt(8)
	s_waitcnt lgkmcnt(0)
	s_setprio 1
	s_barrier
	v_mfma_f32_16x16x32_bf16 v[124:127], v[160:163], v[194:197], 0
	v_mfma_f32_16x16x32_bf16 v[124:127], v[164:167], v[198:201], v[124:127]
	v_mfma_f32_16x16x32_bf16 v[116:119], v[168:171], v[194:197], 0
	v_mfma_f32_16x16x32_bf16 v[116:119], v[172:175], v[198:201], v[116:119]
	v_mfma_f32_16x16x32_bf16 v[108:111], v[160:163], v[202:205], 0
	v_mfma_f32_16x16x32_bf16 v[108:111], v[164:167], v[206:209], v[108:111]
	v_mfma_f32_16x16x32_bf16 v[100:103], v[168:171], v[202:205], 0
	v_mfma_f32_16x16x32_bf16 v[100:103], v[172:175], v[206:209], v[100:103]
	v_mfma_f32_16x16x32_bf16 v[92:95], v[160:163], v[210:213], 0
	v_mfma_f32_16x16x32_bf16 v[92:95], v[164:167], v[214:217], v[92:95]
	v_mfma_f32_16x16x32_bf16 v[84:87], v[168:171], v[210:213], 0
	v_mfma_f32_16x16x32_bf16 v[84:87], v[172:175], v[214:217], v[84:87]
	v_mfma_f32_16x16x32_bf16 v[76:79], v[160:163], v[218:221], 0
	v_mfma_f32_16x16x32_bf16 v[76:79], v[164:167], v[222:225], v[76:79]
	v_mfma_f32_16x16x32_bf16 v[68:71], v[168:171], v[218:221], 0
	v_mfma_f32_16x16x32_bf16 v[68:71], v[172:175], v[222:225], v[68:71]
	s_setprio 0
	s_setprio 1
	v_mfma_f32_16x16x32_bf16 v[120:123], v[176:179], v[194:197], 0
	v_mfma_f32_16x16x32_bf16 v[120:123], v[180:183], v[198:201], v[120:123]
	v_mfma_f32_16x16x32_bf16 v[112:115], v[186:189], v[194:197], 0
	v_mfma_f32_16x16x32_bf16 v[112:115], v[190:193], v[198:201], v[112:115]
	v_mfma_f32_16x16x32_bf16 v[104:107], v[176:179], v[202:205], 0
	v_mfma_f32_16x16x32_bf16 v[104:107], v[180:183], v[206:209], v[104:107]
	v_mfma_f32_16x16x32_bf16 v[96:99], v[186:189], v[202:205], 0
	v_mfma_f32_16x16x32_bf16 v[96:99], v[190:193], v[206:209], v[96:99]
	v_mfma_f32_16x16x32_bf16 v[88:91], v[176:179], v[210:213], 0
	v_mfma_f32_16x16x32_bf16 v[88:91], v[180:183], v[214:217], v[88:91]
	v_mfma_f32_16x16x32_bf16 v[80:83], v[186:189], v[210:213], 0
	v_mfma_f32_16x16x32_bf16 v[80:83], v[190:193], v[214:217], v[80:83]
	v_mfma_f32_16x16x32_bf16 v[72:75], v[176:179], v[218:221], 0
	v_mfma_f32_16x16x32_bf16 v[72:75], v[180:183], v[222:225], v[72:75]
	v_mfma_f32_16x16x32_bf16 v[64:67], v[186:189], v[218:221], 0
	v_mfma_f32_16x16x32_bf16 v[64:67], v[190:193], v[222:225], v[64:67]
	s_barrier
	s_setprio 0
	s_add_i32 s76, s64, s52
	v_lshl_add_u64 v[154:155], s[46:47], 0, v[132:133]
	s_mov_b32 m0, s76
	ds_read_b128 v[194:197], v150 offset:16384
	v_xor_b32_e32 v253, 64, v150
	ds_read_b128 v[198:201], v253 offset:16384
	ds_read_b128 v[202:205], v150 offset:18432
	ds_read_b128 v[206:209], v253 offset:18432
	ds_read_b128 v[210:213], v150 offset:20480
	ds_read_b128 v[214:217], v253 offset:20480
	ds_read_b128 v[218:221], v150 offset:22528
	ds_read_b128 v[222:225], v253 offset:22528
	global_load_lds_dwordx4 v[154:155], off
	s_add_i32 m0, s76, 0x2000
	s_add_u32 s76, s46, 0x40000
	v_lshl_add_u64 v[226:227], s[46:47], 0, v[128:129]
	s_addc_u32 s77, s47, 0
	s_add_i32 s78, s65, s52
	global_load_lds_dwordx4 v[226:227], off
	v_lshl_add_u64 v[228:229], s[76:77], 0, v[132:133]
	s_mov_b32 m0, s78
	v_lshl_add_u64 v[230:231], s[48:49], 0, v[130:131]
	global_load_lds_dwordx4 v[228:229], off
	v_lshl_add_u64 v[228:229], s[76:77], 0, v[128:129]
	s_add_i32 m0, s78, 0x2000
	s_nop 0
	global_load_lds_dwordx4 v[228:229], off
	v_lshl_add_u64 v[228:229], s[48:49], 0, v[134:135]
	s_mov_b32 m0, s55
	s_nop 0
	global_load_lds_dwordx4 v[228:229], off
	s_mov_b32 m0, s56
	s_nop 0
	global_load_lds_dwordx4 v[230:231], off
	s_waitcnt vmcnt(8)
	s_waitcnt lgkmcnt(0)
	s_setprio 1
	s_barrier
	v_mfma_f32_16x16x32_bf16 v[60:63], v[160:163], v[194:197], 0
	v_mfma_f32_16x16x32_bf16 v[60:63], v[164:167], v[198:201], v[60:63]
	v_mfma_f32_16x16x32_bf16 v[52:55], v[168:171], v[194:197], 0
	v_mfma_f32_16x16x32_bf16 v[52:55], v[172:175], v[198:201], v[52:55]
	v_mfma_f32_16x16x32_bf16 v[44:47], v[160:163], v[202:205], 0
	v_mfma_f32_16x16x32_bf16 v[44:47], v[164:167], v[206:209], v[44:47]
	v_mfma_f32_16x16x32_bf16 v[36:39], v[168:171], v[202:205], 0
	v_mfma_f32_16x16x32_bf16 v[36:39], v[172:175], v[206:209], v[36:39]
	v_mfma_f32_16x16x32_bf16 v[28:31], v[160:163], v[210:213], 0
	v_mfma_f32_16x16x32_bf16 v[28:31], v[164:167], v[214:217], v[28:31]
	v_mfma_f32_16x16x32_bf16 v[20:23], v[168:171], v[210:213], 0
	v_mfma_f32_16x16x32_bf16 v[20:23], v[172:175], v[214:217], v[20:23]
	v_mfma_f32_16x16x32_bf16 v[12:15], v[160:163], v[218:221], 0
	v_mfma_f32_16x16x32_bf16 v[12:15], v[164:167], v[222:225], v[12:15]
	v_mfma_f32_16x16x32_bf16 v[4:7], v[168:171], v[218:221], 0
	v_mfma_f32_16x16x32_bf16 v[4:7], v[172:175], v[222:225], v[4:7]
	s_setprio 0
	s_setprio 1
	v_mfma_f32_16x16x32_bf16 v[56:59], v[176:179], v[194:197], 0
	v_mfma_f32_16x16x32_bf16 v[56:59], v[180:183], v[198:201], v[56:59]
	v_mfma_f32_16x16x32_bf16 v[48:51], v[186:189], v[194:197], 0
	v_mfma_f32_16x16x32_bf16 v[48:51], v[190:193], v[198:201], v[48:51]
	v_mfma_f32_16x16x32_bf16 v[40:43], v[176:179], v[202:205], 0
	v_mfma_f32_16x16x32_bf16 v[40:43], v[180:183], v[206:209], v[40:43]
	v_mfma_f32_16x16x32_bf16 v[32:35], v[186:189], v[202:205], 0
	v_mfma_f32_16x16x32_bf16 v[32:35], v[190:193], v[206:209], v[32:35]
	v_mfma_f32_16x16x32_bf16 v[24:27], v[176:179], v[210:213], 0
	v_mfma_f32_16x16x32_bf16 v[24:27], v[180:183], v[214:217], v[24:27]
	v_mfma_f32_16x16x32_bf16 v[16:19], v[186:189], v[210:213], 0
	v_mfma_f32_16x16x32_bf16 v[16:19], v[190:193], v[214:217], v[16:19]
	v_mfma_f32_16x16x32_bf16 v[8:11], v[176:179], v[218:221], 0
	v_mfma_f32_16x16x32_bf16 v[8:11], v[180:183], v[222:225], v[8:11]
	v_mfma_f32_16x16x32_bf16 v[0:3], v[186:189], v[218:221], 0
	v_mfma_f32_16x16x32_bf16 v[0:3], v[190:193], v[222:225], v[0:3]
	s_barrier
	s_setprio 0
	s_add_i32 s76, 0, 0x18000
	v_add_u32_e32 v153, s76, v147
	s_add_i32 s77, 0, 0x1c000
	ds_read_b128 v[160:163], v153
	v_xor_b32_e32 v253, 64, v153
	ds_read_b128 v[164:167], v253
	ds_read_b128 v[168:171], v153 offset:2048
	ds_read_b128 v[172:175], v253 offset:2048
	v_add_u32_e32 v153, s77, v147
	ds_read_b128 v[176:179], v153
	v_xor_b32_e32 v253, 64, v153
	ds_read_b128 v[180:183], v253
	ds_read_b128 v[186:189], v153 offset:2048
	ds_read_b128 v[190:193], v253 offset:2048
	s_add_u32 s48, s48, 0x40000
	s_addc_u32 s49, s49, 0
	s_mov_b32 m0, s57
	v_lshl_add_u64 v[232:233], s[48:49], 0, v[134:135]
	ds_read_b128 v[194:197], v150 offset:32768
	v_xor_b32_e32 v253, 64, v150
	ds_read_b128 v[198:201], v253 offset:32768
	ds_read_b128 v[202:205], v150 offset:34816
	ds_read_b128 v[206:209], v253 offset:34816
	ds_read_b128 v[210:213], v150 offset:36864
	ds_read_b128 v[214:217], v253 offset:36864
	ds_read_b128 v[218:221], v150 offset:38912
	ds_read_b128 v[222:225], v253 offset:38912
	global_load_lds_dwordx4 v[232:233], off
	v_lshl_add_u64 v[232:233], s[48:49], 0, v[130:131]
	s_mov_b32 m0, s58
	s_nop 0
	global_load_lds_dwordx4 v[232:233], off
	s_waitcnt vmcnt(8)
	s_waitcnt lgkmcnt(0)
	s_setprio 1
	s_barrier
	v_mfma_f32_16x16x32_bf16 v[124:127], v[160:163], v[194:197], v[124:127]
	v_mfma_f32_16x16x32_bf16 v[124:127], v[164:167], v[198:201], v[124:127]
	v_mfma_f32_16x16x32_bf16 v[116:119], v[172:175], v[198:201], v[116:119]
	v_mfma_f32_16x16x32_bf16 v[116:119], v[168:171], v[194:197], v[116:119]
	v_mfma_f32_16x16x32_bf16 v[100:103], v[168:171], v[202:205], v[100:103]
	v_mfma_f32_16x16x32_bf16 v[100:103], v[172:175], v[206:209], v[100:103]
	v_mfma_f32_16x16x32_bf16 v[108:111], v[164:167], v[206:209], v[108:111]
	v_mfma_f32_16x16x32_bf16 v[108:111], v[160:163], v[202:205], v[108:111]
	v_mfma_f32_16x16x32_bf16 v[92:95], v[160:163], v[210:213], v[92:95]
	v_mfma_f32_16x16x32_bf16 v[92:95], v[164:167], v[214:217], v[92:95]
	v_mfma_f32_16x16x32_bf16 v[84:87], v[172:175], v[214:217], v[84:87]
	v_mfma_f32_16x16x32_bf16 v[84:87], v[168:171], v[210:213], v[84:87]
	v_mfma_f32_16x16x32_bf16 v[68:71], v[168:171], v[218:221], v[68:71]
	v_mfma_f32_16x16x32_bf16 v[68:71], v[172:175], v[222:225], v[68:71]
	v_mfma_f32_16x16x32_bf16 v[76:79], v[164:167], v[222:225], v[76:79]
	v_mfma_f32_16x16x32_bf16 v[76:79], v[160:163], v[218:221], v[76:79]
	s_setprio 0
	s_setprio 1
	v_mfma_f32_16x16x32_bf16 v[120:123], v[176:179], v[194:197], v[120:123]
	v_mfma_f32_16x16x32_bf16 v[120:123], v[180:183], v[198:201], v[120:123]
	v_mfma_f32_16x16x32_bf16 v[112:115], v[190:193], v[198:201], v[112:115]
	v_mfma_f32_16x16x32_bf16 v[112:115], v[186:189], v[194:197], v[112:115]
	v_mfma_f32_16x16x32_bf16 v[96:99], v[186:189], v[202:205], v[96:99]
	v_mfma_f32_16x16x32_bf16 v[96:99], v[190:193], v[206:209], v[96:99]
	v_mfma_f32_16x16x32_bf16 v[104:107], v[180:183], v[206:209], v[104:107]
	v_mfma_f32_16x16x32_bf16 v[104:107], v[176:179], v[202:205], v[104:107]
	v_mfma_f32_16x16x32_bf16 v[88:91], v[176:179], v[210:213], v[88:91]
	v_mfma_f32_16x16x32_bf16 v[88:91], v[180:183], v[214:217], v[88:91]
	v_mfma_f32_16x16x32_bf16 v[80:83], v[190:193], v[214:217], v[80:83]
	v_mfma_f32_16x16x32_bf16 v[80:83], v[186:189], v[210:213], v[80:83]
	v_mfma_f32_16x16x32_bf16 v[64:67], v[186:189], v[218:221], v[64:67]
	v_mfma_f32_16x16x32_bf16 v[64:67], v[190:193], v[222:225], v[64:67]
	v_mfma_f32_16x16x32_bf16 v[72:75], v[180:183], v[222:225], v[72:75]
	v_mfma_f32_16x16x32_bf16 v[72:75], v[176:179], v[218:221], v[72:75]
	s_barrier
	s_setprio 0
	s_add_i32 s48, s76, s52
	v_lshl_add_u64 v[154:155], v[154:155], 0, s[14:15]
	s_mov_b32 m0, s48
	ds_read_b128 v[194:197], v150 offset:49152
	v_xor_b32_e32 v253, 64, v150
	ds_read_b128 v[198:201], v253 offset:49152
	ds_read_b128 v[202:205], v150 offset:51200
	ds_read_b128 v[206:209], v253 offset:51200
	ds_read_b128 v[210:213], v150 offset:53248
	ds_read_b128 v[214:217], v253 offset:53248
	ds_read_b128 v[218:221], v150 offset:55296
	ds_read_b128 v[222:225], v253 offset:55296
	global_load_lds_dwordx4 v[154:155], off
	s_add_i32 m0, s48, 0x2000
	s_add_u32 s46, s46, 0x40080
	v_lshl_add_u64 v[154:155], v[226:227], 0, s[14:15]
	s_addc_u32 s47, s47, 0
	s_add_i32 s48, s77, s52
	global_load_lds_dwordx4 v[154:155], off
	v_lshl_add_u64 v[154:155], s[46:47], 0, v[132:133]
	s_mov_b32 m0, s48
	s_nop 0
	global_load_lds_dwordx4 v[154:155], off
	v_lshl_add_u64 v[154:155], s[46:47], 0, v[128:129]
	s_add_i32 m0, s48, 0x2000
	s_nop 0
	global_load_lds_dwordx4 v[154:155], off
	v_lshl_add_u64 v[154:155], v[228:229], 0, s[14:15]
	s_mov_b32 m0, s60
	s_nop 0
	global_load_lds_dwordx4 v[154:155], off
	v_lshl_add_u64 v[154:155], v[230:231], 0, s[14:15]
	s_mov_b32 m0, s61
	s_nop 0
	global_load_lds_dwordx4 v[154:155], off
	s_waitcnt vmcnt(8)
	s_waitcnt lgkmcnt(0)
	s_setprio 1
	s_barrier
	v_mfma_f32_16x16x32_bf16 v[60:63], v[160:163], v[194:197], v[60:63]
	v_mfma_f32_16x16x32_bf16 v[60:63], v[164:167], v[198:201], v[60:63]
	v_mfma_f32_16x16x32_bf16 v[52:55], v[172:175], v[198:201], v[52:55]
	v_mfma_f32_16x16x32_bf16 v[52:55], v[168:171], v[194:197], v[52:55]
	v_mfma_f32_16x16x32_bf16 v[36:39], v[168:171], v[202:205], v[36:39]
	v_mfma_f32_16x16x32_bf16 v[36:39], v[172:175], v[206:209], v[36:39]
	v_mfma_f32_16x16x32_bf16 v[44:47], v[164:167], v[206:209], v[44:47]
	v_mfma_f32_16x16x32_bf16 v[44:47], v[160:163], v[202:205], v[44:47]
	v_mfma_f32_16x16x32_bf16 v[28:31], v[160:163], v[210:213], v[28:31]
	v_mfma_f32_16x16x32_bf16 v[28:31], v[164:167], v[214:217], v[28:31]
	v_mfma_f32_16x16x32_bf16 v[20:23], v[172:175], v[214:217], v[20:23]
	v_mfma_f32_16x16x32_bf16 v[20:23], v[168:171], v[210:213], v[20:23]
	v_mfma_f32_16x16x32_bf16 v[4:7], v[168:171], v[218:221], v[4:7]
	v_mfma_f32_16x16x32_bf16 v[4:7], v[172:175], v[222:225], v[4:7]
	v_mfma_f32_16x16x32_bf16 v[12:15], v[164:167], v[222:225], v[12:15]
	v_mfma_f32_16x16x32_bf16 v[12:15], v[160:163], v[218:221], v[12:15]
	s_setprio 0
	s_setprio 1
	v_mfma_f32_16x16x32_bf16 v[56:59], v[176:179], v[194:197], v[56:59]
	v_mfma_f32_16x16x32_bf16 v[56:59], v[180:183], v[198:201], v[56:59]
	v_mfma_f32_16x16x32_bf16 v[48:51], v[190:193], v[198:201], v[48:51]
	v_mfma_f32_16x16x32_bf16 v[48:51], v[186:189], v[194:197], v[48:51]
	v_mfma_f32_16x16x32_bf16 v[32:35], v[186:189], v[202:205], v[32:35]
	v_mfma_f32_16x16x32_bf16 v[32:35], v[190:193], v[206:209], v[32:35]
	v_mfma_f32_16x16x32_bf16 v[40:43], v[180:183], v[206:209], v[40:43]
	v_mfma_f32_16x16x32_bf16 v[40:43], v[176:179], v[202:205], v[40:43]
	v_mfma_f32_16x16x32_bf16 v[24:27], v[176:179], v[210:213], v[24:27]
	v_mfma_f32_16x16x32_bf16 v[24:27], v[180:183], v[214:217], v[24:27]
	v_mfma_f32_16x16x32_bf16 v[16:19], v[190:193], v[214:217], v[16:19]
	v_mfma_f32_16x16x32_bf16 v[16:19], v[186:189], v[210:213], v[16:19]
	v_mfma_f32_16x16x32_bf16 v[0:3], v[186:189], v[218:221], v[0:3]
	v_mfma_f32_16x16x32_bf16 v[0:3], v[190:193], v[222:225], v[0:3]
	v_mfma_f32_16x16x32_bf16 v[8:11], v[180:183], v[222:225], v[8:11]
	v_mfma_f32_16x16x32_bf16 v[8:11], v[176:179], v[218:221], v[8:11]
	s_barrier
	s_setprio 0
	s_add_i32 s75, s75, 2
	s_add_u32 s71, s71, 0x100
	s_addc_u32 s74, s74, 0
	s_add_u32 s44, s44, 0x100
	s_addc_u32 s45, s45, 0
	s_branch .LBB0_76

.LBB0_158:
	s_add_u32 s81, s56, 0x100
	s_addc_u32 s82, s57, 0
	s_mov_b32 s83, -2
	s_waitcnt lgkmcnt(0)
	s_cmp_eq_u32 s70, 1
	s_cbranch_scc1 .Lfa_1
	ds_read_b128 v[128:131], v189
	v_xor_b32_e32 v253, 64, v189
	ds_read_b128 v[132:135], v253
	ds_read_b128 v[136:139], v189 offset:2048
	ds_read_b128 v[140:143], v253 offset:2048
	ds_read_b128 v[144:147], v190
	v_xor_b32_e32 v253, 64, v190
	ds_read_b128 v[148:151], v253
	ds_read_b128 v[172:175], v190 offset:2048
	ds_read_b128 v[176:179], v253 offset:2048
	s_add_u32 s56, s54, 0x100
	s_addc_u32 s57, s55, 0
	s_cmp_eq_u32 s83, 40
	s_cselect_b32 s61, s15, s57
	s_cselect_b32 s60, s14, s56
	s_cselect_b32 s59, s53, s82
	s_cselect_b32 s58, s52, s81
	v_lshl_add_u64 v[222:223], s[54:55], 0, v[166:167]
	s_add_i32 m0, s66, 0xc000
	ds_read_b128 v[180:183], v191
	v_xor_b32_e32 v253, 64, v191
	ds_read_b128 v[194:197], v253
	ds_read_b128 v[198:201], v191 offset:2048
	ds_read_b128 v[202:205], v253 offset:2048
	ds_read_b128 v[206:209], v191 offset:4096
	ds_read_b128 v[210:213], v253 offset:4096
	ds_read_b128 v[214:217], v191 offset:6144
	ds_read_b128 v[218:221], v253 offset:6144
	global_load_lds_dwordx4 v[222:223], off
	v_lshl_add_u64 v[222:223], s[54:55], 0, v[164:165]
	s_add_i32 m0, s66, 0xe000
	s_nop 0
	global_load_lds_dwordx4 v[222:223], off
	s_waitcnt vmcnt(24)
	s_waitcnt lgkmcnt(0)
	s_setprio 1
	s_barrier
	v_mfma_f32_16x16x32_bf16 v[124:127], v[128:131], v[180:183], 0
	v_mfma_f32_16x16x32_bf16 v[124:127], v[132:135], v[194:197], v[124:127]
	v_mfma_f32_16x16x32_bf16 v[120:123], v[136:139], v[180:183], 0
	v_mfma_f32_16x16x32_bf16 v[120:123], v[140:143], v[194:197], v[120:123]
	v_mfma_f32_16x16x32_bf16 v[108:111], v[128:131], v[198:201], 0
	v_mfma_f32_16x16x32_bf16 v[108:111], v[132:135], v[202:205], v[108:111]
	v_mfma_f32_16x16x32_bf16 v[104:107], v[136:139], v[198:201], 0
	v_mfma_f32_16x16x32_bf16 v[104:107], v[140:143], v[202:205], v[104:107]
	v_mfma_f32_16x16x32_bf16 v[92:95], v[128:131], v[206:209], 0
	v_mfma_f32_16x16x32_bf16 v[92:95], v[132:135], v[210:213], v[92:95]
	v_mfma_f32_16x16x32_bf16 v[88:91], v[136:139], v[206:209], 0
	v_mfma_f32_16x16x32_bf16 v[88:91], v[140:143], v[210:213], v[88:91]
	v_mfma_f32_16x16x32_bf16 v[76:79], v[128:131], v[214:217], 0
	v_mfma_f32_16x16x32_bf16 v[76:79], v[132:135], v[218:221], v[76:79]
	v_mfma_f32_16x16x32_bf16 v[72:75], v[136:139], v[214:217], 0
	v_mfma_f32_16x16x32_bf16 v[72:75], v[140:143], v[218:221], v[72:75]
	s_setprio 0
	s_setprio 1
	v_mfma_f32_16x16x32_bf16 v[116:119], v[144:147], v[180:183], 0
	v_mfma_f32_16x16x32_bf16 v[116:119], v[148:151], v[194:197], v[116:119]
	v_mfma_f32_16x16x32_bf16 v[112:115], v[172:175], v[180:183], 0
	v_mfma_f32_16x16x32_bf16 v[112:115], v[176:179], v[194:197], v[112:115]
	v_mfma_f32_16x16x32_bf16 v[100:103], v[144:147], v[198:201], 0
	v_mfma_f32_16x16x32_bf16 v[100:103], v[148:151], v[202:205], v[100:103]
	v_mfma_f32_16x16x32_bf16 v[96:99], v[172:175], v[198:201], 0
	v_mfma_f32_16x16x32_bf16 v[96:99], v[176:179], v[202:205], v[96:99]
	v_mfma_f32_16x16x32_bf16 v[84:87], v[144:147], v[206:209], 0
	v_mfma_f32_16x16x32_bf16 v[84:87], v[148:151], v[210:213], v[84:87]
	v_mfma_f32_16x16x32_bf16 v[80:83], v[172:175], v[206:209], 0
	v_mfma_f32_16x16x32_bf16 v[80:83], v[176:179], v[210:213], v[80:83]
	v_mfma_f32_16x16x32_bf16 v[68:71], v[144:147], v[214:217], 0
	v_mfma_f32_16x16x32_bf16 v[68:71], v[148:151], v[218:221], v[68:71]
	v_mfma_f32_16x16x32_bf16 v[64:67], v[172:175], v[214:217], 0
	v_mfma_f32_16x16x32_bf16 v[64:67], v[176:179], v[218:221], v[64:67]
	s_barrier
	s_setprio 0
	s_add_i32 s54, s77, s65
	v_lshl_add_u64 v[222:223], s[58:59], 0, v[154:155]
	s_mov_b32 m0, s54
	ds_read_b128 v[180:183], v191 offset:16384
	v_xor_b32_e32 v253, 64, v191
	ds_read_b128 v[194:197], v253 offset:16384
	ds_read_b128 v[198:201], v191 offset:18432
	ds_read_b128 v[202:205], v253 offset:18432
	ds_read_b128 v[206:209], v191 offset:20480
	ds_read_b128 v[210:213], v253 offset:20480
	ds_read_b128 v[214:217], v191 offset:22528
	ds_read_b128 v[218:221], v253 offset:22528
	global_load_lds_dwordx4 v[222:223], off
	s_add_i32 m0, s54, 0x2000
	s_add_u32 s54, s58, 0xb0000
	v_lshl_add_u64 v[224:225], s[58:59], 0, v[162:163]
	s_addc_u32 s55, s59, 0
	s_add_i32 s84, s78, s65
	global_load_lds_dwordx4 v[224:225], off
	v_lshl_add_u64 v[226:227], s[54:55], 0, v[154:155]
	s_mov_b32 m0, s84
	v_lshl_add_u64 v[228:229], s[60:61], 0, v[160:161]
	global_load_lds_dwordx4 v[226:227], off
	v_lshl_add_u64 v[226:227], s[54:55], 0, v[162:163]
	s_add_i32 m0, s84, 0x2000
	s_nop 0
	global_load_lds_dwordx4 v[226:227], off
	v_lshl_add_u64 v[226:227], s[60:61], 0, v[152:153]
	s_mov_b32 m0, s66
	s_nop 0
	global_load_lds_dwordx4 v[226:227], off
	s_mov_b32 m0, s67
	s_nop 0
	global_load_lds_dwordx4 v[228:229], off
	s_waitcnt vmcnt(24)
	s_waitcnt lgkmcnt(0)
	s_setprio 1
	s_barrier
	v_mfma_f32_16x16x32_bf16 v[60:63], v[128:131], v[180:183], 0
	v_mfma_f32_16x16x32_bf16 v[60:63], v[132:135], v[194:197], v[60:63]
	v_mfma_f32_16x16x32_bf16 v[56:59], v[136:139], v[180:183], 0
	v_mfma_f32_16x16x32_bf16 v[56:59], v[140:143], v[194:197], v[56:59]
	v_mfma_f32_16x16x32_bf16 v[44:47], v[128:131], v[198:201], 0
	v_mfma_f32_16x16x32_bf16 v[44:47], v[132:135], v[202:205], v[44:47]
	v_mfma_f32_16x16x32_bf16 v[40:43], v[136:139], v[198:201], 0
	v_mfma_f32_16x16x32_bf16 v[40:43], v[140:143], v[202:205], v[40:43]
	v_mfma_f32_16x16x32_bf16 v[28:31], v[128:131], v[206:209], 0
	v_mfma_f32_16x16x32_bf16 v[28:31], v[132:135], v[210:213], v[28:31]
	v_mfma_f32_16x16x32_bf16 v[24:27], v[136:139], v[206:209], 0
	v_mfma_f32_16x16x32_bf16 v[24:27], v[140:143], v[210:213], v[24:27]
	v_mfma_f32_16x16x32_bf16 v[12:15], v[128:131], v[214:217], 0
	v_mfma_f32_16x16x32_bf16 v[12:15], v[132:135], v[218:221], v[12:15]
	v_mfma_f32_16x16x32_bf16 v[8:11], v[136:139], v[214:217], 0
	v_mfma_f32_16x16x32_bf16 v[8:11], v[140:143], v[218:221], v[8:11]
	s_setprio 0
	s_setprio 1
	v_mfma_f32_16x16x32_bf16 v[52:55], v[144:147], v[180:183], 0
	v_mfma_f32_16x16x32_bf16 v[52:55], v[148:151], v[194:197], v[52:55]
	v_mfma_f32_16x16x32_bf16 v[48:51], v[172:175], v[180:183], 0
	v_mfma_f32_16x16x32_bf16 v[48:51], v[176:179], v[194:197], v[48:51]
	v_mfma_f32_16x16x32_bf16 v[36:39], v[144:147], v[198:201], 0
	v_mfma_f32_16x16x32_bf16 v[36:39], v[148:151], v[202:205], v[36:39]
	v_mfma_f32_16x16x32_bf16 v[32:35], v[172:175], v[198:201], 0
	v_mfma_f32_16x16x32_bf16 v[32:35], v[176:179], v[202:205], v[32:35]
	v_mfma_f32_16x16x32_bf16 v[20:23], v[144:147], v[206:209], 0
	v_mfma_f32_16x16x32_bf16 v[20:23], v[148:151], v[210:213], v[20:23]
	v_mfma_f32_16x16x32_bf16 v[16:19], v[172:175], v[206:209], 0
	v_mfma_f32_16x16x32_bf16 v[16:19], v[176:179], v[210:213], v[16:19]
	v_mfma_f32_16x16x32_bf16 v[4:7], v[144:147], v[214:217], 0
	v_mfma_f32_16x16x32_bf16 v[4:7], v[148:151], v[218:221], v[4:7]
	v_mfma_f32_16x16x32_bf16 v[0:3], v[172:175], v[214:217], 0
	v_mfma_f32_16x16x32_bf16 v[0:3], v[176:179], v[218:221], v[0:3]
	s_barrier
	s_setprio 0
	s_add_i32 s84, 0, 0x18000
	s_add_i32 s85, 0, 0x1c000
	v_add_u32_e32 v140, s84, v186
	v_add_u32_e32 v176, s85, v186
	ds_read_b128 v[128:131], v140
	v_xor_b32_e32 v253, 64, v140
	ds_read_b128 v[132:135], v253
	ds_read_b128 v[136:139], v140 offset:2048
	ds_read_b128 v[140:143], v253 offset:2048
	ds_read_b128 v[144:147], v176
	v_xor_b32_e32 v253, 64, v176
	ds_read_b128 v[148:151], v253
	ds_read_b128 v[172:175], v176 offset:2048
	ds_read_b128 v[176:179], v253 offset:2048
	s_add_u32 s54, s60, 0xb0000
	s_addc_u32 s55, s61, 0
	s_mov_b32 m0, s68
	v_lshl_add_u64 v[230:231], s[54:55], 0, v[152:153]
	ds_read_b128 v[180:183], v191 offset:32768
	v_xor_b32_e32 v253, 64, v191
	ds_read_b128 v[194:197], v253 offset:32768
	ds_read_b128 v[198:201], v191 offset:34816
	ds_read_b128 v[202:205], v253 offset:34816
	ds_read_b128 v[206:209], v191 offset:36864
	ds_read_b128 v[210:213], v253 offset:36864
	ds_read_b128 v[214:217], v191 offset:38912
	ds_read_b128 v[218:221], v253 offset:38912
	global_load_lds_dwordx4 v[230:231], off
	v_lshl_add_u64 v[230:231], s[54:55], 0, v[160:161]
	s_mov_b32 m0, s69
	s_nop 0
	global_load_lds_dwordx4 v[230:231], off
	s_waitcnt vmcnt(8)
	s_waitcnt lgkmcnt(0)
	s_setprio 1
	s_barrier
	v_mfma_f32_16x16x32_bf16 v[124:127], v[128:131], v[180:183], v[124:127]
	v_mfma_f32_16x16x32_bf16 v[124:127], v[132:135], v[194:197], v[124:127]
	v_mfma_f32_16x16x32_bf16 v[120:123], v[140:143], v[194:197], v[120:123]
	v_mfma_f32_16x16x32_bf16 v[120:123], v[136:139], v[180:183], v[120:123]
	v_mfma_f32_16x16x32_bf16 v[104:107], v[136:139], v[198:201], v[104:107]
	v_mfma_f32_16x16x32_bf16 v[104:107], v[140:143], v[202:205], v[104:107]
	v_mfma_f32_16x16x32_bf16 v[108:111], v[132:135], v[202:205], v[108:111]
	v_mfma_f32_16x16x32_bf16 v[108:111], v[128:131], v[198:201], v[108:111]
	v_mfma_f32_16x16x32_bf16 v[92:95], v[128:131], v[206:209], v[92:95]
	v_mfma_f32_16x16x32_bf16 v[92:95], v[132:135], v[210:213], v[92:95]
	v_mfma_f32_16x16x32_bf16 v[88:91], v[140:143], v[210:213], v[88:91]
	v_mfma_f32_16x16x32_bf16 v[88:91], v[136:139], v[206:209], v[88:91]
	v_mfma_f32_16x16x32_bf16 v[72:75], v[136:139], v[214:217], v[72:75]
	v_mfma_f32_16x16x32_bf16 v[72:75], v[140:143], v[218:221], v[72:75]
	v_mfma_f32_16x16x32_bf16 v[76:79], v[132:135], v[218:221], v[76:79]
	v_mfma_f32_16x16x32_bf16 v[76:79], v[128:131], v[214:217], v[76:79]
	s_setprio 0
	s_setprio 1
	v_mfma_f32_16x16x32_bf16 v[116:119], v[144:147], v[180:183], v[116:119]
	v_mfma_f32_16x16x32_bf16 v[116:119], v[148:151], v[194:197], v[116:119]
	v_mfma_f32_16x16x32_bf16 v[112:115], v[176:179], v[194:197], v[112:115]
	v_mfma_f32_16x16x32_bf16 v[112:115], v[172:175], v[180:183], v[112:115]
	v_mfma_f32_16x16x32_bf16 v[96:99], v[172:175], v[198:201], v[96:99]
	v_mfma_f32_16x16x32_bf16 v[96:99], v[176:179], v[202:205], v[96:99]
	v_mfma_f32_16x16x32_bf16 v[100:103], v[148:151], v[202:205], v[100:103]
	v_mfma_f32_16x16x32_bf16 v[100:103], v[144:147], v[198:201], v[100:103]
	v_mfma_f32_16x16x32_bf16 v[84:87], v[144:147], v[206:209], v[84:87]
	v_mfma_f32_16x16x32_bf16 v[84:87], v[148:151], v[210:213], v[84:87]
	v_mfma_f32_16x16x32_bf16 v[80:83], v[176:179], v[210:213], v[80:83]
	v_mfma_f32_16x16x32_bf16 v[80:83], v[172:175], v[206:209], v[80:83]
	v_mfma_f32_16x16x32_bf16 v[64:67], v[172:175], v[214:217], v[64:67]
	v_mfma_f32_16x16x32_bf16 v[64:67], v[176:179], v[218:221], v[64:67]
	v_mfma_f32_16x16x32_bf16 v[68:71], v[148:151], v[218:221], v[68:71]
	v_mfma_f32_16x16x32_bf16 v[68:71], v[144:147], v[214:217], v[68:71]
	s_barrier
	s_setprio 0
	s_add_i32 s54, s84, s65
	v_lshl_add_u64 v[222:223], v[222:223], 0, s[28:29]
	s_mov_b32 m0, s54
	ds_read_b128 v[180:183], v191 offset:49152
	v_xor_b32_e32 v253, 64, v191
	ds_read_b128 v[194:197], v253 offset:49152
	ds_read_b128 v[198:201], v191 offset:51200
	ds_read_b128 v[202:205], v253 offset:51200
	ds_read_b128 v[206:209], v191 offset:53248
	ds_read_b128 v[210:213], v253 offset:53248
	ds_read_b128 v[214:217], v191 offset:55296
	ds_read_b128 v[218:221], v253 offset:55296
	global_load_lds_dwordx4 v[222:223], off
	s_add_i32 m0, s54, 0x2000
	s_add_u32 s54, s58, 0xb0080
	v_lshl_add_u64 v[222:223], v[224:225], 0, s[28:29]
	s_addc_u32 s55, s59, 0
	s_add_i32 s58, s85, s65
	global_load_lds_dwordx4 v[222:223], off
	v_lshl_add_u64 v[222:223], s[54:55], 0, v[154:155]
	s_mov_b32 m0, s58
	s_nop 0
	global_load_lds_dwordx4 v[222:223], off
	v_lshl_add_u64 v[222:223], s[54:55], 0, v[162:163]
	s_add_i32 m0, s58, 0x2000
	s_nop 0
	global_load_lds_dwordx4 v[222:223], off
	v_lshl_add_u64 v[222:223], v[226:227], 0, s[28:29]
	s_mov_b32 m0, s3
	s_nop 0
	global_load_lds_dwordx4 v[222:223], off
	v_lshl_add_u64 v[222:223], v[228:229], 0, s[28:29]
	s_mov_b32 m0, s71
	s_nop 0
	global_load_lds_dwordx4 v[222:223], off
	s_waitcnt vmcnt(8)
	s_waitcnt lgkmcnt(0)
	s_setprio 1
	s_barrier
	v_mfma_f32_16x16x32_bf16 v[60:63], v[128:131], v[180:183], v[60:63]
	v_mfma_f32_16x16x32_bf16 v[60:63], v[132:135], v[194:197], v[60:63]
	v_mfma_f32_16x16x32_bf16 v[56:59], v[140:143], v[194:197], v[56:59]
	v_mfma_f32_16x16x32_bf16 v[56:59], v[136:139], v[180:183], v[56:59]
	v_mfma_f32_16x16x32_bf16 v[40:43], v[136:139], v[198:201], v[40:43]
	v_mfma_f32_16x16x32_bf16 v[40:43], v[140:143], v[202:205], v[40:43]
	v_mfma_f32_16x16x32_bf16 v[44:47], v[132:135], v[202:205], v[44:47]
	v_mfma_f32_16x16x32_bf16 v[44:47], v[128:131], v[198:201], v[44:47]
	v_mfma_f32_16x16x32_bf16 v[28:31], v[128:131], v[206:209], v[28:31]
	v_mfma_f32_16x16x32_bf16 v[28:31], v[132:135], v[210:213], v[28:31]
	v_mfma_f32_16x16x32_bf16 v[24:27], v[140:143], v[210:213], v[24:27]
	v_mfma_f32_16x16x32_bf16 v[24:27], v[136:139], v[206:209], v[24:27]
	v_mfma_f32_16x16x32_bf16 v[8:11], v[136:139], v[214:217], v[8:11]
	v_mfma_f32_16x16x32_bf16 v[8:11], v[140:143], v[218:221], v[8:11]
	v_mfma_f32_16x16x32_bf16 v[12:15], v[132:135], v[218:221], v[12:15]
	v_mfma_f32_16x16x32_bf16 v[12:15], v[128:131], v[214:217], v[12:15]
	s_setprio 0
	s_setprio 1
	v_mfma_f32_16x16x32_bf16 v[52:55], v[144:147], v[180:183], v[52:55]
	v_mfma_f32_16x16x32_bf16 v[52:55], v[148:151], v[194:197], v[52:55]
	v_mfma_f32_16x16x32_bf16 v[48:51], v[176:179], v[194:197], v[48:51]
	v_mfma_f32_16x16x32_bf16 v[48:51], v[172:175], v[180:183], v[48:51]
	v_mfma_f32_16x16x32_bf16 v[32:35], v[172:175], v[198:201], v[32:35]
	v_mfma_f32_16x16x32_bf16 v[32:35], v[176:179], v[202:205], v[32:35]
	v_mfma_f32_16x16x32_bf16 v[36:39], v[148:151], v[202:205], v[36:39]
	v_mfma_f32_16x16x32_bf16 v[36:39], v[144:147], v[198:201], v[36:39]
	v_mfma_f32_16x16x32_bf16 v[20:23], v[144:147], v[206:209], v[20:23]
	v_mfma_f32_16x16x32_bf16 v[20:23], v[148:151], v[210:213], v[20:23]
	v_mfma_f32_16x16x32_bf16 v[16:19], v[176:179], v[210:213], v[16:19]
	v_mfma_f32_16x16x32_bf16 v[16:19], v[172:175], v[206:209], v[16:19]
	v_mfma_f32_16x16x32_bf16 v[0:3], v[172:175], v[214:217], v[0:3]
	v_mfma_f32_16x16x32_bf16 v[0:3], v[176:179], v[218:221], v[0:3]
	v_mfma_f32_16x16x32_bf16 v[4:7], v[148:151], v[218:221], v[4:7]
	v_mfma_f32_16x16x32_bf16 v[4:7], v[144:147], v[214:217], v[4:7]
	s_barrier
	s_setprio 0
	s_add_i32 s83, s83, 2
	s_add_u32 s81, s81, 0x100
	s_addc_u32 s82, s82, 0
	s_cmp_gt_u32 s83, 41
	s_mov_b64 s[54:55], s[56:57]
	s_branch .LBB0_159
.Lfa_1:
	ds_read_b128 v[128:131], v189
	v_xor_b32_e32 v253, 64, v189
	ds_read_b128 v[132:135], v253
	ds_read_b128 v[136:139], v189 offset:2048
	ds_read_b128 v[140:143], v253 offset:2048
	ds_read_b128 v[144:147], v190
	v_xor_b32_e32 v253, 64, v190
	ds_read_b128 v[148:151], v253
	ds_read_b128 v[172:175], v190 offset:2048
	ds_read_b128 v[176:179], v253 offset:2048
	s_add_u32 s56, s54, 0x100
	s_addc_u32 s57, s55, 0
	s_cmp_eq_u32 s83, 40
	s_cselect_b32 s61, s15, s57
	s_cselect_b32 s60, s14, s56
	s_cselect_b32 s59, s53, s82
	s_cselect_b32 s58, s52, s81
	v_lshl_add_u64 v[222:223], s[54:55], 0, v[166:167]
	s_add_i32 m0, s66, 0xc000
	ds_read_b128 v[180:183], v191
	v_xor_b32_e32 v253, 64, v191
	ds_read_b128 v[194:197], v253
	ds_read_b128 v[198:201], v191 offset:2048
	ds_read_b128 v[202:205], v253 offset:2048
	ds_read_b128 v[206:209], v191 offset:4096
	ds_read_b128 v[210:213], v253 offset:4096
	ds_read_b128 v[214:217], v191 offset:6144
	ds_read_b128 v[218:221], v253 offset:6144
	global_load_lds_dwordx4 v[222:223], off
	v_lshl_add_u64 v[222:223], s[54:55], 0, v[164:165]
	s_add_i32 m0, s66, 0xe000
	s_nop 0
	global_load_lds_dwordx4 v[222:223], off
	s_waitcnt vmcnt(8)
	s_waitcnt lgkmcnt(0)
	s_setprio 1
	s_barrier
	v_mfma_f32_16x16x32_bf16 v[124:127], v[128:131], v[180:183], 0
	v_mfma_f32_16x16x32_bf16 v[124:127], v[132:135], v[194:197], v[124:127]
	v_mfma_f32_16x16x32_bf16 v[120:123], v[136:139], v[180:183], 0
	v_mfma_f32_16x16x32_bf16 v[120:123], v[140:143], v[194:197], v[120:123]
	v_mfma_f32_16x16x32_bf16 v[108:111], v[128:131], v[198:201], 0
	v_mfma_f32_16x16x32_bf16 v[108:111], v[132:135], v[202:205], v[108:111]
	v_mfma_f32_16x16x32_bf16 v[104:107], v[136:139], v[198:201], 0
	v_mfma_f32_16x16x32_bf16 v[104:107], v[140:143], v[202:205], v[104:107]
	v_mfma_f32_16x16x32_bf16 v[92:95], v[128:131], v[206:209], 0
	v_mfma_f32_16x16x32_bf16 v[92:95], v[132:135], v[210:213], v[92:95]
	v_mfma_f32_16x16x32_bf16 v[88:91], v[136:139], v[206:209], 0
	v_mfma_f32_16x16x32_bf16 v[88:91], v[140:143], v[210:213], v[88:91]
	v_mfma_f32_16x16x32_bf16 v[76:79], v[128:131], v[214:217], 0
	v_mfma_f32_16x16x32_bf16 v[76:79], v[132:135], v[218:221], v[76:79]
	v_mfma_f32_16x16x32_bf16 v[72:75], v[136:139], v[214:217], 0
	v_mfma_f32_16x16x32_bf16 v[72:75], v[140:143], v[218:221], v[72:75]
	s_setprio 0
	s_setprio 1
	v_mfma_f32_16x16x32_bf16 v[116:119], v[144:147], v[180:183], 0
	v_mfma_f32_16x16x32_bf16 v[116:119], v[148:151], v[194:197], v[116:119]
	v_mfma_f32_16x16x32_bf16 v[112:115], v[172:175], v[180:183], 0
	v_mfma_f32_16x16x32_bf16 v[112:115], v[176:179], v[194:197], v[112:115]
	v_mfma_f32_16x16x32_bf16 v[100:103], v[144:147], v[198:201], 0
	v_mfma_f32_16x16x32_bf16 v[100:103], v[148:151], v[202:205], v[100:103]
	v_mfma_f32_16x16x32_bf16 v[96:99], v[172:175], v[198:201], 0
	v_mfma_f32_16x16x32_bf16 v[96:99], v[176:179], v[202:205], v[96:99]
	v_mfma_f32_16x16x32_bf16 v[84:87], v[144:147], v[206:209], 0
	v_mfma_f32_16x16x32_bf16 v[84:87], v[148:151], v[210:213], v[84:87]
	v_mfma_f32_16x16x32_bf16 v[80:83], v[172:175], v[206:209], 0
	v_mfma_f32_16x16x32_bf16 v[80:83], v[176:179], v[210:213], v[80:83]
	v_mfma_f32_16x16x32_bf16 v[68:71], v[144:147], v[214:217], 0
	v_mfma_f32_16x16x32_bf16 v[68:71], v[148:151], v[218:221], v[68:71]
	v_mfma_f32_16x16x32_bf16 v[64:67], v[172:175], v[214:217], 0
	v_mfma_f32_16x16x32_bf16 v[64:67], v[176:179], v[218:221], v[64:67]
	s_barrier
	s_setprio 0
	s_add_i32 s54, s77, s65
	v_lshl_add_u64 v[222:223], s[58:59], 0, v[154:155]
	s_mov_b32 m0, s54
	ds_read_b128 v[180:183], v191 offset:16384
	v_xor_b32_e32 v253, 64, v191
	ds_read_b128 v[194:197], v253 offset:16384
	ds_read_b128 v[198:201], v191 offset:18432
	ds_read_b128 v[202:205], v253 offset:18432
	ds_read_b128 v[206:209], v191 offset:20480
	ds_read_b128 v[210:213], v253 offset:20480
	ds_read_b128 v[214:217], v191 offset:22528
	ds_read_b128 v[218:221], v253 offset:22528
	global_load_lds_dwordx4 v[222:223], off
	s_add_i32 m0, s54, 0x2000
	s_add_u32 s54, s58, 0xb0000
	v_lshl_add_u64 v[224:225], s[58:59], 0, v[162:163]
	s_addc_u32 s55, s59, 0
	s_add_i32 s84, s78, s65
	global_load_lds_dwordx4 v[224:225], off
	v_lshl_add_u64 v[226:227], s[54:55], 0, v[154:155]
	s_mov_b32 m0, s84
	v_lshl_add_u64 v[228:229], s[60:61], 0, v[160:161]
	global_load_lds_dwordx4 v[226:227], off
	v_lshl_add_u64 v[226:227], s[54:55], 0, v[162:163]
	s_add_i32 m0, s84, 0x2000
	s_nop 0
	global_load_lds_dwordx4 v[226:227], off
	v_lshl_add_u64 v[226:227], s[60:61], 0, v[152:153]
	s_mov_b32 m0, s66
	s_nop 0
	global_load_lds_dwordx4 v[226:227], off
	s_mov_b32 m0, s67
	s_nop 0
	global_load_lds_dwordx4 v[228:229], off
	s_waitcnt vmcnt(8)
	s_waitcnt lgkmcnt(0)
	s_setprio 1
	s_barrier
	v_mfma_f32_16x16x32_bf16 v[60:63], v[128:131], v[180:183], 0
	v_mfma_f32_16x16x32_bf16 v[60:63], v[132:135], v[194:197], v[60:63]
	v_mfma_f32_16x16x32_bf16 v[56:59], v[136:139], v[180:183], 0
	v_mfma_f32_16x16x32_bf16 v[56:59], v[140:143], v[194:197], v[56:59]
	v_mfma_f32_16x16x32_bf16 v[44:47], v[128:131], v[198:201], 0
	v_mfma_f32_16x16x32_bf16 v[44:47], v[132:135], v[202:205], v[44:47]
	v_mfma_f32_16x16x32_bf16 v[40:43], v[136:139], v[198:201], 0
	v_mfma_f32_16x16x32_bf16 v[40:43], v[140:143], v[202:205], v[40:43]
	v_mfma_f32_16x16x32_bf16 v[28:31], v[128:131], v[206:209], 0
	v_mfma_f32_16x16x32_bf16 v[28:31], v[132:135], v[210:213], v[28:31]
	v_mfma_f32_16x16x32_bf16 v[24:27], v[136:139], v[206:209], 0
	v_mfma_f32_16x16x32_bf16 v[24:27], v[140:143], v[210:213], v[24:27]
	v_mfma_f32_16x16x32_bf16 v[12:15], v[128:131], v[214:217], 0
	v_mfma_f32_16x16x32_bf16 v[12:15], v[132:135], v[218:221], v[12:15]
	v_mfma_f32_16x16x32_bf16 v[8:11], v[136:139], v[214:217], 0
	v_mfma_f32_16x16x32_bf16 v[8:11], v[140:143], v[218:221], v[8:11]
	s_setprio 0
	s_setprio 1
	v_mfma_f32_16x16x32_bf16 v[52:55], v[144:147], v[180:183], 0
	v_mfma_f32_16x16x32_bf16 v[52:55], v[148:151], v[194:197], v[52:55]
	v_mfma_f32_16x16x32_bf16 v[48:51], v[172:175], v[180:183], 0
	v_mfma_f32_16x16x32_bf16 v[48:51], v[176:179], v[194:197], v[48:51]
	v_mfma_f32_16x16x32_bf16 v[36:39], v[144:147], v[198:201], 0
	v_mfma_f32_16x16x32_bf16 v[36:39], v[148:151], v[202:205], v[36:39]
	v_mfma_f32_16x16x32_bf16 v[32:35], v[172:175], v[198:201], 0
	v_mfma_f32_16x16x32_bf16 v[32:35], v[176:179], v[202:205], v[32:35]
	v_mfma_f32_16x16x32_bf16 v[20:23], v[144:147], v[206:209], 0
	v_mfma_f32_16x16x32_bf16 v[20:23], v[148:151], v[210:213], v[20:23]
	v_mfma_f32_16x16x32_bf16 v[16:19], v[172:175], v[206:209], 0
	v_mfma_f32_16x16x32_bf16 v[16:19], v[176:179], v[210:213], v[16:19]
	v_mfma_f32_16x16x32_bf16 v[4:7], v[144:147], v[214:217], 0
	v_mfma_f32_16x16x32_bf16 v[4:7], v[148:151], v[218:221], v[4:7]
	v_mfma_f32_16x16x32_bf16 v[0:3], v[172:175], v[214:217], 0
	v_mfma_f32_16x16x32_bf16 v[0:3], v[176:179], v[218:221], v[0:3]
	s_barrier
	s_setprio 0
	s_add_i32 s84, 0, 0x18000
	s_add_i32 s85, 0, 0x1c000
	v_add_u32_e32 v140, s84, v186
	v_add_u32_e32 v176, s85, v186
	ds_read_b128 v[128:131], v140
	v_xor_b32_e32 v253, 64, v140
	ds_read_b128 v[132:135], v253
	ds_read_b128 v[136:139], v140 offset:2048
	ds_read_b128 v[140:143], v253 offset:2048
	ds_read_b128 v[144:147], v176
	v_xor_b32_e32 v253, 64, v176
	ds_read_b128 v[148:151], v253
	ds_read_b128 v[172:175], v176 offset:2048
	ds_read_b128 v[176:179], v253 offset:2048
	s_add_u32 s54, s60, 0xb0000
	s_addc_u32 s55, s61, 0
	s_mov_b32 m0, s68
	v_lshl_add_u64 v[230:231], s[54:55], 0, v[152:153]
	ds_read_b128 v[180:183], v191 offset:32768
	v_xor_b32_e32 v253, 64, v191
	ds_read_b128 v[194:197], v253 offset:32768
	ds_read_b128 v[198:201], v191 offset:34816
	ds_read_b128 v[202:205], v253 offset:34816
	ds_read_b128 v[206:209], v191 offset:36864
	ds_read_b128 v[210:213], v253 offset:36864
	ds_read_b128 v[214:217], v191 offset:38912
	ds_read_b128 v[218:221], v253 offset:38912
	global_load_lds_dwordx4 v[230:231], off
	v_lshl_add_u64 v[230:231], s[54:55], 0, v[160:161]
	s_mov_b32 m0, s69
	s_nop 0
	global_load_lds_dwordx4 v[230:231], off
	s_waitcnt vmcnt(8)
	s_waitcnt lgkmcnt(0)
	s_setprio 1
	s_barrier
	v_mfma_f32_16x16x32_bf16 v[124:127], v[128:131], v[180:183], v[124:127]
	v_mfma_f32_16x16x32_bf16 v[124:127], v[132:135], v[194:197], v[124:127]
	v_mfma_f32_16x16x32_bf16 v[120:123], v[140:143], v[194:197], v[120:123]
	v_mfma_f32_16x16x32_bf16 v[120:123], v[136:139], v[180:183], v[120:123]
	v_mfma_f32_16x16x32_bf16 v[104:107], v[136:139], v[198:201], v[104:107]
	v_mfma_f32_16x16x32_bf16 v[104:107], v[140:143], v[202:205], v[104:107]
	v_mfma_f32_16x16x32_bf16 v[108:111], v[132:135], v[202:205], v[108:111]
	v_mfma_f32_16x16x32_bf16 v[108:111], v[128:131], v[198:201], v[108:111]
	v_mfma_f32_16x16x32_bf16 v[92:95], v[128:131], v[206:209], v[92:95]
	v_mfma_f32_16x16x32_bf16 v[92:95], v[132:135], v[210:213], v[92:95]
	v_mfma_f32_16x16x32_bf16 v[88:91], v[140:143], v[210:213], v[88:91]
	v_mfma_f32_16x16x32_bf16 v[88:91], v[136:139], v[206:209], v[88:91]
	v_mfma_f32_16x16x32_bf16 v[72:75], v[136:139], v[214:217], v[72:75]
	v_mfma_f32_16x16x32_bf16 v[72:75], v[140:143], v[218:221], v[72:75]
	v_mfma_f32_16x16x32_bf16 v[76:79], v[132:135], v[218:221], v[76:79]
	v_mfma_f32_16x16x32_bf16 v[76:79], v[128:131], v[214:217], v[76:79]
	s_setprio 0
	s_setprio 1
	v_mfma_f32_16x16x32_bf16 v[116:119], v[144:147], v[180:183], v[116:119]
	v_mfma_f32_16x16x32_bf16 v[116:119], v[148:151], v[194:197], v[116:119]
	v_mfma_f32_16x16x32_bf16 v[112:115], v[176:179], v[194:197], v[112:115]
	v_mfma_f32_16x16x32_bf16 v[112:115], v[172:175], v[180:183], v[112:115]
	v_mfma_f32_16x16x32_bf16 v[96:99], v[172:175], v[198:201], v[96:99]
	v_mfma_f32_16x16x32_bf16 v[96:99], v[176:179], v[202:205], v[96:99]
	v_mfma_f32_16x16x32_bf16 v[100:103], v[148:151], v[202:205], v[100:103]
	v_mfma_f32_16x16x32_bf16 v[100:103], v[144:147], v[198:201], v[100:103]
	v_mfma_f32_16x16x32_bf16 v[84:87], v[144:147], v[206:209], v[84:87]
	v_mfma_f32_16x16x32_bf16 v[84:87], v[148:151], v[210:213], v[84:87]
	v_mfma_f32_16x16x32_bf16 v[80:83], v[176:179], v[210:213], v[80:83]
	v_mfma_f32_16x16x32_bf16 v[80:83], v[172:175], v[206:209], v[80:83]
	v_mfma_f32_16x16x32_bf16 v[64:67], v[172:175], v[214:217], v[64:67]
	v_mfma_f32_16x16x32_bf16 v[64:67], v[176:179], v[218:221], v[64:67]
	v_mfma_f32_16x16x32_bf16 v[68:71], v[148:151], v[218:221], v[68:71]
	v_mfma_f32_16x16x32_bf16 v[68:71], v[144:147], v[214:217], v[68:71]
	s_barrier
	s_setprio 0
	s_add_i32 s54, s84, s65
	v_lshl_add_u64 v[222:223], v[222:223], 0, s[28:29]
	s_mov_b32 m0, s54
	ds_read_b128 v[180:183], v191 offset:49152
	v_xor_b32_e32 v253, 64, v191
	ds_read_b128 v[194:197], v253 offset:49152
	ds_read_b128 v[198:201], v191 offset:51200
	ds_read_b128 v[202:205], v253 offset:51200
	ds_read_b128 v[206:209], v191 offset:53248
	ds_read_b128 v[210:213], v253 offset:53248
	ds_read_b128 v[214:217], v191 offset:55296
	ds_read_b128 v[218:221], v253 offset:55296
	global_load_lds_dwordx4 v[222:223], off
	s_add_i32 m0, s54, 0x2000
	s_add_u32 s54, s58, 0xb0080
	v_lshl_add_u64 v[222:223], v[224:225], 0, s[28:29]
	s_addc_u32 s55, s59, 0
	s_add_i32 s58, s85, s65
	global_load_lds_dwordx4 v[222:223], off
	v_lshl_add_u64 v[222:223], s[54:55], 0, v[154:155]
	s_mov_b32 m0, s58
	s_nop 0
	global_load_lds_dwordx4 v[222:223], off
	v_lshl_add_u64 v[222:223], s[54:55], 0, v[162:163]
	s_add_i32 m0, s58, 0x2000
	s_nop 0
	global_load_lds_dwordx4 v[222:223], off
	v_lshl_add_u64 v[222:223], v[226:227], 0, s[28:29]
	s_mov_b32 m0, s3
	s_nop 0
	global_load_lds_dwordx4 v[222:223], off
	v_lshl_add_u64 v[222:223], v[228:229], 0, s[28:29]
	s_mov_b32 m0, s71
	s_nop 0
	global_load_lds_dwordx4 v[222:223], off
	s_waitcnt vmcnt(8)
	s_waitcnt lgkmcnt(0)
	s_setprio 1
	s_barrier
	v_mfma_f32_16x16x32_bf16 v[60:63], v[128:131], v[180:183], v[60:63]
	v_mfma_f32_16x16x32_bf16 v[60:63], v[132:135], v[194:197], v[60:63]
	v_mfma_f32_16x16x32_bf16 v[56:59], v[140:143], v[194:197], v[56:59]
	v_mfma_f32_16x16x32_bf16 v[56:59], v[136:139], v[180:183], v[56:59]
	v_mfma_f32_16x16x32_bf16 v[40:43], v[136:139], v[198:201], v[40:43]
	v_mfma_f32_16x16x32_bf16 v[40:43], v[140:143], v[202:205], v[40:43]
	v_mfma_f32_16x16x32_bf16 v[44:47], v[132:135], v[202:205], v[44:47]
	v_mfma_f32_16x16x32_bf16 v[44:47], v[128:131], v[198:201], v[44:47]
	v_mfma_f32_16x16x32_bf16 v[28:31], v[128:131], v[206:209], v[28:31]
	v_mfma_f32_16x16x32_bf16 v[28:31], v[132:135], v[210:213], v[28:31]
	v_mfma_f32_16x16x32_bf16 v[24:27], v[140:143], v[210:213], v[24:27]
	v_mfma_f32_16x16x32_bf16 v[24:27], v[136:139], v[206:209], v[24:27]
	v_mfma_f32_16x16x32_bf16 v[8:11], v[136:139], v[214:217], v[8:11]
	v_mfma_f32_16x16x32_bf16 v[8:11], v[140:143], v[218:221], v[8:11]
	v_mfma_f32_16x16x32_bf16 v[12:15], v[132:135], v[218:221], v[12:15]
	v_mfma_f32_16x16x32_bf16 v[12:15], v[128:131], v[214:217], v[12:15]
	s_setprio 0
	s_setprio 1
	v_mfma_f32_16x16x32_bf16 v[52:55], v[144:147], v[180:183], v[52:55]
	v_mfma_f32_16x16x32_bf16 v[52:55], v[148:151], v[194:197], v[52:55]
	v_mfma_f32_16x16x32_bf16 v[48:51], v[176:179], v[194:197], v[48:51]
	v_mfma_f32_16x16x32_bf16 v[48:51], v[172:175], v[180:183], v[48:51]
	v_mfma_f32_16x16x32_bf16 v[32:35], v[172:175], v[198:201], v[32:35]
	v_mfma_f32_16x16x32_bf16 v[32:35], v[176:179], v[202:205], v[32:35]
	v_mfma_f32_16x16x32_bf16 v[36:39], v[148:151], v[202:205], v[36:39]
	v_mfma_f32_16x16x32_bf16 v[36:39], v[144:147], v[198:201], v[36:39]
	v_mfma_f32_16x16x32_bf16 v[20:23], v[144:147], v[206:209], v[20:23]
	v_mfma_f32_16x16x32_bf16 v[20:23], v[148:151], v[210:213], v[20:23]
	v_mfma_f32_16x16x32_bf16 v[16:19], v[176:179], v[210:213], v[16:19]
	v_mfma_f32_16x16x32_bf16 v[16:19], v[172:175], v[206:209], v[16:19]
	v_mfma_f32_16x16x32_bf16 v[0:3], v[172:175], v[214:217], v[0:3]
	v_mfma_f32_16x16x32_bf16 v[0:3], v[176:179], v[218:221], v[0:3]
	v_mfma_f32_16x16x32_bf16 v[4:7], v[148:151], v[218:221], v[4:7]
	v_mfma_f32_16x16x32_bf16 v[4:7], v[144:147], v[214:217], v[4:7]
	s_barrier
	s_setprio 0
	s_add_i32 s83, s83, 2
	s_add_u32 s81, s81, 0x100
	s_addc_u32 s82, s82, 0
	s_cmp_gt_u32 s83, 41
	s_mov_b64 s[54:55], s[56:57]

.LBB0_254:
	s_ashr_i32 s61, s60, 31
	s_lshl_b64 s[62:63], s[60:61], 19
	s_add_u32 s62, s35, s62
	s_addc_u32 s63, s47, s63
	s_and_b64 s[64:65], s[12:13], exec
	s_cselect_b32 s3, s63, s69
	s_cselect_b32 s61, s62, s68
	s_ashr_i32 s59, s58, 31
	s_lshl_b64 s[64:65], s[58:59], 19
	s_add_u32 s64, s49, s64
	s_addc_u32 s65, s70, s65
	s_and_b64 s[92:93], s[12:13], exec
	s_cselect_b32 s91, s65, s67
	s_cselect_b32 s92, s64, s66
	s_lshl_b32 s59, s14, 8
	v_add_u32_e32 v0, s59, v182
	s_add_u32 s93, s66, 0x100
	s_waitcnt lgkmcnt(0)
	v_ashrrev_i32_e32 v1, 31, v0
	s_addc_u32 s94, s67, 0
	v_lshl_add_u64 v[72:73], v[0:1], 4, s[26:27]
	s_add_u32 s14, s68, 0x40080
	s_addc_u32 s15, s69, 0
	s_mov_b32 s95, -2
	s_mov_b64 s[66:67], 0
	s_cmp_eq_u32 s90, 1
	s_cbranch_scc1 .Lfa_2
	v_add_u32_e32 v74, s83, v181
	ds_read_b128 v[88:91], v74
	v_xor_b32_e32 v253, 64, v74
	ds_read_b128 v[108:111], v253
	ds_read_b128 v[128:131], v74 offset:2048
	ds_read_b128 v[144:147], v253 offset:2048
	v_add_u32_e32 v74, s84, v181
	ds_read_b128 v[148:151], v74
	v_xor_b32_e32 v253, 64, v74
	ds_read_b128 v[152:155], v253
	ds_read_b128 v[176:179], v74 offset:2048
	ds_read_b128 v[190:193], v253 offset:2048
	s_add_u32 s68, s14, 0xfffc0080
	s_addc_u32 s69, s15, -1
	s_and_b64 s[66:67], s[66:67], exec
	s_cselect_b32 s69, s3, s69
	s_cselect_b32 s68, s61, s68
	s_cselect_b32 s67, s91, s94
	s_cselect_b32 s66, s92, s93
	v_lshl_add_u64 v[74:75], s[14:15], 0, v[170:171]
	s_add_i32 m0, s74, 0xc000
	ds_read_b128 v[194:197], v187
	v_xor_b32_e32 v253, 64, v187
	ds_read_b128 v[198:201], v253
	ds_read_b128 v[202:205], v187 offset:2048
	ds_read_b128 v[206:209], v253 offset:2048
	ds_read_b128 v[210:213], v187 offset:4096
	ds_read_b128 v[214:217], v253 offset:4096
	ds_read_b128 v[218:221], v187 offset:6144
	ds_read_b128 v[222:225], v253 offset:6144
	global_load_lds_dwordx4 v[74:75], off
	v_lshl_add_u64 v[74:75], s[14:15], 0, v[168:169]
	s_add_i32 m0, s74, 0xe000
	s_nop 0
	global_load_lds_dwordx4 v[74:75], off
	s_waitcnt vmcnt(24)
	s_waitcnt lgkmcnt(0)
	s_setprio 1
	s_barrier
	v_mfma_f32_16x16x32_bf16 v[140:143], v[88:91], v[194:197], 0
	v_mfma_f32_16x16x32_bf16 v[136:139], v[128:131], v[194:197], 0
	v_mfma_f32_16x16x32_bf16 v[120:123], v[88:91], v[202:205], 0
	v_mfma_f32_16x16x32_bf16 v[116:119], v[128:131], v[202:205], 0
	v_mfma_f32_16x16x32_bf16 v[100:103], v[88:91], v[210:213], 0
	v_mfma_f32_16x16x32_bf16 v[96:99], v[128:131], v[210:213], 0
	v_mfma_f32_16x16x32_bf16 v[80:83], v[88:91], v[218:221], 0
	v_mfma_f32_16x16x32_bf16 v[74:77], v[128:131], v[218:221], 0
	v_mfma_f32_16x16x32_bf16 v[140:143], v[108:111], v[198:201], v[140:143]
	v_mfma_f32_16x16x32_bf16 v[136:139], v[144:147], v[198:201], v[136:139]
	v_mfma_f32_16x16x32_bf16 v[120:123], v[108:111], v[206:209], v[120:123]
	v_mfma_f32_16x16x32_bf16 v[116:119], v[144:147], v[206:209], v[116:119]
	v_mfma_f32_16x16x32_bf16 v[100:103], v[108:111], v[214:217], v[100:103]
	v_mfma_f32_16x16x32_bf16 v[96:99], v[144:147], v[214:217], v[96:99]
	v_mfma_f32_16x16x32_bf16 v[80:83], v[108:111], v[222:225], v[80:83]
	v_mfma_f32_16x16x32_bf16 v[74:77], v[144:147], v[222:225], v[74:77]
	s_setprio 0
	s_setprio 1
	v_mfma_f32_16x16x32_bf16 v[132:135], v[148:151], v[194:197], 0
	v_mfma_f32_16x16x32_bf16 v[132:135], v[152:155], v[198:201], v[132:135]
	v_mfma_f32_16x16x32_bf16 v[124:127], v[176:179], v[194:197], 0
	v_mfma_f32_16x16x32_bf16 v[124:127], v[190:193], v[198:201], v[124:127]
	v_mfma_f32_16x16x32_bf16 v[112:115], v[148:151], v[202:205], 0
	v_mfma_f32_16x16x32_bf16 v[112:115], v[152:155], v[206:209], v[112:115]
	v_mfma_f32_16x16x32_bf16 v[104:107], v[176:179], v[202:205], 0
	v_mfma_f32_16x16x32_bf16 v[104:107], v[190:193], v[206:209], v[104:107]
	v_mfma_f32_16x16x32_bf16 v[92:95], v[148:151], v[210:213], 0
	v_mfma_f32_16x16x32_bf16 v[92:95], v[152:155], v[214:217], v[92:95]
	v_mfma_f32_16x16x32_bf16 v[84:87], v[176:179], v[210:213], 0
	v_mfma_f32_16x16x32_bf16 v[84:87], v[190:193], v[214:217], v[84:87]
	v_mfma_f32_16x16x32_bf16 v[68:71], v[148:151], v[218:221], 0
	v_mfma_f32_16x16x32_bf16 v[68:71], v[152:155], v[222:225], v[68:71]
	v_mfma_f32_16x16x32_bf16 v[64:67], v[176:179], v[218:221], 0
	v_mfma_f32_16x16x32_bf16 v[64:67], v[190:193], v[222:225], v[64:67]
	s_barrier
	s_setprio 0
	s_add_i32 s96, s83, s71
	v_lshl_add_u64 v[226:227], s[66:67], 0, v[162:163]
	s_mov_b32 m0, s96
	ds_read_b128 v[194:197], v187 offset:16384
	v_xor_b32_e32 v253, 64, v187
	ds_read_b128 v[198:201], v253 offset:16384
	ds_read_b128 v[202:205], v187 offset:18432
	ds_read_b128 v[206:209], v253 offset:18432
	ds_read_b128 v[210:213], v187 offset:20480
	ds_read_b128 v[214:217], v253 offset:20480
	ds_read_b128 v[218:221], v187 offset:22528
	ds_read_b128 v[222:225], v253 offset:22528
	global_load_lds_dwordx4 v[226:227], off
	s_add_i32 m0, s96, 0x2000
	s_add_u32 s96, s66, 0x40000
	v_lshl_add_u64 v[228:229], s[66:67], 0, v[166:167]
	s_addc_u32 s97, s67, 0
	s_add_i32 vcc_lo, s84, s71
	global_load_lds_dwordx4 v[228:229], off
	v_lshl_add_u64 v[78:79], s[96:97], 0, v[162:163]
	s_mov_b32 m0, vcc_lo
	v_lshl_add_u64 v[230:231], s[68:69], 0, v[160:161]
	global_load_lds_dwordx4 v[78:79], off
	v_lshl_add_u64 v[78:79], s[96:97], 0, v[166:167]
	s_add_i32 m0, vcc_lo, 0x2000
	v_lshl_add_u64 v[232:233], s[68:69], 0, v[164:165]
	global_load_lds_dwordx4 v[78:79], off
	s_mov_b32 m0, s74
	s_nop 0
	global_load_lds_dwordx4 v[230:231], off
	s_mov_b32 m0, s75
	s_nop 0
	global_load_lds_dwordx4 v[232:233], off
	s_waitcnt vmcnt(24)
	s_waitcnt lgkmcnt(0)
	s_setprio 1
	s_barrier
	v_mfma_f32_16x16x32_bf16 v[60:63], v[88:91], v[194:197], 0
	v_mfma_f32_16x16x32_bf16 v[60:63], v[108:111], v[198:201], v[60:63]
	v_mfma_f32_16x16x32_bf16 v[56:59], v[128:131], v[194:197], 0
	v_mfma_f32_16x16x32_bf16 v[56:59], v[144:147], v[198:201], v[56:59]
	v_mfma_f32_16x16x32_bf16 v[44:47], v[88:91], v[202:205], 0
	v_mfma_f32_16x16x32_bf16 v[44:47], v[108:111], v[206:209], v[44:47]
	v_mfma_f32_16x16x32_bf16 v[40:43], v[128:131], v[202:205], 0
	v_mfma_f32_16x16x32_bf16 v[40:43], v[144:147], v[206:209], v[40:43]
	v_mfma_f32_16x16x32_bf16 v[28:31], v[88:91], v[210:213], 0
	v_mfma_f32_16x16x32_bf16 v[28:31], v[108:111], v[214:217], v[28:31]
	v_mfma_f32_16x16x32_bf16 v[24:27], v[128:131], v[210:213], 0
	v_mfma_f32_16x16x32_bf16 v[24:27], v[144:147], v[214:217], v[24:27]
	v_mfma_f32_16x16x32_bf16 v[12:15], v[88:91], v[218:221], 0
	v_mfma_f32_16x16x32_bf16 v[12:15], v[108:111], v[222:225], v[12:15]
	v_mfma_f32_16x16x32_bf16 v[8:11], v[128:131], v[218:221], 0
	v_mfma_f32_16x16x32_bf16 v[8:11], v[144:147], v[222:225], v[8:11]
	s_setprio 0
	s_setprio 1
	v_mfma_f32_16x16x32_bf16 v[52:55], v[148:151], v[194:197], 0
	v_mfma_f32_16x16x32_bf16 v[52:55], v[152:155], v[198:201], v[52:55]
	v_mfma_f32_16x16x32_bf16 v[48:51], v[176:179], v[194:197], 0
	v_mfma_f32_16x16x32_bf16 v[48:51], v[190:193], v[198:201], v[48:51]
	v_mfma_f32_16x16x32_bf16 v[36:39], v[148:151], v[202:205], 0
	v_mfma_f32_16x16x32_bf16 v[36:39], v[152:155], v[206:209], v[36:39]
	v_mfma_f32_16x16x32_bf16 v[32:35], v[176:179], v[202:205], 0
	v_mfma_f32_16x16x32_bf16 v[32:35], v[190:193], v[206:209], v[32:35]
	v_mfma_f32_16x16x32_bf16 v[20:23], v[148:151], v[210:213], 0
	v_mfma_f32_16x16x32_bf16 v[20:23], v[152:155], v[214:217], v[20:23]
	v_mfma_f32_16x16x32_bf16 v[16:19], v[176:179], v[210:213], 0
	v_mfma_f32_16x16x32_bf16 v[16:19], v[190:193], v[214:217], v[16:19]
	v_mfma_f32_16x16x32_bf16 v[4:7], v[148:151], v[218:221], 0
	v_mfma_f32_16x16x32_bf16 v[4:7], v[152:155], v[222:225], v[4:7]
	v_mfma_f32_16x16x32_bf16 v[0:3], v[176:179], v[218:221], 0
	v_mfma_f32_16x16x32_bf16 v[0:3], v[190:193], v[222:225], v[0:3]
	s_barrier
	s_setprio 0
	s_add_i32 s96, 0, 0x18000
	v_add_u32_e32 v78, s96, v181
	s_add_i32 s97, 0, 0x1c000
	ds_read_b128 v[88:91], v78
	v_xor_b32_e32 v253, 64, v78
	ds_read_b128 v[108:111], v253
	ds_read_b128 v[128:131], v78 offset:2048
	ds_read_b128 v[144:147], v253 offset:2048
	v_add_u32_e32 v78, s97, v181
	ds_read_b128 v[148:151], v78
	v_xor_b32_e32 v253, 64, v78
	ds_read_b128 v[152:155], v253
	ds_read_b128 v[176:179], v78 offset:2048
	ds_read_b128 v[190:193], v253 offset:2048
	s_add_u32 s68, s68, 0x40000
	s_addc_u32 s69, s69, 0
	s_mov_b32 m0, s76
	v_lshl_add_u64 v[78:79], s[68:69], 0, v[160:161]
	ds_read_b128 v[194:197], v187 offset:32768
	v_xor_b32_e32 v253, 64, v187
	ds_read_b128 v[198:201], v253 offset:32768
	ds_read_b128 v[202:205], v187 offset:34816
	ds_read_b128 v[206:209], v253 offset:34816
	ds_read_b128 v[210:213], v187 offset:36864
	ds_read_b128 v[214:217], v253 offset:36864
	ds_read_b128 v[218:221], v187 offset:38912
	ds_read_b128 v[222:225], v253 offset:38912
	global_load_lds_dwordx4 v[78:79], off
	v_lshl_add_u64 v[78:79], s[68:69], 0, v[164:165]
	s_mov_b32 m0, s77
	s_nop 0
	global_load_lds_dwordx4 v[78:79], off
	s_waitcnt vmcnt(8)
	s_waitcnt lgkmcnt(0)
	s_setprio 1
	s_barrier
	v_mfma_f32_16x16x32_bf16 v[140:143], v[88:91], v[194:197], v[140:143]
	v_mfma_f32_16x16x32_bf16 v[136:139], v[128:131], v[194:197], v[136:139]
	v_mfma_f32_16x16x32_bf16 v[120:123], v[88:91], v[202:205], v[120:123]
	v_mfma_f32_16x16x32_bf16 v[116:119], v[128:131], v[202:205], v[116:119]
	v_mfma_f32_16x16x32_bf16 v[100:103], v[88:91], v[210:213], v[100:103]
	v_mfma_f32_16x16x32_bf16 v[96:99], v[128:131], v[210:213], v[96:99]
	v_mfma_f32_16x16x32_bf16 v[78:81], v[88:91], v[218:221], v[80:83]
	v_mfma_f32_16x16x32_bf16 v[74:77], v[128:131], v[218:221], v[74:77]
	v_mfma_f32_16x16x32_bf16 v[140:143], v[108:111], v[198:201], v[140:143]
	v_mfma_f32_16x16x32_bf16 v[136:139], v[144:147], v[198:201], v[136:139]
	v_mfma_f32_16x16x32_bf16 v[120:123], v[108:111], v[206:209], v[120:123]
	v_mfma_f32_16x16x32_bf16 v[116:119], v[144:147], v[206:209], v[116:119]
	v_mfma_f32_16x16x32_bf16 v[100:103], v[108:111], v[214:217], v[100:103]
	v_mfma_f32_16x16x32_bf16 v[96:99], v[144:147], v[214:217], v[96:99]
	v_mfma_f32_16x16x32_bf16 v[80:83], v[108:111], v[222:225], v[78:81]
	v_mfma_f32_16x16x32_bf16 v[76:79], v[144:147], v[222:225], v[74:77]
	s_setprio 0
	s_setprio 1
	v_mfma_f32_16x16x32_bf16 v[132:135], v[148:151], v[194:197], v[132:135]
	v_mfma_f32_16x16x32_bf16 v[132:135], v[152:155], v[198:201], v[132:135]
	v_mfma_f32_16x16x32_bf16 v[124:127], v[190:193], v[198:201], v[124:127]
	v_mfma_f32_16x16x32_bf16 v[124:127], v[176:179], v[194:197], v[124:127]
	v_mfma_f32_16x16x32_bf16 v[104:107], v[176:179], v[202:205], v[104:107]
	v_mfma_f32_16x16x32_bf16 v[104:107], v[190:193], v[206:209], v[104:107]
	v_mfma_f32_16x16x32_bf16 v[112:115], v[152:155], v[206:209], v[112:115]
	v_mfma_f32_16x16x32_bf16 v[112:115], v[148:151], v[202:205], v[112:115]
	v_mfma_f32_16x16x32_bf16 v[92:95], v[148:151], v[210:213], v[92:95]
	v_mfma_f32_16x16x32_bf16 v[92:95], v[152:155], v[214:217], v[92:95]
	v_mfma_f32_16x16x32_bf16 v[84:87], v[190:193], v[214:217], v[84:87]
	v_mfma_f32_16x16x32_bf16 v[84:87], v[176:179], v[210:213], v[84:87]
	v_mfma_f32_16x16x32_bf16 v[64:67], v[176:179], v[218:221], v[64:67]
	v_mfma_f32_16x16x32_bf16 v[64:67], v[190:193], v[222:225], v[64:67]
	v_mfma_f32_16x16x32_bf16 v[68:71], v[152:155], v[222:225], v[68:71]
	v_mfma_f32_16x16x32_bf16 v[68:71], v[148:151], v[218:221], v[68:71]
	s_barrier
	s_setprio 0
	s_add_i32 s68, s96, s71
	v_lshl_add_u64 v[74:75], v[226:227], 0, s[28:29]
	s_mov_b32 m0, s68
	ds_read_b128 v[194:197], v187 offset:49152
	v_xor_b32_e32 v253, 64, v187
	ds_read_b128 v[198:201], v253 offset:49152
	ds_read_b128 v[202:205], v187 offset:51200
	ds_read_b128 v[206:209], v253 offset:51200
	ds_read_b128 v[210:213], v187 offset:53248
	ds_read_b128 v[214:217], v253 offset:53248
	ds_read_b128 v[218:221], v187 offset:55296
	ds_read_b128 v[222:225], v253 offset:55296
	global_load_lds_dwordx4 v[74:75], off
	s_add_i32 m0, s68, 0x2000
	s_add_u32 s66, s66, 0x40080
	v_lshl_add_u64 v[74:75], v[228:229], 0, s[28:29]
	s_addc_u32 s67, s67, 0
	s_add_i32 s68, s97, s71
	global_load_lds_dwordx4 v[74:75], off
	v_lshl_add_u64 v[74:75], s[66:67], 0, v[162:163]
	s_mov_b32 m0, s68
	s_nop 0
	global_load_lds_dwordx4 v[74:75], off
	v_lshl_add_u64 v[74:75], s[66:67], 0, v[166:167]
	s_add_i32 m0, s68, 0x2000
	s_nop 0
	global_load_lds_dwordx4 v[74:75], off
	v_lshl_add_u64 v[74:75], v[230:231], 0, s[28:29]
	s_mov_b32 m0, s78
	s_nop 0
	global_load_lds_dwordx4 v[74:75], off
	v_lshl_add_u64 v[74:75], v[232:233], 0, s[28:29]
	s_mov_b32 m0, s79
	s_nop 0
	global_load_lds_dwordx4 v[74:75], off
	s_waitcnt vmcnt(8)
	s_waitcnt lgkmcnt(0)
	s_setprio 1
	s_barrier
	v_mfma_f32_16x16x32_bf16 v[60:63], v[88:91], v[194:197], v[60:63]
	v_mfma_f32_16x16x32_bf16 v[60:63], v[108:111], v[198:201], v[60:63]
	v_mfma_f32_16x16x32_bf16 v[56:59], v[144:147], v[198:201], v[56:59]
	v_mfma_f32_16x16x32_bf16 v[56:59], v[128:131], v[194:197], v[56:59]
	v_mfma_f32_16x16x32_bf16 v[40:43], v[128:131], v[202:205], v[40:43]
	v_mfma_f32_16x16x32_bf16 v[40:43], v[144:147], v[206:209], v[40:43]
	v_mfma_f32_16x16x32_bf16 v[44:47], v[108:111], v[206:209], v[44:47]
	v_mfma_f32_16x16x32_bf16 v[44:47], v[88:91], v[202:205], v[44:47]
	v_mfma_f32_16x16x32_bf16 v[28:31], v[88:91], v[210:213], v[28:31]
	v_mfma_f32_16x16x32_bf16 v[28:31], v[108:111], v[214:217], v[28:31]
	v_mfma_f32_16x16x32_bf16 v[24:27], v[144:147], v[214:217], v[24:27]
	v_mfma_f32_16x16x32_bf16 v[24:27], v[128:131], v[210:213], v[24:27]
	v_mfma_f32_16x16x32_bf16 v[8:11], v[128:131], v[218:221], v[8:11]
	v_mfma_f32_16x16x32_bf16 v[8:11], v[144:147], v[222:225], v[8:11]
	v_mfma_f32_16x16x32_bf16 v[12:15], v[108:111], v[222:225], v[12:15]
	v_mfma_f32_16x16x32_bf16 v[12:15], v[88:91], v[218:221], v[12:15]
	s_setprio 0
	s_setprio 1
	v_mfma_f32_16x16x32_bf16 v[52:55], v[148:151], v[194:197], v[52:55]
	v_mfma_f32_16x16x32_bf16 v[52:55], v[152:155], v[198:201], v[52:55]
	v_mfma_f32_16x16x32_bf16 v[48:51], v[190:193], v[198:201], v[48:51]
	v_mfma_f32_16x16x32_bf16 v[48:51], v[176:179], v[194:197], v[48:51]
	v_mfma_f32_16x16x32_bf16 v[32:35], v[176:179], v[202:205], v[32:35]
	v_mfma_f32_16x16x32_bf16 v[32:35], v[190:193], v[206:209], v[32:35]
	v_mfma_f32_16x16x32_bf16 v[36:39], v[152:155], v[206:209], v[36:39]
	v_mfma_f32_16x16x32_bf16 v[36:39], v[148:151], v[202:205], v[36:39]
	v_mfma_f32_16x16x32_bf16 v[20:23], v[148:151], v[210:213], v[20:23]
	v_mfma_f32_16x16x32_bf16 v[20:23], v[152:155], v[214:217], v[20:23]
	v_mfma_f32_16x16x32_bf16 v[16:19], v[190:193], v[214:217], v[16:19]
	v_mfma_f32_16x16x32_bf16 v[16:19], v[176:179], v[210:213], v[16:19]
	v_mfma_f32_16x16x32_bf16 v[0:3], v[176:179], v[218:221], v[0:3]
	v_mfma_f32_16x16x32_bf16 v[0:3], v[190:193], v[222:225], v[0:3]
	v_mfma_f32_16x16x32_bf16 v[4:7], v[152:155], v[222:225], v[4:7]
	v_mfma_f32_16x16x32_bf16 v[4:7], v[148:151], v[218:221], v[4:7]
	s_barrier
	s_setprio 0
	s_add_i32 s95, s95, 2
	s_add_u32 s93, s93, 0x100
	s_addc_u32 s94, s94, 0
	s_add_u32 s14, s14, 0x100
	s_addc_u32 s15, s15, 0
	s_branch .LBB0_256
.Lfa_2:
	v_add_u32_e32 v74, s83, v181
	ds_read_b128 v[88:91], v74
	v_xor_b32_e32 v253, 64, v74
	ds_read_b128 v[108:111], v253
	ds_read_b128 v[128:131], v74 offset:2048
	ds_read_b128 v[144:147], v253 offset:2048
	v_add_u32_e32 v74, s84, v181
	ds_read_b128 v[148:151], v74
	v_xor_b32_e32 v253, 64, v74
	ds_read_b128 v[152:155], v253
	ds_read_b128 v[176:179], v74 offset:2048
	ds_read_b128 v[190:193], v253 offset:2048
	s_add_u32 s68, s14, 0xfffc0080
	s_addc_u32 s69, s15, -1
	s_and_b64 s[66:67], s[66:67], exec
	s_cselect_b32 s69, s3, s69
	s_cselect_b32 s68, s61, s68
	s_cselect_b32 s67, s91, s94
	s_cselect_b32 s66, s92, s93
	v_lshl_add_u64 v[74:75], s[14:15], 0, v[170:171]
	s_add_i32 m0, s74, 0xc000
	ds_read_b128 v[194:197], v187
	v_xor_b32_e32 v253, 64, v187
	ds_read_b128 v[198:201], v253
	ds_read_b128 v[202:205], v187 offset:2048
	ds_read_b128 v[206:209], v253 offset:2048
	ds_read_b128 v[210:213], v187 offset:4096
	ds_read_b128 v[214:217], v253 offset:4096
	ds_read_b128 v[218:221], v187 offset:6144
	ds_read_b128 v[222:225], v253 offset:6144
	global_load_lds_dwordx4 v[74:75], off
	v_lshl_add_u64 v[74:75], s[14:15], 0, v[168:169]
	s_add_i32 m0, s74, 0xe000
	s_nop 0
	global_load_lds_dwordx4 v[74:75], off
	s_waitcnt vmcnt(8)
	s_waitcnt lgkmcnt(0)
	s_setprio 1
	s_barrier
	v_mfma_f32_16x16x32_bf16 v[140:143], v[88:91], v[194:197], 0
	v_mfma_f32_16x16x32_bf16 v[136:139], v[128:131], v[194:197], 0
	v_mfma_f32_16x16x32_bf16 v[120:123], v[88:91], v[202:205], 0
	v_mfma_f32_16x16x32_bf16 v[116:119], v[128:131], v[202:205], 0
	v_mfma_f32_16x16x32_bf16 v[100:103], v[88:91], v[210:213], 0
	v_mfma_f32_16x16x32_bf16 v[96:99], v[128:131], v[210:213], 0
	v_mfma_f32_16x16x32_bf16 v[80:83], v[88:91], v[218:221], 0
	v_mfma_f32_16x16x32_bf16 v[74:77], v[128:131], v[218:221], 0
	v_mfma_f32_16x16x32_bf16 v[140:143], v[108:111], v[198:201], v[140:143]
	v_mfma_f32_16x16x32_bf16 v[136:139], v[144:147], v[198:201], v[136:139]
	v_mfma_f32_16x16x32_bf16 v[120:123], v[108:111], v[206:209], v[120:123]
	v_mfma_f32_16x16x32_bf16 v[116:119], v[144:147], v[206:209], v[116:119]
	v_mfma_f32_16x16x32_bf16 v[100:103], v[108:111], v[214:217], v[100:103]
	v_mfma_f32_16x16x32_bf16 v[96:99], v[144:147], v[214:217], v[96:99]
	v_mfma_f32_16x16x32_bf16 v[80:83], v[108:111], v[222:225], v[80:83]
	v_mfma_f32_16x16x32_bf16 v[74:77], v[144:147], v[222:225], v[74:77]
	s_setprio 0
	s_setprio 1
	v_mfma_f32_16x16x32_bf16 v[132:135], v[148:151], v[194:197], 0
	v_mfma_f32_16x16x32_bf16 v[132:135], v[152:155], v[198:201], v[132:135]
	v_mfma_f32_16x16x32_bf16 v[124:127], v[176:179], v[194:197], 0
	v_mfma_f32_16x16x32_bf16 v[124:127], v[190:193], v[198:201], v[124:127]
	v_mfma_f32_16x16x32_bf16 v[112:115], v[148:151], v[202:205], 0
	v_mfma_f32_16x16x32_bf16 v[112:115], v[152:155], v[206:209], v[112:115]
	v_mfma_f32_16x16x32_bf16 v[104:107], v[176:179], v[202:205], 0
	v_mfma_f32_16x16x32_bf16 v[104:107], v[190:193], v[206:209], v[104:107]
	v_mfma_f32_16x16x32_bf16 v[92:95], v[148:151], v[210:213], 0
	v_mfma_f32_16x16x32_bf16 v[92:95], v[152:155], v[214:217], v[92:95]
	v_mfma_f32_16x16x32_bf16 v[84:87], v[176:179], v[210:213], 0
	v_mfma_f32_16x16x32_bf16 v[84:87], v[190:193], v[214:217], v[84:87]
	v_mfma_f32_16x16x32_bf16 v[68:71], v[148:151], v[218:221], 0
	v_mfma_f32_16x16x32_bf16 v[68:71], v[152:155], v[222:225], v[68:71]
	v_mfma_f32_16x16x32_bf16 v[64:67], v[176:179], v[218:221], 0
	v_mfma_f32_16x16x32_bf16 v[64:67], v[190:193], v[222:225], v[64:67]
	s_barrier
	s_setprio 0
	s_add_i32 s96, s83, s71
	v_lshl_add_u64 v[226:227], s[66:67], 0, v[162:163]
	s_mov_b32 m0, s96
	ds_read_b128 v[194:197], v187 offset:16384
	v_xor_b32_e32 v253, 64, v187
	ds_read_b128 v[198:201], v253 offset:16384
	ds_read_b128 v[202:205], v187 offset:18432
	ds_read_b128 v[206:209], v253 offset:18432
	ds_read_b128 v[210:213], v187 offset:20480
	ds_read_b128 v[214:217], v253 offset:20480
	ds_read_b128 v[218:221], v187 offset:22528
	ds_read_b128 v[222:225], v253 offset:22528
	global_load_lds_dwordx4 v[226:227], off
	s_add_i32 m0, s96, 0x2000
	s_add_u32 s96, s66, 0x40000
	v_lshl_add_u64 v[228:229], s[66:67], 0, v[166:167]
	s_addc_u32 s97, s67, 0
	s_add_i32 vcc_lo, s84, s71
	global_load_lds_dwordx4 v[228:229], off
	v_lshl_add_u64 v[78:79], s[96:97], 0, v[162:163]
	s_mov_b32 m0, vcc_lo
	v_lshl_add_u64 v[230:231], s[68:69], 0, v[160:161]
	global_load_lds_dwordx4 v[78:79], off
	v_lshl_add_u64 v[78:79], s[96:97], 0, v[166:167]
	s_add_i32 m0, vcc_lo, 0x2000
	v_lshl_add_u64 v[232:233], s[68:69], 0, v[164:165]
	global_load_lds_dwordx4 v[78:79], off
	s_mov_b32 m0, s74
	s_nop 0
	global_load_lds_dwordx4 v[230:231], off
	s_mov_b32 m0, s75
	s_nop 0
	global_load_lds_dwordx4 v[232:233], off
	s_waitcnt vmcnt(8)
	s_waitcnt lgkmcnt(0)
	s_setprio 1
	s_barrier
	v_mfma_f32_16x16x32_bf16 v[60:63], v[88:91], v[194:197], 0
	v_mfma_f32_16x16x32_bf16 v[60:63], v[108:111], v[198:201], v[60:63]
	v_mfma_f32_16x16x32_bf16 v[56:59], v[128:131], v[194:197], 0
	v_mfma_f32_16x16x32_bf16 v[56:59], v[144:147], v[198:201], v[56:59]
	v_mfma_f32_16x16x32_bf16 v[44:47], v[88:91], v[202:205], 0
	v_mfma_f32_16x16x32_bf16 v[44:47], v[108:111], v[206:209], v[44:47]
	v_mfma_f32_16x16x32_bf16 v[40:43], v[128:131], v[202:205], 0
	v_mfma_f32_16x16x32_bf16 v[40:43], v[144:147], v[206:209], v[40:43]
	v_mfma_f32_16x16x32_bf16 v[28:31], v[88:91], v[210:213], 0
	v_mfma_f32_16x16x32_bf16 v[28:31], v[108:111], v[214:217], v[28:31]
	v_mfma_f32_16x16x32_bf16 v[24:27], v[128:131], v[210:213], 0
	v_mfma_f32_16x16x32_bf16 v[24:27], v[144:147], v[214:217], v[24:27]
	v_mfma_f32_16x16x32_bf16 v[12:15], v[88:91], v[218:221], 0
	v_mfma_f32_16x16x32_bf16 v[12:15], v[108:111], v[222:225], v[12:15]
	v_mfma_f32_16x16x32_bf16 v[8:11], v[128:131], v[218:221], 0
	v_mfma_f32_16x16x32_bf16 v[8:11], v[144:147], v[222:225], v[8:11]
	s_setprio 0
	s_setprio 1
	v_mfma_f32_16x16x32_bf16 v[52:55], v[148:151], v[194:197], 0
	v_mfma_f32_16x16x32_bf16 v[52:55], v[152:155], v[198:201], v[52:55]
	v_mfma_f32_16x16x32_bf16 v[48:51], v[176:179], v[194:197], 0
	v_mfma_f32_16x16x32_bf16 v[48:51], v[190:193], v[198:201], v[48:51]
	v_mfma_f32_16x16x32_bf16 v[36:39], v[148:151], v[202:205], 0
	v_mfma_f32_16x16x32_bf16 v[36:39], v[152:155], v[206:209], v[36:39]
	v_mfma_f32_16x16x32_bf16 v[32:35], v[176:179], v[202:205], 0
	v_mfma_f32_16x16x32_bf16 v[32:35], v[190:193], v[206:209], v[32:35]
	v_mfma_f32_16x16x32_bf16 v[20:23], v[148:151], v[210:213], 0
	v_mfma_f32_16x16x32_bf16 v[20:23], v[152:155], v[214:217], v[20:23]
	v_mfma_f32_16x16x32_bf16 v[16:19], v[176:179], v[210:213], 0
	v_mfma_f32_16x16x32_bf16 v[16:19], v[190:193], v[214:217], v[16:19]
	v_mfma_f32_16x16x32_bf16 v[4:7], v[148:151], v[218:221], 0
	v_mfma_f32_16x16x32_bf16 v[4:7], v[152:155], v[222:225], v[4:7]
	v_mfma_f32_16x16x32_bf16 v[0:3], v[176:179], v[218:221], 0
	v_mfma_f32_16x16x32_bf16 v[0:3], v[190:193], v[222:225], v[0:3]
	s_barrier
	s_setprio 0
	s_add_i32 s96, 0, 0x18000
	v_add_u32_e32 v78, s96, v181
	s_add_i32 s97, 0, 0x1c000
	ds_read_b128 v[88:91], v78
	v_xor_b32_e32 v253, 64, v78
	ds_read_b128 v[108:111], v253
	ds_read_b128 v[128:131], v78 offset:2048
	ds_read_b128 v[144:147], v253 offset:2048
	v_add_u32_e32 v78, s97, v181
	ds_read_b128 v[148:151], v78
	v_xor_b32_e32 v253, 64, v78
	ds_read_b128 v[152:155], v253
	ds_read_b128 v[176:179], v78 offset:2048
	ds_read_b128 v[190:193], v253 offset:2048
	s_add_u32 s68, s68, 0x40000
	s_addc_u32 s69, s69, 0
	s_mov_b32 m0, s76
	v_lshl_add_u64 v[78:79], s[68:69], 0, v[160:161]
	ds_read_b128 v[194:197], v187 offset:32768
	v_xor_b32_e32 v253, 64, v187
	ds_read_b128 v[198:201], v253 offset:32768
	ds_read_b128 v[202:205], v187 offset:34816
	ds_read_b128 v[206:209], v253 offset:34816
	ds_read_b128 v[210:213], v187 offset:36864
	ds_read_b128 v[214:217], v253 offset:36864
	ds_read_b128 v[218:221], v187 offset:38912
	ds_read_b128 v[222:225], v253 offset:38912
	global_load_lds_dwordx4 v[78:79], off
	v_lshl_add_u64 v[78:79], s[68:69], 0, v[164:165]
	s_mov_b32 m0, s77
	s_nop 0
	global_load_lds_dwordx4 v[78:79], off
	s_waitcnt vmcnt(8)
	s_waitcnt lgkmcnt(0)
	s_setprio 1
	s_barrier
	v_mfma_f32_16x16x32_bf16 v[140:143], v[88:91], v[194:197], v[140:143]
	v_mfma_f32_16x16x32_bf16 v[136:139], v[128:131], v[194:197], v[136:139]
	v_mfma_f32_16x16x32_bf16 v[120:123], v[88:91], v[202:205], v[120:123]
	v_mfma_f32_16x16x32_bf16 v[116:119], v[128:131], v[202:205], v[116:119]
	v_mfma_f32_16x16x32_bf16 v[100:103], v[88:91], v[210:213], v[100:103]
	v_mfma_f32_16x16x32_bf16 v[96:99], v[128:131], v[210:213], v[96:99]
	v_mfma_f32_16x16x32_bf16 v[78:81], v[88:91], v[218:221], v[80:83]
	v_mfma_f32_16x16x32_bf16 v[74:77], v[128:131], v[218:221], v[74:77]
	v_mfma_f32_16x16x32_bf16 v[140:143], v[108:111], v[198:201], v[140:143]
	v_mfma_f32_16x16x32_bf16 v[136:139], v[144:147], v[198:201], v[136:139]
	v_mfma_f32_16x16x32_bf16 v[120:123], v[108:111], v[206:209], v[120:123]
	v_mfma_f32_16x16x32_bf16 v[116:119], v[144:147], v[206:209], v[116:119]
	v_mfma_f32_16x16x32_bf16 v[100:103], v[108:111], v[214:217], v[100:103]
	v_mfma_f32_16x16x32_bf16 v[96:99], v[144:147], v[214:217], v[96:99]
	v_mfma_f32_16x16x32_bf16 v[80:83], v[108:111], v[222:225], v[78:81]
	v_mfma_f32_16x16x32_bf16 v[76:79], v[144:147], v[222:225], v[74:77]
	s_setprio 0
	s_setprio 1
	v_mfma_f32_16x16x32_bf16 v[132:135], v[148:151], v[194:197], v[132:135]
	v_mfma_f32_16x16x32_bf16 v[132:135], v[152:155], v[198:201], v[132:135]
	v_mfma_f32_16x16x32_bf16 v[124:127], v[190:193], v[198:201], v[124:127]
	v_mfma_f32_16x16x32_bf16 v[124:127], v[176:179], v[194:197], v[124:127]
	v_mfma_f32_16x16x32_bf16 v[104:107], v[176:179], v[202:205], v[104:107]
	v_mfma_f32_16x16x32_bf16 v[104:107], v[190:193], v[206:209], v[104:107]
	v_mfma_f32_16x16x32_bf16 v[112:115], v[152:155], v[206:209], v[112:115]
	v_mfma_f32_16x16x32_bf16 v[112:115], v[148:151], v[202:205], v[112:115]
	v_mfma_f32_16x16x32_bf16 v[92:95], v[148:151], v[210:213], v[92:95]
	v_mfma_f32_16x16x32_bf16 v[92:95], v[152:155], v[214:217], v[92:95]
	v_mfma_f32_16x16x32_bf16 v[84:87], v[190:193], v[214:217], v[84:87]
	v_mfma_f32_16x16x32_bf16 v[84:87], v[176:179], v[210:213], v[84:87]
	v_mfma_f32_16x16x32_bf16 v[64:67], v[176:179], v[218:221], v[64:67]
	v_mfma_f32_16x16x32_bf16 v[64:67], v[190:193], v[222:225], v[64:67]
	v_mfma_f32_16x16x32_bf16 v[68:71], v[152:155], v[222:225], v[68:71]
	v_mfma_f32_16x16x32_bf16 v[68:71], v[148:151], v[218:221], v[68:71]
	s_barrier
	s_setprio 0
	s_add_i32 s68, s96, s71
	v_lshl_add_u64 v[74:75], v[226:227], 0, s[28:29]
	s_mov_b32 m0, s68
	ds_read_b128 v[194:197], v187 offset:49152
	v_xor_b32_e32 v253, 64, v187
	ds_read_b128 v[198:201], v253 offset:49152
	ds_read_b128 v[202:205], v187 offset:51200
	ds_read_b128 v[206:209], v253 offset:51200
	ds_read_b128 v[210:213], v187 offset:53248
	ds_read_b128 v[214:217], v253 offset:53248
	ds_read_b128 v[218:221], v187 offset:55296
	ds_read_b128 v[222:225], v253 offset:55296
	global_load_lds_dwordx4 v[74:75], off
	s_add_i32 m0, s68, 0x2000
	s_add_u32 s66, s66, 0x40080
	v_lshl_add_u64 v[74:75], v[228:229], 0, s[28:29]
	s_addc_u32 s67, s67, 0
	s_add_i32 s68, s97, s71
	global_load_lds_dwordx4 v[74:75], off
	v_lshl_add_u64 v[74:75], s[66:67], 0, v[162:163]
	s_mov_b32 m0, s68
	s_nop 0
	global_load_lds_dwordx4 v[74:75], off
	v_lshl_add_u64 v[74:75], s[66:67], 0, v[166:167]
	s_add_i32 m0, s68, 0x2000
	s_nop 0
	global_load_lds_dwordx4 v[74:75], off
	v_lshl_add_u64 v[74:75], v[230:231], 0, s[28:29]
	s_mov_b32 m0, s78
	s_nop 0
	global_load_lds_dwordx4 v[74:75], off
	v_lshl_add_u64 v[74:75], v[232:233], 0, s[28:29]
	s_mov_b32 m0, s79
	s_nop 0
	global_load_lds_dwordx4 v[74:75], off
	s_waitcnt vmcnt(8)
	s_waitcnt lgkmcnt(0)
	s_setprio 1
	s_barrier
	v_mfma_f32_16x16x32_bf16 v[60:63], v[88:91], v[194:197], v[60:63]
	v_mfma_f32_16x16x32_bf16 v[60:63], v[108:111], v[198:201], v[60:63]
	v_mfma_f32_16x16x32_bf16 v[56:59], v[144:147], v[198:201], v[56:59]
	v_mfma_f32_16x16x32_bf16 v[56:59], v[128:131], v[194:197], v[56:59]
	v_mfma_f32_16x16x32_bf16 v[40:43], v[128:131], v[202:205], v[40:43]
	v_mfma_f32_16x16x32_bf16 v[40:43], v[144:147], v[206:209], v[40:43]
	v_mfma_f32_16x16x32_bf16 v[44:47], v[108:111], v[206:209], v[44:47]
	v_mfma_f32_16x16x32_bf16 v[44:47], v[88:91], v[202:205], v[44:47]
	v_mfma_f32_16x16x32_bf16 v[28:31], v[88:91], v[210:213], v[28:31]
	v_mfma_f32_16x16x32_bf16 v[28:31], v[108:111], v[214:217], v[28:31]
	v_mfma_f32_16x16x32_bf16 v[24:27], v[144:147], v[214:217], v[24:27]
	v_mfma_f32_16x16x32_bf16 v[24:27], v[128:131], v[210:213], v[24:27]
	v_mfma_f32_16x16x32_bf16 v[8:11], v[128:131], v[218:221], v[8:11]
	v_mfma_f32_16x16x32_bf16 v[8:11], v[144:147], v[222:225], v[8:11]
	v_mfma_f32_16x16x32_bf16 v[12:15], v[108:111], v[222:225], v[12:15]
	v_mfma_f32_16x16x32_bf16 v[12:15], v[88:91], v[218:221], v[12:15]
	s_setprio 0
	s_setprio 1
	v_mfma_f32_16x16x32_bf16 v[52:55], v[148:151], v[194:197], v[52:55]
	v_mfma_f32_16x16x32_bf16 v[52:55], v[152:155], v[198:201], v[52:55]
	v_mfma_f32_16x16x32_bf16 v[48:51], v[190:193], v[198:201], v[48:51]
	v_mfma_f32_16x16x32_bf16 v[48:51], v[176:179], v[194:197], v[48:51]
	v_mfma_f32_16x16x32_bf16 v[32:35], v[176:179], v[202:205], v[32:35]
	v_mfma_f32_16x16x32_bf16 v[32:35], v[190:193], v[206:209], v[32:35]
	v_mfma_f32_16x16x32_bf16 v[36:39], v[152:155], v[206:209], v[36:39]
	v_mfma_f32_16x16x32_bf16 v[36:39], v[148:151], v[202:205], v[36:39]
	v_mfma_f32_16x16x32_bf16 v[20:23], v[148:151], v[210:213], v[20:23]
	v_mfma_f32_16x16x32_bf16 v[20:23], v[152:155], v[214:217], v[20:23]
	v_mfma_f32_16x16x32_bf16 v[16:19], v[190:193], v[214:217], v[16:19]
	v_mfma_f32_16x16x32_bf16 v[16:19], v[176:179], v[210:213], v[16:19]
	v_mfma_f32_16x16x32_bf16 v[0:3], v[176:179], v[218:221], v[0:3]
	v_mfma_f32_16x16x32_bf16 v[0:3], v[190:193], v[222:225], v[0:3]
	v_mfma_f32_16x16x32_bf16 v[4:7], v[152:155], v[222:225], v[4:7]
	v_mfma_f32_16x16x32_bf16 v[4:7], v[148:151], v[218:221], v[4:7]
	s_barrier
	s_setprio 0
	s_add_i32 s95, s95, 2
	s_add_u32 s93, s93, 0x100
	s_addc_u32 s94, s94, 0
	s_add_u32 s14, s14, 0x100
	s_addc_u32 s15, s15, 0
	s_branch .LBB0_256

.LBB0_439:
	s_ashr_i32 s53, s52, 31
	s_lshl_b64 s[54:55], s[52:53], 20
	s_add_u32 s54, s35, s54
	s_addc_u32 s55, s66, s55
	s_and_b64 s[56:57], s[12:13], exec
	s_cselect_b32 s15, s55, s63
	s_cselect_b32 s53, s54, s62
	s_ashr_i32 s51, s50, 31
	s_lshl_b64 s[56:57], s[50:51], 20
	s_add_u32 s56, s67, s56
	s_addc_u32 s57, s68, s57
	s_and_b64 s[64:65], s[12:13], exec
	s_cselect_b32 s51, s57, s61
	s_cselect_b32 s59, s56, s60
	s_add_u32 s81, s60, 0x100
	s_addc_u32 s82, s61, 0
	s_add_u32 s60, s62, 0x80080
	s_addc_u32 s61, s63, 0
	s_mov_b32 s83, -2
	s_waitcnt lgkmcnt(0)
	s_cmp_eq_u32 s74, 1
	s_cbranch_scc1 .Lfa_3
	ds_read_b128 v[128:131], v189
	v_xor_b32_e32 v253, 64, v189
	ds_read_b128 v[132:135], v253
	ds_read_b128 v[136:139], v189 offset:2048
	ds_read_b128 v[140:143], v253 offset:2048
	ds_read_b128 v[144:147], v190
	v_xor_b32_e32 v253, 64, v190
	ds_read_b128 v[148:151], v253
	ds_read_b128 v[172:175], v190 offset:2048
	ds_read_b128 v[176:179], v253 offset:2048
	s_add_u32 s62, s60, 0xfff80080
	s_addc_u32 s63, s61, -1
	s_cmp_eq_u32 s83, 28
	s_cselect_b32 s65, s15, s63
	s_cselect_b32 s64, s53, s62
	s_cselect_b32 s63, s51, s82
	s_cselect_b32 s62, s59, s81
	v_lshl_add_u64 v[222:223], s[60:61], 0, v[166:167]
	s_add_i32 m0, s70, 0xc000
	ds_read_b128 v[180:183], v191
	v_xor_b32_e32 v253, 64, v191
	ds_read_b128 v[194:197], v253
	ds_read_b128 v[198:201], v191 offset:2048
	ds_read_b128 v[202:205], v253 offset:2048
	ds_read_b128 v[206:209], v191 offset:4096
	ds_read_b128 v[210:213], v253 offset:4096
	ds_read_b128 v[214:217], v191 offset:6144
	ds_read_b128 v[218:221], v253 offset:6144
	global_load_lds_dwordx4 v[222:223], off
	v_lshl_add_u64 v[222:223], s[60:61], 0, v[164:165]
	s_add_i32 m0, s70, 0xe000
	s_nop 0
	global_load_lds_dwordx4 v[222:223], off
	s_waitcnt vmcnt(24)
	s_waitcnt lgkmcnt(0)
	s_setprio 1
	s_barrier
	v_mfma_f32_16x16x32_bf16 v[124:127], v[128:131], v[180:183], 0
	v_mfma_f32_16x16x32_bf16 v[124:127], v[132:135], v[194:197], v[124:127]
	v_mfma_f32_16x16x32_bf16 v[120:123], v[136:139], v[180:183], 0
	v_mfma_f32_16x16x32_bf16 v[120:123], v[140:143], v[194:197], v[120:123]
	v_mfma_f32_16x16x32_bf16 v[108:111], v[128:131], v[198:201], 0
	v_mfma_f32_16x16x32_bf16 v[108:111], v[132:135], v[202:205], v[108:111]
	v_mfma_f32_16x16x32_bf16 v[104:107], v[136:139], v[198:201], 0
	v_mfma_f32_16x16x32_bf16 v[104:107], v[140:143], v[202:205], v[104:107]
	v_mfma_f32_16x16x32_bf16 v[92:95], v[128:131], v[206:209], 0
	v_mfma_f32_16x16x32_bf16 v[92:95], v[132:135], v[210:213], v[92:95]
	v_mfma_f32_16x16x32_bf16 v[88:91], v[136:139], v[206:209], 0
	v_mfma_f32_16x16x32_bf16 v[88:91], v[140:143], v[210:213], v[88:91]
	v_mfma_f32_16x16x32_bf16 v[76:79], v[128:131], v[214:217], 0
	v_mfma_f32_16x16x32_bf16 v[76:79], v[132:135], v[218:221], v[76:79]
	v_mfma_f32_16x16x32_bf16 v[72:75], v[136:139], v[214:217], 0
	v_mfma_f32_16x16x32_bf16 v[72:75], v[140:143], v[218:221], v[72:75]
	s_setprio 0
	s_setprio 1
	v_mfma_f32_16x16x32_bf16 v[116:119], v[144:147], v[180:183], 0
	v_mfma_f32_16x16x32_bf16 v[116:119], v[148:151], v[194:197], v[116:119]
	v_mfma_f32_16x16x32_bf16 v[112:115], v[172:175], v[180:183], 0
	v_mfma_f32_16x16x32_bf16 v[112:115], v[176:179], v[194:197], v[112:115]
	v_mfma_f32_16x16x32_bf16 v[100:103], v[144:147], v[198:201], 0
	v_mfma_f32_16x16x32_bf16 v[100:103], v[148:151], v[202:205], v[100:103]
	v_mfma_f32_16x16x32_bf16 v[96:99], v[172:175], v[198:201], 0
	v_mfma_f32_16x16x32_bf16 v[96:99], v[176:179], v[202:205], v[96:99]
	v_mfma_f32_16x16x32_bf16 v[84:87], v[144:147], v[206:209], 0
	v_mfma_f32_16x16x32_bf16 v[84:87], v[148:151], v[210:213], v[84:87]
	v_mfma_f32_16x16x32_bf16 v[80:83], v[172:175], v[206:209], 0
	v_mfma_f32_16x16x32_bf16 v[80:83], v[176:179], v[210:213], v[80:83]
	v_mfma_f32_16x16x32_bf16 v[68:71], v[144:147], v[214:217], 0
	v_mfma_f32_16x16x32_bf16 v[68:71], v[148:151], v[218:221], v[68:71]
	v_mfma_f32_16x16x32_bf16 v[64:67], v[172:175], v[214:217], 0
	v_mfma_f32_16x16x32_bf16 v[64:67], v[176:179], v[218:221], v[64:67]
	s_barrier
	s_setprio 0
	s_add_i32 s84, s79, s69
	v_lshl_add_u64 v[222:223], s[62:63], 0, v[154:155]
	s_mov_b32 m0, s84
	ds_read_b128 v[180:183], v191 offset:16384
	v_xor_b32_e32 v253, 64, v191
	ds_read_b128 v[194:197], v253 offset:16384
	ds_read_b128 v[198:201], v191 offset:18432
	ds_read_b128 v[202:205], v253 offset:18432
	ds_read_b128 v[206:209], v191 offset:20480
	ds_read_b128 v[210:213], v253 offset:20480
	ds_read_b128 v[214:217], v191 offset:22528
	ds_read_b128 v[218:221], v253 offset:22528
	global_load_lds_dwordx4 v[222:223], off
	s_add_i32 m0, s84, 0x2000
	s_add_u32 s84, s62, 0x80000
	v_lshl_add_u64 v[224:225], s[62:63], 0, v[162:163]
	s_addc_u32 s85, s63, 0
	s_add_i32 s86, s80, s69
	global_load_lds_dwordx4 v[224:225], off
	v_lshl_add_u64 v[226:227], s[84:85], 0, v[154:155]
	s_mov_b32 m0, s86
	v_lshl_add_u64 v[228:229], s[64:65], 0, v[160:161]
	global_load_lds_dwordx4 v[226:227], off
	v_lshl_add_u64 v[226:227], s[84:85], 0, v[162:163]
	s_add_i32 m0, s86, 0x2000
	s_nop 0
	global_load_lds_dwordx4 v[226:227], off
	v_lshl_add_u64 v[226:227], s[64:65], 0, v[152:153]
	s_mov_b32 m0, s70
	s_nop 0
	global_load_lds_dwordx4 v[226:227], off
	s_mov_b32 m0, s71
	s_nop 0
	global_load_lds_dwordx4 v[228:229], off
	s_waitcnt vmcnt(24)
	s_waitcnt lgkmcnt(0)
	s_setprio 1
	s_barrier
	v_mfma_f32_16x16x32_bf16 v[60:63], v[128:131], v[180:183], 0
	v_mfma_f32_16x16x32_bf16 v[60:63], v[132:135], v[194:197], v[60:63]
	v_mfma_f32_16x16x32_bf16 v[56:59], v[136:139], v[180:183], 0
	v_mfma_f32_16x16x32_bf16 v[56:59], v[140:143], v[194:197], v[56:59]
	v_mfma_f32_16x16x32_bf16 v[44:47], v[128:131], v[198:201], 0
	v_mfma_f32_16x16x32_bf16 v[44:47], v[132:135], v[202:205], v[44:47]
	v_mfma_f32_16x16x32_bf16 v[40:43], v[136:139], v[198:201], 0
	v_mfma_f32_16x16x32_bf16 v[40:43], v[140:143], v[202:205], v[40:43]
	v_mfma_f32_16x16x32_bf16 v[28:31], v[128:131], v[206:209], 0
	v_mfma_f32_16x16x32_bf16 v[28:31], v[132:135], v[210:213], v[28:31]
	v_mfma_f32_16x16x32_bf16 v[24:27], v[136:139], v[206:209], 0
	v_mfma_f32_16x16x32_bf16 v[24:27], v[140:143], v[210:213], v[24:27]
	v_mfma_f32_16x16x32_bf16 v[12:15], v[128:131], v[214:217], 0
	v_mfma_f32_16x16x32_bf16 v[12:15], v[132:135], v[218:221], v[12:15]
	v_mfma_f32_16x16x32_bf16 v[8:11], v[136:139], v[214:217], 0
	v_mfma_f32_16x16x32_bf16 v[8:11], v[140:143], v[218:221], v[8:11]
	s_setprio 0
	s_setprio 1
	v_mfma_f32_16x16x32_bf16 v[52:55], v[144:147], v[180:183], 0
	v_mfma_f32_16x16x32_bf16 v[52:55], v[148:151], v[194:197], v[52:55]
	v_mfma_f32_16x16x32_bf16 v[48:51], v[172:175], v[180:183], 0
	v_mfma_f32_16x16x32_bf16 v[48:51], v[176:179], v[194:197], v[48:51]
	v_mfma_f32_16x16x32_bf16 v[36:39], v[144:147], v[198:201], 0
	v_mfma_f32_16x16x32_bf16 v[36:39], v[148:151], v[202:205], v[36:39]
	v_mfma_f32_16x16x32_bf16 v[32:35], v[172:175], v[198:201], 0
	v_mfma_f32_16x16x32_bf16 v[32:35], v[176:179], v[202:205], v[32:35]
	v_mfma_f32_16x16x32_bf16 v[20:23], v[144:147], v[206:209], 0
	v_mfma_f32_16x16x32_bf16 v[20:23], v[148:151], v[210:213], v[20:23]
	v_mfma_f32_16x16x32_bf16 v[16:19], v[172:175], v[206:209], 0
	v_mfma_f32_16x16x32_bf16 v[16:19], v[176:179], v[210:213], v[16:19]
	v_mfma_f32_16x16x32_bf16 v[4:7], v[144:147], v[214:217], 0
	v_mfma_f32_16x16x32_bf16 v[4:7], v[148:151], v[218:221], v[4:7]
	v_mfma_f32_16x16x32_bf16 v[0:3], v[172:175], v[214:217], 0
	v_mfma_f32_16x16x32_bf16 v[0:3], v[176:179], v[218:221], v[0:3]
	s_barrier
	s_setprio 0
	s_add_i32 s84, 0, 0x18000
	s_add_i32 s85, 0, 0x1c000
	v_add_u32_e32 v140, s84, v186
	v_add_u32_e32 v176, s85, v186
	ds_read_b128 v[128:131], v140
	v_xor_b32_e32 v253, 64, v140
	ds_read_b128 v[132:135], v253
	ds_read_b128 v[136:139], v140 offset:2048
	ds_read_b128 v[140:143], v253 offset:2048
	ds_read_b128 v[144:147], v176
	v_xor_b32_e32 v253, 64, v176
	ds_read_b128 v[148:151], v253
	ds_read_b128 v[172:175], v176 offset:2048
	ds_read_b128 v[176:179], v253 offset:2048
	s_add_u32 s64, s64, 0x80000
	s_addc_u32 s65, s65, 0
	s_mov_b32 m0, s72
	v_lshl_add_u64 v[230:231], s[64:65], 0, v[152:153]
	ds_read_b128 v[180:183], v191 offset:32768
	v_xor_b32_e32 v253, 64, v191
	ds_read_b128 v[194:197], v253 offset:32768
	ds_read_b128 v[198:201], v191 offset:34816
	ds_read_b128 v[202:205], v253 offset:34816
	ds_read_b128 v[206:209], v191 offset:36864
	ds_read_b128 v[210:213], v253 offset:36864
	ds_read_b128 v[214:217], v191 offset:38912
	ds_read_b128 v[218:221], v253 offset:38912
	global_load_lds_dwordx4 v[230:231], off
	v_lshl_add_u64 v[230:231], s[64:65], 0, v[160:161]
	s_mov_b32 m0, s73
	s_nop 0
	global_load_lds_dwordx4 v[230:231], off
	s_waitcnt vmcnt(8)
	s_waitcnt lgkmcnt(0)
	s_setprio 1
	s_barrier
	v_mfma_f32_16x16x32_bf16 v[124:127], v[128:131], v[180:183], v[124:127]
	v_mfma_f32_16x16x32_bf16 v[124:127], v[132:135], v[194:197], v[124:127]
	v_mfma_f32_16x16x32_bf16 v[120:123], v[140:143], v[194:197], v[120:123]
	v_mfma_f32_16x16x32_bf16 v[120:123], v[136:139], v[180:183], v[120:123]
	v_mfma_f32_16x16x32_bf16 v[104:107], v[136:139], v[198:201], v[104:107]
	v_mfma_f32_16x16x32_bf16 v[104:107], v[140:143], v[202:205], v[104:107]
	v_mfma_f32_16x16x32_bf16 v[108:111], v[132:135], v[202:205], v[108:111]
	v_mfma_f32_16x16x32_bf16 v[108:111], v[128:131], v[198:201], v[108:111]
	v_mfma_f32_16x16x32_bf16 v[92:95], v[128:131], v[206:209], v[92:95]
	v_mfma_f32_16x16x32_bf16 v[92:95], v[132:135], v[210:213], v[92:95]
	v_mfma_f32_16x16x32_bf16 v[88:91], v[140:143], v[210:213], v[88:91]
	v_mfma_f32_16x16x32_bf16 v[88:91], v[136:139], v[206:209], v[88:91]
	v_mfma_f32_16x16x32_bf16 v[72:75], v[136:139], v[214:217], v[72:75]
	v_mfma_f32_16x16x32_bf16 v[72:75], v[140:143], v[218:221], v[72:75]
	v_mfma_f32_16x16x32_bf16 v[76:79], v[132:135], v[218:221], v[76:79]
	v_mfma_f32_16x16x32_bf16 v[76:79], v[128:131], v[214:217], v[76:79]
	s_setprio 0
	s_setprio 1
	v_mfma_f32_16x16x32_bf16 v[116:119], v[144:147], v[180:183], v[116:119]
	v_mfma_f32_16x16x32_bf16 v[116:119], v[148:151], v[194:197], v[116:119]
	v_mfma_f32_16x16x32_bf16 v[112:115], v[176:179], v[194:197], v[112:115]
	v_mfma_f32_16x16x32_bf16 v[112:115], v[172:175], v[180:183], v[112:115]
	v_mfma_f32_16x16x32_bf16 v[96:99], v[172:175], v[198:201], v[96:99]
	v_mfma_f32_16x16x32_bf16 v[96:99], v[176:179], v[202:205], v[96:99]
	v_mfma_f32_16x16x32_bf16 v[100:103], v[148:151], v[202:205], v[100:103]
	v_mfma_f32_16x16x32_bf16 v[100:103], v[144:147], v[198:201], v[100:103]
	v_mfma_f32_16x16x32_bf16 v[84:87], v[144:147], v[206:209], v[84:87]
	v_mfma_f32_16x16x32_bf16 v[84:87], v[148:151], v[210:213], v[84:87]
	v_mfma_f32_16x16x32_bf16 v[80:83], v[176:179], v[210:213], v[80:83]
	v_mfma_f32_16x16x32_bf16 v[80:83], v[172:175], v[206:209], v[80:83]
	v_mfma_f32_16x16x32_bf16 v[64:67], v[172:175], v[214:217], v[64:67]
	v_mfma_f32_16x16x32_bf16 v[64:67], v[176:179], v[218:221], v[64:67]
	v_mfma_f32_16x16x32_bf16 v[68:71], v[148:151], v[218:221], v[68:71]
	v_mfma_f32_16x16x32_bf16 v[68:71], v[144:147], v[214:217], v[68:71]
	s_barrier
	s_setprio 0
	s_add_i32 s64, s84, s69
	v_lshl_add_u64 v[222:223], v[222:223], 0, s[26:27]
	s_mov_b32 m0, s64
	ds_read_b128 v[180:183], v191 offset:49152
	v_xor_b32_e32 v253, 64, v191
	ds_read_b128 v[194:197], v253 offset:49152
	ds_read_b128 v[198:201], v191 offset:51200
	ds_read_b128 v[202:205], v253 offset:51200
	ds_read_b128 v[206:209], v191 offset:53248
	ds_read_b128 v[210:213], v253 offset:53248
	ds_read_b128 v[214:217], v191 offset:55296
	ds_read_b128 v[218:221], v253 offset:55296
	global_load_lds_dwordx4 v[222:223], off
	s_add_i32 m0, s64, 0x2000
	s_add_u32 s62, s62, 0x80080
	v_lshl_add_u64 v[222:223], v[224:225], 0, s[26:27]
	s_addc_u32 s63, s63, 0
	s_add_i32 s64, s85, s69
	global_load_lds_dwordx4 v[222:223], off
	v_lshl_add_u64 v[222:223], s[62:63], 0, v[154:155]
	s_mov_b32 m0, s64
	s_nop 0
	global_load_lds_dwordx4 v[222:223], off
	v_lshl_add_u64 v[222:223], s[62:63], 0, v[162:163]
	s_add_i32 m0, s64, 0x2000
	s_nop 0
	global_load_lds_dwordx4 v[222:223], off
	v_lshl_add_u64 v[222:223], v[226:227], 0, s[26:27]
	s_mov_b32 m0, s3
	s_nop 0
	global_load_lds_dwordx4 v[222:223], off
	v_lshl_add_u64 v[222:223], v[228:229], 0, s[26:27]
	s_mov_b32 m0, s75
	s_nop 0
	global_load_lds_dwordx4 v[222:223], off
	s_waitcnt vmcnt(8)
	s_waitcnt lgkmcnt(0)
	s_setprio 1
	s_barrier
	v_mfma_f32_16x16x32_bf16 v[60:63], v[128:131], v[180:183], v[60:63]
	v_mfma_f32_16x16x32_bf16 v[60:63], v[132:135], v[194:197], v[60:63]
	v_mfma_f32_16x16x32_bf16 v[56:59], v[140:143], v[194:197], v[56:59]
	v_mfma_f32_16x16x32_bf16 v[56:59], v[136:139], v[180:183], v[56:59]
	v_mfma_f32_16x16x32_bf16 v[40:43], v[136:139], v[198:201], v[40:43]
	v_mfma_f32_16x16x32_bf16 v[40:43], v[140:143], v[202:205], v[40:43]
	v_mfma_f32_16x16x32_bf16 v[44:47], v[132:135], v[202:205], v[44:47]
	v_mfma_f32_16x16x32_bf16 v[44:47], v[128:131], v[198:201], v[44:47]
	v_mfma_f32_16x16x32_bf16 v[28:31], v[128:131], v[206:209], v[28:31]
	v_mfma_f32_16x16x32_bf16 v[28:31], v[132:135], v[210:213], v[28:31]
	v_mfma_f32_16x16x32_bf16 v[24:27], v[140:143], v[210:213], v[24:27]
	v_mfma_f32_16x16x32_bf16 v[24:27], v[136:139], v[206:209], v[24:27]
	v_mfma_f32_16x16x32_bf16 v[8:11], v[136:139], v[214:217], v[8:11]
	v_mfma_f32_16x16x32_bf16 v[8:11], v[140:143], v[218:221], v[8:11]
	v_mfma_f32_16x16x32_bf16 v[12:15], v[132:135], v[218:221], v[12:15]
	v_mfma_f32_16x16x32_bf16 v[12:15], v[128:131], v[214:217], v[12:15]
	s_setprio 0
	s_setprio 1
	v_mfma_f32_16x16x32_bf16 v[52:55], v[144:147], v[180:183], v[52:55]
	v_mfma_f32_16x16x32_bf16 v[52:55], v[148:151], v[194:197], v[52:55]
	v_mfma_f32_16x16x32_bf16 v[48:51], v[176:179], v[194:197], v[48:51]
	v_mfma_f32_16x16x32_bf16 v[48:51], v[172:175], v[180:183], v[48:51]
	v_mfma_f32_16x16x32_bf16 v[32:35], v[172:175], v[198:201], v[32:35]
	v_mfma_f32_16x16x32_bf16 v[32:35], v[176:179], v[202:205], v[32:35]
	v_mfma_f32_16x16x32_bf16 v[36:39], v[148:151], v[202:205], v[36:39]
	v_mfma_f32_16x16x32_bf16 v[36:39], v[144:147], v[198:201], v[36:39]
	v_mfma_f32_16x16x32_bf16 v[20:23], v[144:147], v[206:209], v[20:23]
	v_mfma_f32_16x16x32_bf16 v[20:23], v[148:151], v[210:213], v[20:23]
	v_mfma_f32_16x16x32_bf16 v[16:19], v[176:179], v[210:213], v[16:19]
	v_mfma_f32_16x16x32_bf16 v[16:19], v[172:175], v[206:209], v[16:19]
	v_mfma_f32_16x16x32_bf16 v[0:3], v[172:175], v[214:217], v[0:3]
	v_mfma_f32_16x16x32_bf16 v[0:3], v[176:179], v[218:221], v[0:3]
	v_mfma_f32_16x16x32_bf16 v[4:7], v[148:151], v[218:221], v[4:7]
	v_mfma_f32_16x16x32_bf16 v[4:7], v[144:147], v[214:217], v[4:7]
	s_barrier
	s_setprio 0
	s_add_i32 s83, s83, 2
	s_add_u32 s81, s81, 0x100
	s_addc_u32 s82, s82, 0
	s_add_u32 s60, s60, 0x100
	s_addc_u32 s61, s61, 0
	s_cmp_gt_u32 s83, 29
	s_branch .LBB0_440
.Lfa_3:
	ds_read_b128 v[128:131], v189
	v_xor_b32_e32 v253, 64, v189
	ds_read_b128 v[132:135], v253
	ds_read_b128 v[136:139], v189 offset:2048
	ds_read_b128 v[140:143], v253 offset:2048
	ds_read_b128 v[144:147], v190
	v_xor_b32_e32 v253, 64, v190
	ds_read_b128 v[148:151], v253
	ds_read_b128 v[172:175], v190 offset:2048
	ds_read_b128 v[176:179], v253 offset:2048
	s_add_u32 s62, s60, 0xfff80080
	s_addc_u32 s63, s61, -1
	s_cmp_eq_u32 s83, 28
	s_cselect_b32 s65, s15, s63
	s_cselect_b32 s64, s53, s62
	s_cselect_b32 s63, s51, s82
	s_cselect_b32 s62, s59, s81
	v_lshl_add_u64 v[222:223], s[60:61], 0, v[166:167]
	s_add_i32 m0, s70, 0xc000
	ds_read_b128 v[180:183], v191
	v_xor_b32_e32 v253, 64, v191
	ds_read_b128 v[194:197], v253
	ds_read_b128 v[198:201], v191 offset:2048
	ds_read_b128 v[202:205], v253 offset:2048
	ds_read_b128 v[206:209], v191 offset:4096
	ds_read_b128 v[210:213], v253 offset:4096
	ds_read_b128 v[214:217], v191 offset:6144
	ds_read_b128 v[218:221], v253 offset:6144
	global_load_lds_dwordx4 v[222:223], off
	v_lshl_add_u64 v[222:223], s[60:61], 0, v[164:165]
	s_add_i32 m0, s70, 0xe000
	s_nop 0
	global_load_lds_dwordx4 v[222:223], off
	s_waitcnt vmcnt(8)
	s_waitcnt lgkmcnt(0)
	s_setprio 1
	s_barrier
	v_mfma_f32_16x16x32_bf16 v[124:127], v[128:131], v[180:183], 0
	v_mfma_f32_16x16x32_bf16 v[124:127], v[132:135], v[194:197], v[124:127]
	v_mfma_f32_16x16x32_bf16 v[120:123], v[136:139], v[180:183], 0
	v_mfma_f32_16x16x32_bf16 v[120:123], v[140:143], v[194:197], v[120:123]
	v_mfma_f32_16x16x32_bf16 v[108:111], v[128:131], v[198:201], 0
	v_mfma_f32_16x16x32_bf16 v[108:111], v[132:135], v[202:205], v[108:111]
	v_mfma_f32_16x16x32_bf16 v[104:107], v[136:139], v[198:201], 0
	v_mfma_f32_16x16x32_bf16 v[104:107], v[140:143], v[202:205], v[104:107]
	v_mfma_f32_16x16x32_bf16 v[92:95], v[128:131], v[206:209], 0
	v_mfma_f32_16x16x32_bf16 v[92:95], v[132:135], v[210:213], v[92:95]
	v_mfma_f32_16x16x32_bf16 v[88:91], v[136:139], v[206:209], 0
	v_mfma_f32_16x16x32_bf16 v[88:91], v[140:143], v[210:213], v[88:91]
	v_mfma_f32_16x16x32_bf16 v[76:79], v[128:131], v[214:217], 0
	v_mfma_f32_16x16x32_bf16 v[76:79], v[132:135], v[218:221], v[76:79]
	v_mfma_f32_16x16x32_bf16 v[72:75], v[136:139], v[214:217], 0
	v_mfma_f32_16x16x32_bf16 v[72:75], v[140:143], v[218:221], v[72:75]
	s_setprio 0
	s_setprio 1
	v_mfma_f32_16x16x32_bf16 v[116:119], v[144:147], v[180:183], 0
	v_mfma_f32_16x16x32_bf16 v[116:119], v[148:151], v[194:197], v[116:119]
	v_mfma_f32_16x16x32_bf16 v[112:115], v[172:175], v[180:183], 0
	v_mfma_f32_16x16x32_bf16 v[112:115], v[176:179], v[194:197], v[112:115]
	v_mfma_f32_16x16x32_bf16 v[100:103], v[144:147], v[198:201], 0
	v_mfma_f32_16x16x32_bf16 v[100:103], v[148:151], v[202:205], v[100:103]
	v_mfma_f32_16x16x32_bf16 v[96:99], v[172:175], v[198:201], 0
	v_mfma_f32_16x16x32_bf16 v[96:99], v[176:179], v[202:205], v[96:99]
	v_mfma_f32_16x16x32_bf16 v[84:87], v[144:147], v[206:209], 0
	v_mfma_f32_16x16x32_bf16 v[84:87], v[148:151], v[210:213], v[84:87]
	v_mfma_f32_16x16x32_bf16 v[80:83], v[172:175], v[206:209], 0
	v_mfma_f32_16x16x32_bf16 v[80:83], v[176:179], v[210:213], v[80:83]
	v_mfma_f32_16x16x32_bf16 v[68:71], v[144:147], v[214:217], 0
	v_mfma_f32_16x16x32_bf16 v[68:71], v[148:151], v[218:221], v[68:71]
	v_mfma_f32_16x16x32_bf16 v[64:67], v[172:175], v[214:217], 0
	v_mfma_f32_16x16x32_bf16 v[64:67], v[176:179], v[218:221], v[64:67]
	s_barrier
	s_setprio 0
	s_add_i32 s84, s79, s69
	v_lshl_add_u64 v[222:223], s[62:63], 0, v[154:155]
	s_mov_b32 m0, s84
	ds_read_b128 v[180:183], v191 offset:16384
	v_xor_b32_e32 v253, 64, v191
	ds_read_b128 v[194:197], v253 offset:16384
	ds_read_b128 v[198:201], v191 offset:18432
	ds_read_b128 v[202:205], v253 offset:18432
	ds_read_b128 v[206:209], v191 offset:20480
	ds_read_b128 v[210:213], v253 offset:20480
	ds_read_b128 v[214:217], v191 offset:22528
	ds_read_b128 v[218:221], v253 offset:22528
	global_load_lds_dwordx4 v[222:223], off
	s_add_i32 m0, s84, 0x2000
	s_add_u32 s84, s62, 0x80000
	v_lshl_add_u64 v[224:225], s[62:63], 0, v[162:163]
	s_addc_u32 s85, s63, 0
	s_add_i32 s86, s80, s69
	global_load_lds_dwordx4 v[224:225], off
	v_lshl_add_u64 v[226:227], s[84:85], 0, v[154:155]
	s_mov_b32 m0, s86
	v_lshl_add_u64 v[228:229], s[64:65], 0, v[160:161]
	global_load_lds_dwordx4 v[226:227], off
	v_lshl_add_u64 v[226:227], s[84:85], 0, v[162:163]
	s_add_i32 m0, s86, 0x2000
	s_nop 0
	global_load_lds_dwordx4 v[226:227], off
	v_lshl_add_u64 v[226:227], s[64:65], 0, v[152:153]
	s_mov_b32 m0, s70
	s_nop 0
	global_load_lds_dwordx4 v[226:227], off
	s_mov_b32 m0, s71
	s_nop 0
	global_load_lds_dwordx4 v[228:229], off
	s_waitcnt vmcnt(8)
	s_waitcnt lgkmcnt(0)
	s_setprio 1
	s_barrier
	v_mfma_f32_16x16x32_bf16 v[60:63], v[128:131], v[180:183], 0
	v_mfma_f32_16x16x32_bf16 v[60:63], v[132:135], v[194:197], v[60:63]
	v_mfma_f32_16x16x32_bf16 v[56:59], v[136:139], v[180:183], 0
	v_mfma_f32_16x16x32_bf16 v[56:59], v[140:143], v[194:197], v[56:59]
	v_mfma_f32_16x16x32_bf16 v[44:47], v[128:131], v[198:201], 0
	v_mfma_f32_16x16x32_bf16 v[44:47], v[132:135], v[202:205], v[44:47]
	v_mfma_f32_16x16x32_bf16 v[40:43], v[136:139], v[198:201], 0
	v_mfma_f32_16x16x32_bf16 v[40:43], v[140:143], v[202:205], v[40:43]
	v_mfma_f32_16x16x32_bf16 v[28:31], v[128:131], v[206:209], 0
	v_mfma_f32_16x16x32_bf16 v[28:31], v[132:135], v[210:213], v[28:31]
	v_mfma_f32_16x16x32_bf16 v[24:27], v[136:139], v[206:209], 0
	v_mfma_f32_16x16x32_bf16 v[24:27], v[140:143], v[210:213], v[24:27]
	v_mfma_f32_16x16x32_bf16 v[12:15], v[128:131], v[214:217], 0
	v_mfma_f32_16x16x32_bf16 v[12:15], v[132:135], v[218:221], v[12:15]
	v_mfma_f32_16x16x32_bf16 v[8:11], v[136:139], v[214:217], 0
	v_mfma_f32_16x16x32_bf16 v[8:11], v[140:143], v[218:221], v[8:11]
	s_setprio 0
	s_setprio 1
	v_mfma_f32_16x16x32_bf16 v[52:55], v[144:147], v[180:183], 0
	v_mfma_f32_16x16x32_bf16 v[52:55], v[148:151], v[194:197], v[52:55]
	v_mfma_f32_16x16x32_bf16 v[48:51], v[172:175], v[180:183], 0
	v_mfma_f32_16x16x32_bf16 v[48:51], v[176:179], v[194:197], v[48:51]
	v_mfma_f32_16x16x32_bf16 v[36:39], v[144:147], v[198:201], 0
	v_mfma_f32_16x16x32_bf16 v[36:39], v[148:151], v[202:205], v[36:39]
	v_mfma_f32_16x16x32_bf16 v[32:35], v[172:175], v[198:201], 0
	v_mfma_f32_16x16x32_bf16 v[32:35], v[176:179], v[202:205], v[32:35]
	v_mfma_f32_16x16x32_bf16 v[20:23], v[144:147], v[206:209], 0
	v_mfma_f32_16x16x32_bf16 v[20:23], v[148:151], v[210:213], v[20:23]
	v_mfma_f32_16x16x32_bf16 v[16:19], v[172:175], v[206:209], 0
	v_mfma_f32_16x16x32_bf16 v[16:19], v[176:179], v[210:213], v[16:19]
	v_mfma_f32_16x16x32_bf16 v[4:7], v[144:147], v[214:217], 0
	v_mfma_f32_16x16x32_bf16 v[4:7], v[148:151], v[218:221], v[4:7]
	v_mfma_f32_16x16x32_bf16 v[0:3], v[172:175], v[214:217], 0
	v_mfma_f32_16x16x32_bf16 v[0:3], v[176:179], v[218:221], v[0:3]
	s_barrier
	s_setprio 0
	s_add_i32 s84, 0, 0x18000
	s_add_i32 s85, 0, 0x1c000
	v_add_u32_e32 v140, s84, v186
	v_add_u32_e32 v176, s85, v186
	ds_read_b128 v[128:131], v140
	v_xor_b32_e32 v253, 64, v140
	ds_read_b128 v[132:135], v253
	ds_read_b128 v[136:139], v140 offset:2048
	ds_read_b128 v[140:143], v253 offset:2048
	ds_read_b128 v[144:147], v176
	v_xor_b32_e32 v253, 64, v176
	ds_read_b128 v[148:151], v253
	ds_read_b128 v[172:175], v176 offset:2048
	ds_read_b128 v[176:179], v253 offset:2048
	s_add_u32 s64, s64, 0x80000
	s_addc_u32 s65, s65, 0
	s_mov_b32 m0, s72
	v_lshl_add_u64 v[230:231], s[64:65], 0, v[152:153]
	ds_read_b128 v[180:183], v191 offset:32768
	v_xor_b32_e32 v253, 64, v191
	ds_read_b128 v[194:197], v253 offset:32768
	ds_read_b128 v[198:201], v191 offset:34816
	ds_read_b128 v[202:205], v253 offset:34816
	ds_read_b128 v[206:209], v191 offset:36864
	ds_read_b128 v[210:213], v253 offset:36864
	ds_read_b128 v[214:217], v191 offset:38912
	ds_read_b128 v[218:221], v253 offset:38912
	global_load_lds_dwordx4 v[230:231], off
	v_lshl_add_u64 v[230:231], s[64:65], 0, v[160:161]
	s_mov_b32 m0, s73
	s_nop 0
	global_load_lds_dwordx4 v[230:231], off
	s_waitcnt vmcnt(8)
	s_waitcnt lgkmcnt(0)
	s_setprio 1
	s_barrier
	v_mfma_f32_16x16x32_bf16 v[124:127], v[128:131], v[180:183], v[124:127]
	v_mfma_f32_16x16x32_bf16 v[124:127], v[132:135], v[194:197], v[124:127]
	v_mfma_f32_16x16x32_bf16 v[120:123], v[140:143], v[194:197], v[120:123]
	v_mfma_f32_16x16x32_bf16 v[120:123], v[136:139], v[180:183], v[120:123]
	v_mfma_f32_16x16x32_bf16 v[104:107], v[136:139], v[198:201], v[104:107]
	v_mfma_f32_16x16x32_bf16 v[104:107], v[140:143], v[202:205], v[104:107]
	v_mfma_f32_16x16x32_bf16 v[108:111], v[132:135], v[202:205], v[108:111]
	v_mfma_f32_16x16x32_bf16 v[108:111], v[128:131], v[198:201], v[108:111]
	v_mfma_f32_16x16x32_bf16 v[92:95], v[128:131], v[206:209], v[92:95]
	v_mfma_f32_16x16x32_bf16 v[92:95], v[132:135], v[210:213], v[92:95]
	v_mfma_f32_16x16x32_bf16 v[88:91], v[140:143], v[210:213], v[88:91]
	v_mfma_f32_16x16x32_bf16 v[88:91], v[136:139], v[206:209], v[88:91]
	v_mfma_f32_16x16x32_bf16 v[72:75], v[136:139], v[214:217], v[72:75]
	v_mfma_f32_16x16x32_bf16 v[72:75], v[140:143], v[218:221], v[72:75]
	v_mfma_f32_16x16x32_bf16 v[76:79], v[132:135], v[218:221], v[76:79]
	v_mfma_f32_16x16x32_bf16 v[76:79], v[128:131], v[214:217], v[76:79]
	s_setprio 0
	s_setprio 1
	v_mfma_f32_16x16x32_bf16 v[116:119], v[144:147], v[180:183], v[116:119]
	v_mfma_f32_16x16x32_bf16 v[116:119], v[148:151], v[194:197], v[116:119]
	v_mfma_f32_16x16x32_bf16 v[112:115], v[176:179], v[194:197], v[112:115]
	v_mfma_f32_16x16x32_bf16 v[112:115], v[172:175], v[180:183], v[112:115]
	v_mfma_f32_16x16x32_bf16 v[96:99], v[172:175], v[198:201], v[96:99]
	v_mfma_f32_16x16x32_bf16 v[96:99], v[176:179], v[202:205], v[96:99]
	v_mfma_f32_16x16x32_bf16 v[100:103], v[148:151], v[202:205], v[100:103]
	v_mfma_f32_16x16x32_bf16 v[100:103], v[144:147], v[198:201], v[100:103]
	v_mfma_f32_16x16x32_bf16 v[84:87], v[144:147], v[206:209], v[84:87]
	v_mfma_f32_16x16x32_bf16 v[84:87], v[148:151], v[210:213], v[84:87]
	v_mfma_f32_16x16x32_bf16 v[80:83], v[176:179], v[210:213], v[80:83]
	v_mfma_f32_16x16x32_bf16 v[80:83], v[172:175], v[206:209], v[80:83]
	v_mfma_f32_16x16x32_bf16 v[64:67], v[172:175], v[214:217], v[64:67]
	v_mfma_f32_16x16x32_bf16 v[64:67], v[176:179], v[218:221], v[64:67]
	v_mfma_f32_16x16x32_bf16 v[68:71], v[148:151], v[218:221], v[68:71]
	v_mfma_f32_16x16x32_bf16 v[68:71], v[144:147], v[214:217], v[68:71]
	s_barrier
	s_setprio 0
	s_add_i32 s64, s84, s69
	v_lshl_add_u64 v[222:223], v[222:223], 0, s[26:27]
	s_mov_b32 m0, s64
	ds_read_b128 v[180:183], v191 offset:49152
	v_xor_b32_e32 v253, 64, v191
	ds_read_b128 v[194:197], v253 offset:49152
	ds_read_b128 v[198:201], v191 offset:51200
	ds_read_b128 v[202:205], v253 offset:51200
	ds_read_b128 v[206:209], v191 offset:53248
	ds_read_b128 v[210:213], v253 offset:53248
	ds_read_b128 v[214:217], v191 offset:55296
	ds_read_b128 v[218:221], v253 offset:55296
	global_load_lds_dwordx4 v[222:223], off
	s_add_i32 m0, s64, 0x2000
	s_add_u32 s62, s62, 0x80080
	v_lshl_add_u64 v[222:223], v[224:225], 0, s[26:27]
	s_addc_u32 s63, s63, 0
	s_add_i32 s64, s85, s69
	global_load_lds_dwordx4 v[222:223], off
	v_lshl_add_u64 v[222:223], s[62:63], 0, v[154:155]
	s_mov_b32 m0, s64
	s_nop 0
	global_load_lds_dwordx4 v[222:223], off
	v_lshl_add_u64 v[222:223], s[62:63], 0, v[162:163]
	s_add_i32 m0, s64, 0x2000
	s_nop 0
	global_load_lds_dwordx4 v[222:223], off
	v_lshl_add_u64 v[222:223], v[226:227], 0, s[26:27]
	s_mov_b32 m0, s3
	s_nop 0
	global_load_lds_dwordx4 v[222:223], off
	v_lshl_add_u64 v[222:223], v[228:229], 0, s[26:27]
	s_mov_b32 m0, s75
	s_nop 0
	global_load_lds_dwordx4 v[222:223], off
	s_waitcnt vmcnt(8)
	s_waitcnt lgkmcnt(0)
	s_setprio 1
	s_barrier
	v_mfma_f32_16x16x32_bf16 v[60:63], v[128:131], v[180:183], v[60:63]
	v_mfma_f32_16x16x32_bf16 v[60:63], v[132:135], v[194:197], v[60:63]
	v_mfma_f32_16x16x32_bf16 v[56:59], v[140:143], v[194:197], v[56:59]
	v_mfma_f32_16x16x32_bf16 v[56:59], v[136:139], v[180:183], v[56:59]
	v_mfma_f32_16x16x32_bf16 v[40:43], v[136:139], v[198:201], v[40:43]
	v_mfma_f32_16x16x32_bf16 v[40:43], v[140:143], v[202:205], v[40:43]
	v_mfma_f32_16x16x32_bf16 v[44:47], v[132:135], v[202:205], v[44:47]
	v_mfma_f32_16x16x32_bf16 v[44:47], v[128:131], v[198:201], v[44:47]
	v_mfma_f32_16x16x32_bf16 v[28:31], v[128:131], v[206:209], v[28:31]
	v_mfma_f32_16x16x32_bf16 v[28:31], v[132:135], v[210:213], v[28:31]
	v_mfma_f32_16x16x32_bf16 v[24:27], v[140:143], v[210:213], v[24:27]
	v_mfma_f32_16x16x32_bf16 v[24:27], v[136:139], v[206:209], v[24:27]
	v_mfma_f32_16x16x32_bf16 v[8:11], v[136:139], v[214:217], v[8:11]
	v_mfma_f32_16x16x32_bf16 v[8:11], v[140:143], v[218:221], v[8:11]
	v_mfma_f32_16x16x32_bf16 v[12:15], v[132:135], v[218:221], v[12:15]
	v_mfma_f32_16x16x32_bf16 v[12:15], v[128:131], v[214:217], v[12:15]
	s_setprio 0
	s_setprio 1
	v_mfma_f32_16x16x32_bf16 v[52:55], v[144:147], v[180:183], v[52:55]
	v_mfma_f32_16x16x32_bf16 v[52:55], v[148:151], v[194:197], v[52:55]
	v_mfma_f32_16x16x32_bf16 v[48:51], v[176:179], v[194:197], v[48:51]
	v_mfma_f32_16x16x32_bf16 v[48:51], v[172:175], v[180:183], v[48:51]
	v_mfma_f32_16x16x32_bf16 v[32:35], v[172:175], v[198:201], v[32:35]
	v_mfma_f32_16x16x32_bf16 v[32:35], v[176:179], v[202:205], v[32:35]
	v_mfma_f32_16x16x32_bf16 v[36:39], v[148:151], v[202:205], v[36:39]
	v_mfma_f32_16x16x32_bf16 v[36:39], v[144:147], v[198:201], v[36:39]
	v_mfma_f32_16x16x32_bf16 v[20:23], v[144:147], v[206:209], v[20:23]
	v_mfma_f32_16x16x32_bf16 v[20:23], v[148:151], v[210:213], v[20:23]
	v_mfma_f32_16x16x32_bf16 v[16:19], v[176:179], v[210:213], v[16:19]
	v_mfma_f32_16x16x32_bf16 v[16:19], v[172:175], v[206:209], v[16:19]
	v_mfma_f32_16x16x32_bf16 v[0:3], v[172:175], v[214:217], v[0:3]
	v_mfma_f32_16x16x32_bf16 v[0:3], v[176:179], v[218:221], v[0:3]
	v_mfma_f32_16x16x32_bf16 v[4:7], v[148:151], v[218:221], v[4:7]
	v_mfma_f32_16x16x32_bf16 v[4:7], v[144:147], v[214:217], v[4:7]
	s_barrier
	s_setprio 0
	s_add_i32 s83, s83, 2
	s_add_u32 s81, s81, 0x100
	s_addc_u32 s82, s82, 0
	s_add_u32 s60, s60, 0x100
	s_addc_u32 s61, s61, 0
	s_cmp_gt_u32 s83, 29

.LBB0_525:
	s_ashr_i32 s29, s28, 31
	s_lshl_b64 s[30:31], s[28:29], 19
	s_add_u32 s30, s3, s30
	s_addc_u32 s31, s35, s31
	s_and_b64 s[44:45], s[10:11], exec
	s_cselect_b32 s29, s31, s51
	s_cselect_b32 s70, s30, s50
	s_ashr_i32 s27, s26, 31
	s_lshl_b64 s[44:45], s[26:27], 19
	s_add_u32 s44, s52, s44
	s_addc_u32 s45, s53, s45
	s_and_b64 s[72:73], s[10:11], exec
	s_cselect_b32 s71, s45, s49
	s_cselect_b32 s72, s44, s48
	s_lshl_b32 s27, s46, 8
	v_add_u32_e32 v0, s27, v148
	s_add_u32 s73, s48, 0x100
	v_ashrrev_i32_e32 v1, 31, v0
	s_addc_u32 s74, s49, 0
	v_lshl_add_u64 v[144:145], v[0:1], 4, s[16:17]
	s_add_u32 s46, s50, 0x40080
	s_addc_u32 s47, s51, 0
	s_mov_b32 s75, -2
	s_mov_b64 s[48:49], 0
	s_cmp_eq_u32 s61, 1
	s_cbranch_scc1 .Lfa_4
	v_add_u32_e32 v153, s66, v147
	ds_read_b128 v[160:163], v153
	v_xor_b32_e32 v253, 64, v153
	ds_read_b128 v[164:167], v253
	ds_read_b128 v[168:171], v153 offset:2048
	ds_read_b128 v[172:175], v253 offset:2048
	v_add_u32_e32 v153, s67, v147
	ds_read_b128 v[176:179], v153
	v_xor_b32_e32 v253, 64, v153
	ds_read_b128 v[180:183], v253
	ds_read_b128 v[186:189], v153 offset:2048
	ds_read_b128 v[190:193], v253 offset:2048
	s_add_u32 s50, s46, 0xfffc0080
	s_addc_u32 s51, s47, -1
	s_and_b64 s[48:49], s[48:49], exec
	s_cselect_b32 s51, s29, s51
	s_cselect_b32 s50, s70, s50
	s_cselect_b32 s49, s71, s74
	s_cselect_b32 s48, s72, s73
	v_lshl_add_u64 v[154:155], s[46:47], 0, v[138:139]
	s_add_i32 m0, s57, 0xc000
	ds_read_b128 v[194:197], v150
	v_xor_b32_e32 v253, 64, v150
	ds_read_b128 v[198:201], v253
	ds_read_b128 v[202:205], v150 offset:2048
	ds_read_b128 v[206:209], v253 offset:2048
	ds_read_b128 v[210:213], v150 offset:4096
	ds_read_b128 v[214:217], v253 offset:4096
	ds_read_b128 v[218:221], v150 offset:6144
	ds_read_b128 v[222:225], v253 offset:6144
	global_load_lds_dwordx4 v[154:155], off
	v_lshl_add_u64 v[154:155], s[46:47], 0, v[136:137]
	s_add_i32 m0, s57, 0xe000
	s_nop 0
	global_load_lds_dwordx4 v[154:155], off
	s_waitcnt vmcnt(16)
	s_waitcnt lgkmcnt(0)
	s_setprio 1
	s_barrier
	v_mfma_f32_16x16x32_bf16 v[124:127], v[160:163], v[194:197], 0
	v_mfma_f32_16x16x32_bf16 v[124:127], v[164:167], v[198:201], v[124:127]
	v_mfma_f32_16x16x32_bf16 v[116:119], v[168:171], v[194:197], 0
	v_mfma_f32_16x16x32_bf16 v[116:119], v[172:175], v[198:201], v[116:119]
	v_mfma_f32_16x16x32_bf16 v[108:111], v[160:163], v[202:205], 0
	v_mfma_f32_16x16x32_bf16 v[108:111], v[164:167], v[206:209], v[108:111]
	v_mfma_f32_16x16x32_bf16 v[100:103], v[168:171], v[202:205], 0
	v_mfma_f32_16x16x32_bf16 v[100:103], v[172:175], v[206:209], v[100:103]
	v_mfma_f32_16x16x32_bf16 v[92:95], v[160:163], v[210:213], 0
	v_mfma_f32_16x16x32_bf16 v[92:95], v[164:167], v[214:217], v[92:95]
	v_mfma_f32_16x16x32_bf16 v[84:87], v[168:171], v[210:213], 0
	v_mfma_f32_16x16x32_bf16 v[84:87], v[172:175], v[214:217], v[84:87]
	v_mfma_f32_16x16x32_bf16 v[76:79], v[160:163], v[218:221], 0
	v_mfma_f32_16x16x32_bf16 v[76:79], v[164:167], v[222:225], v[76:79]
	v_mfma_f32_16x16x32_bf16 v[68:71], v[168:171], v[218:221], 0
	v_mfma_f32_16x16x32_bf16 v[68:71], v[172:175], v[222:225], v[68:71]
	s_setprio 0
	s_setprio 1
	v_mfma_f32_16x16x32_bf16 v[120:123], v[176:179], v[194:197], 0
	v_mfma_f32_16x16x32_bf16 v[120:123], v[180:183], v[198:201], v[120:123]
	v_mfma_f32_16x16x32_bf16 v[112:115], v[186:189], v[194:197], 0
	v_mfma_f32_16x16x32_bf16 v[112:115], v[190:193], v[198:201], v[112:115]
	v_mfma_f32_16x16x32_bf16 v[104:107], v[176:179], v[202:205], 0
	v_mfma_f32_16x16x32_bf16 v[104:107], v[180:183], v[206:209], v[104:107]
	v_mfma_f32_16x16x32_bf16 v[96:99], v[186:189], v[202:205], 0
	v_mfma_f32_16x16x32_bf16 v[96:99], v[190:193], v[206:209], v[96:99]
	v_mfma_f32_16x16x32_bf16 v[88:91], v[176:179], v[210:213], 0
	v_mfma_f32_16x16x32_bf16 v[88:91], v[180:183], v[214:217], v[88:91]
	v_mfma_f32_16x16x32_bf16 v[80:83], v[186:189], v[210:213], 0
	v_mfma_f32_16x16x32_bf16 v[80:83], v[190:193], v[214:217], v[80:83]
	v_mfma_f32_16x16x32_bf16 v[72:75], v[176:179], v[218:221], 0
	v_mfma_f32_16x16x32_bf16 v[72:75], v[180:183], v[222:225], v[72:75]
	v_mfma_f32_16x16x32_bf16 v[64:67], v[186:189], v[218:221], 0
	v_mfma_f32_16x16x32_bf16 v[64:67], v[190:193], v[222:225], v[64:67]
	s_barrier
	s_setprio 0
	s_add_i32 s76, s66, s54
	v_lshl_add_u64 v[154:155], s[48:49], 0, v[132:133]
	s_mov_b32 m0, s76
	ds_read_b128 v[194:197], v150 offset:16384
	v_xor_b32_e32 v253, 64, v150
	ds_read_b128 v[198:201], v253 offset:16384
	ds_read_b128 v[202:205], v150 offset:18432
	ds_read_b128 v[206:209], v253 offset:18432
	ds_read_b128 v[210:213], v150 offset:20480
	ds_read_b128 v[214:217], v253 offset:20480
	ds_read_b128 v[218:221], v150 offset:22528
	ds_read_b128 v[222:225], v253 offset:22528
	global_load_lds_dwordx4 v[154:155], off
	s_add_i32 m0, s76, 0x2000
	s_add_u32 s76, s48, 0x40000
	v_lshl_add_u64 v[226:227], s[48:49], 0, v[128:129]
	s_addc_u32 s77, s49, 0
	s_add_i32 s78, s67, s54
	global_load_lds_dwordx4 v[226:227], off
	v_lshl_add_u64 v[228:229], s[76:77], 0, v[132:133]
	s_mov_b32 m0, s78
	v_lshl_add_u64 v[230:231], s[50:51], 0, v[130:131]
	global_load_lds_dwordx4 v[228:229], off
	v_lshl_add_u64 v[228:229], s[76:77], 0, v[128:129]
	s_add_i32 m0, s78, 0x2000
	s_nop 0
	global_load_lds_dwordx4 v[228:229], off
	v_lshl_add_u64 v[228:229], s[50:51], 0, v[134:135]
	s_mov_b32 m0, s57
	s_nop 0
	global_load_lds_dwordx4 v[228:229], off
	s_mov_b32 m0, s58
	s_nop 0
	global_load_lds_dwordx4 v[230:231], off
	s_waitcnt vmcnt(16)
	s_waitcnt lgkmcnt(0)
	s_setprio 1
	s_barrier
	v_mfma_f32_16x16x32_bf16 v[60:63], v[160:163], v[194:197], 0
	v_mfma_f32_16x16x32_bf16 v[60:63], v[164:167], v[198:201], v[60:63]
	v_mfma_f32_16x16x32_bf16 v[52:55], v[168:171], v[194:197], 0
	v_mfma_f32_16x16x32_bf16 v[52:55], v[172:175], v[198:201], v[52:55]
	v_mfma_f32_16x16x32_bf16 v[44:47], v[160:163], v[202:205], 0
	v_mfma_f32_16x16x32_bf16 v[44:47], v[164:167], v[206:209], v[44:47]
	v_mfma_f32_16x16x32_bf16 v[36:39], v[168:171], v[202:205], 0
	v_mfma_f32_16x16x32_bf16 v[36:39], v[172:175], v[206:209], v[36:39]
	v_mfma_f32_16x16x32_bf16 v[28:31], v[160:163], v[210:213], 0
	v_mfma_f32_16x16x32_bf16 v[28:31], v[164:167], v[214:217], v[28:31]
	v_mfma_f32_16x16x32_bf16 v[20:23], v[168:171], v[210:213], 0
	v_mfma_f32_16x16x32_bf16 v[20:23], v[172:175], v[214:217], v[20:23]
	v_mfma_f32_16x16x32_bf16 v[12:15], v[160:163], v[218:221], 0
	v_mfma_f32_16x16x32_bf16 v[12:15], v[164:167], v[222:225], v[12:15]
	v_mfma_f32_16x16x32_bf16 v[4:7], v[168:171], v[218:221], 0
	v_mfma_f32_16x16x32_bf16 v[4:7], v[172:175], v[222:225], v[4:7]
	s_setprio 0
	s_setprio 1
	v_mfma_f32_16x16x32_bf16 v[56:59], v[176:179], v[194:197], 0
	v_mfma_f32_16x16x32_bf16 v[56:59], v[180:183], v[198:201], v[56:59]
	v_mfma_f32_16x16x32_bf16 v[48:51], v[186:189], v[194:197], 0
	v_mfma_f32_16x16x32_bf16 v[48:51], v[190:193], v[198:201], v[48:51]
	v_mfma_f32_16x16x32_bf16 v[40:43], v[176:179], v[202:205], 0
	v_mfma_f32_16x16x32_bf16 v[40:43], v[180:183], v[206:209], v[40:43]
	v_mfma_f32_16x16x32_bf16 v[32:35], v[186:189], v[202:205], 0
	v_mfma_f32_16x16x32_bf16 v[32:35], v[190:193], v[206:209], v[32:35]
	v_mfma_f32_16x16x32_bf16 v[24:27], v[176:179], v[210:213], 0
	v_mfma_f32_16x16x32_bf16 v[24:27], v[180:183], v[214:217], v[24:27]
	v_mfma_f32_16x16x32_bf16 v[16:19], v[186:189], v[210:213], 0
	v_mfma_f32_16x16x32_bf16 v[16:19], v[190:193], v[214:217], v[16:19]
	v_mfma_f32_16x16x32_bf16 v[8:11], v[176:179], v[218:221], 0
	v_mfma_f32_16x16x32_bf16 v[8:11], v[180:183], v[222:225], v[8:11]
	v_mfma_f32_16x16x32_bf16 v[0:3], v[186:189], v[218:221], 0
	v_mfma_f32_16x16x32_bf16 v[0:3], v[190:193], v[222:225], v[0:3]
	s_barrier
	s_setprio 0
	s_add_i32 s76, 0, 0x18000
	v_add_u32_e32 v153, s76, v147
	s_add_i32 s77, 0, 0x1c000
	ds_read_b128 v[160:163], v153
	v_xor_b32_e32 v253, 64, v153
	ds_read_b128 v[164:167], v253
	ds_read_b128 v[168:171], v153 offset:2048
	ds_read_b128 v[172:175], v253 offset:2048
	v_add_u32_e32 v153, s77, v147
	ds_read_b128 v[176:179], v153
	v_xor_b32_e32 v253, 64, v153
	ds_read_b128 v[180:183], v253
	ds_read_b128 v[186:189], v153 offset:2048
	ds_read_b128 v[190:193], v253 offset:2048
	s_add_u32 s50, s50, 0x40000
	s_addc_u32 s51, s51, 0
	s_mov_b32 m0, s59
	v_lshl_add_u64 v[232:233], s[50:51], 0, v[134:135]
	ds_read_b128 v[194:197], v150 offset:32768
	v_xor_b32_e32 v253, 64, v150
	ds_read_b128 v[198:201], v253 offset:32768
	ds_read_b128 v[202:205], v150 offset:34816
	ds_read_b128 v[206:209], v253 offset:34816
	ds_read_b128 v[210:213], v150 offset:36864
	ds_read_b128 v[214:217], v253 offset:36864
	ds_read_b128 v[218:221], v150 offset:38912
	ds_read_b128 v[222:225], v253 offset:38912
	global_load_lds_dwordx4 v[232:233], off
	v_lshl_add_u64 v[232:233], s[50:51], 0, v[130:131]
	s_mov_b32 m0, s60
	s_nop 0
	global_load_lds_dwordx4 v[232:233], off
	s_waitcnt vmcnt(8)
	s_waitcnt lgkmcnt(0)
	s_setprio 1
	s_barrier
	v_mfma_f32_16x16x32_bf16 v[124:127], v[160:163], v[194:197], v[124:127]
	v_mfma_f32_16x16x32_bf16 v[124:127], v[164:167], v[198:201], v[124:127]
	v_mfma_f32_16x16x32_bf16 v[116:119], v[172:175], v[198:201], v[116:119]
	v_mfma_f32_16x16x32_bf16 v[116:119], v[168:171], v[194:197], v[116:119]
	v_mfma_f32_16x16x32_bf16 v[100:103], v[168:171], v[202:205], v[100:103]
	v_mfma_f32_16x16x32_bf16 v[100:103], v[172:175], v[206:209], v[100:103]
	v_mfma_f32_16x16x32_bf16 v[108:111], v[164:167], v[206:209], v[108:111]
	v_mfma_f32_16x16x32_bf16 v[108:111], v[160:163], v[202:205], v[108:111]
	v_mfma_f32_16x16x32_bf16 v[92:95], v[160:163], v[210:213], v[92:95]
	v_mfma_f32_16x16x32_bf16 v[92:95], v[164:167], v[214:217], v[92:95]
	v_mfma_f32_16x16x32_bf16 v[84:87], v[172:175], v[214:217], v[84:87]
	v_mfma_f32_16x16x32_bf16 v[84:87], v[168:171], v[210:213], v[84:87]
	v_mfma_f32_16x16x32_bf16 v[68:71], v[168:171], v[218:221], v[68:71]
	v_mfma_f32_16x16x32_bf16 v[68:71], v[172:175], v[222:225], v[68:71]
	v_mfma_f32_16x16x32_bf16 v[76:79], v[164:167], v[222:225], v[76:79]
	v_mfma_f32_16x16x32_bf16 v[76:79], v[160:163], v[218:221], v[76:79]
	s_setprio 0
	s_setprio 1
	v_mfma_f32_16x16x32_bf16 v[120:123], v[176:179], v[194:197], v[120:123]
	v_mfma_f32_16x16x32_bf16 v[120:123], v[180:183], v[198:201], v[120:123]
	v_mfma_f32_16x16x32_bf16 v[112:115], v[190:193], v[198:201], v[112:115]
	v_mfma_f32_16x16x32_bf16 v[112:115], v[186:189], v[194:197], v[112:115]
	v_mfma_f32_16x16x32_bf16 v[96:99], v[186:189], v[202:205], v[96:99]
	v_mfma_f32_16x16x32_bf16 v[96:99], v[190:193], v[206:209], v[96:99]
	v_mfma_f32_16x16x32_bf16 v[104:107], v[180:183], v[206:209], v[104:107]
	v_mfma_f32_16x16x32_bf16 v[104:107], v[176:179], v[202:205], v[104:107]
	v_mfma_f32_16x16x32_bf16 v[88:91], v[176:179], v[210:213], v[88:91]
	v_mfma_f32_16x16x32_bf16 v[88:91], v[180:183], v[214:217], v[88:91]
	v_mfma_f32_16x16x32_bf16 v[80:83], v[190:193], v[214:217], v[80:83]
	v_mfma_f32_16x16x32_bf16 v[80:83], v[186:189], v[210:213], v[80:83]
	v_mfma_f32_16x16x32_bf16 v[64:67], v[186:189], v[218:221], v[64:67]
	v_mfma_f32_16x16x32_bf16 v[64:67], v[190:193], v[222:225], v[64:67]
	v_mfma_f32_16x16x32_bf16 v[72:75], v[180:183], v[222:225], v[72:75]
	v_mfma_f32_16x16x32_bf16 v[72:75], v[176:179], v[218:221], v[72:75]
	s_barrier
	s_setprio 0
	s_add_i32 s50, s76, s54
	v_lshl_add_u64 v[154:155], v[154:155], 0, s[20:21]
	s_mov_b32 m0, s50
	ds_read_b128 v[194:197], v150 offset:49152
	v_xor_b32_e32 v253, 64, v150
	ds_read_b128 v[198:201], v253 offset:49152
	ds_read_b128 v[202:205], v150 offset:51200
	ds_read_b128 v[206:209], v253 offset:51200
	ds_read_b128 v[210:213], v150 offset:53248
	ds_read_b128 v[214:217], v253 offset:53248
	ds_read_b128 v[218:221], v150 offset:55296
	ds_read_b128 v[222:225], v253 offset:55296
	global_load_lds_dwordx4 v[154:155], off
	s_add_i32 m0, s50, 0x2000
	s_add_u32 s48, s48, 0x40080
	v_lshl_add_u64 v[154:155], v[226:227], 0, s[20:21]
	s_addc_u32 s49, s49, 0
	s_add_i32 s50, s77, s54
	global_load_lds_dwordx4 v[154:155], off
	v_lshl_add_u64 v[154:155], s[48:49], 0, v[132:133]
	s_mov_b32 m0, s50
	s_nop 0
	global_load_lds_dwordx4 v[154:155], off
	v_lshl_add_u64 v[154:155], s[48:49], 0, v[128:129]
	s_add_i32 m0, s50, 0x2000
	s_nop 0
	global_load_lds_dwordx4 v[154:155], off
	v_lshl_add_u64 v[154:155], v[228:229], 0, s[20:21]
	s_mov_b32 m0, s62
	s_nop 0
	global_load_lds_dwordx4 v[154:155], off
	v_lshl_add_u64 v[154:155], v[230:231], 0, s[20:21]
	s_mov_b32 m0, s63
	s_nop 0
	global_load_lds_dwordx4 v[154:155], off
	s_waitcnt vmcnt(8)
	s_waitcnt lgkmcnt(0)
	s_setprio 1
	s_barrier
	v_mfma_f32_16x16x32_bf16 v[60:63], v[160:163], v[194:197], v[60:63]
	v_mfma_f32_16x16x32_bf16 v[60:63], v[164:167], v[198:201], v[60:63]
	v_mfma_f32_16x16x32_bf16 v[52:55], v[172:175], v[198:201], v[52:55]
	v_mfma_f32_16x16x32_bf16 v[52:55], v[168:171], v[194:197], v[52:55]
	v_mfma_f32_16x16x32_bf16 v[36:39], v[168:171], v[202:205], v[36:39]
	v_mfma_f32_16x16x32_bf16 v[36:39], v[172:175], v[206:209], v[36:39]
	v_mfma_f32_16x16x32_bf16 v[44:47], v[164:167], v[206:209], v[44:47]
	v_mfma_f32_16x16x32_bf16 v[44:47], v[160:163], v[202:205], v[44:47]
	v_mfma_f32_16x16x32_bf16 v[28:31], v[160:163], v[210:213], v[28:31]
	v_mfma_f32_16x16x32_bf16 v[28:31], v[164:167], v[214:217], v[28:31]
	v_mfma_f32_16x16x32_bf16 v[20:23], v[172:175], v[214:217], v[20:23]
	v_mfma_f32_16x16x32_bf16 v[20:23], v[168:171], v[210:213], v[20:23]
	v_mfma_f32_16x16x32_bf16 v[4:7], v[168:171], v[218:221], v[4:7]
	v_mfma_f32_16x16x32_bf16 v[4:7], v[172:175], v[222:225], v[4:7]
	v_mfma_f32_16x16x32_bf16 v[12:15], v[164:167], v[222:225], v[12:15]
	v_mfma_f32_16x16x32_bf16 v[12:15], v[160:163], v[218:221], v[12:15]
	s_setprio 0
	s_setprio 1
	v_mfma_f32_16x16x32_bf16 v[56:59], v[176:179], v[194:197], v[56:59]
	v_mfma_f32_16x16x32_bf16 v[56:59], v[180:183], v[198:201], v[56:59]
	v_mfma_f32_16x16x32_bf16 v[48:51], v[190:193], v[198:201], v[48:51]
	v_mfma_f32_16x16x32_bf16 v[48:51], v[186:189], v[194:197], v[48:51]
	v_mfma_f32_16x16x32_bf16 v[32:35], v[186:189], v[202:205], v[32:35]
	v_mfma_f32_16x16x32_bf16 v[32:35], v[190:193], v[206:209], v[32:35]
	v_mfma_f32_16x16x32_bf16 v[40:43], v[180:183], v[206:209], v[40:43]
	v_mfma_f32_16x16x32_bf16 v[40:43], v[176:179], v[202:205], v[40:43]
	v_mfma_f32_16x16x32_bf16 v[24:27], v[176:179], v[210:213], v[24:27]
	v_mfma_f32_16x16x32_bf16 v[24:27], v[180:183], v[214:217], v[24:27]
	v_mfma_f32_16x16x32_bf16 v[16:19], v[190:193], v[214:217], v[16:19]
	v_mfma_f32_16x16x32_bf16 v[16:19], v[186:189], v[210:213], v[16:19]
	v_mfma_f32_16x16x32_bf16 v[0:3], v[186:189], v[218:221], v[0:3]
	v_mfma_f32_16x16x32_bf16 v[0:3], v[190:193], v[222:225], v[0:3]
	v_mfma_f32_16x16x32_bf16 v[8:11], v[180:183], v[222:225], v[8:11]
	v_mfma_f32_16x16x32_bf16 v[8:11], v[176:179], v[218:221], v[8:11]
	s_barrier
	s_setprio 0
	s_add_i32 s75, s75, 2
	s_add_u32 s73, s73, 0x100
	s_addc_u32 s74, s74, 0
	s_add_u32 s46, s46, 0x100
	s_addc_u32 s47, s47, 0
	s_branch .LBB0_527
.Lfa_4:
	v_add_u32_e32 v153, s66, v147
	ds_read_b128 v[160:163], v153
	v_xor_b32_e32 v253, 64, v153
	ds_read_b128 v[164:167], v253
	ds_read_b128 v[168:171], v153 offset:2048
	ds_read_b128 v[172:175], v253 offset:2048
	v_add_u32_e32 v153, s67, v147
	ds_read_b128 v[176:179], v153
	v_xor_b32_e32 v253, 64, v153
	ds_read_b128 v[180:183], v253
	ds_read_b128 v[186:189], v153 offset:2048
	ds_read_b128 v[190:193], v253 offset:2048
	s_add_u32 s50, s46, 0xfffc0080
	s_addc_u32 s51, s47, -1
	s_and_b64 s[48:49], s[48:49], exec
	s_cselect_b32 s51, s29, s51
	s_cselect_b32 s50, s70, s50
	s_cselect_b32 s49, s71, s74
	s_cselect_b32 s48, s72, s73
	v_lshl_add_u64 v[154:155], s[46:47], 0, v[138:139]
	s_add_i32 m0, s57, 0xc000
	ds_read_b128 v[194:197], v150
	v_xor_b32_e32 v253, 64, v150
	ds_read_b128 v[198:201], v253
	ds_read_b128 v[202:205], v150 offset:2048
	ds_read_b128 v[206:209], v253 offset:2048
	ds_read_b128 v[210:213], v150 offset:4096
	ds_read_b128 v[214:217], v253 offset:4096
	ds_read_b128 v[218:221], v150 offset:6144
	ds_read_b128 v[222:225], v253 offset:6144
	global_load_lds_dwordx4 v[154:155], off
	v_lshl_add_u64 v[154:155], s[46:47], 0, v[136:137]
	s_add_i32 m0, s57, 0xe000
	s_nop 0
	global_load_lds_dwordx4 v[154:155], off
	s_waitcnt vmcnt(8)
	s_waitcnt lgkmcnt(0)
	s_setprio 1
	s_barrier
	v_mfma_f32_16x16x32_bf16 v[124:127], v[160:163], v[194:197], 0
	v_mfma_f32_16x16x32_bf16 v[124:127], v[164:167], v[198:201], v[124:127]
	v_mfma_f32_16x16x32_bf16 v[116:119], v[168:171], v[194:197], 0
	v_mfma_f32_16x16x32_bf16 v[116:119], v[172:175], v[198:201], v[116:119]
	v_mfma_f32_16x16x32_bf16 v[108:111], v[160:163], v[202:205], 0
	v_mfma_f32_16x16x32_bf16 v[108:111], v[164:167], v[206:209], v[108:111]
	v_mfma_f32_16x16x32_bf16 v[100:103], v[168:171], v[202:205], 0
	v_mfma_f32_16x16x32_bf16 v[100:103], v[172:175], v[206:209], v[100:103]
	v_mfma_f32_16x16x32_bf16 v[92:95], v[160:163], v[210:213], 0
	v_mfma_f32_16x16x32_bf16 v[92:95], v[164:167], v[214:217], v[92:95]
	v_mfma_f32_16x16x32_bf16 v[84:87], v[168:171], v[210:213], 0
	v_mfma_f32_16x16x32_bf16 v[84:87], v[172:175], v[214:217], v[84:87]
	v_mfma_f32_16x16x32_bf16 v[76:79], v[160:163], v[218:221], 0
	v_mfma_f32_16x16x32_bf16 v[76:79], v[164:167], v[222:225], v[76:79]
	v_mfma_f32_16x16x32_bf16 v[68:71], v[168:171], v[218:221], 0
	v_mfma_f32_16x16x32_bf16 v[68:71], v[172:175], v[222:225], v[68:71]
	s_setprio 0
	s_setprio 1
	v_mfma_f32_16x16x32_bf16 v[120:123], v[176:179], v[194:197], 0
	v_mfma_f32_16x16x32_bf16 v[120:123], v[180:183], v[198:201], v[120:123]
	v_mfma_f32_16x16x32_bf16 v[112:115], v[186:189], v[194:197], 0
	v_mfma_f32_16x16x32_bf16 v[112:115], v[190:193], v[198:201], v[112:115]
	v_mfma_f32_16x16x32_bf16 v[104:107], v[176:179], v[202:205], 0
	v_mfma_f32_16x16x32_bf16 v[104:107], v[180:183], v[206:209], v[104:107]
	v_mfma_f32_16x16x32_bf16 v[96:99], v[186:189], v[202:205], 0
	v_mfma_f32_16x16x32_bf16 v[96:99], v[190:193], v[206:209], v[96:99]
	v_mfma_f32_16x16x32_bf16 v[88:91], v[176:179], v[210:213], 0
	v_mfma_f32_16x16x32_bf16 v[88:91], v[180:183], v[214:217], v[88:91]
	v_mfma_f32_16x16x32_bf16 v[80:83], v[186:189], v[210:213], 0
	v_mfma_f32_16x16x32_bf16 v[80:83], v[190:193], v[214:217], v[80:83]
	v_mfma_f32_16x16x32_bf16 v[72:75], v[176:179], v[218:221], 0
	v_mfma_f32_16x16x32_bf16 v[72:75], v[180:183], v[222:225], v[72:75]
	v_mfma_f32_16x16x32_bf16 v[64:67], v[186:189], v[218:221], 0
	v_mfma_f32_16x16x32_bf16 v[64:67], v[190:193], v[222:225], v[64:67]
	s_barrier
	s_setprio 0
	s_add_i32 s76, s66, s54
	v_lshl_add_u64 v[154:155], s[48:49], 0, v[132:133]
	s_mov_b32 m0, s76
	ds_read_b128 v[194:197], v150 offset:16384
	v_xor_b32_e32 v253, 64, v150
	ds_read_b128 v[198:201], v253 offset:16384
	ds_read_b128 v[202:205], v150 offset:18432
	ds_read_b128 v[206:209], v253 offset:18432
	ds_read_b128 v[210:213], v150 offset:20480
	ds_read_b128 v[214:217], v253 offset:20480
	ds_read_b128 v[218:221], v150 offset:22528
	ds_read_b128 v[222:225], v253 offset:22528
	global_load_lds_dwordx4 v[154:155], off
	s_add_i32 m0, s76, 0x2000
	s_add_u32 s76, s48, 0x40000
	v_lshl_add_u64 v[226:227], s[48:49], 0, v[128:129]
	s_addc_u32 s77, s49, 0
	s_add_i32 s78, s67, s54
	global_load_lds_dwordx4 v[226:227], off
	v_lshl_add_u64 v[228:229], s[76:77], 0, v[132:133]
	s_mov_b32 m0, s78
	v_lshl_add_u64 v[230:231], s[50:51], 0, v[130:131]
	global_load_lds_dwordx4 v[228:229], off
	v_lshl_add_u64 v[228:229], s[76:77], 0, v[128:129]
	s_add_i32 m0, s78, 0x2000
	s_nop 0
	global_load_lds_dwordx4 v[228:229], off
	v_lshl_add_u64 v[228:229], s[50:51], 0, v[134:135]
	s_mov_b32 m0, s57
	s_nop 0
	global_load_lds_dwordx4 v[228:229], off
	s_mov_b32 m0, s58
	s_nop 0
	global_load_lds_dwordx4 v[230:231], off
	s_waitcnt vmcnt(8)
	s_waitcnt lgkmcnt(0)
	s_setprio 1
	s_barrier
	v_mfma_f32_16x16x32_bf16 v[60:63], v[160:163], v[194:197], 0
	v_mfma_f32_16x16x32_bf16 v[60:63], v[164:167], v[198:201], v[60:63]
	v_mfma_f32_16x16x32_bf16 v[52:55], v[168:171], v[194:197], 0
	v_mfma_f32_16x16x32_bf16 v[52:55], v[172:175], v[198:201], v[52:55]
	v_mfma_f32_16x16x32_bf16 v[44:47], v[160:163], v[202:205], 0
	v_mfma_f32_16x16x32_bf16 v[44:47], v[164:167], v[206:209], v[44:47]
	v_mfma_f32_16x16x32_bf16 v[36:39], v[168:171], v[202:205], 0
	v_mfma_f32_16x16x32_bf16 v[36:39], v[172:175], v[206:209], v[36:39]
	v_mfma_f32_16x16x32_bf16 v[28:31], v[160:163], v[210:213], 0
	v_mfma_f32_16x16x32_bf16 v[28:31], v[164:167], v[214:217], v[28:31]
	v_mfma_f32_16x16x32_bf16 v[20:23], v[168:171], v[210:213], 0
	v_mfma_f32_16x16x32_bf16 v[20:23], v[172:175], v[214:217], v[20:23]
	v_mfma_f32_16x16x32_bf16 v[12:15], v[160:163], v[218:221], 0
	v_mfma_f32_16x16x32_bf16 v[12:15], v[164:167], v[222:225], v[12:15]
	v_mfma_f32_16x16x32_bf16 v[4:7], v[168:171], v[218:221], 0
	v_mfma_f32_16x16x32_bf16 v[4:7], v[172:175], v[222:225], v[4:7]
	s_setprio 0
	s_setprio 1
	v_mfma_f32_16x16x32_bf16 v[56:59], v[176:179], v[194:197], 0
	v_mfma_f32_16x16x32_bf16 v[56:59], v[180:183], v[198:201], v[56:59]
	v_mfma_f32_16x16x32_bf16 v[48:51], v[186:189], v[194:197], 0
	v_mfma_f32_16x16x32_bf16 v[48:51], v[190:193], v[198:201], v[48:51]
	v_mfma_f32_16x16x32_bf16 v[40:43], v[176:179], v[202:205], 0
	v_mfma_f32_16x16x32_bf16 v[40:43], v[180:183], v[206:209], v[40:43]
	v_mfma_f32_16x16x32_bf16 v[32:35], v[186:189], v[202:205], 0
	v_mfma_f32_16x16x32_bf16 v[32:35], v[190:193], v[206:209], v[32:35]
	v_mfma_f32_16x16x32_bf16 v[24:27], v[176:179], v[210:213], 0
	v_mfma_f32_16x16x32_bf16 v[24:27], v[180:183], v[214:217], v[24:27]
	v_mfma_f32_16x16x32_bf16 v[16:19], v[186:189], v[210:213], 0
	v_mfma_f32_16x16x32_bf16 v[16:19], v[190:193], v[214:217], v[16:19]
	v_mfma_f32_16x16x32_bf16 v[8:11], v[176:179], v[218:221], 0
	v_mfma_f32_16x16x32_bf16 v[8:11], v[180:183], v[222:225], v[8:11]
	v_mfma_f32_16x16x32_bf16 v[0:3], v[186:189], v[218:221], 0
	v_mfma_f32_16x16x32_bf16 v[0:3], v[190:193], v[222:225], v[0:3]
	s_barrier
	s_setprio 0
	s_add_i32 s76, 0, 0x18000
	v_add_u32_e32 v153, s76, v147
	s_add_i32 s77, 0, 0x1c000
	ds_read_b128 v[160:163], v153
	v_xor_b32_e32 v253, 64, v153
	ds_read_b128 v[164:167], v253
	ds_read_b128 v[168:171], v153 offset:2048
	ds_read_b128 v[172:175], v253 offset:2048
	v_add_u32_e32 v153, s77, v147
	ds_read_b128 v[176:179], v153
	v_xor_b32_e32 v253, 64, v153
	ds_read_b128 v[180:183], v253
	ds_read_b128 v[186:189], v153 offset:2048
	ds_read_b128 v[190:193], v253 offset:2048
	s_add_u32 s50, s50, 0x40000
	s_addc_u32 s51, s51, 0
	s_mov_b32 m0, s59
	v_lshl_add_u64 v[232:233], s[50:51], 0, v[134:135]
	ds_read_b128 v[194:197], v150 offset:32768
	v_xor_b32_e32 v253, 64, v150
	ds_read_b128 v[198:201], v253 offset:32768
	ds_read_b128 v[202:205], v150 offset:34816
	ds_read_b128 v[206:209], v253 offset:34816
	ds_read_b128 v[210:213], v150 offset:36864
	ds_read_b128 v[214:217], v253 offset:36864
	ds_read_b128 v[218:221], v150 offset:38912
	ds_read_b128 v[222:225], v253 offset:38912
	global_load_lds_dwordx4 v[232:233], off
	v_lshl_add_u64 v[232:233], s[50:51], 0, v[130:131]
	s_mov_b32 m0, s60
	s_nop 0
	global_load_lds_dwordx4 v[232:233], off
	s_waitcnt vmcnt(8)
	s_waitcnt lgkmcnt(0)
	s_setprio 1
	s_barrier
	v_mfma_f32_16x16x32_bf16 v[124:127], v[160:163], v[194:197], v[124:127]
	v_mfma_f32_16x16x32_bf16 v[124:127], v[164:167], v[198:201], v[124:127]
	v_mfma_f32_16x16x32_bf16 v[116:119], v[172:175], v[198:201], v[116:119]
	v_mfma_f32_16x16x32_bf16 v[116:119], v[168:171], v[194:197], v[116:119]
	v_mfma_f32_16x16x32_bf16 v[100:103], v[168:171], v[202:205], v[100:103]
	v_mfma_f32_16x16x32_bf16 v[100:103], v[172:175], v[206:209], v[100:103]
	v_mfma_f32_16x16x32_bf16 v[108:111], v[164:167], v[206:209], v[108:111]
	v_mfma_f32_16x16x32_bf16 v[108:111], v[160:163], v[202:205], v[108:111]
	v_mfma_f32_16x16x32_bf16 v[92:95], v[160:163], v[210:213], v[92:95]
	v_mfma_f32_16x16x32_bf16 v[92:95], v[164:167], v[214:217], v[92:95]
	v_mfma_f32_16x16x32_bf16 v[84:87], v[172:175], v[214:217], v[84:87]
	v_mfma_f32_16x16x32_bf16 v[84:87], v[168:171], v[210:213], v[84:87]
	v_mfma_f32_16x16x32_bf16 v[68:71], v[168:171], v[218:221], v[68:71]
	v_mfma_f32_16x16x32_bf16 v[68:71], v[172:175], v[222:225], v[68:71]
	v_mfma_f32_16x16x32_bf16 v[76:79], v[164:167], v[222:225], v[76:79]
	v_mfma_f32_16x16x32_bf16 v[76:79], v[160:163], v[218:221], v[76:79]
	s_setprio 0
	s_setprio 1
	v_mfma_f32_16x16x32_bf16 v[120:123], v[176:179], v[194:197], v[120:123]
	v_mfma_f32_16x16x32_bf16 v[120:123], v[180:183], v[198:201], v[120:123]
	v_mfma_f32_16x16x32_bf16 v[112:115], v[190:193], v[198:201], v[112:115]
	v_mfma_f32_16x16x32_bf16 v[112:115], v[186:189], v[194:197], v[112:115]
	v_mfma_f32_16x16x32_bf16 v[96:99], v[186:189], v[202:205], v[96:99]
	v_mfma_f32_16x16x32_bf16 v[96:99], v[190:193], v[206:209], v[96:99]
	v_mfma_f32_16x16x32_bf16 v[104:107], v[180:183], v[206:209], v[104:107]
	v_mfma_f32_16x16x32_bf16 v[104:107], v[176:179], v[202:205], v[104:107]
	v_mfma_f32_16x16x32_bf16 v[88:91], v[176:179], v[210:213], v[88:91]
	v_mfma_f32_16x16x32_bf16 v[88:91], v[180:183], v[214:217], v[88:91]
	v_mfma_f32_16x16x32_bf16 v[80:83], v[190:193], v[214:217], v[80:83]
	v_mfma_f32_16x16x32_bf16 v[80:83], v[186:189], v[210:213], v[80:83]
	v_mfma_f32_16x16x32_bf16 v[64:67], v[186:189], v[218:221], v[64:67]
	v_mfma_f32_16x16x32_bf16 v[64:67], v[190:193], v[222:225], v[64:67]
	v_mfma_f32_16x16x32_bf16 v[72:75], v[180:183], v[222:225], v[72:75]
	v_mfma_f32_16x16x32_bf16 v[72:75], v[176:179], v[218:221], v[72:75]
	s_barrier
	s_setprio 0
	s_add_i32 s50, s76, s54
	v_lshl_add_u64 v[154:155], v[154:155], 0, s[20:21]
	s_mov_b32 m0, s50
	ds_read_b128 v[194:197], v150 offset:49152
	v_xor_b32_e32 v253, 64, v150
	ds_read_b128 v[198:201], v253 offset:49152
	ds_read_b128 v[202:205], v150 offset:51200
	ds_read_b128 v[206:209], v253 offset:51200
	ds_read_b128 v[210:213], v150 offset:53248
	ds_read_b128 v[214:217], v253 offset:53248
	ds_read_b128 v[218:221], v150 offset:55296
	ds_read_b128 v[222:225], v253 offset:55296
	global_load_lds_dwordx4 v[154:155], off
	s_add_i32 m0, s50, 0x2000
	s_add_u32 s48, s48, 0x40080
	v_lshl_add_u64 v[154:155], v[226:227], 0, s[20:21]
	s_addc_u32 s49, s49, 0
	s_add_i32 s50, s77, s54
	global_load_lds_dwordx4 v[154:155], off
	v_lshl_add_u64 v[154:155], s[48:49], 0, v[132:133]
	s_mov_b32 m0, s50
	s_nop 0
	global_load_lds_dwordx4 v[154:155], off
	v_lshl_add_u64 v[154:155], s[48:49], 0, v[128:129]
	s_add_i32 m0, s50, 0x2000
	s_nop 0
	global_load_lds_dwordx4 v[154:155], off
	v_lshl_add_u64 v[154:155], v[228:229], 0, s[20:21]
	s_mov_b32 m0, s62
	s_nop 0
	global_load_lds_dwordx4 v[154:155], off
	v_lshl_add_u64 v[154:155], v[230:231], 0, s[20:21]
	s_mov_b32 m0, s63
	s_nop 0
	global_load_lds_dwordx4 v[154:155], off
	s_waitcnt vmcnt(8)
	s_waitcnt lgkmcnt(0)
	s_setprio 1
	s_barrier
	v_mfma_f32_16x16x32_bf16 v[60:63], v[160:163], v[194:197], v[60:63]
	v_mfma_f32_16x16x32_bf16 v[60:63], v[164:167], v[198:201], v[60:63]
	v_mfma_f32_16x16x32_bf16 v[52:55], v[172:175], v[198:201], v[52:55]
	v_mfma_f32_16x16x32_bf16 v[52:55], v[168:171], v[194:197], v[52:55]
	v_mfma_f32_16x16x32_bf16 v[36:39], v[168:171], v[202:205], v[36:39]
	v_mfma_f32_16x16x32_bf16 v[36:39], v[172:175], v[206:209], v[36:39]
	v_mfma_f32_16x16x32_bf16 v[44:47], v[164:167], v[206:209], v[44:47]
	v_mfma_f32_16x16x32_bf16 v[44:47], v[160:163], v[202:205], v[44:47]
	v_mfma_f32_16x16x32_bf16 v[28:31], v[160:163], v[210:213], v[28:31]
	v_mfma_f32_16x16x32_bf16 v[28:31], v[164:167], v[214:217], v[28:31]
	v_mfma_f32_16x16x32_bf16 v[20:23], v[172:175], v[214:217], v[20:23]
	v_mfma_f32_16x16x32_bf16 v[20:23], v[168:171], v[210:213], v[20:23]
	v_mfma_f32_16x16x32_bf16 v[4:7], v[168:171], v[218:221], v[4:7]
	v_mfma_f32_16x16x32_bf16 v[4:7], v[172:175], v[222:225], v[4:7]
	v_mfma_f32_16x16x32_bf16 v[12:15], v[164:167], v[222:225], v[12:15]
	v_mfma_f32_16x16x32_bf16 v[12:15], v[160:163], v[218:221], v[12:15]
	s_setprio 0
	s_setprio 1
	v_mfma_f32_16x16x32_bf16 v[56:59], v[176:179], v[194:197], v[56:59]
	v_mfma_f32_16x16x32_bf16 v[56:59], v[180:183], v[198:201], v[56:59]
	v_mfma_f32_16x16x32_bf16 v[48:51], v[190:193], v[198:201], v[48:51]
	v_mfma_f32_16x16x32_bf16 v[48:51], v[186:189], v[194:197], v[48:51]
	v_mfma_f32_16x16x32_bf16 v[32:35], v[186:189], v[202:205], v[32:35]
	v_mfma_f32_16x16x32_bf16 v[32:35], v[190:193], v[206:209], v[32:35]
	v_mfma_f32_16x16x32_bf16 v[40:43], v[180:183], v[206:209], v[40:43]
	v_mfma_f32_16x16x32_bf16 v[40:43], v[176:179], v[202:205], v[40:43]
	v_mfma_f32_16x16x32_bf16 v[24:27], v[176:179], v[210:213], v[24:27]
	v_mfma_f32_16x16x32_bf16 v[24:27], v[180:183], v[214:217], v[24:27]
	v_mfma_f32_16x16x32_bf16 v[16:19], v[190:193], v[214:217], v[16:19]
	v_mfma_f32_16x16x32_bf16 v[16:19], v[186:189], v[210:213], v[16:19]
	v_mfma_f32_16x16x32_bf16 v[0:3], v[186:189], v[218:221], v[0:3]
	v_mfma_f32_16x16x32_bf16 v[0:3], v[190:193], v[222:225], v[0:3]
	v_mfma_f32_16x16x32_bf16 v[8:11], v[180:183], v[222:225], v[8:11]
	v_mfma_f32_16x16x32_bf16 v[8:11], v[176:179], v[218:221], v[8:11]
	s_barrier
	s_setprio 0
	s_add_i32 s75, s75, 2
	s_add_u32 s73, s73, 0x100
	s_addc_u32 s74, s74, 0
	s_add_u32 s46, s46, 0x100
	s_addc_u32 s47, s47, 0
	s_branch .LBB0_527

.LBB0_609:
	s_add_u32 s79, s56, 0x100
	s_addc_u32 s80, s57, 0
	s_mov_b32 s81, -2
	s_waitcnt lgkmcnt(0)
	s_cmp_eq_u32 s70, 1
	s_cbranch_scc1 .Lfa_5
	ds_read_b128 v[128:131], v189
	v_xor_b32_e32 v253, 64, v189
	ds_read_b128 v[132:135], v253
	ds_read_b128 v[136:139], v189 offset:2048
	ds_read_b128 v[140:143], v253 offset:2048
	ds_read_b128 v[144:147], v190
	v_xor_b32_e32 v253, 64, v190
	ds_read_b128 v[148:151], v253
	ds_read_b128 v[172:175], v190 offset:2048
	ds_read_b128 v[176:179], v253 offset:2048
	s_add_u32 s56, s54, 0x100
	s_addc_u32 s57, s55, 0
	s_cmp_eq_u32 s81, 40
	s_cselect_b32 s61, s17, s57
	s_cselect_b32 s60, s16, s56
	s_cselect_b32 s59, s53, s80
	s_cselect_b32 s58, s52, s79
	v_lshl_add_u64 v[222:223], s[54:55], 0, v[166:167]
	s_add_i32 m0, s66, 0xc000
	ds_read_b128 v[180:183], v191
	v_xor_b32_e32 v253, 64, v191
	ds_read_b128 v[194:197], v253
	ds_read_b128 v[198:201], v191 offset:2048
	ds_read_b128 v[202:205], v253 offset:2048
	ds_read_b128 v[206:209], v191 offset:4096
	ds_read_b128 v[210:213], v253 offset:4096
	ds_read_b128 v[214:217], v191 offset:6144
	ds_read_b128 v[218:221], v253 offset:6144
	global_load_lds_dwordx4 v[222:223], off
	v_lshl_add_u64 v[222:223], s[54:55], 0, v[164:165]
	s_add_i32 m0, s66, 0xe000
	s_nop 0
	global_load_lds_dwordx4 v[222:223], off
	s_waitcnt vmcnt(24)
	s_waitcnt lgkmcnt(0)
	s_setprio 1
	s_barrier
	v_mfma_f32_16x16x32_bf16 v[124:127], v[128:131], v[180:183], 0
	v_mfma_f32_16x16x32_bf16 v[124:127], v[132:135], v[194:197], v[124:127]
	v_mfma_f32_16x16x32_bf16 v[120:123], v[136:139], v[180:183], 0
	v_mfma_f32_16x16x32_bf16 v[120:123], v[140:143], v[194:197], v[120:123]
	v_mfma_f32_16x16x32_bf16 v[108:111], v[128:131], v[198:201], 0
	v_mfma_f32_16x16x32_bf16 v[108:111], v[132:135], v[202:205], v[108:111]
	v_mfma_f32_16x16x32_bf16 v[104:107], v[136:139], v[198:201], 0
	v_mfma_f32_16x16x32_bf16 v[104:107], v[140:143], v[202:205], v[104:107]
	v_mfma_f32_16x16x32_bf16 v[92:95], v[128:131], v[206:209], 0
	v_mfma_f32_16x16x32_bf16 v[92:95], v[132:135], v[210:213], v[92:95]
	v_mfma_f32_16x16x32_bf16 v[88:91], v[136:139], v[206:209], 0
	v_mfma_f32_16x16x32_bf16 v[88:91], v[140:143], v[210:213], v[88:91]
	v_mfma_f32_16x16x32_bf16 v[76:79], v[128:131], v[214:217], 0
	v_mfma_f32_16x16x32_bf16 v[76:79], v[132:135], v[218:221], v[76:79]
	v_mfma_f32_16x16x32_bf16 v[72:75], v[136:139], v[214:217], 0
	v_mfma_f32_16x16x32_bf16 v[72:75], v[140:143], v[218:221], v[72:75]
	s_setprio 0
	s_setprio 1
	v_mfma_f32_16x16x32_bf16 v[116:119], v[144:147], v[180:183], 0
	v_mfma_f32_16x16x32_bf16 v[116:119], v[148:151], v[194:197], v[116:119]
	v_mfma_f32_16x16x32_bf16 v[112:115], v[172:175], v[180:183], 0
	v_mfma_f32_16x16x32_bf16 v[112:115], v[176:179], v[194:197], v[112:115]
	v_mfma_f32_16x16x32_bf16 v[100:103], v[144:147], v[198:201], 0
	v_mfma_f32_16x16x32_bf16 v[100:103], v[148:151], v[202:205], v[100:103]
	v_mfma_f32_16x16x32_bf16 v[96:99], v[172:175], v[198:201], 0
	v_mfma_f32_16x16x32_bf16 v[96:99], v[176:179], v[202:205], v[96:99]
	v_mfma_f32_16x16x32_bf16 v[84:87], v[144:147], v[206:209], 0
	v_mfma_f32_16x16x32_bf16 v[84:87], v[148:151], v[210:213], v[84:87]
	v_mfma_f32_16x16x32_bf16 v[80:83], v[172:175], v[206:209], 0
	v_mfma_f32_16x16x32_bf16 v[80:83], v[176:179], v[210:213], v[80:83]
	v_mfma_f32_16x16x32_bf16 v[68:71], v[144:147], v[214:217], 0
	v_mfma_f32_16x16x32_bf16 v[68:71], v[148:151], v[218:221], v[68:71]
	v_mfma_f32_16x16x32_bf16 v[64:67], v[172:175], v[214:217], 0
	v_mfma_f32_16x16x32_bf16 v[64:67], v[176:179], v[218:221], v[64:67]
	s_barrier
	s_setprio 0
	s_add_i32 s54, s75, s65
	v_lshl_add_u64 v[222:223], s[58:59], 0, v[154:155]
	s_mov_b32 m0, s54
	ds_read_b128 v[180:183], v191 offset:16384
	v_xor_b32_e32 v253, 64, v191
	ds_read_b128 v[194:197], v253 offset:16384
	ds_read_b128 v[198:201], v191 offset:18432
	ds_read_b128 v[202:205], v253 offset:18432
	ds_read_b128 v[206:209], v191 offset:20480
	ds_read_b128 v[210:213], v253 offset:20480
	ds_read_b128 v[214:217], v191 offset:22528
	ds_read_b128 v[218:221], v253 offset:22528
	global_load_lds_dwordx4 v[222:223], off
	s_add_i32 m0, s54, 0x2000
	s_add_u32 s54, s58, 0xb0000
	v_lshl_add_u64 v[224:225], s[58:59], 0, v[162:163]
	s_addc_u32 s55, s59, 0
	s_add_i32 s82, s76, s65
	global_load_lds_dwordx4 v[224:225], off
	v_lshl_add_u64 v[226:227], s[54:55], 0, v[154:155]
	s_mov_b32 m0, s82
	v_lshl_add_u64 v[228:229], s[60:61], 0, v[160:161]
	global_load_lds_dwordx4 v[226:227], off
	v_lshl_add_u64 v[226:227], s[54:55], 0, v[162:163]
	s_add_i32 m0, s82, 0x2000
	s_nop 0
	global_load_lds_dwordx4 v[226:227], off
	v_lshl_add_u64 v[226:227], s[60:61], 0, v[152:153]
	s_mov_b32 m0, s66
	s_nop 0
	global_load_lds_dwordx4 v[226:227], off
	s_mov_b32 m0, s67
	s_nop 0
	global_load_lds_dwordx4 v[228:229], off
	s_waitcnt vmcnt(24)
	s_waitcnt lgkmcnt(0)
	s_setprio 1
	s_barrier
	v_mfma_f32_16x16x32_bf16 v[60:63], v[128:131], v[180:183], 0
	v_mfma_f32_16x16x32_bf16 v[60:63], v[132:135], v[194:197], v[60:63]
	v_mfma_f32_16x16x32_bf16 v[56:59], v[136:139], v[180:183], 0
	v_mfma_f32_16x16x32_bf16 v[56:59], v[140:143], v[194:197], v[56:59]
	v_mfma_f32_16x16x32_bf16 v[44:47], v[128:131], v[198:201], 0
	v_mfma_f32_16x16x32_bf16 v[44:47], v[132:135], v[202:205], v[44:47]
	v_mfma_f32_16x16x32_bf16 v[40:43], v[136:139], v[198:201], 0
	v_mfma_f32_16x16x32_bf16 v[40:43], v[140:143], v[202:205], v[40:43]
	v_mfma_f32_16x16x32_bf16 v[28:31], v[128:131], v[206:209], 0
	v_mfma_f32_16x16x32_bf16 v[28:31], v[132:135], v[210:213], v[28:31]
	v_mfma_f32_16x16x32_bf16 v[24:27], v[136:139], v[206:209], 0
	v_mfma_f32_16x16x32_bf16 v[24:27], v[140:143], v[210:213], v[24:27]
	v_mfma_f32_16x16x32_bf16 v[12:15], v[128:131], v[214:217], 0
	v_mfma_f32_16x16x32_bf16 v[12:15], v[132:135], v[218:221], v[12:15]
	v_mfma_f32_16x16x32_bf16 v[8:11], v[136:139], v[214:217], 0
	v_mfma_f32_16x16x32_bf16 v[8:11], v[140:143], v[218:221], v[8:11]
	s_setprio 0
	s_setprio 1
	v_mfma_f32_16x16x32_bf16 v[52:55], v[144:147], v[180:183], 0
	v_mfma_f32_16x16x32_bf16 v[52:55], v[148:151], v[194:197], v[52:55]
	v_mfma_f32_16x16x32_bf16 v[48:51], v[172:175], v[180:183], 0
	v_mfma_f32_16x16x32_bf16 v[48:51], v[176:179], v[194:197], v[48:51]
	v_mfma_f32_16x16x32_bf16 v[36:39], v[144:147], v[198:201], 0
	v_mfma_f32_16x16x32_bf16 v[36:39], v[148:151], v[202:205], v[36:39]
	v_mfma_f32_16x16x32_bf16 v[32:35], v[172:175], v[198:201], 0
	v_mfma_f32_16x16x32_bf16 v[32:35], v[176:179], v[202:205], v[32:35]
	v_mfma_f32_16x16x32_bf16 v[20:23], v[144:147], v[206:209], 0
	v_mfma_f32_16x16x32_bf16 v[20:23], v[148:151], v[210:213], v[20:23]
	v_mfma_f32_16x16x32_bf16 v[16:19], v[172:175], v[206:209], 0
	v_mfma_f32_16x16x32_bf16 v[16:19], v[176:179], v[210:213], v[16:19]
	v_mfma_f32_16x16x32_bf16 v[4:7], v[144:147], v[214:217], 0
	v_mfma_f32_16x16x32_bf16 v[4:7], v[148:151], v[218:221], v[4:7]
	v_mfma_f32_16x16x32_bf16 v[0:3], v[172:175], v[214:217], 0
	v_mfma_f32_16x16x32_bf16 v[0:3], v[176:179], v[218:221], v[0:3]
	s_barrier
	s_setprio 0
	s_add_i32 s82, 0, 0x18000
	s_add_i32 s83, 0, 0x1c000
	v_add_u32_e32 v140, s82, v186
	v_add_u32_e32 v176, s83, v186
	ds_read_b128 v[128:131], v140
	v_xor_b32_e32 v253, 64, v140
	ds_read_b128 v[132:135], v253
	ds_read_b128 v[136:139], v140 offset:2048
	ds_read_b128 v[140:143], v253 offset:2048
	ds_read_b128 v[144:147], v176
	v_xor_b32_e32 v253, 64, v176
	ds_read_b128 v[148:151], v253
	ds_read_b128 v[172:175], v176 offset:2048
	ds_read_b128 v[176:179], v253 offset:2048
	s_add_u32 s54, s60, 0xb0000
	s_addc_u32 s55, s61, 0
	s_mov_b32 m0, s68
	v_lshl_add_u64 v[230:231], s[54:55], 0, v[152:153]
	ds_read_b128 v[180:183], v191 offset:32768
	v_xor_b32_e32 v253, 64, v191
	ds_read_b128 v[194:197], v253 offset:32768
	ds_read_b128 v[198:201], v191 offset:34816
	ds_read_b128 v[202:205], v253 offset:34816
	ds_read_b128 v[206:209], v191 offset:36864
	ds_read_b128 v[210:213], v253 offset:36864
	ds_read_b128 v[214:217], v191 offset:38912
	ds_read_b128 v[218:221], v253 offset:38912
	global_load_lds_dwordx4 v[230:231], off
	v_lshl_add_u64 v[230:231], s[54:55], 0, v[160:161]
	s_mov_b32 m0, s69
	s_nop 0
	global_load_lds_dwordx4 v[230:231], off
	s_waitcnt vmcnt(8)
	s_waitcnt lgkmcnt(0)
	s_setprio 1
	s_barrier
	v_mfma_f32_16x16x32_bf16 v[124:127], v[128:131], v[180:183], v[124:127]
	v_mfma_f32_16x16x32_bf16 v[124:127], v[132:135], v[194:197], v[124:127]
	v_mfma_f32_16x16x32_bf16 v[120:123], v[140:143], v[194:197], v[120:123]
	v_mfma_f32_16x16x32_bf16 v[120:123], v[136:139], v[180:183], v[120:123]
	v_mfma_f32_16x16x32_bf16 v[104:107], v[136:139], v[198:201], v[104:107]
	v_mfma_f32_16x16x32_bf16 v[104:107], v[140:143], v[202:205], v[104:107]
	v_mfma_f32_16x16x32_bf16 v[108:111], v[132:135], v[202:205], v[108:111]
	v_mfma_f32_16x16x32_bf16 v[108:111], v[128:131], v[198:201], v[108:111]
	v_mfma_f32_16x16x32_bf16 v[92:95], v[128:131], v[206:209], v[92:95]
	v_mfma_f32_16x16x32_bf16 v[92:95], v[132:135], v[210:213], v[92:95]
	v_mfma_f32_16x16x32_bf16 v[88:91], v[140:143], v[210:213], v[88:91]
	v_mfma_f32_16x16x32_bf16 v[88:91], v[136:139], v[206:209], v[88:91]
	v_mfma_f32_16x16x32_bf16 v[72:75], v[136:139], v[214:217], v[72:75]
	v_mfma_f32_16x16x32_bf16 v[72:75], v[140:143], v[218:221], v[72:75]
	v_mfma_f32_16x16x32_bf16 v[76:79], v[132:135], v[218:221], v[76:79]
	v_mfma_f32_16x16x32_bf16 v[76:79], v[128:131], v[214:217], v[76:79]
	s_setprio 0
	s_setprio 1
	v_mfma_f32_16x16x32_bf16 v[116:119], v[144:147], v[180:183], v[116:119]
	v_mfma_f32_16x16x32_bf16 v[116:119], v[148:151], v[194:197], v[116:119]
	v_mfma_f32_16x16x32_bf16 v[112:115], v[176:179], v[194:197], v[112:115]
	v_mfma_f32_16x16x32_bf16 v[112:115], v[172:175], v[180:183], v[112:115]
	v_mfma_f32_16x16x32_bf16 v[96:99], v[172:175], v[198:201], v[96:99]
	v_mfma_f32_16x16x32_bf16 v[96:99], v[176:179], v[202:205], v[96:99]
	v_mfma_f32_16x16x32_bf16 v[100:103], v[148:151], v[202:205], v[100:103]
	v_mfma_f32_16x16x32_bf16 v[100:103], v[144:147], v[198:201], v[100:103]
	v_mfma_f32_16x16x32_bf16 v[84:87], v[144:147], v[206:209], v[84:87]
	v_mfma_f32_16x16x32_bf16 v[84:87], v[148:151], v[210:213], v[84:87]
	v_mfma_f32_16x16x32_bf16 v[80:83], v[176:179], v[210:213], v[80:83]
	v_mfma_f32_16x16x32_bf16 v[80:83], v[172:175], v[206:209], v[80:83]
	v_mfma_f32_16x16x32_bf16 v[64:67], v[172:175], v[214:217], v[64:67]
	v_mfma_f32_16x16x32_bf16 v[64:67], v[176:179], v[218:221], v[64:67]
	v_mfma_f32_16x16x32_bf16 v[68:71], v[148:151], v[218:221], v[68:71]
	v_mfma_f32_16x16x32_bf16 v[68:71], v[144:147], v[214:217], v[68:71]
	s_barrier
	s_setprio 0
	s_add_i32 s54, s82, s65
	v_lshl_add_u64 v[222:223], v[222:223], 0, s[28:29]
	s_mov_b32 m0, s54
	ds_read_b128 v[180:183], v191 offset:49152
	v_xor_b32_e32 v253, 64, v191
	ds_read_b128 v[194:197], v253 offset:49152
	ds_read_b128 v[198:201], v191 offset:51200
	ds_read_b128 v[202:205], v253 offset:51200
	ds_read_b128 v[206:209], v191 offset:53248
	ds_read_b128 v[210:213], v253 offset:53248
	ds_read_b128 v[214:217], v191 offset:55296
	ds_read_b128 v[218:221], v253 offset:55296
	global_load_lds_dwordx4 v[222:223], off
	s_add_i32 m0, s54, 0x2000
	s_add_u32 s54, s58, 0xb0080
	v_lshl_add_u64 v[222:223], v[224:225], 0, s[28:29]
	s_addc_u32 s55, s59, 0
	s_add_i32 s58, s83, s65
	global_load_lds_dwordx4 v[222:223], off
	v_lshl_add_u64 v[222:223], s[54:55], 0, v[154:155]
	s_mov_b32 m0, s58
	s_nop 0
	global_load_lds_dwordx4 v[222:223], off
	v_lshl_add_u64 v[222:223], s[54:55], 0, v[162:163]
	s_add_i32 m0, s58, 0x2000
	s_nop 0
	global_load_lds_dwordx4 v[222:223], off
	v_lshl_add_u64 v[222:223], v[226:227], 0, s[28:29]
	s_mov_b32 m0, s3
	s_nop 0
	global_load_lds_dwordx4 v[222:223], off
	v_lshl_add_u64 v[222:223], v[228:229], 0, s[28:29]
	s_mov_b32 m0, s71
	s_nop 0
	global_load_lds_dwordx4 v[222:223], off
	s_waitcnt vmcnt(8)
	s_waitcnt lgkmcnt(0)
	s_setprio 1
	s_barrier
	v_mfma_f32_16x16x32_bf16 v[60:63], v[128:131], v[180:183], v[60:63]
	v_mfma_f32_16x16x32_bf16 v[60:63], v[132:135], v[194:197], v[60:63]
	v_mfma_f32_16x16x32_bf16 v[56:59], v[140:143], v[194:197], v[56:59]
	v_mfma_f32_16x16x32_bf16 v[56:59], v[136:139], v[180:183], v[56:59]
	v_mfma_f32_16x16x32_bf16 v[40:43], v[136:139], v[198:201], v[40:43]
	v_mfma_f32_16x16x32_bf16 v[40:43], v[140:143], v[202:205], v[40:43]
	v_mfma_f32_16x16x32_bf16 v[44:47], v[132:135], v[202:205], v[44:47]
	v_mfma_f32_16x16x32_bf16 v[44:47], v[128:131], v[198:201], v[44:47]
	v_mfma_f32_16x16x32_bf16 v[28:31], v[128:131], v[206:209], v[28:31]
	v_mfma_f32_16x16x32_bf16 v[28:31], v[132:135], v[210:213], v[28:31]
	v_mfma_f32_16x16x32_bf16 v[24:27], v[140:143], v[210:213], v[24:27]
	v_mfma_f32_16x16x32_bf16 v[24:27], v[136:139], v[206:209], v[24:27]
	v_mfma_f32_16x16x32_bf16 v[8:11], v[136:139], v[214:217], v[8:11]
	v_mfma_f32_16x16x32_bf16 v[8:11], v[140:143], v[218:221], v[8:11]
	v_mfma_f32_16x16x32_bf16 v[12:15], v[132:135], v[218:221], v[12:15]
	v_mfma_f32_16x16x32_bf16 v[12:15], v[128:131], v[214:217], v[12:15]
	s_setprio 0
	s_setprio 1
	v_mfma_f32_16x16x32_bf16 v[52:55], v[144:147], v[180:183], v[52:55]
	v_mfma_f32_16x16x32_bf16 v[52:55], v[148:151], v[194:197], v[52:55]
	v_mfma_f32_16x16x32_bf16 v[48:51], v[176:179], v[194:197], v[48:51]
	v_mfma_f32_16x16x32_bf16 v[48:51], v[172:175], v[180:183], v[48:51]
	v_mfma_f32_16x16x32_bf16 v[32:35], v[172:175], v[198:201], v[32:35]
	v_mfma_f32_16x16x32_bf16 v[32:35], v[176:179], v[202:205], v[32:35]
	v_mfma_f32_16x16x32_bf16 v[36:39], v[148:151], v[202:205], v[36:39]
	v_mfma_f32_16x16x32_bf16 v[36:39], v[144:147], v[198:201], v[36:39]
	v_mfma_f32_16x16x32_bf16 v[20:23], v[144:147], v[206:209], v[20:23]
	v_mfma_f32_16x16x32_bf16 v[20:23], v[148:151], v[210:213], v[20:23]
	v_mfma_f32_16x16x32_bf16 v[16:19], v[176:179], v[210:213], v[16:19]
	v_mfma_f32_16x16x32_bf16 v[16:19], v[172:175], v[206:209], v[16:19]
	v_mfma_f32_16x16x32_bf16 v[0:3], v[172:175], v[214:217], v[0:3]
	v_mfma_f32_16x16x32_bf16 v[0:3], v[176:179], v[218:221], v[0:3]
	v_mfma_f32_16x16x32_bf16 v[4:7], v[148:151], v[218:221], v[4:7]
	v_mfma_f32_16x16x32_bf16 v[4:7], v[144:147], v[214:217], v[4:7]
	s_barrier
	s_setprio 0
	s_add_i32 s81, s81, 2
	s_add_u32 s79, s79, 0x100
	s_addc_u32 s80, s80, 0
	s_cmp_gt_u32 s81, 41
	s_mov_b64 s[54:55], s[56:57]
	s_branch .LBB0_610
.Lfa_5:
	ds_read_b128 v[128:131], v189
	v_xor_b32_e32 v253, 64, v189
	ds_read_b128 v[132:135], v253
	ds_read_b128 v[136:139], v189 offset:2048
	ds_read_b128 v[140:143], v253 offset:2048
	ds_read_b128 v[144:147], v190
	v_xor_b32_e32 v253, 64, v190
	ds_read_b128 v[148:151], v253
	ds_read_b128 v[172:175], v190 offset:2048
	ds_read_b128 v[176:179], v253 offset:2048
	s_add_u32 s56, s54, 0x100
	s_addc_u32 s57, s55, 0
	s_cmp_eq_u32 s81, 40
	s_cselect_b32 s61, s17, s57
	s_cselect_b32 s60, s16, s56
	s_cselect_b32 s59, s53, s80
	s_cselect_b32 s58, s52, s79
	v_lshl_add_u64 v[222:223], s[54:55], 0, v[166:167]
	s_add_i32 m0, s66, 0xc000
	ds_read_b128 v[180:183], v191
	v_xor_b32_e32 v253, 64, v191
	ds_read_b128 v[194:197], v253
	ds_read_b128 v[198:201], v191 offset:2048
	ds_read_b128 v[202:205], v253 offset:2048
	ds_read_b128 v[206:209], v191 offset:4096
	ds_read_b128 v[210:213], v253 offset:4096
	ds_read_b128 v[214:217], v191 offset:6144
	ds_read_b128 v[218:221], v253 offset:6144
	global_load_lds_dwordx4 v[222:223], off
	v_lshl_add_u64 v[222:223], s[54:55], 0, v[164:165]
	s_add_i32 m0, s66, 0xe000
	s_nop 0
	global_load_lds_dwordx4 v[222:223], off
	s_waitcnt vmcnt(8)
	s_waitcnt lgkmcnt(0)
	s_setprio 1
	s_barrier
	v_mfma_f32_16x16x32_bf16 v[124:127], v[128:131], v[180:183], 0
	v_mfma_f32_16x16x32_bf16 v[124:127], v[132:135], v[194:197], v[124:127]
	v_mfma_f32_16x16x32_bf16 v[120:123], v[136:139], v[180:183], 0
	v_mfma_f32_16x16x32_bf16 v[120:123], v[140:143], v[194:197], v[120:123]
	v_mfma_f32_16x16x32_bf16 v[108:111], v[128:131], v[198:201], 0
	v_mfma_f32_16x16x32_bf16 v[108:111], v[132:135], v[202:205], v[108:111]
	v_mfma_f32_16x16x32_bf16 v[104:107], v[136:139], v[198:201], 0
	v_mfma_f32_16x16x32_bf16 v[104:107], v[140:143], v[202:205], v[104:107]
	v_mfma_f32_16x16x32_bf16 v[92:95], v[128:131], v[206:209], 0
	v_mfma_f32_16x16x32_bf16 v[92:95], v[132:135], v[210:213], v[92:95]
	v_mfma_f32_16x16x32_bf16 v[88:91], v[136:139], v[206:209], 0
	v_mfma_f32_16x16x32_bf16 v[88:91], v[140:143], v[210:213], v[88:91]
	v_mfma_f32_16x16x32_bf16 v[76:79], v[128:131], v[214:217], 0
	v_mfma_f32_16x16x32_bf16 v[76:79], v[132:135], v[218:221], v[76:79]
	v_mfma_f32_16x16x32_bf16 v[72:75], v[136:139], v[214:217], 0
	v_mfma_f32_16x16x32_bf16 v[72:75], v[140:143], v[218:221], v[72:75]
	s_setprio 0
	s_setprio 1
	v_mfma_f32_16x16x32_bf16 v[116:119], v[144:147], v[180:183], 0
	v_mfma_f32_16x16x32_bf16 v[116:119], v[148:151], v[194:197], v[116:119]
	v_mfma_f32_16x16x32_bf16 v[112:115], v[172:175], v[180:183], 0
	v_mfma_f32_16x16x32_bf16 v[112:115], v[176:179], v[194:197], v[112:115]
	v_mfma_f32_16x16x32_bf16 v[100:103], v[144:147], v[198:201], 0
	v_mfma_f32_16x16x32_bf16 v[100:103], v[148:151], v[202:205], v[100:103]
	v_mfma_f32_16x16x32_bf16 v[96:99], v[172:175], v[198:201], 0
	v_mfma_f32_16x16x32_bf16 v[96:99], v[176:179], v[202:205], v[96:99]
	v_mfma_f32_16x16x32_bf16 v[84:87], v[144:147], v[206:209], 0
	v_mfma_f32_16x16x32_bf16 v[84:87], v[148:151], v[210:213], v[84:87]
	v_mfma_f32_16x16x32_bf16 v[80:83], v[172:175], v[206:209], 0
	v_mfma_f32_16x16x32_bf16 v[80:83], v[176:179], v[210:213], v[80:83]
	v_mfma_f32_16x16x32_bf16 v[68:71], v[144:147], v[214:217], 0
	v_mfma_f32_16x16x32_bf16 v[68:71], v[148:151], v[218:221], v[68:71]
	v_mfma_f32_16x16x32_bf16 v[64:67], v[172:175], v[214:217], 0
	v_mfma_f32_16x16x32_bf16 v[64:67], v[176:179], v[218:221], v[64:67]
	s_barrier
	s_setprio 0
	s_add_i32 s54, s75, s65
	v_lshl_add_u64 v[222:223], s[58:59], 0, v[154:155]
	s_mov_b32 m0, s54
	ds_read_b128 v[180:183], v191 offset:16384
	v_xor_b32_e32 v253, 64, v191
	ds_read_b128 v[194:197], v253 offset:16384
	ds_read_b128 v[198:201], v191 offset:18432
	ds_read_b128 v[202:205], v253 offset:18432
	ds_read_b128 v[206:209], v191 offset:20480
	ds_read_b128 v[210:213], v253 offset:20480
	ds_read_b128 v[214:217], v191 offset:22528
	ds_read_b128 v[218:221], v253 offset:22528
	global_load_lds_dwordx4 v[222:223], off
	s_add_i32 m0, s54, 0x2000
	s_add_u32 s54, s58, 0xb0000
	v_lshl_add_u64 v[224:225], s[58:59], 0, v[162:163]
	s_addc_u32 s55, s59, 0
	s_add_i32 s82, s76, s65
	global_load_lds_dwordx4 v[224:225], off
	v_lshl_add_u64 v[226:227], s[54:55], 0, v[154:155]
	s_mov_b32 m0, s82
	v_lshl_add_u64 v[228:229], s[60:61], 0, v[160:161]
	global_load_lds_dwordx4 v[226:227], off
	v_lshl_add_u64 v[226:227], s[54:55], 0, v[162:163]
	s_add_i32 m0, s82, 0x2000
	s_nop 0
	global_load_lds_dwordx4 v[226:227], off
	v_lshl_add_u64 v[226:227], s[60:61], 0, v[152:153]
	s_mov_b32 m0, s66
	s_nop 0
	global_load_lds_dwordx4 v[226:227], off
	s_mov_b32 m0, s67
	s_nop 0
	global_load_lds_dwordx4 v[228:229], off
	s_waitcnt vmcnt(8)
	s_waitcnt lgkmcnt(0)
	s_setprio 1
	s_barrier
	v_mfma_f32_16x16x32_bf16 v[60:63], v[128:131], v[180:183], 0
	v_mfma_f32_16x16x32_bf16 v[60:63], v[132:135], v[194:197], v[60:63]
	v_mfma_f32_16x16x32_bf16 v[56:59], v[136:139], v[180:183], 0
	v_mfma_f32_16x16x32_bf16 v[56:59], v[140:143], v[194:197], v[56:59]
	v_mfma_f32_16x16x32_bf16 v[44:47], v[128:131], v[198:201], 0
	v_mfma_f32_16x16x32_bf16 v[44:47], v[132:135], v[202:205], v[44:47]
	v_mfma_f32_16x16x32_bf16 v[40:43], v[136:139], v[198:201], 0
	v_mfma_f32_16x16x32_bf16 v[40:43], v[140:143], v[202:205], v[40:43]
	v_mfma_f32_16x16x32_bf16 v[28:31], v[128:131], v[206:209], 0
	v_mfma_f32_16x16x32_bf16 v[28:31], v[132:135], v[210:213], v[28:31]
	v_mfma_f32_16x16x32_bf16 v[24:27], v[136:139], v[206:209], 0
	v_mfma_f32_16x16x32_bf16 v[24:27], v[140:143], v[210:213], v[24:27]
	v_mfma_f32_16x16x32_bf16 v[12:15], v[128:131], v[214:217], 0
	v_mfma_f32_16x16x32_bf16 v[12:15], v[132:135], v[218:221], v[12:15]
	v_mfma_f32_16x16x32_bf16 v[8:11], v[136:139], v[214:217], 0
	v_mfma_f32_16x16x32_bf16 v[8:11], v[140:143], v[218:221], v[8:11]
	s_setprio 0
	s_setprio 1
	v_mfma_f32_16x16x32_bf16 v[52:55], v[144:147], v[180:183], 0
	v_mfma_f32_16x16x32_bf16 v[52:55], v[148:151], v[194:197], v[52:55]
	v_mfma_f32_16x16x32_bf16 v[48:51], v[172:175], v[180:183], 0
	v_mfma_f32_16x16x32_bf16 v[48:51], v[176:179], v[194:197], v[48:51]
	v_mfma_f32_16x16x32_bf16 v[36:39], v[144:147], v[198:201], 0
	v_mfma_f32_16x16x32_bf16 v[36:39], v[148:151], v[202:205], v[36:39]
	v_mfma_f32_16x16x32_bf16 v[32:35], v[172:175], v[198:201], 0
	v_mfma_f32_16x16x32_bf16 v[32:35], v[176:179], v[202:205], v[32:35]
	v_mfma_f32_16x16x32_bf16 v[20:23], v[144:147], v[206:209], 0
	v_mfma_f32_16x16x32_bf16 v[20:23], v[148:151], v[210:213], v[20:23]
	v_mfma_f32_16x16x32_bf16 v[16:19], v[172:175], v[206:209], 0
	v_mfma_f32_16x16x32_bf16 v[16:19], v[176:179], v[210:213], v[16:19]
	v_mfma_f32_16x16x32_bf16 v[4:7], v[144:147], v[214:217], 0
	v_mfma_f32_16x16x32_bf16 v[4:7], v[148:151], v[218:221], v[4:7]
	v_mfma_f32_16x16x32_bf16 v[0:3], v[172:175], v[214:217], 0
	v_mfma_f32_16x16x32_bf16 v[0:3], v[176:179], v[218:221], v[0:3]
	s_barrier
	s_setprio 0
	s_add_i32 s82, 0, 0x18000
	s_add_i32 s83, 0, 0x1c000
	v_add_u32_e32 v140, s82, v186
	v_add_u32_e32 v176, s83, v186
	ds_read_b128 v[128:131], v140
	v_xor_b32_e32 v253, 64, v140
	ds_read_b128 v[132:135], v253
	ds_read_b128 v[136:139], v140 offset:2048
	ds_read_b128 v[140:143], v253 offset:2048
	ds_read_b128 v[144:147], v176
	v_xor_b32_e32 v253, 64, v176
	ds_read_b128 v[148:151], v253
	ds_read_b128 v[172:175], v176 offset:2048
	ds_read_b128 v[176:179], v253 offset:2048
	s_add_u32 s54, s60, 0xb0000
	s_addc_u32 s55, s61, 0
	s_mov_b32 m0, s68
	v_lshl_add_u64 v[230:231], s[54:55], 0, v[152:153]
	ds_read_b128 v[180:183], v191 offset:32768
	v_xor_b32_e32 v253, 64, v191
	ds_read_b128 v[194:197], v253 offset:32768
	ds_read_b128 v[198:201], v191 offset:34816
	ds_read_b128 v[202:205], v253 offset:34816
	ds_read_b128 v[206:209], v191 offset:36864
	ds_read_b128 v[210:213], v253 offset:36864
	ds_read_b128 v[214:217], v191 offset:38912
	ds_read_b128 v[218:221], v253 offset:38912
	global_load_lds_dwordx4 v[230:231], off
	v_lshl_add_u64 v[230:231], s[54:55], 0, v[160:161]
	s_mov_b32 m0, s69
	s_nop 0
	global_load_lds_dwordx4 v[230:231], off
	s_waitcnt vmcnt(8)
	s_waitcnt lgkmcnt(0)
	s_setprio 1
	s_barrier
	v_mfma_f32_16x16x32_bf16 v[124:127], v[128:131], v[180:183], v[124:127]
	v_mfma_f32_16x16x32_bf16 v[124:127], v[132:135], v[194:197], v[124:127]
	v_mfma_f32_16x16x32_bf16 v[120:123], v[140:143], v[194:197], v[120:123]
	v_mfma_f32_16x16x32_bf16 v[120:123], v[136:139], v[180:183], v[120:123]
	v_mfma_f32_16x16x32_bf16 v[104:107], v[136:139], v[198:201], v[104:107]
	v_mfma_f32_16x16x32_bf16 v[104:107], v[140:143], v[202:205], v[104:107]
	v_mfma_f32_16x16x32_bf16 v[108:111], v[132:135], v[202:205], v[108:111]
	v_mfma_f32_16x16x32_bf16 v[108:111], v[128:131], v[198:201], v[108:111]
	v_mfma_f32_16x16x32_bf16 v[92:95], v[128:131], v[206:209], v[92:95]
	v_mfma_f32_16x16x32_bf16 v[92:95], v[132:135], v[210:213], v[92:95]
	v_mfma_f32_16x16x32_bf16 v[88:91], v[140:143], v[210:213], v[88:91]
	v_mfma_f32_16x16x32_bf16 v[88:91], v[136:139], v[206:209], v[88:91]
	v_mfma_f32_16x16x32_bf16 v[72:75], v[136:139], v[214:217], v[72:75]
	v_mfma_f32_16x16x32_bf16 v[72:75], v[140:143], v[218:221], v[72:75]
	v_mfma_f32_16x16x32_bf16 v[76:79], v[132:135], v[218:221], v[76:79]
	v_mfma_f32_16x16x32_bf16 v[76:79], v[128:131], v[214:217], v[76:79]
	s_setprio 0
	s_setprio 1
	v_mfma_f32_16x16x32_bf16 v[116:119], v[144:147], v[180:183], v[116:119]
	v_mfma_f32_16x16x32_bf16 v[116:119], v[148:151], v[194:197], v[116:119]
	v_mfma_f32_16x16x32_bf16 v[112:115], v[176:179], v[194:197], v[112:115]
	v_mfma_f32_16x16x32_bf16 v[112:115], v[172:175], v[180:183], v[112:115]
	v_mfma_f32_16x16x32_bf16 v[96:99], v[172:175], v[198:201], v[96:99]
	v_mfma_f32_16x16x32_bf16 v[96:99], v[176:179], v[202:205], v[96:99]
	v_mfma_f32_16x16x32_bf16 v[100:103], v[148:151], v[202:205], v[100:103]
	v_mfma_f32_16x16x32_bf16 v[100:103], v[144:147], v[198:201], v[100:103]
	v_mfma_f32_16x16x32_bf16 v[84:87], v[144:147], v[206:209], v[84:87]
	v_mfma_f32_16x16x32_bf16 v[84:87], v[148:151], v[210:213], v[84:87]
	v_mfma_f32_16x16x32_bf16 v[80:83], v[176:179], v[210:213], v[80:83]
	v_mfma_f32_16x16x32_bf16 v[80:83], v[172:175], v[206:209], v[80:83]
	v_mfma_f32_16x16x32_bf16 v[64:67], v[172:175], v[214:217], v[64:67]
	v_mfma_f32_16x16x32_bf16 v[64:67], v[176:179], v[218:221], v[64:67]
	v_mfma_f32_16x16x32_bf16 v[68:71], v[148:151], v[218:221], v[68:71]
	v_mfma_f32_16x16x32_bf16 v[68:71], v[144:147], v[214:217], v[68:71]
	s_barrier
	s_setprio 0
	s_add_i32 s54, s82, s65
	v_lshl_add_u64 v[222:223], v[222:223], 0, s[28:29]
	s_mov_b32 m0, s54
	ds_read_b128 v[180:183], v191 offset:49152
	v_xor_b32_e32 v253, 64, v191
	ds_read_b128 v[194:197], v253 offset:49152
	ds_read_b128 v[198:201], v191 offset:51200
	ds_read_b128 v[202:205], v253 offset:51200
	ds_read_b128 v[206:209], v191 offset:53248
	ds_read_b128 v[210:213], v253 offset:53248
	ds_read_b128 v[214:217], v191 offset:55296
	ds_read_b128 v[218:221], v253 offset:55296
	global_load_lds_dwordx4 v[222:223], off
	s_add_i32 m0, s54, 0x2000
	s_add_u32 s54, s58, 0xb0080
	v_lshl_add_u64 v[222:223], v[224:225], 0, s[28:29]
	s_addc_u32 s55, s59, 0
	s_add_i32 s58, s83, s65
	global_load_lds_dwordx4 v[222:223], off
	v_lshl_add_u64 v[222:223], s[54:55], 0, v[154:155]
	s_mov_b32 m0, s58
	s_nop 0
	global_load_lds_dwordx4 v[222:223], off
	v_lshl_add_u64 v[222:223], s[54:55], 0, v[162:163]
	s_add_i32 m0, s58, 0x2000
	s_nop 0
	global_load_lds_dwordx4 v[222:223], off
	v_lshl_add_u64 v[222:223], v[226:227], 0, s[28:29]
	s_mov_b32 m0, s3
	s_nop 0
	global_load_lds_dwordx4 v[222:223], off
	v_lshl_add_u64 v[222:223], v[228:229], 0, s[28:29]
	s_mov_b32 m0, s71
	s_nop 0
	global_load_lds_dwordx4 v[222:223], off
	s_waitcnt vmcnt(8)
	s_waitcnt lgkmcnt(0)
	s_setprio 1
	s_barrier
	v_mfma_f32_16x16x32_bf16 v[60:63], v[128:131], v[180:183], v[60:63]
	v_mfma_f32_16x16x32_bf16 v[60:63], v[132:135], v[194:197], v[60:63]
	v_mfma_f32_16x16x32_bf16 v[56:59], v[140:143], v[194:197], v[56:59]
	v_mfma_f32_16x16x32_bf16 v[56:59], v[136:139], v[180:183], v[56:59]
	v_mfma_f32_16x16x32_bf16 v[40:43], v[136:139], v[198:201], v[40:43]
	v_mfma_f32_16x16x32_bf16 v[40:43], v[140:143], v[202:205], v[40:43]
	v_mfma_f32_16x16x32_bf16 v[44:47], v[132:135], v[202:205], v[44:47]
	v_mfma_f32_16x16x32_bf16 v[44:47], v[128:131], v[198:201], v[44:47]
	v_mfma_f32_16x16x32_bf16 v[28:31], v[128:131], v[206:209], v[28:31]
	v_mfma_f32_16x16x32_bf16 v[28:31], v[132:135], v[210:213], v[28:31]
	v_mfma_f32_16x16x32_bf16 v[24:27], v[140:143], v[210:213], v[24:27]
	v_mfma_f32_16x16x32_bf16 v[24:27], v[136:139], v[206:209], v[24:27]
	v_mfma_f32_16x16x32_bf16 v[8:11], v[136:139], v[214:217], v[8:11]
	v_mfma_f32_16x16x32_bf16 v[8:11], v[140:143], v[218:221], v[8:11]
	v_mfma_f32_16x16x32_bf16 v[12:15], v[132:135], v[218:221], v[12:15]
	v_mfma_f32_16x16x32_bf16 v[12:15], v[128:131], v[214:217], v[12:15]
	s_setprio 0
	s_setprio 1
	v_mfma_f32_16x16x32_bf16 v[52:55], v[144:147], v[180:183], v[52:55]
	v_mfma_f32_16x16x32_bf16 v[52:55], v[148:151], v[194:197], v[52:55]
	v_mfma_f32_16x16x32_bf16 v[48:51], v[176:179], v[194:197], v[48:51]
	v_mfma_f32_16x16x32_bf16 v[48:51], v[172:175], v[180:183], v[48:51]
	v_mfma_f32_16x16x32_bf16 v[32:35], v[172:175], v[198:201], v[32:35]
	v_mfma_f32_16x16x32_bf16 v[32:35], v[176:179], v[202:205], v[32:35]
	v_mfma_f32_16x16x32_bf16 v[36:39], v[148:151], v[202:205], v[36:39]
	v_mfma_f32_16x16x32_bf16 v[36:39], v[144:147], v[198:201], v[36:39]
	v_mfma_f32_16x16x32_bf16 v[20:23], v[144:147], v[206:209], v[20:23]
	v_mfma_f32_16x16x32_bf16 v[20:23], v[148:151], v[210:213], v[20:23]
	v_mfma_f32_16x16x32_bf16 v[16:19], v[176:179], v[210:213], v[16:19]
	v_mfma_f32_16x16x32_bf16 v[16:19], v[172:175], v[206:209], v[16:19]
	v_mfma_f32_16x16x32_bf16 v[0:3], v[172:175], v[214:217], v[0:3]
	v_mfma_f32_16x16x32_bf16 v[0:3], v[176:179], v[218:221], v[0:3]
	v_mfma_f32_16x16x32_bf16 v[4:7], v[148:151], v[218:221], v[4:7]
	v_mfma_f32_16x16x32_bf16 v[4:7], v[144:147], v[214:217], v[4:7]
	s_barrier
	s_setprio 0
	s_add_i32 s81, s81, 2
	s_add_u32 s79, s79, 0x100
	s_addc_u32 s80, s80, 0
	s_cmp_gt_u32 s81, 41
	s_mov_b64 s[54:55], s[56:57]

.LBB0_873:
	s_ashr_i32 s49, s48, 31
	s_lshl_b64 s[50:51], s[48:49], 19
	s_add_u32 s50, s35, s50
	s_addc_u32 s51, s60, s51
	s_and_b64 s[52:53], s[10:11], exec
	s_cselect_b32 s49, s51, s59
	s_cselect_b32 s80, s50, s58
	s_ashr_i32 s47, s46, 31
	s_lshl_b64 s[52:53], s[46:47], 19
	s_add_u32 s52, s61, s52
	s_addc_u32 s53, s62, s53
	s_and_b64 s[82:83], s[10:11], exec
	s_cselect_b32 s81, s53, s57
	s_cselect_b32 s82, s52, s56
	s_lshl_b32 s47, s54, 8
	v_add_u32_e32 v0, s47, v151
	s_add_u32 s83, s56, 0x100
	v_ashrrev_i32_e32 v1, 31, v0
	s_addc_u32 s84, s57, 0
	v_lshl_add_u64 v[144:145], v[0:1], 4, s[20:21]
	s_add_u32 s54, s58, 0x40080
	s_addc_u32 s55, s59, 0
	s_mov_b32 s85, -2
	s_mov_b64 s[56:57], 0
	s_cmp_eq_u32 s68, 1
	s_cbranch_scc1 .Lfa_8
	v_add_u32_e32 v146, s73, v149
	ds_read_b128 v[162:165], v146
	v_xor_b32_e32 v253, 64, v146
	ds_read_b128 v[166:169], v253
	ds_read_b128 v[170:173], v146 offset:2048
	ds_read_b128 v[174:177], v253 offset:2048
	v_add_u32_e32 v146, s74, v149
	ds_read_b128 v[178:181], v146
	v_xor_b32_e32 v253, 64, v146
	ds_read_b128 v[186:189], v253
	ds_read_b128 v[190:193], v146 offset:2048
	ds_read_b128 v[194:197], v253 offset:2048
	s_add_u32 s58, s54, 0xfffc0080
	s_addc_u32 s59, s55, -1
	s_and_b64 s[56:57], s[56:57], exec
	s_cselect_b32 s59, s49, s59
	s_cselect_b32 s58, s80, s58
	s_cselect_b32 s57, s81, s84
	s_cselect_b32 s56, s82, s83
	v_lshl_add_u64 v[182:183], s[54:55], 0, v[138:139]
	s_add_i32 m0, s64, 0xc000
	ds_read_b128 v[198:201], v154
	v_xor_b32_e32 v253, 64, v154
	ds_read_b128 v[202:205], v253
	ds_read_b128 v[206:209], v154 offset:2048
	ds_read_b128 v[210:213], v253 offset:2048
	ds_read_b128 v[214:217], v154 offset:4096
	ds_read_b128 v[218:221], v253 offset:4096
	ds_read_b128 v[222:225], v154 offset:6144
	ds_read_b128 v[226:229], v253 offset:6144
	global_load_lds_dwordx4 v[182:183], off
	v_lshl_add_u64 v[182:183], s[54:55], 0, v[136:137]
	s_add_i32 m0, s64, 0xe000
	s_nop 0
	global_load_lds_dwordx4 v[182:183], off
	s_waitcnt vmcnt(24)
	s_waitcnt lgkmcnt(0)
	s_setprio 1
	s_barrier
	v_mfma_f32_16x16x32_bf16 v[124:127], v[162:165], v[198:201], 0
	v_mfma_f32_16x16x32_bf16 v[124:127], v[166:169], v[202:205], v[124:127]
	v_mfma_f32_16x16x32_bf16 v[120:123], v[170:173], v[198:201], 0
	v_mfma_f32_16x16x32_bf16 v[120:123], v[174:177], v[202:205], v[120:123]
	v_mfma_f32_16x16x32_bf16 v[112:115], v[162:165], v[206:209], 0
	v_mfma_f32_16x16x32_bf16 v[112:115], v[166:169], v[210:213], v[112:115]
	v_mfma_f32_16x16x32_bf16 v[104:107], v[170:173], v[206:209], 0
	v_mfma_f32_16x16x32_bf16 v[104:107], v[174:177], v[210:213], v[104:107]
	v_mfma_f32_16x16x32_bf16 v[96:99], v[162:165], v[214:217], 0
	v_mfma_f32_16x16x32_bf16 v[96:99], v[166:169], v[218:221], v[96:99]
	v_mfma_f32_16x16x32_bf16 v[88:91], v[170:173], v[214:217], 0
	v_mfma_f32_16x16x32_bf16 v[88:91], v[174:177], v[218:221], v[88:91]
	v_mfma_f32_16x16x32_bf16 v[80:83], v[162:165], v[222:225], 0
	v_mfma_f32_16x16x32_bf16 v[80:83], v[166:169], v[226:229], v[80:83]
	v_mfma_f32_16x16x32_bf16 v[72:75], v[170:173], v[222:225], 0
	v_mfma_f32_16x16x32_bf16 v[72:75], v[174:177], v[226:229], v[72:75]
	s_setprio 0
	s_setprio 1
	v_mfma_f32_16x16x32_bf16 v[116:119], v[178:181], v[198:201], 0
	v_mfma_f32_16x16x32_bf16 v[116:119], v[186:189], v[202:205], v[116:119]
	v_mfma_f32_16x16x32_bf16 v[108:111], v[190:193], v[198:201], 0
	v_mfma_f32_16x16x32_bf16 v[108:111], v[194:197], v[202:205], v[108:111]
	v_mfma_f32_16x16x32_bf16 v[100:103], v[178:181], v[206:209], 0
	v_mfma_f32_16x16x32_bf16 v[100:103], v[186:189], v[210:213], v[100:103]
	v_mfma_f32_16x16x32_bf16 v[92:95], v[190:193], v[206:209], 0
	v_mfma_f32_16x16x32_bf16 v[92:95], v[194:197], v[210:213], v[92:95]
	v_mfma_f32_16x16x32_bf16 v[84:87], v[178:181], v[214:217], 0
	v_mfma_f32_16x16x32_bf16 v[84:87], v[186:189], v[218:221], v[84:87]
	v_mfma_f32_16x16x32_bf16 v[76:79], v[190:193], v[214:217], 0
	v_mfma_f32_16x16x32_bf16 v[76:79], v[194:197], v[218:221], v[76:79]
	v_mfma_f32_16x16x32_bf16 v[68:71], v[178:181], v[222:225], 0
	v_mfma_f32_16x16x32_bf16 v[68:71], v[186:189], v[226:229], v[68:71]
	v_mfma_f32_16x16x32_bf16 v[64:67], v[190:193], v[222:225], 0
	v_mfma_f32_16x16x32_bf16 v[64:67], v[194:197], v[226:229], v[64:67]
	s_barrier
	s_setprio 0
	s_add_i32 s86, s73, s63
	v_lshl_add_u64 v[182:183], s[56:57], 0, v[130:131]
	s_mov_b32 m0, s86
	ds_read_b128 v[198:201], v154 offset:16384
	v_xor_b32_e32 v253, 64, v154
	ds_read_b128 v[202:205], v253 offset:16384
	ds_read_b128 v[206:209], v154 offset:18432
	ds_read_b128 v[210:213], v253 offset:18432
	ds_read_b128 v[214:217], v154 offset:20480
	ds_read_b128 v[218:221], v253 offset:20480
	ds_read_b128 v[222:225], v154 offset:22528
	ds_read_b128 v[226:229], v253 offset:22528
	global_load_lds_dwordx4 v[182:183], off
	s_add_i32 m0, s86, 0x2000
	s_add_u32 s86, s56, 0x40000
	v_lshl_add_u64 v[230:231], s[56:57], 0, v[134:135]
	s_addc_u32 s87, s57, 0
	s_add_i32 s88, s74, s63
	global_load_lds_dwordx4 v[230:231], off
	v_lshl_add_u64 v[232:233], s[86:87], 0, v[130:131]
	s_mov_b32 m0, s88
	v_lshl_add_u64 v[234:235], s[58:59], 0, v[132:133]
	global_load_lds_dwordx4 v[232:233], off
	v_lshl_add_u64 v[232:233], s[86:87], 0, v[134:135]
	s_add_i32 m0, s88, 0x2000
	s_nop 0
	global_load_lds_dwordx4 v[232:233], off
	v_lshl_add_u64 v[232:233], s[58:59], 0, v[128:129]
	s_mov_b32 m0, s64
	s_nop 0
	global_load_lds_dwordx4 v[232:233], off
	s_mov_b32 m0, s65
	s_nop 0
	global_load_lds_dwordx4 v[234:235], off
	s_waitcnt vmcnt(24)
	s_waitcnt lgkmcnt(0)
	s_setprio 1
	s_barrier
	v_mfma_f32_16x16x32_bf16 v[60:63], v[162:165], v[198:201], 0
	v_mfma_f32_16x16x32_bf16 v[60:63], v[166:169], v[202:205], v[60:63]
	v_mfma_f32_16x16x32_bf16 v[56:59], v[170:173], v[198:201], 0
	v_mfma_f32_16x16x32_bf16 v[56:59], v[174:177], v[202:205], v[56:59]
	v_mfma_f32_16x16x32_bf16 v[48:51], v[162:165], v[206:209], 0
	v_mfma_f32_16x16x32_bf16 v[48:51], v[166:169], v[210:213], v[48:51]
	v_mfma_f32_16x16x32_bf16 v[40:43], v[170:173], v[206:209], 0
	v_mfma_f32_16x16x32_bf16 v[40:43], v[174:177], v[210:213], v[40:43]
	v_mfma_f32_16x16x32_bf16 v[32:35], v[162:165], v[214:217], 0
	v_mfma_f32_16x16x32_bf16 v[32:35], v[166:169], v[218:221], v[32:35]
	v_mfma_f32_16x16x32_bf16 v[24:27], v[170:173], v[214:217], 0
	v_mfma_f32_16x16x32_bf16 v[24:27], v[174:177], v[218:221], v[24:27]
	v_mfma_f32_16x16x32_bf16 v[16:19], v[162:165], v[222:225], 0
	v_mfma_f32_16x16x32_bf16 v[16:19], v[166:169], v[226:229], v[16:19]
	v_mfma_f32_16x16x32_bf16 v[8:11], v[170:173], v[222:225], 0
	v_mfma_f32_16x16x32_bf16 v[8:11], v[174:177], v[226:229], v[8:11]
	s_setprio 0
	s_setprio 1
	v_mfma_f32_16x16x32_bf16 v[52:55], v[178:181], v[198:201], 0
	v_mfma_f32_16x16x32_bf16 v[52:55], v[186:189], v[202:205], v[52:55]
	v_mfma_f32_16x16x32_bf16 v[44:47], v[190:193], v[198:201], 0
	v_mfma_f32_16x16x32_bf16 v[44:47], v[194:197], v[202:205], v[44:47]
	v_mfma_f32_16x16x32_bf16 v[36:39], v[178:181], v[206:209], 0
	v_mfma_f32_16x16x32_bf16 v[36:39], v[186:189], v[210:213], v[36:39]
	v_mfma_f32_16x16x32_bf16 v[28:31], v[190:193], v[206:209], 0
	v_mfma_f32_16x16x32_bf16 v[28:31], v[194:197], v[210:213], v[28:31]
	v_mfma_f32_16x16x32_bf16 v[20:23], v[178:181], v[214:217], 0
	v_mfma_f32_16x16x32_bf16 v[20:23], v[186:189], v[218:221], v[20:23]
	v_mfma_f32_16x16x32_bf16 v[12:15], v[190:193], v[214:217], 0
	v_mfma_f32_16x16x32_bf16 v[12:15], v[194:197], v[218:221], v[12:15]
	v_mfma_f32_16x16x32_bf16 v[4:7], v[178:181], v[222:225], 0
	v_mfma_f32_16x16x32_bf16 v[4:7], v[186:189], v[226:229], v[4:7]
	v_mfma_f32_16x16x32_bf16 v[0:3], v[190:193], v[222:225], 0
	v_mfma_f32_16x16x32_bf16 v[0:3], v[194:197], v[226:229], v[0:3]
	s_barrier
	s_setprio 0
	s_add_i32 s86, 0, 0x18000
	v_add_u32_e32 v146, s86, v149
	s_add_i32 s87, 0, 0x1c000
	ds_read_b128 v[162:165], v146
	v_xor_b32_e32 v253, 64, v146
	ds_read_b128 v[166:169], v253
	ds_read_b128 v[170:173], v146 offset:2048
	ds_read_b128 v[174:177], v253 offset:2048
	v_add_u32_e32 v146, s87, v149
	ds_read_b128 v[178:181], v146
	v_xor_b32_e32 v253, 64, v146
	ds_read_b128 v[186:189], v253
	ds_read_b128 v[190:193], v146 offset:2048
	ds_read_b128 v[194:197], v253 offset:2048
	s_add_u32 s58, s58, 0x40000
	s_addc_u32 s59, s59, 0
	s_mov_b32 m0, s66
	v_lshl_add_u64 v[236:237], s[58:59], 0, v[128:129]
	ds_read_b128 v[198:201], v154 offset:32768
	v_xor_b32_e32 v253, 64, v154
	ds_read_b128 v[202:205], v253 offset:32768
	ds_read_b128 v[206:209], v154 offset:34816
	ds_read_b128 v[210:213], v253 offset:34816
	ds_read_b128 v[214:217], v154 offset:36864
	ds_read_b128 v[218:221], v253 offset:36864
	ds_read_b128 v[222:225], v154 offset:38912
	ds_read_b128 v[226:229], v253 offset:38912
	global_load_lds_dwordx4 v[236:237], off
	v_lshl_add_u64 v[236:237], s[58:59], 0, v[132:133]
	s_mov_b32 m0, s67
	s_nop 0
	global_load_lds_dwordx4 v[236:237], off
	s_waitcnt vmcnt(8)
	s_waitcnt lgkmcnt(0)
	s_setprio 1
	s_barrier
	v_mfma_f32_16x16x32_bf16 v[124:127], v[162:165], v[198:201], v[124:127]
	v_mfma_f32_16x16x32_bf16 v[124:127], v[166:169], v[202:205], v[124:127]
	v_mfma_f32_16x16x32_bf16 v[120:123], v[174:177], v[202:205], v[120:123]
	v_mfma_f32_16x16x32_bf16 v[120:123], v[170:173], v[198:201], v[120:123]
	v_mfma_f32_16x16x32_bf16 v[104:107], v[170:173], v[206:209], v[104:107]
	v_mfma_f32_16x16x32_bf16 v[104:107], v[174:177], v[210:213], v[104:107]
	v_mfma_f32_16x16x32_bf16 v[112:115], v[166:169], v[210:213], v[112:115]
	v_mfma_f32_16x16x32_bf16 v[112:115], v[162:165], v[206:209], v[112:115]
	v_mfma_f32_16x16x32_bf16 v[96:99], v[162:165], v[214:217], v[96:99]
	v_mfma_f32_16x16x32_bf16 v[96:99], v[166:169], v[218:221], v[96:99]
	v_mfma_f32_16x16x32_bf16 v[88:91], v[174:177], v[218:221], v[88:91]
	v_mfma_f32_16x16x32_bf16 v[88:91], v[170:173], v[214:217], v[88:91]
	v_mfma_f32_16x16x32_bf16 v[72:75], v[170:173], v[222:225], v[72:75]
	v_mfma_f32_16x16x32_bf16 v[72:75], v[174:177], v[226:229], v[72:75]
	v_mfma_f32_16x16x32_bf16 v[80:83], v[166:169], v[226:229], v[80:83]
	v_mfma_f32_16x16x32_bf16 v[80:83], v[162:165], v[222:225], v[80:83]
	s_setprio 0
	s_setprio 1
	v_mfma_f32_16x16x32_bf16 v[116:119], v[178:181], v[198:201], v[116:119]
	v_mfma_f32_16x16x32_bf16 v[116:119], v[186:189], v[202:205], v[116:119]
	v_mfma_f32_16x16x32_bf16 v[108:111], v[194:197], v[202:205], v[108:111]
	v_mfma_f32_16x16x32_bf16 v[108:111], v[190:193], v[198:201], v[108:111]
	v_mfma_f32_16x16x32_bf16 v[92:95], v[190:193], v[206:209], v[92:95]
	v_mfma_f32_16x16x32_bf16 v[92:95], v[194:197], v[210:213], v[92:95]
	v_mfma_f32_16x16x32_bf16 v[100:103], v[186:189], v[210:213], v[100:103]
	v_mfma_f32_16x16x32_bf16 v[100:103], v[178:181], v[206:209], v[100:103]
	v_mfma_f32_16x16x32_bf16 v[84:87], v[178:181], v[214:217], v[84:87]
	v_mfma_f32_16x16x32_bf16 v[84:87], v[186:189], v[218:221], v[84:87]
	v_mfma_f32_16x16x32_bf16 v[76:79], v[194:197], v[218:221], v[76:79]
	v_mfma_f32_16x16x32_bf16 v[76:79], v[190:193], v[214:217], v[76:79]
	v_mfma_f32_16x16x32_bf16 v[64:67], v[190:193], v[222:225], v[64:67]
	v_mfma_f32_16x16x32_bf16 v[64:67], v[194:197], v[226:229], v[64:67]
	v_mfma_f32_16x16x32_bf16 v[68:71], v[186:189], v[226:229], v[68:71]
	v_mfma_f32_16x16x32_bf16 v[68:71], v[178:181], v[222:225], v[68:71]
	s_barrier
	s_setprio 0
	s_add_i32 s58, s86, s63
	v_lshl_add_u64 v[182:183], v[182:183], 0, s[22:23]
	s_mov_b32 m0, s58
	ds_read_b128 v[198:201], v154 offset:49152
	v_xor_b32_e32 v253, 64, v154
	ds_read_b128 v[202:205], v253 offset:49152
	ds_read_b128 v[206:209], v154 offset:51200
	ds_read_b128 v[210:213], v253 offset:51200
	ds_read_b128 v[214:217], v154 offset:53248
	ds_read_b128 v[218:221], v253 offset:53248
	ds_read_b128 v[222:225], v154 offset:55296
	ds_read_b128 v[226:229], v253 offset:55296
	global_load_lds_dwordx4 v[182:183], off
	s_add_i32 m0, s58, 0x2000
	s_add_u32 s56, s56, 0x40080
	v_lshl_add_u64 v[182:183], v[230:231], 0, s[22:23]
	s_addc_u32 s57, s57, 0
	s_add_i32 s58, s87, s63
	global_load_lds_dwordx4 v[182:183], off
	v_lshl_add_u64 v[182:183], s[56:57], 0, v[130:131]
	s_mov_b32 m0, s58
	s_nop 0
	global_load_lds_dwordx4 v[182:183], off
	v_lshl_add_u64 v[182:183], s[56:57], 0, v[134:135]
	s_add_i32 m0, s58, 0x2000
	s_nop 0
	global_load_lds_dwordx4 v[182:183], off
	v_lshl_add_u64 v[182:183], v[232:233], 0, s[22:23]
	s_mov_b32 m0, s69
	s_nop 0
	global_load_lds_dwordx4 v[182:183], off
	v_lshl_add_u64 v[182:183], v[234:235], 0, s[22:23]
	s_mov_b32 m0, s70
	s_nop 0
	global_load_lds_dwordx4 v[182:183], off
	s_waitcnt vmcnt(8)
	s_waitcnt lgkmcnt(0)
	s_setprio 1
	s_barrier
	v_mfma_f32_16x16x32_bf16 v[60:63], v[162:165], v[198:201], v[60:63]
	v_mfma_f32_16x16x32_bf16 v[60:63], v[166:169], v[202:205], v[60:63]
	v_mfma_f32_16x16x32_bf16 v[56:59], v[174:177], v[202:205], v[56:59]
	v_mfma_f32_16x16x32_bf16 v[56:59], v[170:173], v[198:201], v[56:59]
	v_mfma_f32_16x16x32_bf16 v[40:43], v[170:173], v[206:209], v[40:43]
	v_mfma_f32_16x16x32_bf16 v[40:43], v[174:177], v[210:213], v[40:43]
	v_mfma_f32_16x16x32_bf16 v[48:51], v[166:169], v[210:213], v[48:51]
	v_mfma_f32_16x16x32_bf16 v[48:51], v[162:165], v[206:209], v[48:51]
	v_mfma_f32_16x16x32_bf16 v[32:35], v[162:165], v[214:217], v[32:35]
	v_mfma_f32_16x16x32_bf16 v[32:35], v[166:169], v[218:221], v[32:35]
	v_mfma_f32_16x16x32_bf16 v[24:27], v[174:177], v[218:221], v[24:27]
	v_mfma_f32_16x16x32_bf16 v[24:27], v[170:173], v[214:217], v[24:27]
	v_mfma_f32_16x16x32_bf16 v[8:11], v[170:173], v[222:225], v[8:11]
	v_mfma_f32_16x16x32_bf16 v[8:11], v[174:177], v[226:229], v[8:11]
	v_mfma_f32_16x16x32_bf16 v[16:19], v[166:169], v[226:229], v[16:19]
	v_mfma_f32_16x16x32_bf16 v[16:19], v[162:165], v[222:225], v[16:19]
	s_setprio 0
	s_setprio 1
	v_mfma_f32_16x16x32_bf16 v[52:55], v[178:181], v[198:201], v[52:55]
	v_mfma_f32_16x16x32_bf16 v[52:55], v[186:189], v[202:205], v[52:55]
	v_mfma_f32_16x16x32_bf16 v[44:47], v[194:197], v[202:205], v[44:47]
	v_mfma_f32_16x16x32_bf16 v[44:47], v[190:193], v[198:201], v[44:47]
	v_mfma_f32_16x16x32_bf16 v[28:31], v[190:193], v[206:209], v[28:31]
	v_mfma_f32_16x16x32_bf16 v[28:31], v[194:197], v[210:213], v[28:31]
	v_mfma_f32_16x16x32_bf16 v[36:39], v[186:189], v[210:213], v[36:39]
	v_mfma_f32_16x16x32_bf16 v[36:39], v[178:181], v[206:209], v[36:39]
	v_mfma_f32_16x16x32_bf16 v[20:23], v[178:181], v[214:217], v[20:23]
	v_mfma_f32_16x16x32_bf16 v[20:23], v[186:189], v[218:221], v[20:23]
	v_mfma_f32_16x16x32_bf16 v[12:15], v[194:197], v[218:221], v[12:15]
	v_mfma_f32_16x16x32_bf16 v[12:15], v[190:193], v[214:217], v[12:15]
	v_mfma_f32_16x16x32_bf16 v[0:3], v[190:193], v[222:225], v[0:3]
	v_mfma_f32_16x16x32_bf16 v[0:3], v[194:197], v[226:229], v[0:3]
	v_mfma_f32_16x16x32_bf16 v[4:7], v[186:189], v[226:229], v[4:7]
	v_mfma_f32_16x16x32_bf16 v[4:7], v[178:181], v[222:225], v[4:7]
	s_barrier
	s_setprio 0
	s_add_i32 s85, s85, 2
	s_add_u32 s83, s83, 0x100
	s_addc_u32 s84, s84, 0
	s_add_u32 s54, s54, 0x100
	s_addc_u32 s55, s55, 0
	s_branch .LBB0_875
.Lfa_8:
	v_add_u32_e32 v146, s73, v149
	ds_read_b128 v[162:165], v146
	v_xor_b32_e32 v253, 64, v146
	ds_read_b128 v[166:169], v253
	ds_read_b128 v[170:173], v146 offset:2048
	ds_read_b128 v[174:177], v253 offset:2048
	v_add_u32_e32 v146, s74, v149
	ds_read_b128 v[178:181], v146
	v_xor_b32_e32 v253, 64, v146
	ds_read_b128 v[186:189], v253
	ds_read_b128 v[190:193], v146 offset:2048
	ds_read_b128 v[194:197], v253 offset:2048
	s_add_u32 s58, s54, 0xfffc0080
	s_addc_u32 s59, s55, -1
	s_and_b64 s[56:57], s[56:57], exec
	s_cselect_b32 s59, s49, s59
	s_cselect_b32 s58, s80, s58
	s_cselect_b32 s57, s81, s84
	s_cselect_b32 s56, s82, s83
	v_lshl_add_u64 v[182:183], s[54:55], 0, v[138:139]
	s_add_i32 m0, s64, 0xc000
	ds_read_b128 v[198:201], v154
	v_xor_b32_e32 v253, 64, v154
	ds_read_b128 v[202:205], v253
	ds_read_b128 v[206:209], v154 offset:2048
	ds_read_b128 v[210:213], v253 offset:2048
	ds_read_b128 v[214:217], v154 offset:4096
	ds_read_b128 v[218:221], v253 offset:4096
	ds_read_b128 v[222:225], v154 offset:6144
	ds_read_b128 v[226:229], v253 offset:6144
	global_load_lds_dwordx4 v[182:183], off
	v_lshl_add_u64 v[182:183], s[54:55], 0, v[136:137]
	s_add_i32 m0, s64, 0xe000
	s_nop 0
	global_load_lds_dwordx4 v[182:183], off
	s_waitcnt vmcnt(8)
	s_waitcnt lgkmcnt(0)
	s_setprio 1
	s_barrier
	v_mfma_f32_16x16x32_bf16 v[124:127], v[162:165], v[198:201], 0
	v_mfma_f32_16x16x32_bf16 v[124:127], v[166:169], v[202:205], v[124:127]
	v_mfma_f32_16x16x32_bf16 v[120:123], v[170:173], v[198:201], 0
	v_mfma_f32_16x16x32_bf16 v[120:123], v[174:177], v[202:205], v[120:123]
	v_mfma_f32_16x16x32_bf16 v[112:115], v[162:165], v[206:209], 0
	v_mfma_f32_16x16x32_bf16 v[112:115], v[166:169], v[210:213], v[112:115]
	v_mfma_f32_16x16x32_bf16 v[104:107], v[170:173], v[206:209], 0
	v_mfma_f32_16x16x32_bf16 v[104:107], v[174:177], v[210:213], v[104:107]
	v_mfma_f32_16x16x32_bf16 v[96:99], v[162:165], v[214:217], 0
	v_mfma_f32_16x16x32_bf16 v[96:99], v[166:169], v[218:221], v[96:99]
	v_mfma_f32_16x16x32_bf16 v[88:91], v[170:173], v[214:217], 0
	v_mfma_f32_16x16x32_bf16 v[88:91], v[174:177], v[218:221], v[88:91]
	v_mfma_f32_16x16x32_bf16 v[80:83], v[162:165], v[222:225], 0
	v_mfma_f32_16x16x32_bf16 v[80:83], v[166:169], v[226:229], v[80:83]
	v_mfma_f32_16x16x32_bf16 v[72:75], v[170:173], v[222:225], 0
	v_mfma_f32_16x16x32_bf16 v[72:75], v[174:177], v[226:229], v[72:75]
	s_setprio 0
	s_setprio 1
	v_mfma_f32_16x16x32_bf16 v[116:119], v[178:181], v[198:201], 0
	v_mfma_f32_16x16x32_bf16 v[116:119], v[186:189], v[202:205], v[116:119]
	v_mfma_f32_16x16x32_bf16 v[108:111], v[190:193], v[198:201], 0
	v_mfma_f32_16x16x32_bf16 v[108:111], v[194:197], v[202:205], v[108:111]
	v_mfma_f32_16x16x32_bf16 v[100:103], v[178:181], v[206:209], 0
	v_mfma_f32_16x16x32_bf16 v[100:103], v[186:189], v[210:213], v[100:103]
	v_mfma_f32_16x16x32_bf16 v[92:95], v[190:193], v[206:209], 0
	v_mfma_f32_16x16x32_bf16 v[92:95], v[194:197], v[210:213], v[92:95]
	v_mfma_f32_16x16x32_bf16 v[84:87], v[178:181], v[214:217], 0
	v_mfma_f32_16x16x32_bf16 v[84:87], v[186:189], v[218:221], v[84:87]
	v_mfma_f32_16x16x32_bf16 v[76:79], v[190:193], v[214:217], 0
	v_mfma_f32_16x16x32_bf16 v[76:79], v[194:197], v[218:221], v[76:79]
	v_mfma_f32_16x16x32_bf16 v[68:71], v[178:181], v[222:225], 0
	v_mfma_f32_16x16x32_bf16 v[68:71], v[186:189], v[226:229], v[68:71]
	v_mfma_f32_16x16x32_bf16 v[64:67], v[190:193], v[222:225], 0
	v_mfma_f32_16x16x32_bf16 v[64:67], v[194:197], v[226:229], v[64:67]
	s_barrier
	s_setprio 0
	s_add_i32 s86, s73, s63
	v_lshl_add_u64 v[182:183], s[56:57], 0, v[130:131]
	s_mov_b32 m0, s86
	ds_read_b128 v[198:201], v154 offset:16384
	v_xor_b32_e32 v253, 64, v154
	ds_read_b128 v[202:205], v253 offset:16384
	ds_read_b128 v[206:209], v154 offset:18432
	ds_read_b128 v[210:213], v253 offset:18432
	ds_read_b128 v[214:217], v154 offset:20480
	ds_read_b128 v[218:221], v253 offset:20480
	ds_read_b128 v[222:225], v154 offset:22528
	ds_read_b128 v[226:229], v253 offset:22528
	global_load_lds_dwordx4 v[182:183], off
	s_add_i32 m0, s86, 0x2000
	s_add_u32 s86, s56, 0x40000
	v_lshl_add_u64 v[230:231], s[56:57], 0, v[134:135]
	s_addc_u32 s87, s57, 0
	s_add_i32 s88, s74, s63
	global_load_lds_dwordx4 v[230:231], off
	v_lshl_add_u64 v[232:233], s[86:87], 0, v[130:131]
	s_mov_b32 m0, s88
	v_lshl_add_u64 v[234:235], s[58:59], 0, v[132:133]
	global_load_lds_dwordx4 v[232:233], off
	v_lshl_add_u64 v[232:233], s[86:87], 0, v[134:135]
	s_add_i32 m0, s88, 0x2000
	s_nop 0
	global_load_lds_dwordx4 v[232:233], off
	v_lshl_add_u64 v[232:233], s[58:59], 0, v[128:129]
	s_mov_b32 m0, s64
	s_nop 0
	global_load_lds_dwordx4 v[232:233], off
	s_mov_b32 m0, s65
	s_nop 0
	global_load_lds_dwordx4 v[234:235], off
	s_waitcnt vmcnt(8)
	s_waitcnt lgkmcnt(0)
	s_setprio 1
	s_barrier
	v_mfma_f32_16x16x32_bf16 v[60:63], v[162:165], v[198:201], 0
	v_mfma_f32_16x16x32_bf16 v[60:63], v[166:169], v[202:205], v[60:63]
	v_mfma_f32_16x16x32_bf16 v[56:59], v[170:173], v[198:201], 0
	v_mfma_f32_16x16x32_bf16 v[56:59], v[174:177], v[202:205], v[56:59]
	v_mfma_f32_16x16x32_bf16 v[48:51], v[162:165], v[206:209], 0
	v_mfma_f32_16x16x32_bf16 v[48:51], v[166:169], v[210:213], v[48:51]
	v_mfma_f32_16x16x32_bf16 v[40:43], v[170:173], v[206:209], 0
	v_mfma_f32_16x16x32_bf16 v[40:43], v[174:177], v[210:213], v[40:43]
	v_mfma_f32_16x16x32_bf16 v[32:35], v[162:165], v[214:217], 0
	v_mfma_f32_16x16x32_bf16 v[32:35], v[166:169], v[218:221], v[32:35]
	v_mfma_f32_16x16x32_bf16 v[24:27], v[170:173], v[214:217], 0
	v_mfma_f32_16x16x32_bf16 v[24:27], v[174:177], v[218:221], v[24:27]
	v_mfma_f32_16x16x32_bf16 v[16:19], v[162:165], v[222:225], 0
	v_mfma_f32_16x16x32_bf16 v[16:19], v[166:169], v[226:229], v[16:19]
	v_mfma_f32_16x16x32_bf16 v[8:11], v[170:173], v[222:225], 0
	v_mfma_f32_16x16x32_bf16 v[8:11], v[174:177], v[226:229], v[8:11]
	s_setprio 0
	s_setprio 1
	v_mfma_f32_16x16x32_bf16 v[52:55], v[178:181], v[198:201], 0
	v_mfma_f32_16x16x32_bf16 v[52:55], v[186:189], v[202:205], v[52:55]
	v_mfma_f32_16x16x32_bf16 v[44:47], v[190:193], v[198:201], 0
	v_mfma_f32_16x16x32_bf16 v[44:47], v[194:197], v[202:205], v[44:47]
	v_mfma_f32_16x16x32_bf16 v[36:39], v[178:181], v[206:209], 0
	v_mfma_f32_16x16x32_bf16 v[36:39], v[186:189], v[210:213], v[36:39]
	v_mfma_f32_16x16x32_bf16 v[28:31], v[190:193], v[206:209], 0
	v_mfma_f32_16x16x32_bf16 v[28:31], v[194:197], v[210:213], v[28:31]
	v_mfma_f32_16x16x32_bf16 v[20:23], v[178:181], v[214:217], 0
	v_mfma_f32_16x16x32_bf16 v[20:23], v[186:189], v[218:221], v[20:23]
	v_mfma_f32_16x16x32_bf16 v[12:15], v[190:193], v[214:217], 0
	v_mfma_f32_16x16x32_bf16 v[12:15], v[194:197], v[218:221], v[12:15]
	v_mfma_f32_16x16x32_bf16 v[4:7], v[178:181], v[222:225], 0
	v_mfma_f32_16x16x32_bf16 v[4:7], v[186:189], v[226:229], v[4:7]
	v_mfma_f32_16x16x32_bf16 v[0:3], v[190:193], v[222:225], 0
	v_mfma_f32_16x16x32_bf16 v[0:3], v[194:197], v[226:229], v[0:3]
	s_barrier
	s_setprio 0
	s_add_i32 s86, 0, 0x18000
	v_add_u32_e32 v146, s86, v149
	s_add_i32 s87, 0, 0x1c000
	ds_read_b128 v[162:165], v146
	v_xor_b32_e32 v253, 64, v146
	ds_read_b128 v[166:169], v253
	ds_read_b128 v[170:173], v146 offset:2048
	ds_read_b128 v[174:177], v253 offset:2048
	v_add_u32_e32 v146, s87, v149
	ds_read_b128 v[178:181], v146
	v_xor_b32_e32 v253, 64, v146
	ds_read_b128 v[186:189], v253
	ds_read_b128 v[190:193], v146 offset:2048
	ds_read_b128 v[194:197], v253 offset:2048
	s_add_u32 s58, s58, 0x40000
	s_addc_u32 s59, s59, 0
	s_mov_b32 m0, s66
	v_lshl_add_u64 v[236:237], s[58:59], 0, v[128:129]
	ds_read_b128 v[198:201], v154 offset:32768
	v_xor_b32_e32 v253, 64, v154
	ds_read_b128 v[202:205], v253 offset:32768
	ds_read_b128 v[206:209], v154 offset:34816
	ds_read_b128 v[210:213], v253 offset:34816
	ds_read_b128 v[214:217], v154 offset:36864
	ds_read_b128 v[218:221], v253 offset:36864
	ds_read_b128 v[222:225], v154 offset:38912
	ds_read_b128 v[226:229], v253 offset:38912
	global_load_lds_dwordx4 v[236:237], off
	v_lshl_add_u64 v[236:237], s[58:59], 0, v[132:133]
	s_mov_b32 m0, s67
	s_nop 0
	global_load_lds_dwordx4 v[236:237], off
	s_waitcnt vmcnt(8)
	s_waitcnt lgkmcnt(0)
	s_setprio 1
	s_barrier
	v_mfma_f32_16x16x32_bf16 v[124:127], v[162:165], v[198:201], v[124:127]
	v_mfma_f32_16x16x32_bf16 v[124:127], v[166:169], v[202:205], v[124:127]
	v_mfma_f32_16x16x32_bf16 v[120:123], v[174:177], v[202:205], v[120:123]
	v_mfma_f32_16x16x32_bf16 v[120:123], v[170:173], v[198:201], v[120:123]
	v_mfma_f32_16x16x32_bf16 v[104:107], v[170:173], v[206:209], v[104:107]
	v_mfma_f32_16x16x32_bf16 v[104:107], v[174:177], v[210:213], v[104:107]
	v_mfma_f32_16x16x32_bf16 v[112:115], v[166:169], v[210:213], v[112:115]
	v_mfma_f32_16x16x32_bf16 v[112:115], v[162:165], v[206:209], v[112:115]
	v_mfma_f32_16x16x32_bf16 v[96:99], v[162:165], v[214:217], v[96:99]
	v_mfma_f32_16x16x32_bf16 v[96:99], v[166:169], v[218:221], v[96:99]
	v_mfma_f32_16x16x32_bf16 v[88:91], v[174:177], v[218:221], v[88:91]
	v_mfma_f32_16x16x32_bf16 v[88:91], v[170:173], v[214:217], v[88:91]
	v_mfma_f32_16x16x32_bf16 v[72:75], v[170:173], v[222:225], v[72:75]
	v_mfma_f32_16x16x32_bf16 v[72:75], v[174:177], v[226:229], v[72:75]
	v_mfma_f32_16x16x32_bf16 v[80:83], v[166:169], v[226:229], v[80:83]
	v_mfma_f32_16x16x32_bf16 v[80:83], v[162:165], v[222:225], v[80:83]
	s_setprio 0
	s_setprio 1
	v_mfma_f32_16x16x32_bf16 v[116:119], v[178:181], v[198:201], v[116:119]
	v_mfma_f32_16x16x32_bf16 v[116:119], v[186:189], v[202:205], v[116:119]
	v_mfma_f32_16x16x32_bf16 v[108:111], v[194:197], v[202:205], v[108:111]
	v_mfma_f32_16x16x32_bf16 v[108:111], v[190:193], v[198:201], v[108:111]
	v_mfma_f32_16x16x32_bf16 v[92:95], v[190:193], v[206:209], v[92:95]
	v_mfma_f32_16x16x32_bf16 v[92:95], v[194:197], v[210:213], v[92:95]
	v_mfma_f32_16x16x32_bf16 v[100:103], v[186:189], v[210:213], v[100:103]
	v_mfma_f32_16x16x32_bf16 v[100:103], v[178:181], v[206:209], v[100:103]
	v_mfma_f32_16x16x32_bf16 v[84:87], v[178:181], v[214:217], v[84:87]
	v_mfma_f32_16x16x32_bf16 v[84:87], v[186:189], v[218:221], v[84:87]
	v_mfma_f32_16x16x32_bf16 v[76:79], v[194:197], v[218:221], v[76:79]
	v_mfma_f32_16x16x32_bf16 v[76:79], v[190:193], v[214:217], v[76:79]
	v_mfma_f32_16x16x32_bf16 v[64:67], v[190:193], v[222:225], v[64:67]
	v_mfma_f32_16x16x32_bf16 v[64:67], v[194:197], v[226:229], v[64:67]
	v_mfma_f32_16x16x32_bf16 v[68:71], v[186:189], v[226:229], v[68:71]
	v_mfma_f32_16x16x32_bf16 v[68:71], v[178:181], v[222:225], v[68:71]
	s_barrier
	s_setprio 0
	s_add_i32 s58, s86, s63
	v_lshl_add_u64 v[182:183], v[182:183], 0, s[22:23]
	s_mov_b32 m0, s58
	ds_read_b128 v[198:201], v154 offset:49152
	v_xor_b32_e32 v253, 64, v154
	ds_read_b128 v[202:205], v253 offset:49152
	ds_read_b128 v[206:209], v154 offset:51200
	ds_read_b128 v[210:213], v253 offset:51200
	ds_read_b128 v[214:217], v154 offset:53248
	ds_read_b128 v[218:221], v253 offset:53248
	ds_read_b128 v[222:225], v154 offset:55296
	ds_read_b128 v[226:229], v253 offset:55296
	global_load_lds_dwordx4 v[182:183], off
	s_add_i32 m0, s58, 0x2000
	s_add_u32 s56, s56, 0x40080
	v_lshl_add_u64 v[182:183], v[230:231], 0, s[22:23]
	s_addc_u32 s57, s57, 0
	s_add_i32 s58, s87, s63
	global_load_lds_dwordx4 v[182:183], off
	v_lshl_add_u64 v[182:183], s[56:57], 0, v[130:131]
	s_mov_b32 m0, s58
	s_nop 0
	global_load_lds_dwordx4 v[182:183], off
	v_lshl_add_u64 v[182:183], s[56:57], 0, v[134:135]
	s_add_i32 m0, s58, 0x2000
	s_nop 0
	global_load_lds_dwordx4 v[182:183], off
	v_lshl_add_u64 v[182:183], v[232:233], 0, s[22:23]
	s_mov_b32 m0, s69
	s_nop 0
	global_load_lds_dwordx4 v[182:183], off
	v_lshl_add_u64 v[182:183], v[234:235], 0, s[22:23]
	s_mov_b32 m0, s70
	s_nop 0
	global_load_lds_dwordx4 v[182:183], off
	s_waitcnt vmcnt(8)
	s_waitcnt lgkmcnt(0)
	s_setprio 1
	s_barrier
	v_mfma_f32_16x16x32_bf16 v[60:63], v[162:165], v[198:201], v[60:63]
	v_mfma_f32_16x16x32_bf16 v[60:63], v[166:169], v[202:205], v[60:63]
	v_mfma_f32_16x16x32_bf16 v[56:59], v[174:177], v[202:205], v[56:59]
	v_mfma_f32_16x16x32_bf16 v[56:59], v[170:173], v[198:201], v[56:59]
	v_mfma_f32_16x16x32_bf16 v[40:43], v[170:173], v[206:209], v[40:43]
	v_mfma_f32_16x16x32_bf16 v[40:43], v[174:177], v[210:213], v[40:43]
	v_mfma_f32_16x16x32_bf16 v[48:51], v[166:169], v[210:213], v[48:51]
	v_mfma_f32_16x16x32_bf16 v[48:51], v[162:165], v[206:209], v[48:51]
	v_mfma_f32_16x16x32_bf16 v[32:35], v[162:165], v[214:217], v[32:35]
	v_mfma_f32_16x16x32_bf16 v[32:35], v[166:169], v[218:221], v[32:35]
	v_mfma_f32_16x16x32_bf16 v[24:27], v[174:177], v[218:221], v[24:27]
	v_mfma_f32_16x16x32_bf16 v[24:27], v[170:173], v[214:217], v[24:27]
	v_mfma_f32_16x16x32_bf16 v[8:11], v[170:173], v[222:225], v[8:11]
	v_mfma_f32_16x16x32_bf16 v[8:11], v[174:177], v[226:229], v[8:11]
	v_mfma_f32_16x16x32_bf16 v[16:19], v[166:169], v[226:229], v[16:19]
	v_mfma_f32_16x16x32_bf16 v[16:19], v[162:165], v[222:225], v[16:19]
	s_setprio 0
	s_setprio 1
	v_mfma_f32_16x16x32_bf16 v[52:55], v[178:181], v[198:201], v[52:55]
	v_mfma_f32_16x16x32_bf16 v[52:55], v[186:189], v[202:205], v[52:55]
	v_mfma_f32_16x16x32_bf16 v[44:47], v[194:197], v[202:205], v[44:47]
	v_mfma_f32_16x16x32_bf16 v[44:47], v[190:193], v[198:201], v[44:47]
	v_mfma_f32_16x16x32_bf16 v[28:31], v[190:193], v[206:209], v[28:31]
	v_mfma_f32_16x16x32_bf16 v[28:31], v[194:197], v[210:213], v[28:31]
	v_mfma_f32_16x16x32_bf16 v[36:39], v[186:189], v[210:213], v[36:39]
	v_mfma_f32_16x16x32_bf16 v[36:39], v[178:181], v[206:209], v[36:39]
	v_mfma_f32_16x16x32_bf16 v[20:23], v[178:181], v[214:217], v[20:23]
	v_mfma_f32_16x16x32_bf16 v[20:23], v[186:189], v[218:221], v[20:23]
	v_mfma_f32_16x16x32_bf16 v[12:15], v[194:197], v[218:221], v[12:15]
	v_mfma_f32_16x16x32_bf16 v[12:15], v[190:193], v[214:217], v[12:15]
	v_mfma_f32_16x16x32_bf16 v[0:3], v[190:193], v[222:225], v[0:3]
	v_mfma_f32_16x16x32_bf16 v[0:3], v[194:197], v[226:229], v[0:3]
	v_mfma_f32_16x16x32_bf16 v[4:7], v[186:189], v[226:229], v[4:7]
	v_mfma_f32_16x16x32_bf16 v[4:7], v[178:181], v[222:225], v[4:7]
	s_barrier
	s_setprio 0
	s_add_i32 s85, s85, 2
	s_add_u32 s83, s83, 0x100
	s_addc_u32 s84, s84, 0
	s_add_u32 s54, s54, 0x100
	s_addc_u32 s55, s55, 0
	s_branch .LBB0_875

.LBB0_1010:
	s_ashr_i32 s51, s50, 31
	s_lshl_b64 s[52:53], s[50:51], 19
	s_add_u32 s52, s33, s52
	s_addc_u32 s53, s35, s53
	s_and_b64 s[54:55], s[12:13], exec
	s_cselect_b32 s15, s53, s61
	s_cselect_b32 s51, s52, s60
	s_ashr_i32 s49, s48, 31
	s_lshl_b64 s[54:55], s[48:49], 19
	s_add_u32 s54, s64, s54
	s_addc_u32 s55, s65, s55
	s_and_b64 s[62:63], s[12:13], exec
	s_cselect_b32 s49, s55, s59
	s_cselect_b32 s57, s54, s58
	s_add_u32 s78, s58, 0x100
	s_addc_u32 s79, s59, 0
	s_add_u32 s58, s60, 0x40080
	s_addc_u32 s59, s61, 0
	s_mov_b32 s80, -2
	s_waitcnt lgkmcnt(0)
	s_cmp_eq_u32 s71, 1
	s_cbranch_scc1 .Lfa_9
	ds_read_b128 v[128:131], v188
	v_xor_b32_e32 v253, 64, v188
	ds_read_b128 v[132:135], v253
	ds_read_b128 v[136:139], v188 offset:2048
	ds_read_b128 v[140:143], v253 offset:2048
	ds_read_b128 v[144:147], v189
	v_xor_b32_e32 v253, 64, v189
	ds_read_b128 v[148:151], v253
	ds_read_b128 v[172:175], v189 offset:2048
	ds_read_b128 v[176:179], v253 offset:2048
	s_add_u32 s60, s58, 0xfffc0080
	s_addc_u32 s61, s59, -1
	s_cmp_eq_u32 s80, 12
	s_cselect_b32 s63, s15, s61
	s_cselect_b32 s62, s51, s60
	s_cselect_b32 s61, s49, s79
	s_cselect_b32 s60, s57, s78
	v_lshl_add_u64 v[220:221], s[58:59], 0, v[166:167]
	s_add_i32 m0, s67, 0xc000
	ds_read_b128 v[180:183], v190
	v_xor_b32_e32 v253, 64, v190
	ds_read_b128 v[192:195], v253
	ds_read_b128 v[196:199], v190 offset:2048
	ds_read_b128 v[200:203], v253 offset:2048
	ds_read_b128 v[204:207], v190 offset:4096
	ds_read_b128 v[208:211], v253 offset:4096
	ds_read_b128 v[212:215], v190 offset:6144
	ds_read_b128 v[216:219], v253 offset:6144
	global_load_lds_dwordx4 v[220:221], off
	v_lshl_add_u64 v[220:221], s[58:59], 0, v[164:165]
	s_add_i32 m0, s67, 0xe000
	s_nop 0
	global_load_lds_dwordx4 v[220:221], off
	s_waitcnt vmcnt(24)
	s_waitcnt lgkmcnt(0)
	s_setprio 1
	s_barrier
	v_mfma_f32_16x16x32_bf16 v[124:127], v[128:131], v[180:183], 0
	v_mfma_f32_16x16x32_bf16 v[124:127], v[132:135], v[192:195], v[124:127]
	v_mfma_f32_16x16x32_bf16 v[120:123], v[136:139], v[180:183], 0
	v_mfma_f32_16x16x32_bf16 v[120:123], v[140:143], v[192:195], v[120:123]
	v_mfma_f32_16x16x32_bf16 v[108:111], v[128:131], v[196:199], 0
	v_mfma_f32_16x16x32_bf16 v[108:111], v[132:135], v[200:203], v[108:111]
	v_mfma_f32_16x16x32_bf16 v[104:107], v[136:139], v[196:199], 0
	v_mfma_f32_16x16x32_bf16 v[104:107], v[140:143], v[200:203], v[104:107]
	v_mfma_f32_16x16x32_bf16 v[92:95], v[128:131], v[204:207], 0
	v_mfma_f32_16x16x32_bf16 v[92:95], v[132:135], v[208:211], v[92:95]
	v_mfma_f32_16x16x32_bf16 v[88:91], v[136:139], v[204:207], 0
	v_mfma_f32_16x16x32_bf16 v[88:91], v[140:143], v[208:211], v[88:91]
	v_mfma_f32_16x16x32_bf16 v[76:79], v[128:131], v[212:215], 0
	v_mfma_f32_16x16x32_bf16 v[76:79], v[132:135], v[216:219], v[76:79]
	v_mfma_f32_16x16x32_bf16 v[72:75], v[136:139], v[212:215], 0
	v_mfma_f32_16x16x32_bf16 v[72:75], v[140:143], v[216:219], v[72:75]
	s_setprio 0
	s_setprio 1
	v_mfma_f32_16x16x32_bf16 v[116:119], v[144:147], v[180:183], 0
	v_mfma_f32_16x16x32_bf16 v[116:119], v[148:151], v[192:195], v[116:119]
	v_mfma_f32_16x16x32_bf16 v[112:115], v[172:175], v[180:183], 0
	v_mfma_f32_16x16x32_bf16 v[112:115], v[176:179], v[192:195], v[112:115]
	v_mfma_f32_16x16x32_bf16 v[100:103], v[144:147], v[196:199], 0
	v_mfma_f32_16x16x32_bf16 v[100:103], v[148:151], v[200:203], v[100:103]
	v_mfma_f32_16x16x32_bf16 v[96:99], v[172:175], v[196:199], 0
	v_mfma_f32_16x16x32_bf16 v[96:99], v[176:179], v[200:203], v[96:99]
	v_mfma_f32_16x16x32_bf16 v[84:87], v[144:147], v[204:207], 0
	v_mfma_f32_16x16x32_bf16 v[84:87], v[148:151], v[208:211], v[84:87]
	v_mfma_f32_16x16x32_bf16 v[80:83], v[172:175], v[204:207], 0
	v_mfma_f32_16x16x32_bf16 v[80:83], v[176:179], v[208:211], v[80:83]
	v_mfma_f32_16x16x32_bf16 v[68:71], v[144:147], v[212:215], 0
	v_mfma_f32_16x16x32_bf16 v[68:71], v[148:151], v[216:219], v[68:71]
	v_mfma_f32_16x16x32_bf16 v[64:67], v[172:175], v[212:215], 0
	v_mfma_f32_16x16x32_bf16 v[64:67], v[176:179], v[216:219], v[64:67]
	s_barrier
	s_setprio 0
	s_add_i32 s81, s76, s66
	v_lshl_add_u64 v[220:221], s[60:61], 0, v[154:155]
	s_mov_b32 m0, s81
	ds_read_b128 v[180:183], v190 offset:16384
	v_xor_b32_e32 v253, 64, v190
	ds_read_b128 v[192:195], v253 offset:16384
	ds_read_b128 v[196:199], v190 offset:18432
	ds_read_b128 v[200:203], v253 offset:18432
	ds_read_b128 v[204:207], v190 offset:20480
	ds_read_b128 v[208:211], v253 offset:20480
	ds_read_b128 v[212:215], v190 offset:22528
	ds_read_b128 v[216:219], v253 offset:22528
	global_load_lds_dwordx4 v[220:221], off
	s_add_i32 m0, s81, 0x2000
	s_add_u32 s82, s60, 0x40000
	v_lshl_add_u64 v[222:223], s[60:61], 0, v[162:163]
	s_addc_u32 s83, s61, 0
	s_add_i32 s81, s77, s66
	global_load_lds_dwordx4 v[222:223], off
	v_lshl_add_u64 v[224:225], s[82:83], 0, v[154:155]
	s_mov_b32 m0, s81
	v_lshl_add_u64 v[226:227], s[62:63], 0, v[160:161]
	global_load_lds_dwordx4 v[224:225], off
	v_lshl_add_u64 v[224:225], s[82:83], 0, v[162:163]
	s_add_i32 m0, s81, 0x2000
	s_nop 0
	global_load_lds_dwordx4 v[224:225], off
	v_lshl_add_u64 v[224:225], s[62:63], 0, v[152:153]
	s_mov_b32 m0, s67
	s_nop 0
	global_load_lds_dwordx4 v[224:225], off
	s_mov_b32 m0, s68
	s_nop 0
	global_load_lds_dwordx4 v[226:227], off
	s_waitcnt vmcnt(24)
	s_waitcnt lgkmcnt(0)
	s_setprio 1
	s_barrier
	v_mfma_f32_16x16x32_bf16 v[60:63], v[128:131], v[180:183], 0
	v_mfma_f32_16x16x32_bf16 v[60:63], v[132:135], v[192:195], v[60:63]
	v_mfma_f32_16x16x32_bf16 v[56:59], v[136:139], v[180:183], 0
	v_mfma_f32_16x16x32_bf16 v[56:59], v[140:143], v[192:195], v[56:59]
	v_mfma_f32_16x16x32_bf16 v[44:47], v[128:131], v[196:199], 0
	v_mfma_f32_16x16x32_bf16 v[44:47], v[132:135], v[200:203], v[44:47]
	v_mfma_f32_16x16x32_bf16 v[40:43], v[136:139], v[196:199], 0
	v_mfma_f32_16x16x32_bf16 v[40:43], v[140:143], v[200:203], v[40:43]
	v_mfma_f32_16x16x32_bf16 v[28:31], v[128:131], v[204:207], 0
	v_mfma_f32_16x16x32_bf16 v[28:31], v[132:135], v[208:211], v[28:31]
	v_mfma_f32_16x16x32_bf16 v[24:27], v[136:139], v[204:207], 0
	v_mfma_f32_16x16x32_bf16 v[24:27], v[140:143], v[208:211], v[24:27]
	v_mfma_f32_16x16x32_bf16 v[12:15], v[128:131], v[212:215], 0
	v_mfma_f32_16x16x32_bf16 v[12:15], v[132:135], v[216:219], v[12:15]
	v_mfma_f32_16x16x32_bf16 v[8:11], v[136:139], v[212:215], 0
	v_mfma_f32_16x16x32_bf16 v[8:11], v[140:143], v[216:219], v[8:11]
	s_setprio 0
	s_setprio 1
	v_mfma_f32_16x16x32_bf16 v[52:55], v[144:147], v[180:183], 0
	v_mfma_f32_16x16x32_bf16 v[52:55], v[148:151], v[192:195], v[52:55]
	v_mfma_f32_16x16x32_bf16 v[48:51], v[172:175], v[180:183], 0
	v_mfma_f32_16x16x32_bf16 v[48:51], v[176:179], v[192:195], v[48:51]
	v_mfma_f32_16x16x32_bf16 v[36:39], v[144:147], v[196:199], 0
	v_mfma_f32_16x16x32_bf16 v[36:39], v[148:151], v[200:203], v[36:39]
	v_mfma_f32_16x16x32_bf16 v[32:35], v[172:175], v[196:199], 0
	v_mfma_f32_16x16x32_bf16 v[32:35], v[176:179], v[200:203], v[32:35]
	v_mfma_f32_16x16x32_bf16 v[20:23], v[144:147], v[204:207], 0
	v_mfma_f32_16x16x32_bf16 v[20:23], v[148:151], v[208:211], v[20:23]
	v_mfma_f32_16x16x32_bf16 v[16:19], v[172:175], v[204:207], 0
	v_mfma_f32_16x16x32_bf16 v[16:19], v[176:179], v[208:211], v[16:19]
	v_mfma_f32_16x16x32_bf16 v[4:7], v[144:147], v[212:215], 0
	v_mfma_f32_16x16x32_bf16 v[4:7], v[148:151], v[216:219], v[4:7]
	v_mfma_f32_16x16x32_bf16 v[0:3], v[172:175], v[212:215], 0
	v_mfma_f32_16x16x32_bf16 v[0:3], v[176:179], v[216:219], v[0:3]
	s_barrier
	s_setprio 0
	s_add_i32 s81, 0, 0x18000
	s_add_i32 s82, 0, 0x1c000
	v_add_u32_e32 v140, s81, v185
	v_add_u32_e32 v176, s82, v185
	ds_read_b128 v[128:131], v140
	v_xor_b32_e32 v253, 64, v140
	ds_read_b128 v[132:135], v253
	ds_read_b128 v[136:139], v140 offset:2048
	ds_read_b128 v[140:143], v253 offset:2048
	ds_read_b128 v[144:147], v176
	v_xor_b32_e32 v253, 64, v176
	ds_read_b128 v[148:151], v253
	ds_read_b128 v[172:175], v176 offset:2048
	ds_read_b128 v[176:179], v253 offset:2048
	s_add_u32 s62, s62, 0x40000
	s_addc_u32 s63, s63, 0
	s_mov_b32 m0, s69
	v_lshl_add_u64 v[228:229], s[62:63], 0, v[152:153]
	ds_read_b128 v[180:183], v190 offset:32768
	v_xor_b32_e32 v253, 64, v190
	ds_read_b128 v[192:195], v253 offset:32768
	ds_read_b128 v[196:199], v190 offset:34816
	ds_read_b128 v[200:203], v253 offset:34816
	ds_read_b128 v[204:207], v190 offset:36864
	ds_read_b128 v[208:211], v253 offset:36864
	ds_read_b128 v[212:215], v190 offset:38912
	ds_read_b128 v[216:219], v253 offset:38912
	global_load_lds_dwordx4 v[228:229], off
	v_lshl_add_u64 v[228:229], s[62:63], 0, v[160:161]
	s_mov_b32 m0, s70
	s_nop 0
	global_load_lds_dwordx4 v[228:229], off
	s_waitcnt vmcnt(8)
	s_waitcnt lgkmcnt(0)
	s_setprio 1
	s_barrier
	v_mfma_f32_16x16x32_bf16 v[124:127], v[128:131], v[180:183], v[124:127]
	v_mfma_f32_16x16x32_bf16 v[124:127], v[132:135], v[192:195], v[124:127]
	v_mfma_f32_16x16x32_bf16 v[120:123], v[140:143], v[192:195], v[120:123]
	v_mfma_f32_16x16x32_bf16 v[120:123], v[136:139], v[180:183], v[120:123]
	v_mfma_f32_16x16x32_bf16 v[104:107], v[136:139], v[196:199], v[104:107]
	v_mfma_f32_16x16x32_bf16 v[104:107], v[140:143], v[200:203], v[104:107]
	v_mfma_f32_16x16x32_bf16 v[108:111], v[132:135], v[200:203], v[108:111]
	v_mfma_f32_16x16x32_bf16 v[108:111], v[128:131], v[196:199], v[108:111]
	v_mfma_f32_16x16x32_bf16 v[92:95], v[128:131], v[204:207], v[92:95]
	v_mfma_f32_16x16x32_bf16 v[92:95], v[132:135], v[208:211], v[92:95]
	v_mfma_f32_16x16x32_bf16 v[88:91], v[140:143], v[208:211], v[88:91]
	v_mfma_f32_16x16x32_bf16 v[88:91], v[136:139], v[204:207], v[88:91]
	v_mfma_f32_16x16x32_bf16 v[72:75], v[136:139], v[212:215], v[72:75]
	v_mfma_f32_16x16x32_bf16 v[72:75], v[140:143], v[216:219], v[72:75]
	v_mfma_f32_16x16x32_bf16 v[76:79], v[132:135], v[216:219], v[76:79]
	v_mfma_f32_16x16x32_bf16 v[76:79], v[128:131], v[212:215], v[76:79]
	s_setprio 0
	s_setprio 1
	v_mfma_f32_16x16x32_bf16 v[116:119], v[144:147], v[180:183], v[116:119]
	v_mfma_f32_16x16x32_bf16 v[116:119], v[148:151], v[192:195], v[116:119]
	v_mfma_f32_16x16x32_bf16 v[112:115], v[176:179], v[192:195], v[112:115]
	v_mfma_f32_16x16x32_bf16 v[112:115], v[172:175], v[180:183], v[112:115]
	v_mfma_f32_16x16x32_bf16 v[96:99], v[172:175], v[196:199], v[96:99]
	v_mfma_f32_16x16x32_bf16 v[96:99], v[176:179], v[200:203], v[96:99]
	v_mfma_f32_16x16x32_bf16 v[100:103], v[148:151], v[200:203], v[100:103]
	v_mfma_f32_16x16x32_bf16 v[100:103], v[144:147], v[196:199], v[100:103]
	v_mfma_f32_16x16x32_bf16 v[84:87], v[144:147], v[204:207], v[84:87]
	v_mfma_f32_16x16x32_bf16 v[84:87], v[148:151], v[208:211], v[84:87]
	v_mfma_f32_16x16x32_bf16 v[80:83], v[176:179], v[208:211], v[80:83]
	v_mfma_f32_16x16x32_bf16 v[80:83], v[172:175], v[204:207], v[80:83]
	v_mfma_f32_16x16x32_bf16 v[64:67], v[172:175], v[212:215], v[64:67]
	v_mfma_f32_16x16x32_bf16 v[64:67], v[176:179], v[216:219], v[64:67]
	v_mfma_f32_16x16x32_bf16 v[68:71], v[148:151], v[216:219], v[68:71]
	v_mfma_f32_16x16x32_bf16 v[68:71], v[144:147], v[212:215], v[68:71]
	s_barrier
	s_setprio 0
	s_add_i32 s62, s81, s66
	v_lshl_add_u64 v[220:221], v[220:221], 0, s[26:27]
	s_mov_b32 m0, s62
	ds_read_b128 v[180:183], v190 offset:49152
	v_xor_b32_e32 v253, 64, v190
	ds_read_b128 v[192:195], v253 offset:49152
	ds_read_b128 v[196:199], v190 offset:51200
	ds_read_b128 v[200:203], v253 offset:51200
	ds_read_b128 v[204:207], v190 offset:53248
	ds_read_b128 v[208:211], v253 offset:53248
	ds_read_b128 v[212:215], v190 offset:55296
	ds_read_b128 v[216:219], v253 offset:55296
	global_load_lds_dwordx4 v[220:221], off
	s_add_i32 m0, s62, 0x2000
	s_add_u32 s60, s60, 0x40080
	v_lshl_add_u64 v[220:221], v[222:223], 0, s[26:27]
	s_addc_u32 s61, s61, 0
	s_add_i32 s62, s82, s66
	global_load_lds_dwordx4 v[220:221], off
	v_lshl_add_u64 v[220:221], s[60:61], 0, v[154:155]
	s_mov_b32 m0, s62
	s_nop 0
	global_load_lds_dwordx4 v[220:221], off
	v_lshl_add_u64 v[220:221], s[60:61], 0, v[162:163]
	s_add_i32 m0, s62, 0x2000
	s_nop 0
	global_load_lds_dwordx4 v[220:221], off
	v_lshl_add_u64 v[220:221], v[224:225], 0, s[26:27]
	s_mov_b32 m0, s3
	s_nop 0
	global_load_lds_dwordx4 v[220:221], off
	v_lshl_add_u64 v[220:221], v[226:227], 0, s[26:27]
	s_mov_b32 m0, s72
	s_nop 0
	global_load_lds_dwordx4 v[220:221], off
	s_waitcnt vmcnt(8)
	s_waitcnt lgkmcnt(0)
	s_setprio 1
	s_barrier
	v_mfma_f32_16x16x32_bf16 v[60:63], v[128:131], v[180:183], v[60:63]
	v_mfma_f32_16x16x32_bf16 v[60:63], v[132:135], v[192:195], v[60:63]
	v_mfma_f32_16x16x32_bf16 v[56:59], v[140:143], v[192:195], v[56:59]
	v_mfma_f32_16x16x32_bf16 v[56:59], v[136:139], v[180:183], v[56:59]
	v_mfma_f32_16x16x32_bf16 v[40:43], v[136:139], v[196:199], v[40:43]
	v_mfma_f32_16x16x32_bf16 v[40:43], v[140:143], v[200:203], v[40:43]
	v_mfma_f32_16x16x32_bf16 v[44:47], v[132:135], v[200:203], v[44:47]
	v_mfma_f32_16x16x32_bf16 v[44:47], v[128:131], v[196:199], v[44:47]
	v_mfma_f32_16x16x32_bf16 v[28:31], v[128:131], v[204:207], v[28:31]
	v_mfma_f32_16x16x32_bf16 v[28:31], v[132:135], v[208:211], v[28:31]
	v_mfma_f32_16x16x32_bf16 v[24:27], v[140:143], v[208:211], v[24:27]
	v_mfma_f32_16x16x32_bf16 v[24:27], v[136:139], v[204:207], v[24:27]
	v_mfma_f32_16x16x32_bf16 v[8:11], v[136:139], v[212:215], v[8:11]
	v_mfma_f32_16x16x32_bf16 v[8:11], v[140:143], v[216:219], v[8:11]
	v_mfma_f32_16x16x32_bf16 v[12:15], v[132:135], v[216:219], v[12:15]
	v_mfma_f32_16x16x32_bf16 v[12:15], v[128:131], v[212:215], v[12:15]
	s_setprio 0
	s_setprio 1
	v_mfma_f32_16x16x32_bf16 v[52:55], v[144:147], v[180:183], v[52:55]
	v_mfma_f32_16x16x32_bf16 v[52:55], v[148:151], v[192:195], v[52:55]
	v_mfma_f32_16x16x32_bf16 v[48:51], v[176:179], v[192:195], v[48:51]
	v_mfma_f32_16x16x32_bf16 v[48:51], v[172:175], v[180:183], v[48:51]
	v_mfma_f32_16x16x32_bf16 v[32:35], v[172:175], v[196:199], v[32:35]
	v_mfma_f32_16x16x32_bf16 v[32:35], v[176:179], v[200:203], v[32:35]
	v_mfma_f32_16x16x32_bf16 v[36:39], v[148:151], v[200:203], v[36:39]
	v_mfma_f32_16x16x32_bf16 v[36:39], v[144:147], v[196:199], v[36:39]
	v_mfma_f32_16x16x32_bf16 v[20:23], v[144:147], v[204:207], v[20:23]
	v_mfma_f32_16x16x32_bf16 v[20:23], v[148:151], v[208:211], v[20:23]
	v_mfma_f32_16x16x32_bf16 v[16:19], v[176:179], v[208:211], v[16:19]
	v_mfma_f32_16x16x32_bf16 v[16:19], v[172:175], v[204:207], v[16:19]
	v_mfma_f32_16x16x32_bf16 v[0:3], v[172:175], v[212:215], v[0:3]
	v_mfma_f32_16x16x32_bf16 v[0:3], v[176:179], v[216:219], v[0:3]
	v_mfma_f32_16x16x32_bf16 v[4:7], v[148:151], v[216:219], v[4:7]
	v_mfma_f32_16x16x32_bf16 v[4:7], v[144:147], v[212:215], v[4:7]
	s_barrier
	s_setprio 0
	s_add_i32 s80, s80, 2
	s_add_u32 s78, s78, 0x100
	s_addc_u32 s79, s79, 0
	s_add_u32 s58, s58, 0x100
	s_addc_u32 s59, s59, 0
	s_cmp_gt_u32 s80, 13
	s_branch .LBB0_1011
.Lfa_9:
	ds_read_b128 v[128:131], v188
	v_xor_b32_e32 v253, 64, v188
	ds_read_b128 v[132:135], v253
	ds_read_b128 v[136:139], v188 offset:2048
	ds_read_b128 v[140:143], v253 offset:2048
	ds_read_b128 v[144:147], v189
	v_xor_b32_e32 v253, 64, v189
	ds_read_b128 v[148:151], v253
	ds_read_b128 v[172:175], v189 offset:2048
	ds_read_b128 v[176:179], v253 offset:2048
	s_add_u32 s60, s58, 0xfffc0080
	s_addc_u32 s61, s59, -1
	s_cmp_eq_u32 s80, 12
	s_cselect_b32 s63, s15, s61
	s_cselect_b32 s62, s51, s60
	s_cselect_b32 s61, s49, s79
	s_cselect_b32 s60, s57, s78
	v_lshl_add_u64 v[220:221], s[58:59], 0, v[166:167]
	s_add_i32 m0, s67, 0xc000
	ds_read_b128 v[180:183], v190
	v_xor_b32_e32 v253, 64, v190
	ds_read_b128 v[192:195], v253
	ds_read_b128 v[196:199], v190 offset:2048
	ds_read_b128 v[200:203], v253 offset:2048
	ds_read_b128 v[204:207], v190 offset:4096
	ds_read_b128 v[208:211], v253 offset:4096
	ds_read_b128 v[212:215], v190 offset:6144
	ds_read_b128 v[216:219], v253 offset:6144
	global_load_lds_dwordx4 v[220:221], off
	v_lshl_add_u64 v[220:221], s[58:59], 0, v[164:165]
	s_add_i32 m0, s67, 0xe000
	s_nop 0
	global_load_lds_dwordx4 v[220:221], off
	s_waitcnt vmcnt(8)
	s_waitcnt lgkmcnt(0)
	s_setprio 1
	s_barrier
	v_mfma_f32_16x16x32_bf16 v[124:127], v[128:131], v[180:183], 0
	v_mfma_f32_16x16x32_bf16 v[124:127], v[132:135], v[192:195], v[124:127]
	v_mfma_f32_16x16x32_bf16 v[120:123], v[136:139], v[180:183], 0
	v_mfma_f32_16x16x32_bf16 v[120:123], v[140:143], v[192:195], v[120:123]
	v_mfma_f32_16x16x32_bf16 v[108:111], v[128:131], v[196:199], 0
	v_mfma_f32_16x16x32_bf16 v[108:111], v[132:135], v[200:203], v[108:111]
	v_mfma_f32_16x16x32_bf16 v[104:107], v[136:139], v[196:199], 0
	v_mfma_f32_16x16x32_bf16 v[104:107], v[140:143], v[200:203], v[104:107]
	v_mfma_f32_16x16x32_bf16 v[92:95], v[128:131], v[204:207], 0
	v_mfma_f32_16x16x32_bf16 v[92:95], v[132:135], v[208:211], v[92:95]
	v_mfma_f32_16x16x32_bf16 v[88:91], v[136:139], v[204:207], 0
	v_mfma_f32_16x16x32_bf16 v[88:91], v[140:143], v[208:211], v[88:91]
	v_mfma_f32_16x16x32_bf16 v[76:79], v[128:131], v[212:215], 0
	v_mfma_f32_16x16x32_bf16 v[76:79], v[132:135], v[216:219], v[76:79]
	v_mfma_f32_16x16x32_bf16 v[72:75], v[136:139], v[212:215], 0
	v_mfma_f32_16x16x32_bf16 v[72:75], v[140:143], v[216:219], v[72:75]
	s_setprio 0
	s_setprio 1
	v_mfma_f32_16x16x32_bf16 v[116:119], v[144:147], v[180:183], 0
	v_mfma_f32_16x16x32_bf16 v[116:119], v[148:151], v[192:195], v[116:119]
	v_mfma_f32_16x16x32_bf16 v[112:115], v[172:175], v[180:183], 0
	v_mfma_f32_16x16x32_bf16 v[112:115], v[176:179], v[192:195], v[112:115]
	v_mfma_f32_16x16x32_bf16 v[100:103], v[144:147], v[196:199], 0
	v_mfma_f32_16x16x32_bf16 v[100:103], v[148:151], v[200:203], v[100:103]
	v_mfma_f32_16x16x32_bf16 v[96:99], v[172:175], v[196:199], 0
	v_mfma_f32_16x16x32_bf16 v[96:99], v[176:179], v[200:203], v[96:99]
	v_mfma_f32_16x16x32_bf16 v[84:87], v[144:147], v[204:207], 0
	v_mfma_f32_16x16x32_bf16 v[84:87], v[148:151], v[208:211], v[84:87]
	v_mfma_f32_16x16x32_bf16 v[80:83], v[172:175], v[204:207], 0
	v_mfma_f32_16x16x32_bf16 v[80:83], v[176:179], v[208:211], v[80:83]
	v_mfma_f32_16x16x32_bf16 v[68:71], v[144:147], v[212:215], 0
	v_mfma_f32_16x16x32_bf16 v[68:71], v[148:151], v[216:219], v[68:71]
	v_mfma_f32_16x16x32_bf16 v[64:67], v[172:175], v[212:215], 0
	v_mfma_f32_16x16x32_bf16 v[64:67], v[176:179], v[216:219], v[64:67]
	s_barrier
	s_setprio 0
	s_add_i32 s81, s76, s66
	v_lshl_add_u64 v[220:221], s[60:61], 0, v[154:155]
	s_mov_b32 m0, s81
	ds_read_b128 v[180:183], v190 offset:16384
	v_xor_b32_e32 v253, 64, v190
	ds_read_b128 v[192:195], v253 offset:16384
	ds_read_b128 v[196:199], v190 offset:18432
	ds_read_b128 v[200:203], v253 offset:18432
	ds_read_b128 v[204:207], v190 offset:20480
	ds_read_b128 v[208:211], v253 offset:20480
	ds_read_b128 v[212:215], v190 offset:22528
	ds_read_b128 v[216:219], v253 offset:22528
	global_load_lds_dwordx4 v[220:221], off
	s_add_i32 m0, s81, 0x2000
	s_add_u32 s82, s60, 0x40000
	v_lshl_add_u64 v[222:223], s[60:61], 0, v[162:163]
	s_addc_u32 s83, s61, 0
	s_add_i32 s81, s77, s66
	global_load_lds_dwordx4 v[222:223], off
	v_lshl_add_u64 v[224:225], s[82:83], 0, v[154:155]
	s_mov_b32 m0, s81
	v_lshl_add_u64 v[226:227], s[62:63], 0, v[160:161]
	global_load_lds_dwordx4 v[224:225], off
	v_lshl_add_u64 v[224:225], s[82:83], 0, v[162:163]
	s_add_i32 m0, s81, 0x2000
	s_nop 0
	global_load_lds_dwordx4 v[224:225], off
	v_lshl_add_u64 v[224:225], s[62:63], 0, v[152:153]
	s_mov_b32 m0, s67
	s_nop 0
	global_load_lds_dwordx4 v[224:225], off
	s_mov_b32 m0, s68
	s_nop 0
	global_load_lds_dwordx4 v[226:227], off
	s_waitcnt vmcnt(8)
	s_waitcnt lgkmcnt(0)
	s_setprio 1
	s_barrier
	v_mfma_f32_16x16x32_bf16 v[60:63], v[128:131], v[180:183], 0
	v_mfma_f32_16x16x32_bf16 v[60:63], v[132:135], v[192:195], v[60:63]
	v_mfma_f32_16x16x32_bf16 v[56:59], v[136:139], v[180:183], 0
	v_mfma_f32_16x16x32_bf16 v[56:59], v[140:143], v[192:195], v[56:59]
	v_mfma_f32_16x16x32_bf16 v[44:47], v[128:131], v[196:199], 0
	v_mfma_f32_16x16x32_bf16 v[44:47], v[132:135], v[200:203], v[44:47]
	v_mfma_f32_16x16x32_bf16 v[40:43], v[136:139], v[196:199], 0
	v_mfma_f32_16x16x32_bf16 v[40:43], v[140:143], v[200:203], v[40:43]
	v_mfma_f32_16x16x32_bf16 v[28:31], v[128:131], v[204:207], 0
	v_mfma_f32_16x16x32_bf16 v[28:31], v[132:135], v[208:211], v[28:31]
	v_mfma_f32_16x16x32_bf16 v[24:27], v[136:139], v[204:207], 0
	v_mfma_f32_16x16x32_bf16 v[24:27], v[140:143], v[208:211], v[24:27]
	v_mfma_f32_16x16x32_bf16 v[12:15], v[128:131], v[212:215], 0
	v_mfma_f32_16x16x32_bf16 v[12:15], v[132:135], v[216:219], v[12:15]
	v_mfma_f32_16x16x32_bf16 v[8:11], v[136:139], v[212:215], 0
	v_mfma_f32_16x16x32_bf16 v[8:11], v[140:143], v[216:219], v[8:11]
	s_setprio 0
	s_setprio 1
	v_mfma_f32_16x16x32_bf16 v[52:55], v[144:147], v[180:183], 0
	v_mfma_f32_16x16x32_bf16 v[52:55], v[148:151], v[192:195], v[52:55]
	v_mfma_f32_16x16x32_bf16 v[48:51], v[172:175], v[180:183], 0
	v_mfma_f32_16x16x32_bf16 v[48:51], v[176:179], v[192:195], v[48:51]
	v_mfma_f32_16x16x32_bf16 v[36:39], v[144:147], v[196:199], 0
	v_mfma_f32_16x16x32_bf16 v[36:39], v[148:151], v[200:203], v[36:39]
	v_mfma_f32_16x16x32_bf16 v[32:35], v[172:175], v[196:199], 0
	v_mfma_f32_16x16x32_bf16 v[32:35], v[176:179], v[200:203], v[32:35]
	v_mfma_f32_16x16x32_bf16 v[20:23], v[144:147], v[204:207], 0
	v_mfma_f32_16x16x32_bf16 v[20:23], v[148:151], v[208:211], v[20:23]
	v_mfma_f32_16x16x32_bf16 v[16:19], v[172:175], v[204:207], 0
	v_mfma_f32_16x16x32_bf16 v[16:19], v[176:179], v[208:211], v[16:19]
	v_mfma_f32_16x16x32_bf16 v[4:7], v[144:147], v[212:215], 0
	v_mfma_f32_16x16x32_bf16 v[4:7], v[148:151], v[216:219], v[4:7]
	v_mfma_f32_16x16x32_bf16 v[0:3], v[172:175], v[212:215], 0
	v_mfma_f32_16x16x32_bf16 v[0:3], v[176:179], v[216:219], v[0:3]
	s_barrier
	s_setprio 0
	s_add_i32 s81, 0, 0x18000
	s_add_i32 s82, 0, 0x1c000
	v_add_u32_e32 v140, s81, v185
	v_add_u32_e32 v176, s82, v185
	ds_read_b128 v[128:131], v140
	v_xor_b32_e32 v253, 64, v140
	ds_read_b128 v[132:135], v253
	ds_read_b128 v[136:139], v140 offset:2048
	ds_read_b128 v[140:143], v253 offset:2048
	ds_read_b128 v[144:147], v176
	v_xor_b32_e32 v253, 64, v176
	ds_read_b128 v[148:151], v253
	ds_read_b128 v[172:175], v176 offset:2048
	ds_read_b128 v[176:179], v253 offset:2048
	s_add_u32 s62, s62, 0x40000
	s_addc_u32 s63, s63, 0
	s_mov_b32 m0, s69
	v_lshl_add_u64 v[228:229], s[62:63], 0, v[152:153]
	ds_read_b128 v[180:183], v190 offset:32768
	v_xor_b32_e32 v253, 64, v190
	ds_read_b128 v[192:195], v253 offset:32768
	ds_read_b128 v[196:199], v190 offset:34816
	ds_read_b128 v[200:203], v253 offset:34816
	ds_read_b128 v[204:207], v190 offset:36864
	ds_read_b128 v[208:211], v253 offset:36864
	ds_read_b128 v[212:215], v190 offset:38912
	ds_read_b128 v[216:219], v253 offset:38912
	global_load_lds_dwordx4 v[228:229], off
	v_lshl_add_u64 v[228:229], s[62:63], 0, v[160:161]
	s_mov_b32 m0, s70
	s_nop 0
	global_load_lds_dwordx4 v[228:229], off
	s_waitcnt vmcnt(8)
	s_waitcnt lgkmcnt(0)
	s_setprio 1
	s_barrier
	v_mfma_f32_16x16x32_bf16 v[124:127], v[128:131], v[180:183], v[124:127]
	v_mfma_f32_16x16x32_bf16 v[124:127], v[132:135], v[192:195], v[124:127]
	v_mfma_f32_16x16x32_bf16 v[120:123], v[140:143], v[192:195], v[120:123]
	v_mfma_f32_16x16x32_bf16 v[120:123], v[136:139], v[180:183], v[120:123]
	v_mfma_f32_16x16x32_bf16 v[104:107], v[136:139], v[196:199], v[104:107]
	v_mfma_f32_16x16x32_bf16 v[104:107], v[140:143], v[200:203], v[104:107]
	v_mfma_f32_16x16x32_bf16 v[108:111], v[132:135], v[200:203], v[108:111]
	v_mfma_f32_16x16x32_bf16 v[108:111], v[128:131], v[196:199], v[108:111]
	v_mfma_f32_16x16x32_bf16 v[92:95], v[128:131], v[204:207], v[92:95]
	v_mfma_f32_16x16x32_bf16 v[92:95], v[132:135], v[208:211], v[92:95]
	v_mfma_f32_16x16x32_bf16 v[88:91], v[140:143], v[208:211], v[88:91]
	v_mfma_f32_16x16x32_bf16 v[88:91], v[136:139], v[204:207], v[88:91]
	v_mfma_f32_16x16x32_bf16 v[72:75], v[136:139], v[212:215], v[72:75]
	v_mfma_f32_16x16x32_bf16 v[72:75], v[140:143], v[216:219], v[72:75]
	v_mfma_f32_16x16x32_bf16 v[76:79], v[132:135], v[216:219], v[76:79]
	v_mfma_f32_16x16x32_bf16 v[76:79], v[128:131], v[212:215], v[76:79]
	s_setprio 0
	s_setprio 1
	v_mfma_f32_16x16x32_bf16 v[116:119], v[144:147], v[180:183], v[116:119]
	v_mfma_f32_16x16x32_bf16 v[116:119], v[148:151], v[192:195], v[116:119]
	v_mfma_f32_16x16x32_bf16 v[112:115], v[176:179], v[192:195], v[112:115]
	v_mfma_f32_16x16x32_bf16 v[112:115], v[172:175], v[180:183], v[112:115]
	v_mfma_f32_16x16x32_bf16 v[96:99], v[172:175], v[196:199], v[96:99]
	v_mfma_f32_16x16x32_bf16 v[96:99], v[176:179], v[200:203], v[96:99]
	v_mfma_f32_16x16x32_bf16 v[100:103], v[148:151], v[200:203], v[100:103]
	v_mfma_f32_16x16x32_bf16 v[100:103], v[144:147], v[196:199], v[100:103]
	v_mfma_f32_16x16x32_bf16 v[84:87], v[144:147], v[204:207], v[84:87]
	v_mfma_f32_16x16x32_bf16 v[84:87], v[148:151], v[208:211], v[84:87]
	v_mfma_f32_16x16x32_bf16 v[80:83], v[176:179], v[208:211], v[80:83]
	v_mfma_f32_16x16x32_bf16 v[80:83], v[172:175], v[204:207], v[80:83]
	v_mfma_f32_16x16x32_bf16 v[64:67], v[172:175], v[212:215], v[64:67]
	v_mfma_f32_16x16x32_bf16 v[64:67], v[176:179], v[216:219], v[64:67]
	v_mfma_f32_16x16x32_bf16 v[68:71], v[148:151], v[216:219], v[68:71]
	v_mfma_f32_16x16x32_bf16 v[68:71], v[144:147], v[212:215], v[68:71]
	s_barrier
	s_setprio 0
	s_add_i32 s62, s81, s66
	v_lshl_add_u64 v[220:221], v[220:221], 0, s[26:27]
	s_mov_b32 m0, s62
	ds_read_b128 v[180:183], v190 offset:49152
	v_xor_b32_e32 v253, 64, v190
	ds_read_b128 v[192:195], v253 offset:49152
	ds_read_b128 v[196:199], v190 offset:51200
	ds_read_b128 v[200:203], v253 offset:51200
	ds_read_b128 v[204:207], v190 offset:53248
	ds_read_b128 v[208:211], v253 offset:53248
	ds_read_b128 v[212:215], v190 offset:55296
	ds_read_b128 v[216:219], v253 offset:55296
	global_load_lds_dwordx4 v[220:221], off
	s_add_i32 m0, s62, 0x2000
	s_add_u32 s60, s60, 0x40080
	v_lshl_add_u64 v[220:221], v[222:223], 0, s[26:27]
	s_addc_u32 s61, s61, 0
	s_add_i32 s62, s82, s66
	global_load_lds_dwordx4 v[220:221], off
	v_lshl_add_u64 v[220:221], s[60:61], 0, v[154:155]
	s_mov_b32 m0, s62
	s_nop 0
	global_load_lds_dwordx4 v[220:221], off
	v_lshl_add_u64 v[220:221], s[60:61], 0, v[162:163]
	s_add_i32 m0, s62, 0x2000
	s_nop 0
	global_load_lds_dwordx4 v[220:221], off
	v_lshl_add_u64 v[220:221], v[224:225], 0, s[26:27]
	s_mov_b32 m0, s3
	s_nop 0
	global_load_lds_dwordx4 v[220:221], off
	v_lshl_add_u64 v[220:221], v[226:227], 0, s[26:27]
	s_mov_b32 m0, s72
	s_nop 0
	global_load_lds_dwordx4 v[220:221], off
	s_waitcnt vmcnt(8)
	s_waitcnt lgkmcnt(0)
	s_setprio 1
	s_barrier
	v_mfma_f32_16x16x32_bf16 v[60:63], v[128:131], v[180:183], v[60:63]
	v_mfma_f32_16x16x32_bf16 v[60:63], v[132:135], v[192:195], v[60:63]
	v_mfma_f32_16x16x32_bf16 v[56:59], v[140:143], v[192:195], v[56:59]
	v_mfma_f32_16x16x32_bf16 v[56:59], v[136:139], v[180:183], v[56:59]
	v_mfma_f32_16x16x32_bf16 v[40:43], v[136:139], v[196:199], v[40:43]
	v_mfma_f32_16x16x32_bf16 v[40:43], v[140:143], v[200:203], v[40:43]
	v_mfma_f32_16x16x32_bf16 v[44:47], v[132:135], v[200:203], v[44:47]
	v_mfma_f32_16x16x32_bf16 v[44:47], v[128:131], v[196:199], v[44:47]
	v_mfma_f32_16x16x32_bf16 v[28:31], v[128:131], v[204:207], v[28:31]
	v_mfma_f32_16x16x32_bf16 v[28:31], v[132:135], v[208:211], v[28:31]
	v_mfma_f32_16x16x32_bf16 v[24:27], v[140:143], v[208:211], v[24:27]
	v_mfma_f32_16x16x32_bf16 v[24:27], v[136:139], v[204:207], v[24:27]
	v_mfma_f32_16x16x32_bf16 v[8:11], v[136:139], v[212:215], v[8:11]
	v_mfma_f32_16x16x32_bf16 v[8:11], v[140:143], v[216:219], v[8:11]
	v_mfma_f32_16x16x32_bf16 v[12:15], v[132:135], v[216:219], v[12:15]
	v_mfma_f32_16x16x32_bf16 v[12:15], v[128:131], v[212:215], v[12:15]
	s_setprio 0
	s_setprio 1
	v_mfma_f32_16x16x32_bf16 v[52:55], v[144:147], v[180:183], v[52:55]
	v_mfma_f32_16x16x32_bf16 v[52:55], v[148:151], v[192:195], v[52:55]
	v_mfma_f32_16x16x32_bf16 v[48:51], v[176:179], v[192:195], v[48:51]
	v_mfma_f32_16x16x32_bf16 v[48:51], v[172:175], v[180:183], v[48:51]
	v_mfma_f32_16x16x32_bf16 v[32:35], v[172:175], v[196:199], v[32:35]
	v_mfma_f32_16x16x32_bf16 v[32:35], v[176:179], v[200:203], v[32:35]
	v_mfma_f32_16x16x32_bf16 v[36:39], v[148:151], v[200:203], v[36:39]
	v_mfma_f32_16x16x32_bf16 v[36:39], v[144:147], v[196:199], v[36:39]
	v_mfma_f32_16x16x32_bf16 v[20:23], v[144:147], v[204:207], v[20:23]
	v_mfma_f32_16x16x32_bf16 v[20:23], v[148:151], v[208:211], v[20:23]
	v_mfma_f32_16x16x32_bf16 v[16:19], v[176:179], v[208:211], v[16:19]
	v_mfma_f32_16x16x32_bf16 v[16:19], v[172:175], v[204:207], v[16:19]
	v_mfma_f32_16x16x32_bf16 v[0:3], v[172:175], v[212:215], v[0:3]
	v_mfma_f32_16x16x32_bf16 v[0:3], v[176:179], v[216:219], v[0:3]
	v_mfma_f32_16x16x32_bf16 v[4:7], v[148:151], v[216:219], v[4:7]
	v_mfma_f32_16x16x32_bf16 v[4:7], v[144:147], v[212:215], v[4:7]
	s_barrier
	s_setprio 0
	s_add_i32 s80, s80, 2
	s_add_u32 s78, s78, 0x100
	s_addc_u32 s79, s79, 0
	s_add_u32 s58, s58, 0x100
	s_addc_u32 s59, s59, 0
	s_cmp_gt_u32 s80, 13

.LBB0_1096:
	s_ashr_i32 s25, s24, 31
	s_lshl_b64 s[26:27], s[24:25], 19
	s_add_u32 s26, s3, s26
	s_addc_u32 s27, s33, s27
	s_and_b64 s[28:29], s[6:7], exec
	s_cselect_b32 s25, s27, s47
	s_cselect_b32 s65, s26, s46
	s_ashr_i32 s23, s22, 31
	s_lshl_b64 s[28:29], s[22:23], 19
	s_add_u32 s28, s35, s28
	s_addc_u32 s29, s48, s29
	s_and_b64 s[66:67], s[6:7], exec
	s_cselect_b32 s66, s29, s45
	s_cselect_b32 s67, s28, s44
	s_lshl_b32 s23, s30, 8
	v_add_u32_e32 v0, s23, v148
	s_add_u32 s68, s44, 0x100
	v_ashrrev_i32_e32 v1, 31, v0
	s_addc_u32 s69, s45, 0
	v_lshl_add_u64 v[144:145], v[0:1], 4, s[12:13]
	s_add_u32 s30, s46, 0x40080
	s_addc_u32 s31, s47, 0
	s_mov_b32 s70, -2
	s_mov_b64 s[44:45], 0
	s_cmp_eq_u32 s56, 1
	s_cbranch_scc1 .Lfa_10
	v_add_u32_e32 v153, s61, v147
	ds_read_b128 v[160:163], v153
	v_xor_b32_e32 v253, 64, v153
	ds_read_b128 v[164:167], v253
	ds_read_b128 v[168:171], v153 offset:2048
	ds_read_b128 v[172:175], v253 offset:2048
	v_add_u32_e32 v153, s62, v147
	ds_read_b128 v[176:179], v153
	v_xor_b32_e32 v253, 64, v153
	ds_read_b128 v[180:183], v253
	ds_read_b128 v[184:187], v153 offset:2048
	ds_read_b128 v[188:191], v253 offset:2048
	s_add_u32 s46, s30, 0xfffc0080
	s_addc_u32 s47, s31, -1
	s_and_b64 s[44:45], s[44:45], exec
	s_cselect_b32 s47, s25, s47
	s_cselect_b32 s46, s65, s46
	s_cselect_b32 s45, s66, s69
	s_cselect_b32 s44, s67, s68
	v_lshl_add_u64 v[154:155], s[30:31], 0, v[138:139]
	s_add_i32 m0, s52, 0xc000
	ds_read_b128 v[192:195], v150
	v_xor_b32_e32 v253, 64, v150
	ds_read_b128 v[196:199], v253
	ds_read_b128 v[200:203], v150 offset:2048
	ds_read_b128 v[204:207], v253 offset:2048
	ds_read_b128 v[208:211], v150 offset:4096
	ds_read_b128 v[212:215], v253 offset:4096
	ds_read_b128 v[216:219], v150 offset:6144
	ds_read_b128 v[220:223], v253 offset:6144
	global_load_lds_dwordx4 v[154:155], off
	v_lshl_add_u64 v[154:155], s[30:31], 0, v[136:137]
	s_add_i32 m0, s52, 0xe000
	s_nop 0
	global_load_lds_dwordx4 v[154:155], off
	s_waitcnt vmcnt(16)
	s_waitcnt lgkmcnt(0)
	s_setprio 1
	s_barrier
	v_mfma_f32_16x16x32_bf16 v[124:127], v[160:163], v[192:195], 0
	v_mfma_f32_16x16x32_bf16 v[124:127], v[164:167], v[196:199], v[124:127]
	v_mfma_f32_16x16x32_bf16 v[116:119], v[168:171], v[192:195], 0
	v_mfma_f32_16x16x32_bf16 v[116:119], v[172:175], v[196:199], v[116:119]
	v_mfma_f32_16x16x32_bf16 v[108:111], v[160:163], v[200:203], 0
	v_mfma_f32_16x16x32_bf16 v[108:111], v[164:167], v[204:207], v[108:111]
	v_mfma_f32_16x16x32_bf16 v[100:103], v[168:171], v[200:203], 0
	v_mfma_f32_16x16x32_bf16 v[100:103], v[172:175], v[204:207], v[100:103]
	v_mfma_f32_16x16x32_bf16 v[92:95], v[160:163], v[208:211], 0
	v_mfma_f32_16x16x32_bf16 v[92:95], v[164:167], v[212:215], v[92:95]
	v_mfma_f32_16x16x32_bf16 v[84:87], v[168:171], v[208:211], 0
	v_mfma_f32_16x16x32_bf16 v[84:87], v[172:175], v[212:215], v[84:87]
	v_mfma_f32_16x16x32_bf16 v[76:79], v[160:163], v[216:219], 0
	v_mfma_f32_16x16x32_bf16 v[76:79], v[164:167], v[220:223], v[76:79]
	v_mfma_f32_16x16x32_bf16 v[68:71], v[168:171], v[216:219], 0
	v_mfma_f32_16x16x32_bf16 v[68:71], v[172:175], v[220:223], v[68:71]
	s_setprio 0
	s_setprio 1
	v_mfma_f32_16x16x32_bf16 v[120:123], v[176:179], v[192:195], 0
	v_mfma_f32_16x16x32_bf16 v[120:123], v[180:183], v[196:199], v[120:123]
	v_mfma_f32_16x16x32_bf16 v[112:115], v[184:187], v[192:195], 0
	v_mfma_f32_16x16x32_bf16 v[112:115], v[188:191], v[196:199], v[112:115]
	v_mfma_f32_16x16x32_bf16 v[104:107], v[176:179], v[200:203], 0
	v_mfma_f32_16x16x32_bf16 v[104:107], v[180:183], v[204:207], v[104:107]
	v_mfma_f32_16x16x32_bf16 v[96:99], v[184:187], v[200:203], 0
	v_mfma_f32_16x16x32_bf16 v[96:99], v[188:191], v[204:207], v[96:99]
	v_mfma_f32_16x16x32_bf16 v[88:91], v[176:179], v[208:211], 0
	v_mfma_f32_16x16x32_bf16 v[88:91], v[180:183], v[212:215], v[88:91]
	v_mfma_f32_16x16x32_bf16 v[80:83], v[184:187], v[208:211], 0
	v_mfma_f32_16x16x32_bf16 v[80:83], v[188:191], v[212:215], v[80:83]
	v_mfma_f32_16x16x32_bf16 v[72:75], v[176:179], v[216:219], 0
	v_mfma_f32_16x16x32_bf16 v[72:75], v[180:183], v[220:223], v[72:75]
	v_mfma_f32_16x16x32_bf16 v[64:67], v[184:187], v[216:219], 0
	v_mfma_f32_16x16x32_bf16 v[64:67], v[188:191], v[220:223], v[64:67]
	s_barrier
	s_setprio 0
	s_add_i32 s71, s61, s49
	v_lshl_add_u64 v[154:155], s[44:45], 0, v[132:133]
	s_mov_b32 m0, s71
	ds_read_b128 v[192:195], v150 offset:16384
	v_xor_b32_e32 v253, 64, v150
	ds_read_b128 v[196:199], v253 offset:16384
	ds_read_b128 v[200:203], v150 offset:18432
	ds_read_b128 v[204:207], v253 offset:18432
	ds_read_b128 v[208:211], v150 offset:20480
	ds_read_b128 v[212:215], v253 offset:20480
	ds_read_b128 v[216:219], v150 offset:22528
	ds_read_b128 v[220:223], v253 offset:22528
	global_load_lds_dwordx4 v[154:155], off
	s_add_i32 m0, s71, 0x2000
	s_add_u32 s72, s44, 0x40000
	v_lshl_add_u64 v[224:225], s[44:45], 0, v[128:129]
	s_addc_u32 s73, s45, 0
	s_add_i32 s71, s62, s49
	global_load_lds_dwordx4 v[224:225], off
	v_lshl_add_u64 v[226:227], s[72:73], 0, v[132:133]
	s_mov_b32 m0, s71
	v_lshl_add_u64 v[228:229], s[46:47], 0, v[130:131]
	global_load_lds_dwordx4 v[226:227], off
	v_lshl_add_u64 v[226:227], s[72:73], 0, v[128:129]
	s_add_i32 m0, s71, 0x2000
	s_nop 0
	global_load_lds_dwordx4 v[226:227], off
	v_lshl_add_u64 v[226:227], s[46:47], 0, v[134:135]
	s_mov_b32 m0, s52
	s_nop 0
	global_load_lds_dwordx4 v[226:227], off
	s_mov_b32 m0, s53
	s_nop 0
	global_load_lds_dwordx4 v[228:229], off
	s_waitcnt vmcnt(16)
	s_waitcnt lgkmcnt(0)
	s_setprio 1
	s_barrier
	v_mfma_f32_16x16x32_bf16 v[60:63], v[160:163], v[192:195], 0
	v_mfma_f32_16x16x32_bf16 v[60:63], v[164:167], v[196:199], v[60:63]
	v_mfma_f32_16x16x32_bf16 v[52:55], v[168:171], v[192:195], 0
	v_mfma_f32_16x16x32_bf16 v[52:55], v[172:175], v[196:199], v[52:55]
	v_mfma_f32_16x16x32_bf16 v[44:47], v[160:163], v[200:203], 0
	v_mfma_f32_16x16x32_bf16 v[44:47], v[164:167], v[204:207], v[44:47]
	v_mfma_f32_16x16x32_bf16 v[36:39], v[168:171], v[200:203], 0
	v_mfma_f32_16x16x32_bf16 v[36:39], v[172:175], v[204:207], v[36:39]
	v_mfma_f32_16x16x32_bf16 v[28:31], v[160:163], v[208:211], 0
	v_mfma_f32_16x16x32_bf16 v[28:31], v[164:167], v[212:215], v[28:31]
	v_mfma_f32_16x16x32_bf16 v[20:23], v[168:171], v[208:211], 0
	v_mfma_f32_16x16x32_bf16 v[20:23], v[172:175], v[212:215], v[20:23]
	v_mfma_f32_16x16x32_bf16 v[12:15], v[160:163], v[216:219], 0
	v_mfma_f32_16x16x32_bf16 v[12:15], v[164:167], v[220:223], v[12:15]
	v_mfma_f32_16x16x32_bf16 v[4:7], v[168:171], v[216:219], 0
	v_mfma_f32_16x16x32_bf16 v[4:7], v[172:175], v[220:223], v[4:7]
	s_setprio 0
	s_setprio 1
	v_mfma_f32_16x16x32_bf16 v[56:59], v[176:179], v[192:195], 0
	v_mfma_f32_16x16x32_bf16 v[56:59], v[180:183], v[196:199], v[56:59]
	v_mfma_f32_16x16x32_bf16 v[48:51], v[184:187], v[192:195], 0
	v_mfma_f32_16x16x32_bf16 v[48:51], v[188:191], v[196:199], v[48:51]
	v_mfma_f32_16x16x32_bf16 v[40:43], v[176:179], v[200:203], 0
	v_mfma_f32_16x16x32_bf16 v[40:43], v[180:183], v[204:207], v[40:43]
	v_mfma_f32_16x16x32_bf16 v[32:35], v[184:187], v[200:203], 0
	v_mfma_f32_16x16x32_bf16 v[32:35], v[188:191], v[204:207], v[32:35]
	v_mfma_f32_16x16x32_bf16 v[24:27], v[176:179], v[208:211], 0
	v_mfma_f32_16x16x32_bf16 v[24:27], v[180:183], v[212:215], v[24:27]
	v_mfma_f32_16x16x32_bf16 v[16:19], v[184:187], v[208:211], 0
	v_mfma_f32_16x16x32_bf16 v[16:19], v[188:191], v[212:215], v[16:19]
	v_mfma_f32_16x16x32_bf16 v[8:11], v[176:179], v[216:219], 0
	v_mfma_f32_16x16x32_bf16 v[8:11], v[180:183], v[220:223], v[8:11]
	v_mfma_f32_16x16x32_bf16 v[0:3], v[184:187], v[216:219], 0
	v_mfma_f32_16x16x32_bf16 v[0:3], v[188:191], v[220:223], v[0:3]
	s_barrier
	s_setprio 0
	s_add_i32 s71, 0, 0x18000
	v_add_u32_e32 v153, s71, v147
	s_add_i32 s72, 0, 0x1c000
	ds_read_b128 v[160:163], v153
	v_xor_b32_e32 v253, 64, v153
	ds_read_b128 v[164:167], v253
	ds_read_b128 v[168:171], v153 offset:2048
	ds_read_b128 v[172:175], v253 offset:2048
	v_add_u32_e32 v153, s72, v147
	ds_read_b128 v[176:179], v153
	v_xor_b32_e32 v253, 64, v153
	ds_read_b128 v[180:183], v253
	ds_read_b128 v[184:187], v153 offset:2048
	ds_read_b128 v[188:191], v253 offset:2048
	s_add_u32 s46, s46, 0x40000
	s_addc_u32 s47, s47, 0
	s_mov_b32 m0, s54
	v_lshl_add_u64 v[230:231], s[46:47], 0, v[134:135]
	ds_read_b128 v[192:195], v150 offset:32768
	v_xor_b32_e32 v253, 64, v150
	ds_read_b128 v[196:199], v253 offset:32768
	ds_read_b128 v[200:203], v150 offset:34816
	ds_read_b128 v[204:207], v253 offset:34816
	ds_read_b128 v[208:211], v150 offset:36864
	ds_read_b128 v[212:215], v253 offset:36864
	ds_read_b128 v[216:219], v150 offset:38912
	ds_read_b128 v[220:223], v253 offset:38912
	global_load_lds_dwordx4 v[230:231], off
	v_lshl_add_u64 v[230:231], s[46:47], 0, v[130:131]
	s_mov_b32 m0, s55
	s_nop 0
	global_load_lds_dwordx4 v[230:231], off
	s_waitcnt vmcnt(8)
	s_waitcnt lgkmcnt(0)
	s_setprio 1
	s_barrier
	v_mfma_f32_16x16x32_bf16 v[124:127], v[160:163], v[192:195], v[124:127]
	v_mfma_f32_16x16x32_bf16 v[124:127], v[164:167], v[196:199], v[124:127]
	v_mfma_f32_16x16x32_bf16 v[116:119], v[172:175], v[196:199], v[116:119]
	v_mfma_f32_16x16x32_bf16 v[116:119], v[168:171], v[192:195], v[116:119]
	v_mfma_f32_16x16x32_bf16 v[100:103], v[168:171], v[200:203], v[100:103]
	v_mfma_f32_16x16x32_bf16 v[100:103], v[172:175], v[204:207], v[100:103]
	v_mfma_f32_16x16x32_bf16 v[108:111], v[164:167], v[204:207], v[108:111]
	v_mfma_f32_16x16x32_bf16 v[108:111], v[160:163], v[200:203], v[108:111]
	v_mfma_f32_16x16x32_bf16 v[92:95], v[160:163], v[208:211], v[92:95]
	v_mfma_f32_16x16x32_bf16 v[92:95], v[164:167], v[212:215], v[92:95]
	v_mfma_f32_16x16x32_bf16 v[84:87], v[172:175], v[212:215], v[84:87]
	v_mfma_f32_16x16x32_bf16 v[84:87], v[168:171], v[208:211], v[84:87]
	v_mfma_f32_16x16x32_bf16 v[68:71], v[168:171], v[216:219], v[68:71]
	v_mfma_f32_16x16x32_bf16 v[68:71], v[172:175], v[220:223], v[68:71]
	v_mfma_f32_16x16x32_bf16 v[76:79], v[164:167], v[220:223], v[76:79]
	v_mfma_f32_16x16x32_bf16 v[76:79], v[160:163], v[216:219], v[76:79]
	s_setprio 0
	s_setprio 1
	v_mfma_f32_16x16x32_bf16 v[120:123], v[176:179], v[192:195], v[120:123]
	v_mfma_f32_16x16x32_bf16 v[120:123], v[180:183], v[196:199], v[120:123]
	v_mfma_f32_16x16x32_bf16 v[112:115], v[188:191], v[196:199], v[112:115]
	v_mfma_f32_16x16x32_bf16 v[112:115], v[184:187], v[192:195], v[112:115]
	v_mfma_f32_16x16x32_bf16 v[96:99], v[184:187], v[200:203], v[96:99]
	v_mfma_f32_16x16x32_bf16 v[96:99], v[188:191], v[204:207], v[96:99]
	v_mfma_f32_16x16x32_bf16 v[104:107], v[180:183], v[204:207], v[104:107]
	v_mfma_f32_16x16x32_bf16 v[104:107], v[176:179], v[200:203], v[104:107]
	v_mfma_f32_16x16x32_bf16 v[88:91], v[176:179], v[208:211], v[88:91]
	v_mfma_f32_16x16x32_bf16 v[88:91], v[180:183], v[212:215], v[88:91]
	v_mfma_f32_16x16x32_bf16 v[80:83], v[188:191], v[212:215], v[80:83]
	v_mfma_f32_16x16x32_bf16 v[80:83], v[184:187], v[208:211], v[80:83]
	v_mfma_f32_16x16x32_bf16 v[64:67], v[184:187], v[216:219], v[64:67]
	v_mfma_f32_16x16x32_bf16 v[64:67], v[188:191], v[220:223], v[64:67]
	v_mfma_f32_16x16x32_bf16 v[72:75], v[180:183], v[220:223], v[72:75]
	v_mfma_f32_16x16x32_bf16 v[72:75], v[176:179], v[216:219], v[72:75]
	s_barrier
	s_setprio 0
	s_add_i32 s46, s71, s49
	v_lshl_add_u64 v[154:155], v[154:155], 0, s[14:15]
	s_mov_b32 m0, s46
	ds_read_b128 v[192:195], v150 offset:49152
	v_xor_b32_e32 v253, 64, v150
	ds_read_b128 v[196:199], v253 offset:49152
	ds_read_b128 v[200:203], v150 offset:51200
	ds_read_b128 v[204:207], v253 offset:51200
	ds_read_b128 v[208:211], v150 offset:53248
	ds_read_b128 v[212:215], v253 offset:53248
	ds_read_b128 v[216:219], v150 offset:55296
	ds_read_b128 v[220:223], v253 offset:55296
	global_load_lds_dwordx4 v[154:155], off
	s_add_i32 m0, s46, 0x2000
	s_add_u32 s44, s44, 0x40080
	v_lshl_add_u64 v[154:155], v[224:225], 0, s[14:15]
	s_addc_u32 s45, s45, 0
	s_add_i32 s46, s72, s49
	global_load_lds_dwordx4 v[154:155], off
	v_lshl_add_u64 v[154:155], s[44:45], 0, v[132:133]
	s_mov_b32 m0, s46
	s_nop 0
	global_load_lds_dwordx4 v[154:155], off
	v_lshl_add_u64 v[154:155], s[44:45], 0, v[128:129]
	s_add_i32 m0, s46, 0x2000
	s_nop 0
	global_load_lds_dwordx4 v[154:155], off
	v_lshl_add_u64 v[154:155], v[226:227], 0, s[14:15]
	s_mov_b32 m0, s57
	s_nop 0
	global_load_lds_dwordx4 v[154:155], off
	v_lshl_add_u64 v[154:155], v[228:229], 0, s[14:15]
	s_mov_b32 m0, s58
	s_nop 0
	global_load_lds_dwordx4 v[154:155], off
	s_waitcnt vmcnt(8)
	s_waitcnt lgkmcnt(0)
	s_setprio 1
	s_barrier
	v_mfma_f32_16x16x32_bf16 v[60:63], v[160:163], v[192:195], v[60:63]
	v_mfma_f32_16x16x32_bf16 v[60:63], v[164:167], v[196:199], v[60:63]
	v_mfma_f32_16x16x32_bf16 v[52:55], v[172:175], v[196:199], v[52:55]
	v_mfma_f32_16x16x32_bf16 v[52:55], v[168:171], v[192:195], v[52:55]
	v_mfma_f32_16x16x32_bf16 v[36:39], v[168:171], v[200:203], v[36:39]
	v_mfma_f32_16x16x32_bf16 v[36:39], v[172:175], v[204:207], v[36:39]
	v_mfma_f32_16x16x32_bf16 v[44:47], v[164:167], v[204:207], v[44:47]
	v_mfma_f32_16x16x32_bf16 v[44:47], v[160:163], v[200:203], v[44:47]
	v_mfma_f32_16x16x32_bf16 v[28:31], v[160:163], v[208:211], v[28:31]
	v_mfma_f32_16x16x32_bf16 v[28:31], v[164:167], v[212:215], v[28:31]
	v_mfma_f32_16x16x32_bf16 v[20:23], v[172:175], v[212:215], v[20:23]
	v_mfma_f32_16x16x32_bf16 v[20:23], v[168:171], v[208:211], v[20:23]
	v_mfma_f32_16x16x32_bf16 v[4:7], v[168:171], v[216:219], v[4:7]
	v_mfma_f32_16x16x32_bf16 v[4:7], v[172:175], v[220:223], v[4:7]
	v_mfma_f32_16x16x32_bf16 v[12:15], v[164:167], v[220:223], v[12:15]
	v_mfma_f32_16x16x32_bf16 v[12:15], v[160:163], v[216:219], v[12:15]
	s_setprio 0
	s_setprio 1
	v_mfma_f32_16x16x32_bf16 v[56:59], v[176:179], v[192:195], v[56:59]
	v_mfma_f32_16x16x32_bf16 v[56:59], v[180:183], v[196:199], v[56:59]
	v_mfma_f32_16x16x32_bf16 v[48:51], v[188:191], v[196:199], v[48:51]
	v_mfma_f32_16x16x32_bf16 v[48:51], v[184:187], v[192:195], v[48:51]
	v_mfma_f32_16x16x32_bf16 v[32:35], v[184:187], v[200:203], v[32:35]
	v_mfma_f32_16x16x32_bf16 v[32:35], v[188:191], v[204:207], v[32:35]
	v_mfma_f32_16x16x32_bf16 v[40:43], v[180:183], v[204:207], v[40:43]
	v_mfma_f32_16x16x32_bf16 v[40:43], v[176:179], v[200:203], v[40:43]
	v_mfma_f32_16x16x32_bf16 v[24:27], v[176:179], v[208:211], v[24:27]
	v_mfma_f32_16x16x32_bf16 v[24:27], v[180:183], v[212:215], v[24:27]
	v_mfma_f32_16x16x32_bf16 v[16:19], v[188:191], v[212:215], v[16:19]
	v_mfma_f32_16x16x32_bf16 v[16:19], v[184:187], v[208:211], v[16:19]
	v_mfma_f32_16x16x32_bf16 v[0:3], v[184:187], v[216:219], v[0:3]
	v_mfma_f32_16x16x32_bf16 v[0:3], v[188:191], v[220:223], v[0:3]
	v_mfma_f32_16x16x32_bf16 v[8:11], v[180:183], v[220:223], v[8:11]
	v_mfma_f32_16x16x32_bf16 v[8:11], v[176:179], v[216:219], v[8:11]
	s_barrier
	s_setprio 0
	s_add_i32 s70, s70, 2
	s_add_u32 s68, s68, 0x100
	s_addc_u32 s69, s69, 0
	s_add_u32 s30, s30, 0x100
	s_addc_u32 s31, s31, 0
	s_branch .LBB0_1098
.Lfa_10:
	v_add_u32_e32 v153, s61, v147
	ds_read_b128 v[160:163], v153
	v_xor_b32_e32 v253, 64, v153
	ds_read_b128 v[164:167], v253
	ds_read_b128 v[168:171], v153 offset:2048
	ds_read_b128 v[172:175], v253 offset:2048
	v_add_u32_e32 v153, s62, v147
	ds_read_b128 v[176:179], v153
	v_xor_b32_e32 v253, 64, v153
	ds_read_b128 v[180:183], v253
	ds_read_b128 v[184:187], v153 offset:2048
	ds_read_b128 v[188:191], v253 offset:2048
	s_add_u32 s46, s30, 0xfffc0080
	s_addc_u32 s47, s31, -1
	s_and_b64 s[44:45], s[44:45], exec
	s_cselect_b32 s47, s25, s47
	s_cselect_b32 s46, s65, s46
	s_cselect_b32 s45, s66, s69
	s_cselect_b32 s44, s67, s68
	v_lshl_add_u64 v[154:155], s[30:31], 0, v[138:139]
	s_add_i32 m0, s52, 0xc000
	ds_read_b128 v[192:195], v150
	v_xor_b32_e32 v253, 64, v150
	ds_read_b128 v[196:199], v253
	ds_read_b128 v[200:203], v150 offset:2048
	ds_read_b128 v[204:207], v253 offset:2048
	ds_read_b128 v[208:211], v150 offset:4096
	ds_read_b128 v[212:215], v253 offset:4096
	ds_read_b128 v[216:219], v150 offset:6144
	ds_read_b128 v[220:223], v253 offset:6144
	global_load_lds_dwordx4 v[154:155], off
	v_lshl_add_u64 v[154:155], s[30:31], 0, v[136:137]
	s_add_i32 m0, s52, 0xe000
	s_nop 0
	global_load_lds_dwordx4 v[154:155], off
	s_waitcnt vmcnt(8)
	s_waitcnt lgkmcnt(0)
	s_setprio 1
	s_barrier
	v_mfma_f32_16x16x32_bf16 v[124:127], v[160:163], v[192:195], 0
	v_mfma_f32_16x16x32_bf16 v[124:127], v[164:167], v[196:199], v[124:127]
	v_mfma_f32_16x16x32_bf16 v[116:119], v[168:171], v[192:195], 0
	v_mfma_f32_16x16x32_bf16 v[116:119], v[172:175], v[196:199], v[116:119]
	v_mfma_f32_16x16x32_bf16 v[108:111], v[160:163], v[200:203], 0
	v_mfma_f32_16x16x32_bf16 v[108:111], v[164:167], v[204:207], v[108:111]
	v_mfma_f32_16x16x32_bf16 v[100:103], v[168:171], v[200:203], 0
	v_mfma_f32_16x16x32_bf16 v[100:103], v[172:175], v[204:207], v[100:103]
	v_mfma_f32_16x16x32_bf16 v[92:95], v[160:163], v[208:211], 0
	v_mfma_f32_16x16x32_bf16 v[92:95], v[164:167], v[212:215], v[92:95]
	v_mfma_f32_16x16x32_bf16 v[84:87], v[168:171], v[208:211], 0
	v_mfma_f32_16x16x32_bf16 v[84:87], v[172:175], v[212:215], v[84:87]
	v_mfma_f32_16x16x32_bf16 v[76:79], v[160:163], v[216:219], 0
	v_mfma_f32_16x16x32_bf16 v[76:79], v[164:167], v[220:223], v[76:79]
	v_mfma_f32_16x16x32_bf16 v[68:71], v[168:171], v[216:219], 0
	v_mfma_f32_16x16x32_bf16 v[68:71], v[172:175], v[220:223], v[68:71]
	s_setprio 0
	s_setprio 1
	v_mfma_f32_16x16x32_bf16 v[120:123], v[176:179], v[192:195], 0
	v_mfma_f32_16x16x32_bf16 v[120:123], v[180:183], v[196:199], v[120:123]
	v_mfma_f32_16x16x32_bf16 v[112:115], v[184:187], v[192:195], 0
	v_mfma_f32_16x16x32_bf16 v[112:115], v[188:191], v[196:199], v[112:115]
	v_mfma_f32_16x16x32_bf16 v[104:107], v[176:179], v[200:203], 0
	v_mfma_f32_16x16x32_bf16 v[104:107], v[180:183], v[204:207], v[104:107]
	v_mfma_f32_16x16x32_bf16 v[96:99], v[184:187], v[200:203], 0
	v_mfma_f32_16x16x32_bf16 v[96:99], v[188:191], v[204:207], v[96:99]
	v_mfma_f32_16x16x32_bf16 v[88:91], v[176:179], v[208:211], 0
	v_mfma_f32_16x16x32_bf16 v[88:91], v[180:183], v[212:215], v[88:91]
	v_mfma_f32_16x16x32_bf16 v[80:83], v[184:187], v[208:211], 0
	v_mfma_f32_16x16x32_bf16 v[80:83], v[188:191], v[212:215], v[80:83]
	v_mfma_f32_16x16x32_bf16 v[72:75], v[176:179], v[216:219], 0
	v_mfma_f32_16x16x32_bf16 v[72:75], v[180:183], v[220:223], v[72:75]
	v_mfma_f32_16x16x32_bf16 v[64:67], v[184:187], v[216:219], 0
	v_mfma_f32_16x16x32_bf16 v[64:67], v[188:191], v[220:223], v[64:67]
	s_barrier
	s_setprio 0
	s_add_i32 s71, s61, s49
	v_lshl_add_u64 v[154:155], s[44:45], 0, v[132:133]
	s_mov_b32 m0, s71
	ds_read_b128 v[192:195], v150 offset:16384
	v_xor_b32_e32 v253, 64, v150
	ds_read_b128 v[196:199], v253 offset:16384
	ds_read_b128 v[200:203], v150 offset:18432
	ds_read_b128 v[204:207], v253 offset:18432
	ds_read_b128 v[208:211], v150 offset:20480
	ds_read_b128 v[212:215], v253 offset:20480
	ds_read_b128 v[216:219], v150 offset:22528
	ds_read_b128 v[220:223], v253 offset:22528
	global_load_lds_dwordx4 v[154:155], off
	s_add_i32 m0, s71, 0x2000
	s_add_u32 s72, s44, 0x40000
	v_lshl_add_u64 v[224:225], s[44:45], 0, v[128:129]
	s_addc_u32 s73, s45, 0
	s_add_i32 s71, s62, s49
	global_load_lds_dwordx4 v[224:225], off
	v_lshl_add_u64 v[226:227], s[72:73], 0, v[132:133]
	s_mov_b32 m0, s71
	v_lshl_add_u64 v[228:229], s[46:47], 0, v[130:131]
	global_load_lds_dwordx4 v[226:227], off
	v_lshl_add_u64 v[226:227], s[72:73], 0, v[128:129]
	s_add_i32 m0, s71, 0x2000
	s_nop 0
	global_load_lds_dwordx4 v[226:227], off
	v_lshl_add_u64 v[226:227], s[46:47], 0, v[134:135]
	s_mov_b32 m0, s52
	s_nop 0
	global_load_lds_dwordx4 v[226:227], off
	s_mov_b32 m0, s53
	s_nop 0
	global_load_lds_dwordx4 v[228:229], off
	s_waitcnt vmcnt(8)
	s_waitcnt lgkmcnt(0)
	s_setprio 1
	s_barrier
	v_mfma_f32_16x16x32_bf16 v[60:63], v[160:163], v[192:195], 0
	v_mfma_f32_16x16x32_bf16 v[60:63], v[164:167], v[196:199], v[60:63]
	v_mfma_f32_16x16x32_bf16 v[52:55], v[168:171], v[192:195], 0
	v_mfma_f32_16x16x32_bf16 v[52:55], v[172:175], v[196:199], v[52:55]
	v_mfma_f32_16x16x32_bf16 v[44:47], v[160:163], v[200:203], 0
	v_mfma_f32_16x16x32_bf16 v[44:47], v[164:167], v[204:207], v[44:47]
	v_mfma_f32_16x16x32_bf16 v[36:39], v[168:171], v[200:203], 0
	v_mfma_f32_16x16x32_bf16 v[36:39], v[172:175], v[204:207], v[36:39]
	v_mfma_f32_16x16x32_bf16 v[28:31], v[160:163], v[208:211], 0
	v_mfma_f32_16x16x32_bf16 v[28:31], v[164:167], v[212:215], v[28:31]
	v_mfma_f32_16x16x32_bf16 v[20:23], v[168:171], v[208:211], 0
	v_mfma_f32_16x16x32_bf16 v[20:23], v[172:175], v[212:215], v[20:23]
	v_mfma_f32_16x16x32_bf16 v[12:15], v[160:163], v[216:219], 0
	v_mfma_f32_16x16x32_bf16 v[12:15], v[164:167], v[220:223], v[12:15]
	v_mfma_f32_16x16x32_bf16 v[4:7], v[168:171], v[216:219], 0
	v_mfma_f32_16x16x32_bf16 v[4:7], v[172:175], v[220:223], v[4:7]
	s_setprio 0
	s_setprio 1
	v_mfma_f32_16x16x32_bf16 v[56:59], v[176:179], v[192:195], 0
	v_mfma_f32_16x16x32_bf16 v[56:59], v[180:183], v[196:199], v[56:59]
	v_mfma_f32_16x16x32_bf16 v[48:51], v[184:187], v[192:195], 0
	v_mfma_f32_16x16x32_bf16 v[48:51], v[188:191], v[196:199], v[48:51]
	v_mfma_f32_16x16x32_bf16 v[40:43], v[176:179], v[200:203], 0
	v_mfma_f32_16x16x32_bf16 v[40:43], v[180:183], v[204:207], v[40:43]
	v_mfma_f32_16x16x32_bf16 v[32:35], v[184:187], v[200:203], 0
	v_mfma_f32_16x16x32_bf16 v[32:35], v[188:191], v[204:207], v[32:35]
	v_mfma_f32_16x16x32_bf16 v[24:27], v[176:179], v[208:211], 0
	v_mfma_f32_16x16x32_bf16 v[24:27], v[180:183], v[212:215], v[24:27]
	v_mfma_f32_16x16x32_bf16 v[16:19], v[184:187], v[208:211], 0
	v_mfma_f32_16x16x32_bf16 v[16:19], v[188:191], v[212:215], v[16:19]
	v_mfma_f32_16x16x32_bf16 v[8:11], v[176:179], v[216:219], 0
	v_mfma_f32_16x16x32_bf16 v[8:11], v[180:183], v[220:223], v[8:11]
	v_mfma_f32_16x16x32_bf16 v[0:3], v[184:187], v[216:219], 0
	v_mfma_f32_16x16x32_bf16 v[0:3], v[188:191], v[220:223], v[0:3]
	s_barrier
	s_setprio 0
	s_add_i32 s71, 0, 0x18000
	v_add_u32_e32 v153, s71, v147
	s_add_i32 s72, 0, 0x1c000
	ds_read_b128 v[160:163], v153
	v_xor_b32_e32 v253, 64, v153
	ds_read_b128 v[164:167], v253
	ds_read_b128 v[168:171], v153 offset:2048
	ds_read_b128 v[172:175], v253 offset:2048
	v_add_u32_e32 v153, s72, v147
	ds_read_b128 v[176:179], v153
	v_xor_b32_e32 v253, 64, v153
	ds_read_b128 v[180:183], v253
	ds_read_b128 v[184:187], v153 offset:2048
	ds_read_b128 v[188:191], v253 offset:2048
	s_add_u32 s46, s46, 0x40000
	s_addc_u32 s47, s47, 0
	s_mov_b32 m0, s54
	v_lshl_add_u64 v[230:231], s[46:47], 0, v[134:135]
	ds_read_b128 v[192:195], v150 offset:32768
	v_xor_b32_e32 v253, 64, v150
	ds_read_b128 v[196:199], v253 offset:32768
	ds_read_b128 v[200:203], v150 offset:34816
	ds_read_b128 v[204:207], v253 offset:34816
	ds_read_b128 v[208:211], v150 offset:36864
	ds_read_b128 v[212:215], v253 offset:36864
	ds_read_b128 v[216:219], v150 offset:38912
	ds_read_b128 v[220:223], v253 offset:38912
	global_load_lds_dwordx4 v[230:231], off
	v_lshl_add_u64 v[230:231], s[46:47], 0, v[130:131]
	s_mov_b32 m0, s55
	s_nop 0
	global_load_lds_dwordx4 v[230:231], off
	s_waitcnt vmcnt(8)
	s_waitcnt lgkmcnt(0)
	s_setprio 1
	s_barrier
	v_mfma_f32_16x16x32_bf16 v[124:127], v[160:163], v[192:195], v[124:127]
	v_mfma_f32_16x16x32_bf16 v[124:127], v[164:167], v[196:199], v[124:127]
	v_mfma_f32_16x16x32_bf16 v[116:119], v[172:175], v[196:199], v[116:119]
	v_mfma_f32_16x16x32_bf16 v[116:119], v[168:171], v[192:195], v[116:119]
	v_mfma_f32_16x16x32_bf16 v[100:103], v[168:171], v[200:203], v[100:103]
	v_mfma_f32_16x16x32_bf16 v[100:103], v[172:175], v[204:207], v[100:103]
	v_mfma_f32_16x16x32_bf16 v[108:111], v[164:167], v[204:207], v[108:111]
	v_mfma_f32_16x16x32_bf16 v[108:111], v[160:163], v[200:203], v[108:111]
	v_mfma_f32_16x16x32_bf16 v[92:95], v[160:163], v[208:211], v[92:95]
	v_mfma_f32_16x16x32_bf16 v[92:95], v[164:167], v[212:215], v[92:95]
	v_mfma_f32_16x16x32_bf16 v[84:87], v[172:175], v[212:215], v[84:87]
	v_mfma_f32_16x16x32_bf16 v[84:87], v[168:171], v[208:211], v[84:87]
	v_mfma_f32_16x16x32_bf16 v[68:71], v[168:171], v[216:219], v[68:71]
	v_mfma_f32_16x16x32_bf16 v[68:71], v[172:175], v[220:223], v[68:71]
	v_mfma_f32_16x16x32_bf16 v[76:79], v[164:167], v[220:223], v[76:79]
	v_mfma_f32_16x16x32_bf16 v[76:79], v[160:163], v[216:219], v[76:79]
	s_setprio 0
	s_setprio 1
	v_mfma_f32_16x16x32_bf16 v[120:123], v[176:179], v[192:195], v[120:123]
	v_mfma_f32_16x16x32_bf16 v[120:123], v[180:183], v[196:199], v[120:123]
	v_mfma_f32_16x16x32_bf16 v[112:115], v[188:191], v[196:199], v[112:115]
	v_mfma_f32_16x16x32_bf16 v[112:115], v[184:187], v[192:195], v[112:115]
	v_mfma_f32_16x16x32_bf16 v[96:99], v[184:187], v[200:203], v[96:99]
	v_mfma_f32_16x16x32_bf16 v[96:99], v[188:191], v[204:207], v[96:99]
	v_mfma_f32_16x16x32_bf16 v[104:107], v[180:183], v[204:207], v[104:107]
	v_mfma_f32_16x16x32_bf16 v[104:107], v[176:179], v[200:203], v[104:107]
	v_mfma_f32_16x16x32_bf16 v[88:91], v[176:179], v[208:211], v[88:91]
	v_mfma_f32_16x16x32_bf16 v[88:91], v[180:183], v[212:215], v[88:91]
	v_mfma_f32_16x16x32_bf16 v[80:83], v[188:191], v[212:215], v[80:83]
	v_mfma_f32_16x16x32_bf16 v[80:83], v[184:187], v[208:211], v[80:83]
	v_mfma_f32_16x16x32_bf16 v[64:67], v[184:187], v[216:219], v[64:67]
	v_mfma_f32_16x16x32_bf16 v[64:67], v[188:191], v[220:223], v[64:67]
	v_mfma_f32_16x16x32_bf16 v[72:75], v[180:183], v[220:223], v[72:75]
	v_mfma_f32_16x16x32_bf16 v[72:75], v[176:179], v[216:219], v[72:75]
	s_barrier
	s_setprio 0
	s_add_i32 s46, s71, s49
	v_lshl_add_u64 v[154:155], v[154:155], 0, s[14:15]
	s_mov_b32 m0, s46
	ds_read_b128 v[192:195], v150 offset:49152
	v_xor_b32_e32 v253, 64, v150
	ds_read_b128 v[196:199], v253 offset:49152
	ds_read_b128 v[200:203], v150 offset:51200
	ds_read_b128 v[204:207], v253 offset:51200
	ds_read_b128 v[208:211], v150 offset:53248
	ds_read_b128 v[212:215], v253 offset:53248
	ds_read_b128 v[216:219], v150 offset:55296
	ds_read_b128 v[220:223], v253 offset:55296
	global_load_lds_dwordx4 v[154:155], off
	s_add_i32 m0, s46, 0x2000
	s_add_u32 s44, s44, 0x40080
	v_lshl_add_u64 v[154:155], v[224:225], 0, s[14:15]
	s_addc_u32 s45, s45, 0
	s_add_i32 s46, s72, s49
	global_load_lds_dwordx4 v[154:155], off
	v_lshl_add_u64 v[154:155], s[44:45], 0, v[132:133]
	s_mov_b32 m0, s46
	s_nop 0
	global_load_lds_dwordx4 v[154:155], off
	v_lshl_add_u64 v[154:155], s[44:45], 0, v[128:129]
	s_add_i32 m0, s46, 0x2000
	s_nop 0
	global_load_lds_dwordx4 v[154:155], off
	v_lshl_add_u64 v[154:155], v[226:227], 0, s[14:15]
	s_mov_b32 m0, s57
	s_nop 0
	global_load_lds_dwordx4 v[154:155], off
	v_lshl_add_u64 v[154:155], v[228:229], 0, s[14:15]
	s_mov_b32 m0, s58
	s_nop 0
	global_load_lds_dwordx4 v[154:155], off
	s_waitcnt vmcnt(8)
	s_waitcnt lgkmcnt(0)
	s_setprio 1
	s_barrier
	v_mfma_f32_16x16x32_bf16 v[60:63], v[160:163], v[192:195], v[60:63]
	v_mfma_f32_16x16x32_bf16 v[60:63], v[164:167], v[196:199], v[60:63]
	v_mfma_f32_16x16x32_bf16 v[52:55], v[172:175], v[196:199], v[52:55]
	v_mfma_f32_16x16x32_bf16 v[52:55], v[168:171], v[192:195], v[52:55]
	v_mfma_f32_16x16x32_bf16 v[36:39], v[168:171], v[200:203], v[36:39]
	v_mfma_f32_16x16x32_bf16 v[36:39], v[172:175], v[204:207], v[36:39]
	v_mfma_f32_16x16x32_bf16 v[44:47], v[164:167], v[204:207], v[44:47]
	v_mfma_f32_16x16x32_bf16 v[44:47], v[160:163], v[200:203], v[44:47]
	v_mfma_f32_16x16x32_bf16 v[28:31], v[160:163], v[208:211], v[28:31]
	v_mfma_f32_16x16x32_bf16 v[28:31], v[164:167], v[212:215], v[28:31]
	v_mfma_f32_16x16x32_bf16 v[20:23], v[172:175], v[212:215], v[20:23]
	v_mfma_f32_16x16x32_bf16 v[20:23], v[168:171], v[208:211], v[20:23]
	v_mfma_f32_16x16x32_bf16 v[4:7], v[168:171], v[216:219], v[4:7]
	v_mfma_f32_16x16x32_bf16 v[4:7], v[172:175], v[220:223], v[4:7]
	v_mfma_f32_16x16x32_bf16 v[12:15], v[164:167], v[220:223], v[12:15]
	v_mfma_f32_16x16x32_bf16 v[12:15], v[160:163], v[216:219], v[12:15]
	s_setprio 0
	s_setprio 1
	v_mfma_f32_16x16x32_bf16 v[56:59], v[176:179], v[192:195], v[56:59]
	v_mfma_f32_16x16x32_bf16 v[56:59], v[180:183], v[196:199], v[56:59]
	v_mfma_f32_16x16x32_bf16 v[48:51], v[188:191], v[196:199], v[48:51]
	v_mfma_f32_16x16x32_bf16 v[48:51], v[184:187], v[192:195], v[48:51]
	v_mfma_f32_16x16x32_bf16 v[32:35], v[184:187], v[200:203], v[32:35]
	v_mfma_f32_16x16x32_bf16 v[32:35], v[188:191], v[204:207], v[32:35]
	v_mfma_f32_16x16x32_bf16 v[40:43], v[180:183], v[204:207], v[40:43]
	v_mfma_f32_16x16x32_bf16 v[40:43], v[176:179], v[200:203], v[40:43]
	v_mfma_f32_16x16x32_bf16 v[24:27], v[176:179], v[208:211], v[24:27]
	v_mfma_f32_16x16x32_bf16 v[24:27], v[180:183], v[212:215], v[24:27]
	v_mfma_f32_16x16x32_bf16 v[16:19], v[188:191], v[212:215], v[16:19]
	v_mfma_f32_16x16x32_bf16 v[16:19], v[184:187], v[208:211], v[16:19]
	v_mfma_f32_16x16x32_bf16 v[0:3], v[184:187], v[216:219], v[0:3]
	v_mfma_f32_16x16x32_bf16 v[0:3], v[188:191], v[220:223], v[0:3]
	v_mfma_f32_16x16x32_bf16 v[8:11], v[180:183], v[220:223], v[8:11]
	v_mfma_f32_16x16x32_bf16 v[8:11], v[176:179], v[216:219], v[8:11]
	s_barrier
	s_setprio 0
	s_add_i32 s70, s70, 2
	s_add_u32 s68, s68, 0x100
	s_addc_u32 s69, s69, 0
	s_add_u32 s30, s30, 0x100
	s_addc_u32 s31, s31, 0
	s_branch .LBB0_1098

.LBB0_1180:
	s_add_u32 s72, s50, 0x100
	s_addc_u32 s73, s51, 0
	s_mov_b32 s74, -2
	s_waitcnt lgkmcnt(0)
	s_cmp_eq_u32 s63, 1
	s_cbranch_scc1 .Lfa_11
	ds_read_b128 v[128:131], v188
	v_xor_b32_e32 v253, 64, v188
	ds_read_b128 v[132:135], v253
	ds_read_b128 v[136:139], v188 offset:2048
	ds_read_b128 v[140:143], v253 offset:2048
	ds_read_b128 v[144:147], v189
	v_xor_b32_e32 v253, 64, v189
	ds_read_b128 v[148:151], v253
	ds_read_b128 v[172:175], v189 offset:2048
	ds_read_b128 v[176:179], v253 offset:2048
	s_add_u32 s50, s48, 0x100
	s_addc_u32 s51, s49, 0
	s_cmp_eq_u32 s74, 40
	s_cselect_b32 s55, s11, s51
	s_cselect_b32 s54, s10, s50
	s_cselect_b32 s53, s47, s73
	s_cselect_b32 s52, s46, s72
	v_lshl_add_u64 v[220:221], s[48:49], 0, v[166:167]
	s_add_i32 m0, s59, 0xc000
	ds_read_b128 v[180:183], v190
	v_xor_b32_e32 v253, 64, v190
	ds_read_b128 v[192:195], v253
	ds_read_b128 v[196:199], v190 offset:2048
	ds_read_b128 v[200:203], v253 offset:2048
	ds_read_b128 v[204:207], v190 offset:4096
	ds_read_b128 v[208:211], v253 offset:4096
	ds_read_b128 v[212:215], v190 offset:6144
	ds_read_b128 v[216:219], v253 offset:6144
	global_load_lds_dwordx4 v[220:221], off
	v_lshl_add_u64 v[220:221], s[48:49], 0, v[164:165]
	s_add_i32 m0, s59, 0xe000
	s_nop 0
	global_load_lds_dwordx4 v[220:221], off
	s_waitcnt vmcnt(24)
	s_waitcnt lgkmcnt(0)
	s_setprio 1
	s_barrier
	v_mfma_f32_16x16x32_bf16 v[124:127], v[128:131], v[180:183], 0
	v_mfma_f32_16x16x32_bf16 v[124:127], v[132:135], v[192:195], v[124:127]
	v_mfma_f32_16x16x32_bf16 v[120:123], v[136:139], v[180:183], 0
	v_mfma_f32_16x16x32_bf16 v[120:123], v[140:143], v[192:195], v[120:123]
	v_mfma_f32_16x16x32_bf16 v[108:111], v[128:131], v[196:199], 0
	v_mfma_f32_16x16x32_bf16 v[108:111], v[132:135], v[200:203], v[108:111]
	v_mfma_f32_16x16x32_bf16 v[104:107], v[136:139], v[196:199], 0
	v_mfma_f32_16x16x32_bf16 v[104:107], v[140:143], v[200:203], v[104:107]
	v_mfma_f32_16x16x32_bf16 v[92:95], v[128:131], v[204:207], 0
	v_mfma_f32_16x16x32_bf16 v[92:95], v[132:135], v[208:211], v[92:95]
	v_mfma_f32_16x16x32_bf16 v[88:91], v[136:139], v[204:207], 0
	v_mfma_f32_16x16x32_bf16 v[88:91], v[140:143], v[208:211], v[88:91]
	v_mfma_f32_16x16x32_bf16 v[76:79], v[128:131], v[212:215], 0
	v_mfma_f32_16x16x32_bf16 v[76:79], v[132:135], v[216:219], v[76:79]
	v_mfma_f32_16x16x32_bf16 v[72:75], v[136:139], v[212:215], 0
	v_mfma_f32_16x16x32_bf16 v[72:75], v[140:143], v[216:219], v[72:75]
	s_setprio 0
	s_setprio 1
	v_mfma_f32_16x16x32_bf16 v[116:119], v[144:147], v[180:183], 0
	v_mfma_f32_16x16x32_bf16 v[116:119], v[148:151], v[192:195], v[116:119]
	v_mfma_f32_16x16x32_bf16 v[112:115], v[172:175], v[180:183], 0
	v_mfma_f32_16x16x32_bf16 v[112:115], v[176:179], v[192:195], v[112:115]
	v_mfma_f32_16x16x32_bf16 v[100:103], v[144:147], v[196:199], 0
	v_mfma_f32_16x16x32_bf16 v[100:103], v[148:151], v[200:203], v[100:103]
	v_mfma_f32_16x16x32_bf16 v[96:99], v[172:175], v[196:199], 0
	v_mfma_f32_16x16x32_bf16 v[96:99], v[176:179], v[200:203], v[96:99]
	v_mfma_f32_16x16x32_bf16 v[84:87], v[144:147], v[204:207], 0
	v_mfma_f32_16x16x32_bf16 v[84:87], v[148:151], v[208:211], v[84:87]
	v_mfma_f32_16x16x32_bf16 v[80:83], v[172:175], v[204:207], 0
	v_mfma_f32_16x16x32_bf16 v[80:83], v[176:179], v[208:211], v[80:83]
	v_mfma_f32_16x16x32_bf16 v[68:71], v[144:147], v[212:215], 0
	v_mfma_f32_16x16x32_bf16 v[68:71], v[148:151], v[216:219], v[68:71]
	v_mfma_f32_16x16x32_bf16 v[64:67], v[172:175], v[212:215], 0
	v_mfma_f32_16x16x32_bf16 v[64:67], v[176:179], v[216:219], v[64:67]
	s_barrier
	s_setprio 0
	s_add_i32 s48, s68, s58
	v_lshl_add_u64 v[220:221], s[52:53], 0, v[154:155]
	s_mov_b32 m0, s48
	ds_read_b128 v[180:183], v190 offset:16384
	v_xor_b32_e32 v253, 64, v190
	ds_read_b128 v[192:195], v253 offset:16384
	ds_read_b128 v[196:199], v190 offset:18432
	ds_read_b128 v[200:203], v253 offset:18432
	ds_read_b128 v[204:207], v190 offset:20480
	ds_read_b128 v[208:211], v253 offset:20480
	ds_read_b128 v[212:215], v190 offset:22528
	ds_read_b128 v[216:219], v253 offset:22528
	global_load_lds_dwordx4 v[220:221], off
	s_add_i32 m0, s48, 0x2000
	s_add_u32 s48, s52, 0xb0000
	v_lshl_add_u64 v[222:223], s[52:53], 0, v[162:163]
	s_addc_u32 s49, s53, 0
	s_add_i32 s75, s69, s58
	global_load_lds_dwordx4 v[222:223], off
	v_lshl_add_u64 v[224:225], s[48:49], 0, v[154:155]
	s_mov_b32 m0, s75
	v_lshl_add_u64 v[226:227], s[54:55], 0, v[160:161]
	global_load_lds_dwordx4 v[224:225], off
	v_lshl_add_u64 v[224:225], s[48:49], 0, v[162:163]
	s_add_i32 m0, s75, 0x2000
	s_nop 0
	global_load_lds_dwordx4 v[224:225], off
	v_lshl_add_u64 v[224:225], s[54:55], 0, v[152:153]
	s_mov_b32 m0, s59
	s_nop 0
	global_load_lds_dwordx4 v[224:225], off
	s_mov_b32 m0, s60
	s_nop 0
	global_load_lds_dwordx4 v[226:227], off
	s_waitcnt vmcnt(24)
	s_waitcnt lgkmcnt(0)
	s_setprio 1
	s_barrier
	v_mfma_f32_16x16x32_bf16 v[60:63], v[128:131], v[180:183], 0
	v_mfma_f32_16x16x32_bf16 v[60:63], v[132:135], v[192:195], v[60:63]
	v_mfma_f32_16x16x32_bf16 v[56:59], v[136:139], v[180:183], 0
	v_mfma_f32_16x16x32_bf16 v[56:59], v[140:143], v[192:195], v[56:59]
	v_mfma_f32_16x16x32_bf16 v[44:47], v[128:131], v[196:199], 0
	v_mfma_f32_16x16x32_bf16 v[44:47], v[132:135], v[200:203], v[44:47]
	v_mfma_f32_16x16x32_bf16 v[40:43], v[136:139], v[196:199], 0
	v_mfma_f32_16x16x32_bf16 v[40:43], v[140:143], v[200:203], v[40:43]
	v_mfma_f32_16x16x32_bf16 v[28:31], v[128:131], v[204:207], 0
	v_mfma_f32_16x16x32_bf16 v[28:31], v[132:135], v[208:211], v[28:31]
	v_mfma_f32_16x16x32_bf16 v[24:27], v[136:139], v[204:207], 0
	v_mfma_f32_16x16x32_bf16 v[24:27], v[140:143], v[208:211], v[24:27]
	v_mfma_f32_16x16x32_bf16 v[12:15], v[128:131], v[212:215], 0
	v_mfma_f32_16x16x32_bf16 v[12:15], v[132:135], v[216:219], v[12:15]
	v_mfma_f32_16x16x32_bf16 v[8:11], v[136:139], v[212:215], 0
	v_mfma_f32_16x16x32_bf16 v[8:11], v[140:143], v[216:219], v[8:11]
	s_setprio 0
	s_setprio 1
	v_mfma_f32_16x16x32_bf16 v[52:55], v[144:147], v[180:183], 0
	v_mfma_f32_16x16x32_bf16 v[52:55], v[148:151], v[192:195], v[52:55]
	v_mfma_f32_16x16x32_bf16 v[48:51], v[172:175], v[180:183], 0
	v_mfma_f32_16x16x32_bf16 v[48:51], v[176:179], v[192:195], v[48:51]
	v_mfma_f32_16x16x32_bf16 v[36:39], v[144:147], v[196:199], 0
	v_mfma_f32_16x16x32_bf16 v[36:39], v[148:151], v[200:203], v[36:39]
	v_mfma_f32_16x16x32_bf16 v[32:35], v[172:175], v[196:199], 0
	v_mfma_f32_16x16x32_bf16 v[32:35], v[176:179], v[200:203], v[32:35]
	v_mfma_f32_16x16x32_bf16 v[20:23], v[144:147], v[204:207], 0
	v_mfma_f32_16x16x32_bf16 v[20:23], v[148:151], v[208:211], v[20:23]
	v_mfma_f32_16x16x32_bf16 v[16:19], v[172:175], v[204:207], 0
	v_mfma_f32_16x16x32_bf16 v[16:19], v[176:179], v[208:211], v[16:19]
	v_mfma_f32_16x16x32_bf16 v[4:7], v[144:147], v[212:215], 0
	v_mfma_f32_16x16x32_bf16 v[4:7], v[148:151], v[216:219], v[4:7]
	v_mfma_f32_16x16x32_bf16 v[0:3], v[172:175], v[212:215], 0
	v_mfma_f32_16x16x32_bf16 v[0:3], v[176:179], v[216:219], v[0:3]
	s_barrier
	s_setprio 0
	s_add_i32 s75, 0, 0x18000
	s_add_i32 s76, 0, 0x1c000
	v_add_u32_e32 v140, s75, v185
	v_add_u32_e32 v176, s76, v185
	ds_read_b128 v[128:131], v140
	v_xor_b32_e32 v253, 64, v140
	ds_read_b128 v[132:135], v253
	ds_read_b128 v[136:139], v140 offset:2048
	ds_read_b128 v[140:143], v253 offset:2048
	ds_read_b128 v[144:147], v176
	v_xor_b32_e32 v253, 64, v176
	ds_read_b128 v[148:151], v253
	ds_read_b128 v[172:175], v176 offset:2048
	ds_read_b128 v[176:179], v253 offset:2048
	s_add_u32 s48, s54, 0xb0000
	s_addc_u32 s49, s55, 0
	s_mov_b32 m0, s61
	v_lshl_add_u64 v[228:229], s[48:49], 0, v[152:153]
	ds_read_b128 v[180:183], v190 offset:32768
	v_xor_b32_e32 v253, 64, v190
	ds_read_b128 v[192:195], v253 offset:32768
	ds_read_b128 v[196:199], v190 offset:34816
	ds_read_b128 v[200:203], v253 offset:34816
	ds_read_b128 v[204:207], v190 offset:36864
	ds_read_b128 v[208:211], v253 offset:36864
	ds_read_b128 v[212:215], v190 offset:38912
	ds_read_b128 v[216:219], v253 offset:38912
	global_load_lds_dwordx4 v[228:229], off
	v_lshl_add_u64 v[228:229], s[48:49], 0, v[160:161]
	s_mov_b32 m0, s62
	s_nop 0
	global_load_lds_dwordx4 v[228:229], off
	s_waitcnt vmcnt(8)
	s_waitcnt lgkmcnt(0)
	s_setprio 1
	s_barrier
	v_mfma_f32_16x16x32_bf16 v[124:127], v[128:131], v[180:183], v[124:127]
	v_mfma_f32_16x16x32_bf16 v[124:127], v[132:135], v[192:195], v[124:127]
	v_mfma_f32_16x16x32_bf16 v[120:123], v[140:143], v[192:195], v[120:123]
	v_mfma_f32_16x16x32_bf16 v[120:123], v[136:139], v[180:183], v[120:123]
	v_mfma_f32_16x16x32_bf16 v[104:107], v[136:139], v[196:199], v[104:107]
	v_mfma_f32_16x16x32_bf16 v[104:107], v[140:143], v[200:203], v[104:107]
	v_mfma_f32_16x16x32_bf16 v[108:111], v[132:135], v[200:203], v[108:111]
	v_mfma_f32_16x16x32_bf16 v[108:111], v[128:131], v[196:199], v[108:111]
	v_mfma_f32_16x16x32_bf16 v[92:95], v[128:131], v[204:207], v[92:95]
	v_mfma_f32_16x16x32_bf16 v[92:95], v[132:135], v[208:211], v[92:95]
	v_mfma_f32_16x16x32_bf16 v[88:91], v[140:143], v[208:211], v[88:91]
	v_mfma_f32_16x16x32_bf16 v[88:91], v[136:139], v[204:207], v[88:91]
	v_mfma_f32_16x16x32_bf16 v[72:75], v[136:139], v[212:215], v[72:75]
	v_mfma_f32_16x16x32_bf16 v[72:75], v[140:143], v[216:219], v[72:75]
	v_mfma_f32_16x16x32_bf16 v[76:79], v[132:135], v[216:219], v[76:79]
	v_mfma_f32_16x16x32_bf16 v[76:79], v[128:131], v[212:215], v[76:79]
	s_setprio 0
	s_setprio 1
	v_mfma_f32_16x16x32_bf16 v[116:119], v[144:147], v[180:183], v[116:119]
	v_mfma_f32_16x16x32_bf16 v[116:119], v[148:151], v[192:195], v[116:119]
	v_mfma_f32_16x16x32_bf16 v[112:115], v[176:179], v[192:195], v[112:115]
	v_mfma_f32_16x16x32_bf16 v[112:115], v[172:175], v[180:183], v[112:115]
	v_mfma_f32_16x16x32_bf16 v[96:99], v[172:175], v[196:199], v[96:99]
	v_mfma_f32_16x16x32_bf16 v[96:99], v[176:179], v[200:203], v[96:99]
	v_mfma_f32_16x16x32_bf16 v[100:103], v[148:151], v[200:203], v[100:103]
	v_mfma_f32_16x16x32_bf16 v[100:103], v[144:147], v[196:199], v[100:103]
	v_mfma_f32_16x16x32_bf16 v[84:87], v[144:147], v[204:207], v[84:87]
	v_mfma_f32_16x16x32_bf16 v[84:87], v[148:151], v[208:211], v[84:87]
	v_mfma_f32_16x16x32_bf16 v[80:83], v[176:179], v[208:211], v[80:83]
	v_mfma_f32_16x16x32_bf16 v[80:83], v[172:175], v[204:207], v[80:83]
	v_mfma_f32_16x16x32_bf16 v[64:67], v[172:175], v[212:215], v[64:67]
	v_mfma_f32_16x16x32_bf16 v[64:67], v[176:179], v[216:219], v[64:67]
	v_mfma_f32_16x16x32_bf16 v[68:71], v[148:151], v[216:219], v[68:71]
	v_mfma_f32_16x16x32_bf16 v[68:71], v[144:147], v[212:215], v[68:71]
	s_barrier
	s_setprio 0
	s_add_i32 s48, s75, s58
	v_lshl_add_u64 v[220:221], v[220:221], 0, s[22:23]
	s_mov_b32 m0, s48
	ds_read_b128 v[180:183], v190 offset:49152
	v_xor_b32_e32 v253, 64, v190
	ds_read_b128 v[192:195], v253 offset:49152
	ds_read_b128 v[196:199], v190 offset:51200
	ds_read_b128 v[200:203], v253 offset:51200
	ds_read_b128 v[204:207], v190 offset:53248
	ds_read_b128 v[208:211], v253 offset:53248
	ds_read_b128 v[212:215], v190 offset:55296
	ds_read_b128 v[216:219], v253 offset:55296
	global_load_lds_dwordx4 v[220:221], off
	s_add_i32 m0, s48, 0x2000
	s_add_u32 s48, s52, 0xb0080
	v_lshl_add_u64 v[220:221], v[222:223], 0, s[22:23]
	s_addc_u32 s49, s53, 0
	s_add_i32 s52, s76, s58
	global_load_lds_dwordx4 v[220:221], off
	v_lshl_add_u64 v[220:221], s[48:49], 0, v[154:155]
	s_mov_b32 m0, s52
	s_nop 0
	global_load_lds_dwordx4 v[220:221], off
	v_lshl_add_u64 v[220:221], s[48:49], 0, v[162:163]
	s_add_i32 m0, s52, 0x2000
	s_nop 0
	global_load_lds_dwordx4 v[220:221], off
	v_lshl_add_u64 v[220:221], v[224:225], 0, s[22:23]
	s_mov_b32 m0, s3
	s_nop 0
	global_load_lds_dwordx4 v[220:221], off
	v_lshl_add_u64 v[220:221], v[226:227], 0, s[22:23]
	s_mov_b32 m0, s64
	s_nop 0
	global_load_lds_dwordx4 v[220:221], off
	s_waitcnt vmcnt(8)
	s_waitcnt lgkmcnt(0)
	s_setprio 1
	s_barrier
	v_mfma_f32_16x16x32_bf16 v[60:63], v[128:131], v[180:183], v[60:63]
	v_mfma_f32_16x16x32_bf16 v[60:63], v[132:135], v[192:195], v[60:63]
	v_mfma_f32_16x16x32_bf16 v[56:59], v[140:143], v[192:195], v[56:59]
	v_mfma_f32_16x16x32_bf16 v[56:59], v[136:139], v[180:183], v[56:59]
	v_mfma_f32_16x16x32_bf16 v[40:43], v[136:139], v[196:199], v[40:43]
	v_mfma_f32_16x16x32_bf16 v[40:43], v[140:143], v[200:203], v[40:43]
	v_mfma_f32_16x16x32_bf16 v[44:47], v[132:135], v[200:203], v[44:47]
	v_mfma_f32_16x16x32_bf16 v[44:47], v[128:131], v[196:199], v[44:47]
	v_mfma_f32_16x16x32_bf16 v[28:31], v[128:131], v[204:207], v[28:31]
	v_mfma_f32_16x16x32_bf16 v[28:31], v[132:135], v[208:211], v[28:31]
	v_mfma_f32_16x16x32_bf16 v[24:27], v[140:143], v[208:211], v[24:27]
	v_mfma_f32_16x16x32_bf16 v[24:27], v[136:139], v[204:207], v[24:27]
	v_mfma_f32_16x16x32_bf16 v[8:11], v[136:139], v[212:215], v[8:11]
	v_mfma_f32_16x16x32_bf16 v[8:11], v[140:143], v[216:219], v[8:11]
	v_mfma_f32_16x16x32_bf16 v[12:15], v[132:135], v[216:219], v[12:15]
	v_mfma_f32_16x16x32_bf16 v[12:15], v[128:131], v[212:215], v[12:15]
	s_setprio 0
	s_setprio 1
	v_mfma_f32_16x16x32_bf16 v[52:55], v[144:147], v[180:183], v[52:55]
	v_mfma_f32_16x16x32_bf16 v[52:55], v[148:151], v[192:195], v[52:55]
	v_mfma_f32_16x16x32_bf16 v[48:51], v[176:179], v[192:195], v[48:51]
	v_mfma_f32_16x16x32_bf16 v[48:51], v[172:175], v[180:183], v[48:51]
	v_mfma_f32_16x16x32_bf16 v[32:35], v[172:175], v[196:199], v[32:35]
	v_mfma_f32_16x16x32_bf16 v[32:35], v[176:179], v[200:203], v[32:35]
	v_mfma_f32_16x16x32_bf16 v[36:39], v[148:151], v[200:203], v[36:39]
	v_mfma_f32_16x16x32_bf16 v[36:39], v[144:147], v[196:199], v[36:39]
	v_mfma_f32_16x16x32_bf16 v[20:23], v[144:147], v[204:207], v[20:23]
	v_mfma_f32_16x16x32_bf16 v[20:23], v[148:151], v[208:211], v[20:23]
	v_mfma_f32_16x16x32_bf16 v[16:19], v[176:179], v[208:211], v[16:19]
	v_mfma_f32_16x16x32_bf16 v[16:19], v[172:175], v[204:207], v[16:19]
	v_mfma_f32_16x16x32_bf16 v[0:3], v[172:175], v[212:215], v[0:3]
	v_mfma_f32_16x16x32_bf16 v[0:3], v[176:179], v[216:219], v[0:3]
	v_mfma_f32_16x16x32_bf16 v[4:7], v[148:151], v[216:219], v[4:7]
	v_mfma_f32_16x16x32_bf16 v[4:7], v[144:147], v[212:215], v[4:7]
	s_barrier
	s_setprio 0
	s_add_i32 s74, s74, 2
	s_add_u32 s72, s72, 0x100
	s_addc_u32 s73, s73, 0
	s_cmp_gt_u32 s74, 41
	s_mov_b64 s[48:49], s[50:51]
	s_branch .LBB0_1181
.Lfa_11:
	ds_read_b128 v[128:131], v188
	v_xor_b32_e32 v253, 64, v188
	ds_read_b128 v[132:135], v253
	ds_read_b128 v[136:139], v188 offset:2048
	ds_read_b128 v[140:143], v253 offset:2048
	ds_read_b128 v[144:147], v189
	v_xor_b32_e32 v253, 64, v189
	ds_read_b128 v[148:151], v253
	ds_read_b128 v[172:175], v189 offset:2048
	ds_read_b128 v[176:179], v253 offset:2048
	s_add_u32 s50, s48, 0x100
	s_addc_u32 s51, s49, 0
	s_cmp_eq_u32 s74, 40
	s_cselect_b32 s55, s11, s51
	s_cselect_b32 s54, s10, s50
	s_cselect_b32 s53, s47, s73
	s_cselect_b32 s52, s46, s72
	v_lshl_add_u64 v[220:221], s[48:49], 0, v[166:167]
	s_add_i32 m0, s59, 0xc000
	ds_read_b128 v[180:183], v190
	v_xor_b32_e32 v253, 64, v190
	ds_read_b128 v[192:195], v253
	ds_read_b128 v[196:199], v190 offset:2048
	ds_read_b128 v[200:203], v253 offset:2048
	ds_read_b128 v[204:207], v190 offset:4096
	ds_read_b128 v[208:211], v253 offset:4096
	ds_read_b128 v[212:215], v190 offset:6144
	ds_read_b128 v[216:219], v253 offset:6144
	global_load_lds_dwordx4 v[220:221], off
	v_lshl_add_u64 v[220:221], s[48:49], 0, v[164:165]
	s_add_i32 m0, s59, 0xe000
	s_nop 0
	global_load_lds_dwordx4 v[220:221], off
	s_waitcnt vmcnt(8)
	s_waitcnt lgkmcnt(0)
	s_setprio 1
	s_barrier
	v_mfma_f32_16x16x32_bf16 v[124:127], v[128:131], v[180:183], 0
	v_mfma_f32_16x16x32_bf16 v[124:127], v[132:135], v[192:195], v[124:127]
	v_mfma_f32_16x16x32_bf16 v[120:123], v[136:139], v[180:183], 0
	v_mfma_f32_16x16x32_bf16 v[120:123], v[140:143], v[192:195], v[120:123]
	v_mfma_f32_16x16x32_bf16 v[108:111], v[128:131], v[196:199], 0
	v_mfma_f32_16x16x32_bf16 v[108:111], v[132:135], v[200:203], v[108:111]
	v_mfma_f32_16x16x32_bf16 v[104:107], v[136:139], v[196:199], 0
	v_mfma_f32_16x16x32_bf16 v[104:107], v[140:143], v[200:203], v[104:107]
	v_mfma_f32_16x16x32_bf16 v[92:95], v[128:131], v[204:207], 0
	v_mfma_f32_16x16x32_bf16 v[92:95], v[132:135], v[208:211], v[92:95]
	v_mfma_f32_16x16x32_bf16 v[88:91], v[136:139], v[204:207], 0
	v_mfma_f32_16x16x32_bf16 v[88:91], v[140:143], v[208:211], v[88:91]
	v_mfma_f32_16x16x32_bf16 v[76:79], v[128:131], v[212:215], 0
	v_mfma_f32_16x16x32_bf16 v[76:79], v[132:135], v[216:219], v[76:79]
	v_mfma_f32_16x16x32_bf16 v[72:75], v[136:139], v[212:215], 0
	v_mfma_f32_16x16x32_bf16 v[72:75], v[140:143], v[216:219], v[72:75]
	s_setprio 0
	s_setprio 1
	v_mfma_f32_16x16x32_bf16 v[116:119], v[144:147], v[180:183], 0
	v_mfma_f32_16x16x32_bf16 v[116:119], v[148:151], v[192:195], v[116:119]
	v_mfma_f32_16x16x32_bf16 v[112:115], v[172:175], v[180:183], 0
	v_mfma_f32_16x16x32_bf16 v[112:115], v[176:179], v[192:195], v[112:115]
	v_mfma_f32_16x16x32_bf16 v[100:103], v[144:147], v[196:199], 0
	v_mfma_f32_16x16x32_bf16 v[100:103], v[148:151], v[200:203], v[100:103]
	v_mfma_f32_16x16x32_bf16 v[96:99], v[172:175], v[196:199], 0
	v_mfma_f32_16x16x32_bf16 v[96:99], v[176:179], v[200:203], v[96:99]
	v_mfma_f32_16x16x32_bf16 v[84:87], v[144:147], v[204:207], 0
	v_mfma_f32_16x16x32_bf16 v[84:87], v[148:151], v[208:211], v[84:87]
	v_mfma_f32_16x16x32_bf16 v[80:83], v[172:175], v[204:207], 0
	v_mfma_f32_16x16x32_bf16 v[80:83], v[176:179], v[208:211], v[80:83]
	v_mfma_f32_16x16x32_bf16 v[68:71], v[144:147], v[212:215], 0
	v_mfma_f32_16x16x32_bf16 v[68:71], v[148:151], v[216:219], v[68:71]
	v_mfma_f32_16x16x32_bf16 v[64:67], v[172:175], v[212:215], 0
	v_mfma_f32_16x16x32_bf16 v[64:67], v[176:179], v[216:219], v[64:67]
	s_barrier
	s_setprio 0
	s_add_i32 s48, s68, s58
	v_lshl_add_u64 v[220:221], s[52:53], 0, v[154:155]
	s_mov_b32 m0, s48
	ds_read_b128 v[180:183], v190 offset:16384
	v_xor_b32_e32 v253, 64, v190
	ds_read_b128 v[192:195], v253 offset:16384
	ds_read_b128 v[196:199], v190 offset:18432
	ds_read_b128 v[200:203], v253 offset:18432
	ds_read_b128 v[204:207], v190 offset:20480
	ds_read_b128 v[208:211], v253 offset:20480
	ds_read_b128 v[212:215], v190 offset:22528
	ds_read_b128 v[216:219], v253 offset:22528
	global_load_lds_dwordx4 v[220:221], off
	s_add_i32 m0, s48, 0x2000
	s_add_u32 s48, s52, 0xb0000
	v_lshl_add_u64 v[222:223], s[52:53], 0, v[162:163]
	s_addc_u32 s49, s53, 0
	s_add_i32 s75, s69, s58
	global_load_lds_dwordx4 v[222:223], off
	v_lshl_add_u64 v[224:225], s[48:49], 0, v[154:155]
	s_mov_b32 m0, s75
	v_lshl_add_u64 v[226:227], s[54:55], 0, v[160:161]
	global_load_lds_dwordx4 v[224:225], off
	v_lshl_add_u64 v[224:225], s[48:49], 0, v[162:163]
	s_add_i32 m0, s75, 0x2000
	s_nop 0
	global_load_lds_dwordx4 v[224:225], off
	v_lshl_add_u64 v[224:225], s[54:55], 0, v[152:153]
	s_mov_b32 m0, s59
	s_nop 0
	global_load_lds_dwordx4 v[224:225], off
	s_mov_b32 m0, s60
	s_nop 0
	global_load_lds_dwordx4 v[226:227], off
	s_waitcnt vmcnt(8)
	s_waitcnt lgkmcnt(0)
	s_setprio 1
	s_barrier
	v_mfma_f32_16x16x32_bf16 v[60:63], v[128:131], v[180:183], 0
	v_mfma_f32_16x16x32_bf16 v[60:63], v[132:135], v[192:195], v[60:63]
	v_mfma_f32_16x16x32_bf16 v[56:59], v[136:139], v[180:183], 0
	v_mfma_f32_16x16x32_bf16 v[56:59], v[140:143], v[192:195], v[56:59]
	v_mfma_f32_16x16x32_bf16 v[44:47], v[128:131], v[196:199], 0
	v_mfma_f32_16x16x32_bf16 v[44:47], v[132:135], v[200:203], v[44:47]
	v_mfma_f32_16x16x32_bf16 v[40:43], v[136:139], v[196:199], 0
	v_mfma_f32_16x16x32_bf16 v[40:43], v[140:143], v[200:203], v[40:43]
	v_mfma_f32_16x16x32_bf16 v[28:31], v[128:131], v[204:207], 0
	v_mfma_f32_16x16x32_bf16 v[28:31], v[132:135], v[208:211], v[28:31]
	v_mfma_f32_16x16x32_bf16 v[24:27], v[136:139], v[204:207], 0
	v_mfma_f32_16x16x32_bf16 v[24:27], v[140:143], v[208:211], v[24:27]
	v_mfma_f32_16x16x32_bf16 v[12:15], v[128:131], v[212:215], 0
	v_mfma_f32_16x16x32_bf16 v[12:15], v[132:135], v[216:219], v[12:15]
	v_mfma_f32_16x16x32_bf16 v[8:11], v[136:139], v[212:215], 0
	v_mfma_f32_16x16x32_bf16 v[8:11], v[140:143], v[216:219], v[8:11]
	s_setprio 0
	s_setprio 1
	v_mfma_f32_16x16x32_bf16 v[52:55], v[144:147], v[180:183], 0
	v_mfma_f32_16x16x32_bf16 v[52:55], v[148:151], v[192:195], v[52:55]
	v_mfma_f32_16x16x32_bf16 v[48:51], v[172:175], v[180:183], 0
	v_mfma_f32_16x16x32_bf16 v[48:51], v[176:179], v[192:195], v[48:51]
	v_mfma_f32_16x16x32_bf16 v[36:39], v[144:147], v[196:199], 0
	v_mfma_f32_16x16x32_bf16 v[36:39], v[148:151], v[200:203], v[36:39]
	v_mfma_f32_16x16x32_bf16 v[32:35], v[172:175], v[196:199], 0
	v_mfma_f32_16x16x32_bf16 v[32:35], v[176:179], v[200:203], v[32:35]
	v_mfma_f32_16x16x32_bf16 v[20:23], v[144:147], v[204:207], 0
	v_mfma_f32_16x16x32_bf16 v[20:23], v[148:151], v[208:211], v[20:23]
	v_mfma_f32_16x16x32_bf16 v[16:19], v[172:175], v[204:207], 0
	v_mfma_f32_16x16x32_bf16 v[16:19], v[176:179], v[208:211], v[16:19]
	v_mfma_f32_16x16x32_bf16 v[4:7], v[144:147], v[212:215], 0
	v_mfma_f32_16x16x32_bf16 v[4:7], v[148:151], v[216:219], v[4:7]
	v_mfma_f32_16x16x32_bf16 v[0:3], v[172:175], v[212:215], 0
	v_mfma_f32_16x16x32_bf16 v[0:3], v[176:179], v[216:219], v[0:3]
	s_barrier
	s_setprio 0
	s_add_i32 s75, 0, 0x18000
	s_add_i32 s76, 0, 0x1c000
	v_add_u32_e32 v140, s75, v185
	v_add_u32_e32 v176, s76, v185
	ds_read_b128 v[128:131], v140
	v_xor_b32_e32 v253, 64, v140
	ds_read_b128 v[132:135], v253
	ds_read_b128 v[136:139], v140 offset:2048
	ds_read_b128 v[140:143], v253 offset:2048
	ds_read_b128 v[144:147], v176
	v_xor_b32_e32 v253, 64, v176
	ds_read_b128 v[148:151], v253
	ds_read_b128 v[172:175], v176 offset:2048
	ds_read_b128 v[176:179], v253 offset:2048
	s_add_u32 s48, s54, 0xb0000
	s_addc_u32 s49, s55, 0
	s_mov_b32 m0, s61
	v_lshl_add_u64 v[228:229], s[48:49], 0, v[152:153]
	ds_read_b128 v[180:183], v190 offset:32768
	v_xor_b32_e32 v253, 64, v190
	ds_read_b128 v[192:195], v253 offset:32768
	ds_read_b128 v[196:199], v190 offset:34816
	ds_read_b128 v[200:203], v253 offset:34816
	ds_read_b128 v[204:207], v190 offset:36864
	ds_read_b128 v[208:211], v253 offset:36864
	ds_read_b128 v[212:215], v190 offset:38912
	ds_read_b128 v[216:219], v253 offset:38912
	global_load_lds_dwordx4 v[228:229], off
	v_lshl_add_u64 v[228:229], s[48:49], 0, v[160:161]
	s_mov_b32 m0, s62
	s_nop 0
	global_load_lds_dwordx4 v[228:229], off
	s_waitcnt vmcnt(8)
	s_waitcnt lgkmcnt(0)
	s_setprio 1
	s_barrier
	v_mfma_f32_16x16x32_bf16 v[124:127], v[128:131], v[180:183], v[124:127]
	v_mfma_f32_16x16x32_bf16 v[124:127], v[132:135], v[192:195], v[124:127]
	v_mfma_f32_16x16x32_bf16 v[120:123], v[140:143], v[192:195], v[120:123]
	v_mfma_f32_16x16x32_bf16 v[120:123], v[136:139], v[180:183], v[120:123]
	v_mfma_f32_16x16x32_bf16 v[104:107], v[136:139], v[196:199], v[104:107]
	v_mfma_f32_16x16x32_bf16 v[104:107], v[140:143], v[200:203], v[104:107]
	v_mfma_f32_16x16x32_bf16 v[108:111], v[132:135], v[200:203], v[108:111]
	v_mfma_f32_16x16x32_bf16 v[108:111], v[128:131], v[196:199], v[108:111]
	v_mfma_f32_16x16x32_bf16 v[92:95], v[128:131], v[204:207], v[92:95]
	v_mfma_f32_16x16x32_bf16 v[92:95], v[132:135], v[208:211], v[92:95]
	v_mfma_f32_16x16x32_bf16 v[88:91], v[140:143], v[208:211], v[88:91]
	v_mfma_f32_16x16x32_bf16 v[88:91], v[136:139], v[204:207], v[88:91]
	v_mfma_f32_16x16x32_bf16 v[72:75], v[136:139], v[212:215], v[72:75]
	v_mfma_f32_16x16x32_bf16 v[72:75], v[140:143], v[216:219], v[72:75]
	v_mfma_f32_16x16x32_bf16 v[76:79], v[132:135], v[216:219], v[76:79]
	v_mfma_f32_16x16x32_bf16 v[76:79], v[128:131], v[212:215], v[76:79]
	s_setprio 0
	s_setprio 1
	v_mfma_f32_16x16x32_bf16 v[116:119], v[144:147], v[180:183], v[116:119]
	v_mfma_f32_16x16x32_bf16 v[116:119], v[148:151], v[192:195], v[116:119]
	v_mfma_f32_16x16x32_bf16 v[112:115], v[176:179], v[192:195], v[112:115]
	v_mfma_f32_16x16x32_bf16 v[112:115], v[172:175], v[180:183], v[112:115]
	v_mfma_f32_16x16x32_bf16 v[96:99], v[172:175], v[196:199], v[96:99]
	v_mfma_f32_16x16x32_bf16 v[96:99], v[176:179], v[200:203], v[96:99]
	v_mfma_f32_16x16x32_bf16 v[100:103], v[148:151], v[200:203], v[100:103]
	v_mfma_f32_16x16x32_bf16 v[100:103], v[144:147], v[196:199], v[100:103]
	v_mfma_f32_16x16x32_bf16 v[84:87], v[144:147], v[204:207], v[84:87]
	v_mfma_f32_16x16x32_bf16 v[84:87], v[148:151], v[208:211], v[84:87]
	v_mfma_f32_16x16x32_bf16 v[80:83], v[176:179], v[208:211], v[80:83]
	v_mfma_f32_16x16x32_bf16 v[80:83], v[172:175], v[204:207], v[80:83]
	v_mfma_f32_16x16x32_bf16 v[64:67], v[172:175], v[212:215], v[64:67]
	v_mfma_f32_16x16x32_bf16 v[64:67], v[176:179], v[216:219], v[64:67]
	v_mfma_f32_16x16x32_bf16 v[68:71], v[148:151], v[216:219], v[68:71]
	v_mfma_f32_16x16x32_bf16 v[68:71], v[144:147], v[212:215], v[68:71]
	s_barrier
	s_setprio 0
	s_add_i32 s48, s75, s58
	v_lshl_add_u64 v[220:221], v[220:221], 0, s[22:23]
	s_mov_b32 m0, s48
	ds_read_b128 v[180:183], v190 offset:49152
	v_xor_b32_e32 v253, 64, v190
	ds_read_b128 v[192:195], v253 offset:49152
	ds_read_b128 v[196:199], v190 offset:51200
	ds_read_b128 v[200:203], v253 offset:51200
	ds_read_b128 v[204:207], v190 offset:53248
	ds_read_b128 v[208:211], v253 offset:53248
	ds_read_b128 v[212:215], v190 offset:55296
	ds_read_b128 v[216:219], v253 offset:55296
	global_load_lds_dwordx4 v[220:221], off
	s_add_i32 m0, s48, 0x2000
	s_add_u32 s48, s52, 0xb0080
	v_lshl_add_u64 v[220:221], v[222:223], 0, s[22:23]
	s_addc_u32 s49, s53, 0
	s_add_i32 s52, s76, s58
	global_load_lds_dwordx4 v[220:221], off
	v_lshl_add_u64 v[220:221], s[48:49], 0, v[154:155]
	s_mov_b32 m0, s52
	s_nop 0
	global_load_lds_dwordx4 v[220:221], off
	v_lshl_add_u64 v[220:221], s[48:49], 0, v[162:163]
	s_add_i32 m0, s52, 0x2000
	s_nop 0
	global_load_lds_dwordx4 v[220:221], off
	v_lshl_add_u64 v[220:221], v[224:225], 0, s[22:23]
	s_mov_b32 m0, s3
	s_nop 0
	global_load_lds_dwordx4 v[220:221], off
	v_lshl_add_u64 v[220:221], v[226:227], 0, s[22:23]
	s_mov_b32 m0, s64
	s_nop 0
	global_load_lds_dwordx4 v[220:221], off
	s_waitcnt vmcnt(8)
	s_waitcnt lgkmcnt(0)
	s_setprio 1
	s_barrier
	v_mfma_f32_16x16x32_bf16 v[60:63], v[128:131], v[180:183], v[60:63]
	v_mfma_f32_16x16x32_bf16 v[60:63], v[132:135], v[192:195], v[60:63]
	v_mfma_f32_16x16x32_bf16 v[56:59], v[140:143], v[192:195], v[56:59]
	v_mfma_f32_16x16x32_bf16 v[56:59], v[136:139], v[180:183], v[56:59]
	v_mfma_f32_16x16x32_bf16 v[40:43], v[136:139], v[196:199], v[40:43]
	v_mfma_f32_16x16x32_bf16 v[40:43], v[140:143], v[200:203], v[40:43]
	v_mfma_f32_16x16x32_bf16 v[44:47], v[132:135], v[200:203], v[44:47]
	v_mfma_f32_16x16x32_bf16 v[44:47], v[128:131], v[196:199], v[44:47]
	v_mfma_f32_16x16x32_bf16 v[28:31], v[128:131], v[204:207], v[28:31]
	v_mfma_f32_16x16x32_bf16 v[28:31], v[132:135], v[208:211], v[28:31]
	v_mfma_f32_16x16x32_bf16 v[24:27], v[140:143], v[208:211], v[24:27]
	v_mfma_f32_16x16x32_bf16 v[24:27], v[136:139], v[204:207], v[24:27]
	v_mfma_f32_16x16x32_bf16 v[8:11], v[136:139], v[212:215], v[8:11]
	v_mfma_f32_16x16x32_bf16 v[8:11], v[140:143], v[216:219], v[8:11]
	v_mfma_f32_16x16x32_bf16 v[12:15], v[132:135], v[216:219], v[12:15]
	v_mfma_f32_16x16x32_bf16 v[12:15], v[128:131], v[212:215], v[12:15]
	s_setprio 0
	s_setprio 1
	v_mfma_f32_16x16x32_bf16 v[52:55], v[144:147], v[180:183], v[52:55]
	v_mfma_f32_16x16x32_bf16 v[52:55], v[148:151], v[192:195], v[52:55]
	v_mfma_f32_16x16x32_bf16 v[48:51], v[176:179], v[192:195], v[48:51]
	v_mfma_f32_16x16x32_bf16 v[48:51], v[172:175], v[180:183], v[48:51]
	v_mfma_f32_16x16x32_bf16 v[32:35], v[172:175], v[196:199], v[32:35]
	v_mfma_f32_16x16x32_bf16 v[32:35], v[176:179], v[200:203], v[32:35]
	v_mfma_f32_16x16x32_bf16 v[36:39], v[148:151], v[200:203], v[36:39]
	v_mfma_f32_16x16x32_bf16 v[36:39], v[144:147], v[196:199], v[36:39]
	v_mfma_f32_16x16x32_bf16 v[20:23], v[144:147], v[204:207], v[20:23]
	v_mfma_f32_16x16x32_bf16 v[20:23], v[148:151], v[208:211], v[20:23]
	v_mfma_f32_16x16x32_bf16 v[16:19], v[176:179], v[208:211], v[16:19]
	v_mfma_f32_16x16x32_bf16 v[16:19], v[172:175], v[204:207], v[16:19]
	v_mfma_f32_16x16x32_bf16 v[0:3], v[172:175], v[212:215], v[0:3]
	v_mfma_f32_16x16x32_bf16 v[0:3], v[176:179], v[216:219], v[0:3]
	v_mfma_f32_16x16x32_bf16 v[4:7], v[148:151], v[216:219], v[4:7]
	v_mfma_f32_16x16x32_bf16 v[4:7], v[144:147], v[212:215], v[4:7]
	s_barrier
	s_setprio 0
	s_add_i32 s74, s74, 2
	s_add_u32 s72, s72, 0x100
	s_addc_u32 s73, s73, 0
	s_cmp_gt_u32 s74, 41
	s_mov_b64 s[48:49], s[50:51]
